# f32->bf16 RNE packing: bit-trick sequences (and/bfe + add3 + and/or/perm) replaced by v_cvt_pk_bf16_f32 where the pair pattern is provably local (227 sites); same rounding
# speedup vs baseline: 1.0105x; 1.0061x over previous
.LBB0_59:
	s_or_b64 exec, exec, s[24:25]
	v_lshl_add_u64 v[44:45], v[18:19], 0, v[128:129]
	global_load_dwordx4 v[92:95], v[44:45], off nt
	global_load_dwordx4 v[96:99], v[44:45], off offset:1024 nt
	global_load_dwordx4 v[100:103], v[44:45], off offset:2048 nt
	global_load_dwordx4 v[104:107], v[44:45], off offset:3072 nt
	global_load_dwordx4 v[108:111], v[2:3], off
	global_load_dwordx4 v[112:115], v[2:3], off offset:1024
	global_load_dwordx4 v[116:119], v[2:3], off offset:2048
	global_load_dwordx4 v[120:123], v[2:3], off offset:3072
	v_lshrrev_b32_e32 v9, 10, v16
	s_movk_i32 s16, 0x1800
	v_lshlrev_b64 v[16:17], 12, v[14:15]
	v_mad_u32_u24 v9, v9, s16, s16
	v_lshl_add_u64 v[46:47], v[4:5], 0, v[16:17]
	v_cndmask_b32_e64 v16, v9, 0, s[36:37]
	v_ashrrev_i32_e32 v17, 31, v16
	s_mov_b64 s[24:25], 0x5801000
	v_lshl_add_u64 v[16:17], v[16:17], 2, s[86:87]
	v_lshl_add_u64 v[48:49], v[16:17], 0, s[24:25]
	v_lshl_add_u64 v[32:33], v[48:49], 0, v[128:129]
	v_lshlrev_b64 v[36:37], 11, v[14:15]
	v_lshl_add_u64 v[50:51], v[6:7], 0, v[36:37]
	global_load_dwordx4 v[132:135], v[32:33], off
	global_load_dwordx4 v[136:139], v[32:33], off offset:1024
	global_load_dwordx4 v[140:143], v[32:33], off offset:2048
	global_load_dwordx4 v[144:147], v[32:33], off offset:3072
	s_waitcnt vmcnt(0)
	global_store_dwordx4 v[46:47], v[92:95], off
	v_pk_mul_f32 v[18:19], v[94:95], v[110:111]
	v_pk_mul_f32 v[16:17], v[92:93], v[108:109]
	v_pk_add_f32 v[34:35], v[134:135], 1.0 op_sel_hi:[1,0]
	v_pk_add_f32 v[32:33], v[132:133], 1.0 op_sel_hi:[1,0]
	v_pk_mul_f32 v[18:19], v[18:19], v[34:35]
	v_pk_mul_f32 v[16:17], v[16:17], v[32:33]
	s_waitcnt lgkmcnt(0)
	v_and_b32_sdwa v11, v16, v170 dst_sel:DWORD dst_unused:UNUSED_PAD src0_sel:WORD_1 src1_sel:DWORD
	v_and_b32_sdwa v27, v17, v170 dst_sel:DWORD dst_unused:UNUSED_PAD src0_sel:WORD_1 src1_sel:DWORD
	v_add3_u32 v11, v16, v11, s56
	v_add3_u32 v16, v17, v27, s56
	v_and_b32_e32 v16, 0xffff0000, v16
	v_cvt_pk_bf16_f32 v17, v18, v19
	v_or_b32_sdwa v16, v16, v11 dst_sel:DWORD dst_unused:UNUSED_PAD src0_sel:DWORD src1_sel:WORD_1
	global_store_dwordx2 v[50:51], v[16:17], off
	v_mov_b32_e32 v9, v129
	v_lshl_add_u64 v[36:37], v[48:49], 0, v[8:9]
	global_store_dwordx4 v[46:47], v[96:99], off offset:1024
	v_pk_mul_f32 v[34:35], v[98:99], v[114:115]
	v_pk_mul_f32 v[32:33], v[96:97], v[112:113]
	v_pk_add_f32 v[38:39], v[138:139], 1.0 op_sel_hi:[1,0]
	v_pk_add_f32 v[36:37], v[136:137], 1.0 op_sel_hi:[1,0]
	v_pk_mul_f32 v[34:35], v[34:35], v[38:39]
	v_pk_mul_f32 v[32:33], v[32:33], v[36:37]
	v_and_b32_sdwa v27, v33, v170 dst_sel:DWORD dst_unused:UNUSED_PAD src0_sel:WORD_1 src1_sel:DWORD
	v_and_b32_sdwa v11, v32, v170 dst_sel:DWORD dst_unused:UNUSED_PAD src0_sel:WORD_1 src1_sel:DWORD
	v_add3_u32 v27, v33, v27, s56
	v_add3_u32 v11, v32, v11, s56
	v_and_b32_e32 v27, 0xffff0000, v27
	v_cvt_pk_bf16_f32 v33, v34, v35
	v_or_b32_sdwa v32, v27, v11 dst_sel:DWORD dst_unused:UNUSED_PAD src0_sel:DWORD src1_sel:WORD_1
	global_store_dwordx2 v[50:51], v[32:33], off offset:512
	v_mov_b32_e32 v11, v129
	v_lshl_add_u64 v[40:41], v[48:49], 0, v[10:11]
	global_store_dwordx4 v[46:47], v[100:103], off offset:2048
	v_pk_mul_f32 v[38:39], v[102:103], v[118:119]
	v_pk_mul_f32 v[36:37], v[100:101], v[116:117]
	v_pk_add_f32 v[42:43], v[142:143], 1.0 op_sel_hi:[1,0]
	v_pk_add_f32 v[40:41], v[140:141], 1.0 op_sel_hi:[1,0]
	v_pk_mul_f32 v[38:39], v[38:39], v[42:43]
	v_pk_mul_f32 v[36:37], v[36:37], v[40:41]
	v_and_b32_sdwa v27, v37, v170 dst_sel:DWORD dst_unused:UNUSED_PAD src0_sel:WORD_1 src1_sel:DWORD
	v_and_b32_sdwa v11, v36, v170 dst_sel:DWORD dst_unused:UNUSED_PAD src0_sel:WORD_1 src1_sel:DWORD
	v_add3_u32 v27, v37, v27, s56
	v_add3_u32 v11, v36, v11, s56
	v_and_b32_e32 v27, 0xffff0000, v27
	v_cvt_pk_bf16_f32 v37, v38, v39
	v_or_b32_sdwa v36, v27, v11 dst_sel:DWORD dst_unused:UNUSED_PAD src0_sel:DWORD src1_sel:WORD_1
	global_store_dwordx2 v[50:51], v[36:37], off offset:1024
	v_mov_b32_e32 v13, v129
	v_lshl_add_u64 v[44:45], v[48:49], 0, v[12:13]
	v_mul_f32_e32 v9, v93, v93
	v_mul_f32_e32 v11, v97, v97
	v_fmac_f32_e32 v9, v92, v92
	v_fmac_f32_e32 v11, v96, v96
	v_fmac_f32_e32 v9, v94, v94
	v_fmac_f32_e32 v11, v98, v98
	v_fmac_f32_e32 v9, v95, v95
	v_fmac_f32_e32 v11, v99, v99
	v_add_f32_e32 v9, v9, v11
	v_mul_f32_e32 v11, v101, v101
	v_fmac_f32_e32 v11, v100, v100
	v_fmac_f32_e32 v11, v102, v102
	v_fmac_f32_e32 v11, v103, v103
	v_add_f32_e32 v9, v9, v11
	global_store_dwordx4 v[46:47], v[104:107], off offset:3072
	v_mul_f32_e32 v11, v105, v105
	v_fmac_f32_e32 v11, v104, v104
	v_fmac_f32_e32 v11, v106, v106
	v_fmac_f32_e32 v11, v107, v107
	v_add_f32_e32 v9, v9, v11
	ds_bpermute_b32 v11, v20, v9
	s_waitcnt lgkmcnt(0)
	v_add_f32_e32 v9, v9, v11
	ds_bpermute_b32 v11, v21, v9
	s_waitcnt lgkmcnt(0)
	v_add_f32_e32 v9, v9, v11
	ds_bpermute_b32 v11, v22, v9
	s_waitcnt lgkmcnt(0)
	v_add_f32_e32 v9, v9, v11
	ds_bpermute_b32 v11, v23, v9
	s_waitcnt lgkmcnt(0)
	v_add_f32_e32 v9, v9, v11
	ds_bpermute_b32 v11, v24, v9
	s_waitcnt lgkmcnt(0)
	v_add_f32_e32 v9, v9, v11
	ds_bpermute_b32 v11, v25, v9
	v_pk_mul_f32 v[16:17], v[106:107], v[122:123]
	v_pk_mul_f32 v[18:19], v[104:105], v[120:121]
	v_pk_add_f32 v[28:29], v[146:147], 1.0 op_sel_hi:[1,0]
	v_pk_add_f32 v[30:31], v[144:145], 1.0 op_sel_hi:[1,0]
	v_pk_mul_f32 v[16:17], v[16:17], v[28:29]
	v_pk_mul_f32 v[18:19], v[18:19], v[30:31]
	v_and_b32_sdwa v13, v16, v170 dst_sel:DWORD dst_unused:UNUSED_PAD src0_sel:WORD_1 src1_sel:DWORD
	v_and_b32_sdwa v28, v17, v170 dst_sel:DWORD dst_unused:UNUSED_PAD src0_sel:WORD_1 src1_sel:DWORD
	v_and_b32_sdwa v29, v19, v170 dst_sel:DWORD dst_unused:UNUSED_PAD src0_sel:WORD_1 src1_sel:DWORD
	v_and_b32_sdwa v27, v18, v170 dst_sel:DWORD dst_unused:UNUSED_PAD src0_sel:WORD_1 src1_sel:DWORD
	v_add3_u32 v13, v16, v13, s56
	v_add3_u32 v16, v17, v28, s56
	v_add3_u32 v17, v19, v29, s56
	v_add3_u32 v18, v18, v27, s56
	v_and_b32_e32 v16, 0xffff0000, v16
	v_and_b32_e32 v19, 0xffff0000, v17
	v_or_b32_sdwa v17, v16, v13 dst_sel:DWORD dst_unused:UNUSED_PAD src0_sel:DWORD src1_sel:WORD_1
	v_or_b32_sdwa v16, v19, v18 dst_sel:DWORD dst_unused:UNUSED_PAD src0_sel:DWORD src1_sel:WORD_1
	global_store_dwordx2 v[50:51], v[16:17], off offset:1536
	s_and_saveexec_b64 s[24:25], vcc
	s_cbranch_execz .LBB0_54
	s_waitcnt lgkmcnt(0)
	v_add_f32_e32 v9, v9, v11
	v_cndmask_b32_e64 v9, 0, v9, s[0:1]
	v_lshl_add_u64 v[14:15], v[14:15], 2, v[0:1]
	global_store_dword v[14:15], v9, off
	s_branch .LBB0_54

.LBB0_82:
	s_or_b64 exec, exec, s[24:25]
	v_add_u32_e32 v66, s2, v142
	v_lshlrev_b32_e32 v65, 2, v66
	v_and_b32_e32 v65, 0xfffff000, v65
	v_or_b32_e32 v64, s27, v147
	v_add_u32_e32 v65, 0xffff9000, v65
	v_cmp_lt_i32_e32 vcc, s13, v66
	s_waitcnt lgkmcnt(0)
	s_barrier
	v_cndmask_b32_e32 v128, 0, v65, vcc
	v_ashrrev_i32_e32 v65, 31, v64
	v_lshl_add_u64 v[68:69], v[128:129], 2, s[0:1]
	s_waitcnt vmcnt(6)
	v_lshlrev_b64 v[100:101], 2, v[64:65]
	s_waitcnt vmcnt(3)
	v_lshl_add_u64 v[110:111], v[68:69], 0, v[100:101]
	global_load_dwordx4 v[96:99], v[110:111], off
	v_readlane_b32 s3, v250, 8
	s_add_i32 s3, s26, s3
	s_cmpk_lt_i32 s3, 0xa00
	s_cselect_b32 s24, s3, s26
	s_ashr_i32 s25, s24, 31
	s_lshr_b32 s25, s25, 25
	s_add_i32 s25, s24, s25
	v_ashrrev_i32_e32 v67, 31, v66
	s_ashr_i32 s26, s25, 7
	s_and_b32 s25, s25, 0xffffff80
	v_lshlrev_b64 v[66:67], 13, v[66:67]
	s_sub_i32 s24, s24, s25
	v_lshlrev_b64 v[108:109], 1, v[64:65]
	v_lshl_add_u64 v[64:65], s[30:31], 0, v[66:67]
	s_lshl_b32 s25, s26, 2
	s_and_b32 s26, s24, 3
	s_ashr_i32 s24, s24, 2
	v_lshl_add_u64 v[114:115], v[64:65], 0, v[108:109]
	v_lshl_add_u32 v64, s24, 7, v130
	v_ashrrev_i32_e32 v65, 31, v64
	v_lshlrev_b64 v[64:65], 11, v[64:65]
	v_lshl_add_u64 v[64:65], v[136:137], 0, v[64:65]
	v_add_co_u32_e32 v84, vcc, s11, v64
	s_or_b32 s25, s26, s25
	s_nop 0
	v_addc_co_u32_e32 v85, vcc, 0, v65, vcc
	v_lshl_add_u32 v66, s25, 7, v130
	v_add_co_u32_e32 v72, vcc, s33, v64
	ds_read_b32 v106, v148
	ds_read_b32 v112, v150
	ds_read_b32 v102, v152
	ds_read_b32 v104, v154
	v_ashrrev_i32_e32 v67, 31, v66
	v_addc_co_u32_e32 v73, vcc, 0, v65, vcc
	v_lshlrev_b64 v[66:67], 11, v[66:67]
	v_add_co_u32_e32 v74, vcc, s59, v64
	v_lshl_add_u64 v[66:67], v[134:135], 0, v[66:67]
	s_nop 0
	v_addc_co_u32_e32 v75, vcc, 0, v65, vcc
	v_add_co_u32_e32 v80, vcc, s11, v66
	s_cmpk_gt_i32 s3, 0x9ff
	s_nop 0
	v_addc_co_u32_e32 v81, vcc, 0, v67, vcc
	v_add_co_u32_e32 v82, vcc, s33, v66
	s_mov_b32 s26, s3
	s_nop 0
	v_addc_co_u32_e32 v83, vcc, 0, v67, vcc
	v_add_co_u32_e32 v86, vcc, s59, v66
	s_waitcnt vmcnt(0) lgkmcnt(3)
	v_pk_fma_f32 v[62:63], v[62:63], v[106:107], v[98:99] op_sel_hi:[1,0,1]
	v_pk_fma_f32 v[60:61], v[60:61], v[106:107], v[96:97] op_sel_hi:[1,0,1]
	v_max_f32_e32 v97, 0, v63
	v_max_f32_e32 v96, 0, v61
	v_max_f32_e32 v60, 0, v60
	v_max_f32_e32 v61, 0, v62
	v_pk_mul_f32 v[62:63], v[96:97], v[96:97]
	v_pk_mul_f32 v[60:61], v[60:61], v[60:61]
	v_addc_co_u32_e32 v87, vcc, 0, v67, vcc
	v_cvt_pk_bf16_f32 v61, v61, v63
	v_cvt_pk_bf16_f32 v60, v60, v62
	global_load_dwordx4 v[68:71], v[66:67], off
	global_load_dwordx4 v[76:79], v[64:65], off
	global_load_dwordx4 v[88:91], v[72:73], off
	global_load_dwordx4 v[92:95], v[74:75], off
	s_nop 0
	global_load_dwordx4 v[64:67], v[80:81], off
	global_load_dwordx4 v[72:75], v[82:83], off
	s_nop 0
	global_load_dwordx4 v[80:83], v[86:87], off
	s_nop 0
	global_load_dwordx4 v[84:87], v[84:85], off
	s_nop 0
	global_store_dwordx2 v[114:115], v[60:61], off
	global_load_dwordx4 v[60:63], v[110:111], off offset:64
	s_waitcnt vmcnt(0)
	v_pk_fma_f32 v[58:59], v[58:59], v[106:107], v[62:63] op_sel_hi:[1,0,1]
	v_pk_fma_f32 v[56:57], v[56:57], v[106:107], v[60:61] op_sel_hi:[1,0,1]
	v_max_f32_e32 v61, 0, v59
	v_max_f32_e32 v60, 0, v57
	v_max_f32_e32 v56, 0, v56
	v_max_f32_e32 v57, 0, v58
	v_pk_mul_f32 v[58:59], v[60:61], v[60:61]
	v_pk_mul_f32 v[56:57], v[56:57], v[56:57]
	v_cvt_pk_bf16_f32 v57, v57, v59
	v_cvt_pk_bf16_f32 v56, v56, v58
	global_store_dwordx2 v[114:115], v[56:57], off offset:32
	global_load_dwordx4 v[56:59], v[110:111], off offset:128
	s_waitcnt vmcnt(0)
	v_pk_fma_f32 v[54:55], v[54:55], v[106:107], v[58:59] op_sel_hi:[1,0,1]
	v_pk_fma_f32 v[52:53], v[52:53], v[106:107], v[56:57] op_sel_hi:[1,0,1]
	v_max_f32_e32 v57, 0, v55
	v_max_f32_e32 v56, 0, v53
	v_max_f32_e32 v52, 0, v52
	v_max_f32_e32 v53, 0, v54
	v_pk_mul_f32 v[54:55], v[56:57], v[56:57]
	v_pk_mul_f32 v[52:53], v[52:53], v[52:53]
	v_cvt_pk_bf16_f32 v53, v53, v55
	v_cvt_pk_bf16_f32 v52, v52, v54
	global_store_dwordx2 v[114:115], v[52:53], off offset:64
	global_load_dwordx4 v[52:55], v[110:111], off offset:192
	v_add_u32_e32 v56, s2, v149
	v_lshlrev_b32_e32 v57, 2, v56
	v_and_b32_e32 v57, 0xfffff000, v57
	v_add_u32_e32 v57, 0xffff9000, v57
	v_cmp_lt_i32_e32 vcc, s13, v56
	s_waitcnt vmcnt(0)
	v_pk_fma_f32 v[50:51], v[50:51], v[106:107], v[54:55] op_sel_hi:[1,0,1]
	v_pk_fma_f32 v[48:49], v[48:49], v[106:107], v[52:53] op_sel_hi:[1,0,1]
	v_max_f32_e32 v53, 0, v51
	v_max_f32_e32 v52, 0, v49
	v_max_f32_e32 v48, 0, v48
	v_max_f32_e32 v49, 0, v50
	v_pk_mul_f32 v[50:51], v[52:53], v[52:53]
	v_pk_mul_f32 v[48:49], v[48:49], v[48:49]
	v_cndmask_b32_e32 v128, 0, v57, vcc
	v_lshl_add_u64 v[58:59], v[128:129], 2, s[0:1]
	v_cvt_pk_bf16_f32 v49, v49, v51
	v_cvt_pk_bf16_f32 v48, v48, v50
	v_lshl_add_u64 v[58:59], v[58:59], 0, v[100:101]
	global_store_dwordx2 v[114:115], v[48:49], off offset:96
	global_load_dwordx4 v[48:51], v[58:59], off
	v_ashrrev_i32_e32 v57, 31, v56
	v_lshlrev_b64 v[52:53], 13, v[56:57]
	v_lshl_add_u64 v[52:53], s[30:31], 0, v[52:53]
	v_lshl_add_u64 v[52:53], v[52:53], 0, v[108:109]
	s_waitcnt vmcnt(0) lgkmcnt(2)
	v_pk_fma_f32 v[46:47], v[46:47], v[112:113], v[50:51] op_sel_hi:[1,0,1]
	v_pk_fma_f32 v[44:45], v[44:45], v[112:113], v[48:49] op_sel_hi:[1,0,1]
	v_max_f32_e32 v49, 0, v47
	v_max_f32_e32 v48, 0, v45
	v_max_f32_e32 v44, 0, v44
	v_max_f32_e32 v45, 0, v46
	v_pk_mul_f32 v[46:47], v[48:49], v[48:49]
	v_pk_mul_f32 v[44:45], v[44:45], v[44:45]
	v_cvt_pk_bf16_f32 v45, v45, v47
	v_cvt_pk_bf16_f32 v44, v44, v46
	global_store_dwordx2 v[52:53], v[44:45], off
	global_load_dwordx4 v[44:47], v[58:59], off offset:64
	s_waitcnt vmcnt(0)
	v_pk_fma_f32 v[42:43], v[42:43], v[112:113], v[46:47] op_sel_hi:[1,0,1]
	v_pk_fma_f32 v[40:41], v[40:41], v[112:113], v[44:45] op_sel_hi:[1,0,1]
	v_max_f32_e32 v45, 0, v43
	v_max_f32_e32 v44, 0, v41
	v_max_f32_e32 v40, 0, v40
	v_max_f32_e32 v41, 0, v42
	v_pk_mul_f32 v[42:43], v[44:45], v[44:45]
	v_pk_mul_f32 v[40:41], v[40:41], v[40:41]
	v_cvt_pk_bf16_f32 v41, v41, v43
	v_cvt_pk_bf16_f32 v40, v40, v42
	global_store_dwordx2 v[52:53], v[40:41], off offset:32
	global_load_dwordx4 v[40:43], v[58:59], off offset:128
	s_waitcnt vmcnt(0)
	v_pk_fma_f32 v[38:39], v[38:39], v[112:113], v[42:43] op_sel_hi:[1,0,1]
	v_pk_fma_f32 v[36:37], v[36:37], v[112:113], v[40:41] op_sel_hi:[1,0,1]
	v_max_f32_e32 v41, 0, v39
	v_max_f32_e32 v40, 0, v37
	v_max_f32_e32 v36, 0, v36
	v_max_f32_e32 v37, 0, v38
	v_pk_mul_f32 v[38:39], v[40:41], v[40:41]
	v_pk_mul_f32 v[36:37], v[36:37], v[36:37]
	v_cvt_pk_bf16_f32 v37, v37, v39
	v_cvt_pk_bf16_f32 v36, v36, v38
	global_store_dwordx2 v[52:53], v[36:37], off offset:64
	global_load_dwordx4 v[36:39], v[58:59], off offset:192
	v_add_u32_e32 v40, s2, v151
	v_lshlrev_b32_e32 v41, 2, v40
	v_and_b32_e32 v41, 0xfffff000, v41
	v_add_u32_e32 v41, 0xffff9000, v41
	v_cmp_lt_i32_e32 vcc, s13, v40
	s_waitcnt vmcnt(0)
	v_pk_fma_f32 v[34:35], v[34:35], v[112:113], v[38:39] op_sel_hi:[1,0,1]
	v_pk_fma_f32 v[32:33], v[32:33], v[112:113], v[36:37] op_sel_hi:[1,0,1]
	v_max_f32_e32 v37, 0, v35
	v_max_f32_e32 v36, 0, v33
	v_max_f32_e32 v32, 0, v32
	v_max_f32_e32 v33, 0, v34
	v_pk_mul_f32 v[34:35], v[36:37], v[36:37]
	v_pk_mul_f32 v[32:33], v[32:33], v[32:33]
	v_cndmask_b32_e32 v128, 0, v41, vcc
	v_lshl_add_u64 v[42:43], v[128:129], 2, s[0:1]
	v_cvt_pk_bf16_f32 v33, v33, v35
	v_cvt_pk_bf16_f32 v32, v32, v34
	v_lshl_add_u64 v[42:43], v[42:43], 0, v[100:101]
	global_store_dwordx2 v[52:53], v[32:33], off offset:96
	global_load_dwordx4 v[34:37], v[42:43], off
	v_ashrrev_i32_e32 v41, 31, v40
	v_lshlrev_b64 v[32:33], 13, v[40:41]
	v_lshl_add_u64 v[32:33], s[30:31], 0, v[32:33]
	v_lshl_add_u64 v[32:33], v[32:33], 0, v[108:109]
	s_waitcnt vmcnt(0) lgkmcnt(1)
	v_pk_fma_f32 v[30:31], v[30:31], v[102:103], v[36:37] op_sel_hi:[1,0,1]
	v_pk_fma_f32 v[28:29], v[28:29], v[102:103], v[34:35] op_sel_hi:[1,0,1]
	v_max_f32_e32 v35, 0, v31
	v_max_f32_e32 v34, 0, v29
	v_max_f32_e32 v28, 0, v28
	v_max_f32_e32 v29, 0, v30
	v_pk_mul_f32 v[30:31], v[34:35], v[34:35]
	v_pk_mul_f32 v[28:29], v[28:29], v[28:29]
	v_cvt_pk_bf16_f32 v29, v29, v31
	v_cvt_pk_bf16_f32 v28, v28, v30
	global_store_dwordx2 v[32:33], v[28:29], off
	global_load_dwordx4 v[28:31], v[42:43], off offset:64
	s_waitcnt vmcnt(0)
	v_pk_fma_f32 v[26:27], v[26:27], v[102:103], v[30:31] op_sel_hi:[1,0,1]
	v_pk_fma_f32 v[24:25], v[24:25], v[102:103], v[28:29] op_sel_hi:[1,0,1]
	v_max_f32_e32 v29, 0, v27
	v_max_f32_e32 v28, 0, v25
	v_max_f32_e32 v24, 0, v24
	v_max_f32_e32 v25, 0, v26
	v_pk_mul_f32 v[26:27], v[28:29], v[28:29]
	v_pk_mul_f32 v[24:25], v[24:25], v[24:25]
	v_cvt_pk_bf16_f32 v25, v25, v27
	v_cvt_pk_bf16_f32 v24, v24, v26
	global_store_dwordx2 v[32:33], v[24:25], off offset:32
	global_load_dwordx4 v[24:27], v[42:43], off offset:128
	s_waitcnt vmcnt(0)
	v_pk_fma_f32 v[22:23], v[22:23], v[102:103], v[26:27] op_sel_hi:[1,0,1]
	v_pk_fma_f32 v[20:21], v[20:21], v[102:103], v[24:25] op_sel_hi:[1,0,1]
	v_max_f32_e32 v25, 0, v23
	v_max_f32_e32 v24, 0, v21
	v_max_f32_e32 v20, 0, v20
	v_max_f32_e32 v21, 0, v22
	v_pk_mul_f32 v[22:23], v[24:25], v[24:25]
	v_pk_mul_f32 v[20:21], v[20:21], v[20:21]
	v_cvt_pk_bf16_f32 v21, v21, v23
	v_cvt_pk_bf16_f32 v20, v20, v22
	global_store_dwordx2 v[32:33], v[20:21], off offset:64
	global_load_dwordx4 v[20:23], v[42:43], off offset:192
	v_add_u32_e32 v24, s2, v153
	v_lshlrev_b32_e32 v25, 2, v24
	v_and_b32_e32 v25, 0xfffff000, v25
	v_add_u32_e32 v25, 0xffff9000, v25
	v_cmp_lt_i32_e32 vcc, s13, v24
	s_waitcnt vmcnt(0)
	v_pk_fma_f32 v[18:19], v[18:19], v[102:103], v[22:23] op_sel_hi:[1,0,1]
	v_pk_fma_f32 v[16:17], v[16:17], v[102:103], v[20:21] op_sel_hi:[1,0,1]
	v_max_f32_e32 v21, 0, v19
	v_max_f32_e32 v20, 0, v17
	v_max_f32_e32 v16, 0, v16
	v_max_f32_e32 v17, 0, v18
	v_pk_mul_f32 v[18:19], v[20:21], v[20:21]
	v_pk_mul_f32 v[16:17], v[16:17], v[16:17]
	v_cndmask_b32_e32 v128, 0, v25, vcc
	v_lshl_add_u64 v[26:27], v[128:129], 2, s[0:1]
	v_cvt_pk_bf16_f32 v17, v17, v19
	v_cvt_pk_bf16_f32 v16, v16, v18
	v_lshl_add_u64 v[26:27], v[26:27], 0, v[100:101]
	global_store_dwordx2 v[32:33], v[16:17], off offset:96
	global_load_dwordx4 v[16:19], v[26:27], off
	v_ashrrev_i32_e32 v25, 31, v24
	v_lshlrev_b64 v[20:21], 13, v[24:25]
	v_lshl_add_u64 v[20:21], s[30:31], 0, v[20:21]
	v_lshl_add_u64 v[20:21], v[20:21], 0, v[108:109]
	s_waitcnt vmcnt(0) lgkmcnt(0)
	v_pk_fma_f32 v[14:15], v[14:15], v[104:105], v[18:19] op_sel_hi:[1,0,1]
	v_pk_fma_f32 v[12:13], v[12:13], v[104:105], v[16:17] op_sel_hi:[1,0,1]
	v_max_f32_e32 v17, 0, v15
	v_max_f32_e32 v16, 0, v13
	v_max_f32_e32 v12, 0, v12
	v_max_f32_e32 v13, 0, v14
	v_pk_mul_f32 v[14:15], v[16:17], v[16:17]
	v_pk_mul_f32 v[12:13], v[12:13], v[12:13]
	v_cvt_pk_bf16_f32 v13, v13, v15
	v_cvt_pk_bf16_f32 v12, v12, v14
	global_store_dwordx2 v[20:21], v[12:13], off
	global_load_dwordx4 v[12:15], v[26:27], off offset:64
	s_waitcnt vmcnt(0)
	v_pk_fma_f32 v[10:11], v[10:11], v[104:105], v[14:15] op_sel_hi:[1,0,1]
	v_pk_fma_f32 v[8:9], v[8:9], v[104:105], v[12:13] op_sel_hi:[1,0,1]
	v_max_f32_e32 v13, 0, v11
	v_max_f32_e32 v12, 0, v9
	v_max_f32_e32 v8, 0, v8
	v_max_f32_e32 v9, 0, v10
	v_pk_mul_f32 v[10:11], v[12:13], v[12:13]
	v_pk_mul_f32 v[8:9], v[8:9], v[8:9]
	v_cvt_pk_bf16_f32 v9, v9, v11
	v_cvt_pk_bf16_f32 v8, v8, v10
	global_store_dwordx2 v[20:21], v[8:9], off offset:32
	global_load_dwordx4 v[8:11], v[26:27], off offset:128
	s_waitcnt vmcnt(0)
	v_pk_fma_f32 v[6:7], v[6:7], v[104:105], v[10:11] op_sel_hi:[1,0,1]
	v_pk_fma_f32 v[4:5], v[4:5], v[104:105], v[8:9] op_sel_hi:[1,0,1]
	v_max_f32_e32 v9, 0, v7
	v_max_f32_e32 v8, 0, v5
	v_max_f32_e32 v4, 0, v4
	v_max_f32_e32 v5, 0, v6
	v_pk_mul_f32 v[6:7], v[8:9], v[8:9]
	v_pk_mul_f32 v[4:5], v[4:5], v[4:5]
	v_cvt_pk_bf16_f32 v5, v5, v7
	v_cvt_pk_bf16_f32 v4, v4, v6
	global_store_dwordx2 v[20:21], v[4:5], off offset:64
	global_load_dwordx4 v[4:7], v[26:27], off offset:192
	s_waitcnt vmcnt(0)
	v_pk_fma_f32 v[2:3], v[2:3], v[104:105], v[6:7] op_sel_hi:[1,0,1]
	v_pk_fma_f32 v[0:1], v[0:1], v[104:105], v[4:5] op_sel_hi:[1,0,1]
	v_max_f32_e32 v5, 0, v3
	v_max_f32_e32 v4, 0, v1
	v_max_f32_e32 v0, 0, v0
	v_max_f32_e32 v1, 0, v2
	v_pk_mul_f32 v[2:3], v[4:5], v[4:5]
	v_pk_mul_f32 v[0:1], v[0:1], v[0:1]
	v_cvt_pk_bf16_f32 v1, v1, v3
	v_cvt_pk_bf16_f32 v0, v0, v2
	global_store_dwordx2 v[20:21], v[0:1], off offset:96
	s_cbranch_scc1 .LBB0_87

.Ltail92:
	s_add_i32 s0, s1, 2
	v_add_u32_e32 v111, v104, v105
	ds_read_b128 v[136:139], v111 offset:16384
	ds_read_b128 v[140:143], v111 offset:18432
	ds_read_b128 v[144:147], v111 offset:20480
	ds_read_b128 v[148:151], v111 offset:22528
	v_add_u32_e32 v110, v103, v105
	ds_read_b128 v[116:119], v110
	s_add_i32 s1, s1, 4
	ds_read_b128 v[120:123], v110 offset:2048
	s_min_u32 s1, s1, 15
	v_add_u32_e32 v113, v104, v114
	s_lshl_b32 s92, s1, 7
	ds_read_b128 v[124:127], v110 offset:4096
	v_add_u32_e32 v112, v103, v114
	ds_read_b128 v[194:197], v113 offset:16384
	ds_read_b128 v[198:201], v113 offset:18432
	ds_read_b128 v[202:205], v113 offset:20480
	ds_read_b128 v[206:209], v113 offset:22528
	v_lshl_add_u64 v[164:165], v[98:99], 0, s[92:93]
	ds_read_b128 v[132:135], v110 offset:6144
	ds_read_b128 v[152:155], v112
	ds_read_b128 v[156:159], v112 offset:2048
	ds_read_b128 v[160:163], v112 offset:4096
	ds_read_b128 v[190:193], v112 offset:6144
	s_waitcnt lgkmcnt(11)
	v_mfma_f32_16x16x32_bf16 v[92:95], v[136:139], v[116:119], v[92:95]
	v_mfma_f32_16x16x32_bf16 v[88:91], v[140:143], v[116:119], v[88:91]
	v_mfma_f32_16x16x32_bf16 v[52:55], v[144:147], v[116:119], v[52:55]
	v_mfma_f32_16x16x32_bf16 v[48:51], v[148:151], v[116:119], v[48:51]
	s_waitcnt vmcnt(7)
	ds_write_b128 v109, v[56:59] offset:32768
	v_add_co_u32_e32 v56, vcc, s11, v164
	s_waitcnt lgkmcnt(11)
	v_mfma_f32_16x16x32_bf16 v[44:47], v[136:139], v[120:123], v[44:47]
	v_addc_co_u32_e32 v57, vcc, 0, v165, vcc
	v_mfma_f32_16x16x32_bf16 v[40:43], v[140:143], v[120:123], v[40:43]
	v_mfma_f32_16x16x32_bf16 v[36:39], v[144:147], v[120:123], v[36:39]
	v_mfma_f32_16x16x32_bf16 v[32:35], v[148:151], v[120:123], v[32:35]
	v_add_co_u32_e32 v56, vcc, s33, v164
	s_waitcnt vmcnt(6)
	ds_write_b128 v109, v[60:63] offset:36864
	s_nop 0
	v_addc_co_u32_e32 v57, vcc, 0, v165, vcc
	s_waitcnt lgkmcnt(11)
	v_mfma_f32_16x16x32_bf16 v[28:31], v[136:139], v[124:127], v[28:31]
	v_mfma_f32_16x16x32_bf16 v[24:27], v[140:143], v[124:127], v[24:27]
	v_mfma_f32_16x16x32_bf16 v[20:23], v[144:147], v[124:127], v[20:23]
	v_mfma_f32_16x16x32_bf16 v[16:19], v[148:151], v[124:127], v[16:19]
	v_add_co_u32_e32 v56, vcc, s59, v164
	s_waitcnt vmcnt(5)
	ds_write_b128 v109, v[64:67] offset:40960
	s_nop 0
	v_addc_co_u32_e32 v57, vcc, 0, v165, vcc
	v_lshl_add_u64 v[64:65], v[100:101], 0, s[92:93]
	v_add_co_u32_e32 v66, vcc, s11, v64
	s_waitcnt lgkmcnt(7)
	v_mfma_f32_16x16x32_bf16 v[12:15], v[136:139], v[132:135], v[12:15]
	v_addc_co_u32_e32 v67, vcc, 0, v65, vcc
	v_mfma_f32_16x16x32_bf16 v[8:11], v[140:143], v[132:135], v[8:11]
	v_mfma_f32_16x16x32_bf16 v[4:7], v[144:147], v[132:135], v[4:7]
	v_mfma_f32_16x16x32_bf16 v[0:3], v[148:151], v[132:135], v[0:3]
	s_waitcnt vmcnt(4)
	ds_write_b128 v109, v[72:75] offset:45056
	s_waitcnt lgkmcnt(7)
	v_mfma_f32_16x16x32_bf16 v[56:59], v[194:197], v[152:155], v[92:95]
	v_mfma_f32_16x16x32_bf16 v[60:63], v[198:201], v[152:155], v[88:91]
	v_mfma_f32_16x16x32_bf16 v[52:55], v[202:205], v[152:155], v[52:55]
	v_mfma_f32_16x16x32_bf16 v[48:51], v[206:209], v[152:155], v[48:51]
	s_waitcnt vmcnt(3)
	ds_write_b128 v109, v[68:71] offset:49152
	s_waitcnt lgkmcnt(7)
	v_mfma_f32_16x16x32_bf16 v[44:47], v[194:197], v[156:159], v[44:47]
	v_mfma_f32_16x16x32_bf16 v[40:43], v[198:201], v[156:159], v[40:43]
	v_mfma_f32_16x16x32_bf16 v[36:39], v[202:205], v[156:159], v[36:39]
	v_mfma_f32_16x16x32_bf16 v[32:35], v[206:209], v[156:159], v[32:35]
	v_add_co_u32_e32 v66, vcc, s33, v64
	s_waitcnt vmcnt(2)
	ds_write_b128 v109, v[76:79] offset:53248
	v_addc_co_u32_e32 v67, vcc, 0, v65, vcc
	v_add_co_u32_e32 v64, vcc, s59, v64
	s_waitcnt lgkmcnt(7)
	v_mfma_f32_16x16x32_bf16 v[28:31], v[194:197], v[160:163], v[28:31]
	v_addc_co_u32_e32 v65, vcc, 0, v65, vcc
	v_mfma_f32_16x16x32_bf16 v[24:27], v[198:201], v[160:163], v[24:27]
	v_mfma_f32_16x16x32_bf16 v[20:23], v[202:205], v[160:163], v[20:23]
	v_mfma_f32_16x16x32_bf16 v[16:19], v[206:209], v[160:163], v[16:19]
	s_waitcnt vmcnt(1)
	ds_write_b128 v109, v[80:83] offset:57344
	s_waitcnt lgkmcnt(7)
	v_mfma_f32_16x16x32_bf16 v[12:15], v[194:197], v[190:193], v[12:15]
	v_mfma_f32_16x16x32_bf16 v[8:11], v[198:201], v[190:193], v[8:11]
	v_mfma_f32_16x16x32_bf16 v[4:7], v[202:205], v[190:193], v[4:7]
	v_mfma_f32_16x16x32_bf16 v[0:3], v[206:209], v[190:193], v[0:3]
	s_waitcnt vmcnt(0)
	ds_write_b128 v109, v[84:87] offset:61440
	s_waitcnt lgkmcnt(0)
	s_barrier
	ds_read_b128 v[84:87], v111 offset:51200
	ds_read_b128 v[80:83], v111 offset:49152
	ds_read_b128 v[88:91], v111 offset:53248
	ds_read_b128 v[92:95], v111 offset:55296
	ds_read_b128 v[64:67], v110 offset:32768
	s_min_u32 s1, s0, 12
	s_lshl_b32 s92, s1, 7
	ds_read_b128 v[68:71], v110 offset:34816
	v_lshl_add_u64 v[164:165], v[98:99], 0, s[92:93]
	ds_read_b128 v[72:75], v110 offset:36864
	ds_read_b128 v[76:79], v110 offset:38912
	ds_read_b128 v[152:155], v112 offset:32768
	ds_read_b128 v[156:159], v112 offset:34816
	ds_read_b128 v[160:163], v112 offset:36864
	ds_read_b128 v[190:193], v112 offset:38912
	ds_read_b128 v[194:197], v113 offset:49152
	ds_read_b128 v[198:201], v113 offset:51200
	ds_read_b128 v[202:205], v113 offset:53248
	ds_read_b128 v[206:209], v113 offset:55296
	s_waitcnt lgkmcnt(11)
	v_mfma_f32_16x16x32_bf16 v[214:217], v[84:87], v[64:67], v[60:63]
	v_mfma_f32_16x16x32_bf16 v[210:213], v[80:83], v[64:67], v[56:59]
	s_nop 1
	v_add_co_u32_e32 v60, vcc, s11, v164
	s_nop 1
	v_addc_co_u32_e32 v61, vcc, 0, v165, vcc
	v_mfma_f32_16x16x32_bf16 v[52:55], v[88:91], v[64:67], v[52:55]
	v_mfma_f32_16x16x32_bf16 v[48:51], v[92:95], v[64:67], v[48:51]
	v_add_co_u32_e32 v64, vcc, s33, v164
	s_nop 0
	v_addc_co_u32_e32 v65, vcc, 0, v165, vcc
	s_waitcnt lgkmcnt(10)
	v_mfma_f32_16x16x32_bf16 v[44:47], v[80:83], v[68:71], v[44:47]
	v_mfma_f32_16x16x32_bf16 v[40:43], v[84:87], v[68:71], v[40:43]
	v_mfma_f32_16x16x32_bf16 v[36:39], v[88:91], v[68:71], v[36:39]
	v_mfma_f32_16x16x32_bf16 v[32:35], v[92:95], v[68:71], v[32:35]
	v_add_co_u32_e32 v68, vcc, s59, v164
	s_waitcnt lgkmcnt(9)
	v_mfma_f32_16x16x32_bf16 v[28:31], v[80:83], v[72:75], v[28:31]
	v_addc_co_u32_e32 v69, vcc, 0, v165, vcc
	v_mfma_f32_16x16x32_bf16 v[24:27], v[84:87], v[72:75], v[24:27]
	v_mfma_f32_16x16x32_bf16 v[20:23], v[88:91], v[72:75], v[20:23]
	v_mfma_f32_16x16x32_bf16 v[16:19], v[92:95], v[72:75], v[16:19]
	s_waitcnt lgkmcnt(8)
	v_mfma_f32_16x16x32_bf16 v[8:11], v[84:87], v[76:79], v[8:11]
	v_lshl_add_u64 v[84:85], v[100:101], 0, s[92:93]
	v_mfma_f32_16x16x32_bf16 v[12:15], v[80:83], v[76:79], v[12:15]
	v_mfma_f32_16x16x32_bf16 v[4:7], v[88:91], v[76:79], v[4:7]
	v_mfma_f32_16x16x32_bf16 v[0:3], v[92:95], v[76:79], v[0:3]
	v_add_co_u32_e32 v76, vcc, s11, v84
	s_nop 0
	v_addc_co_u32_e32 v77, vcc, 0, v85, vcc
	v_add_co_u32_e32 v80, vcc, s33, v84
	v_addc_co_u32_e32 v81, vcc, 0, v85, vcc
	s_waitcnt lgkmcnt(3)
	v_mfma_f32_16x16x32_bf16 v[92:95], v[194:197], v[152:155], v[210:213]
	s_waitcnt lgkmcnt(2)
	v_mfma_f32_16x16x32_bf16 v[88:91], v[198:201], v[152:155], v[214:217]
	s_waitcnt lgkmcnt(1)
	v_mfma_f32_16x16x32_bf16 v[52:55], v[202:205], v[152:155], v[52:55]
	s_waitcnt lgkmcnt(0)
	v_mfma_f32_16x16x32_bf16 v[48:51], v[206:209], v[152:155], v[48:51]
	v_add_co_u32_e32 v84, vcc, s59, v84
	v_addc_co_u32_e32 v85, vcc, 0, v85, vcc
	v_mfma_f32_16x16x32_bf16 v[44:47], v[194:197], v[156:159], v[44:47]
	v_mfma_f32_16x16x32_bf16 v[40:43], v[198:201], v[156:159], v[40:43]
	v_mfma_f32_16x16x32_bf16 v[36:39], v[202:205], v[156:159], v[36:39]
	v_mfma_f32_16x16x32_bf16 v[32:35], v[206:209], v[156:159], v[32:35]
	v_mfma_f32_16x16x32_bf16 v[28:31], v[194:197], v[160:163], v[28:31]
	v_mfma_f32_16x16x32_bf16 v[24:27], v[198:201], v[160:163], v[24:27]
	v_mfma_f32_16x16x32_bf16 v[20:23], v[202:205], v[160:163], v[20:23]
	v_mfma_f32_16x16x32_bf16 v[16:19], v[206:209], v[160:163], v[16:19]
	v_mfma_f32_16x16x32_bf16 v[12:15], v[194:197], v[190:193], v[12:15]
	v_mfma_f32_16x16x32_bf16 v[8:11], v[198:201], v[190:193], v[8:11]
	v_mfma_f32_16x16x32_bf16 v[4:7], v[202:205], v[190:193], v[4:7]
	v_mfma_f32_16x16x32_bf16 v[0:3], v[206:209], v[190:193], v[0:3]
	s_mov_b32 s1, s0
	s_waitcnt lgkmcnt(0)
	s_barrier
	s_mul_i32 s0, s69, 0x12000
	v_readlane_b32 s16, v250, 25
	s_add_u32 s24, s16, s0
	v_readlane_b32 s0, v251, 5
	v_lshlrev_b32_e32 v114, 6, v102
	v_readlane_b32 s17, v250, 26
	s_waitcnt vmcnt(5)
	v_add_u32_e32 v64, s0, v108
	v_readlane_b32 s0, v251, 6
	v_add_u32_e32 v56, 0xffffe000, v64
	v_or_b32_e32 v62, v64, v107
	v_or_b32_e32 v65, s0, v114
	v_lshrrev_b32_e32 v56, 10, v56
	s_movk_i32 s0, 0x1800
	v_mad_u32_u24 v56, v56, s0, s0
	v_cmp_lt_i32_e32 vcc, s13, v62
	s_addc_u32 s25, s17, 0
	v_lshlrev_b32_e32 v115, 2, v97
	v_cndmask_b32_e32 v56, 0, v56, vcc
	s_add_u32 s40, s24, 0x2000
	v_or_b32_e32 v58, v65, v115
	v_ashrrev_i32_e32 v57, 31, v56
	s_addc_u32 s41, s25, 0
	s_waitcnt vmcnt(4)
	v_lshlrev_b64 v[74:75], 2, v[56:57]
	v_ashrrev_i32_e32 v59, 31, v58
	v_ashrrev_i32_e32 v63, 31, v62
	v_lshl_add_u64 v[56:57], s[40:41], 0, v[74:75]
	v_lshlrev_b64 v[60:61], 2, v[58:59]
	v_readlane_b32 s0, v250, 15
	s_waitcnt vmcnt(1)
	v_lshl_add_u64 v[82:83], v[56:57], 0, v[60:61]
	v_lshlrev_b64 v[56:57], 12, v[62:63]
	v_readlane_b32 s1, v250, 16
	v_readlane_b32 s16, v250, 21
	v_lshlrev_b64 v[78:79], 11, v[62:63]
	v_lshl_add_u64 v[56:57], s[0:1], 0, v[56:57]
	s_waitcnt vmcnt(0)
	v_lshl_add_u64 v[84:85], v[56:57], 0, v[60:61]
	global_load_dwordx4 v[116:119], v[82:83], off
	global_load_dwordx4 v[120:123], v[82:83], off offset:64
	global_load_dwordx4 v[124:127], v[82:83], off offset:128
	global_load_dwordx4 v[132:135], v[82:83], off offset:192
	global_load_dwordx4 v[190:193], v[84:85], off
	global_load_dwordx4 v[194:197], v[84:85], off offset:64
	global_load_dwordx4 v[198:201], v[84:85], off offset:128
	global_load_dwordx4 v[202:205], v[84:85], off offset:192
	v_add_co_u32_e32 v164, vcc, 0x10000, v84
	s_nop 1
	v_addc_co_u32_e32 v165, vcc, 0, v85, vcc
	v_add_co_u32_e32 v222, vcc, 0x20000, v84
	s_nop 1
	v_addc_co_u32_e32 v223, vcc, 0, v85, vcc
	v_add_co_u32_e32 v224, vcc, 0x30000, v84
	s_nop 1
	v_addc_co_u32_e32 v225, vcc, 0, v85, vcc
	global_load_dwordx4 v[206:209], v[164:165], off
	global_load_dwordx4 v[210:213], v[164:165], off offset:64
	global_load_dwordx4 v[214:217], v[164:165], off offset:128
	global_load_dwordx4 v[218:221], v[164:165], off offset:192
	s_lshl_b32 s0, s69, 12
	v_readlane_b32 s68, v250, 41
	v_readlane_b32 s72, v250, 45
	v_readlane_b32 s73, v250, 46
	s_add_u32 s0, s72, s0
	s_addc_u32 s1, s73, 0
	s_add_u32 s42, s24, 0x4000
	s_addc_u32 s43, s25, 0
	v_lshl_add_u64 v[74:75], s[42:43], 0, v[74:75]
	v_lshl_add_u64 v[56:57], s[0:1], 0, v[60:61]
	v_lshl_add_u64 v[86:87], v[74:75], 0, v[60:61]
	v_readlane_b32 s17, v250, 22
	v_readlane_b32 s69, v250, 42
	v_readlane_b32 s69, v254, 49
	v_lshl_add_u64 v[78:79], s[16:17], 0, v[78:79]
	s_mul_i32 s24, s69, 0x140000
	s_add_u32 s24, s86, s24
	v_lshrrev_b32_e32 v65, 6, v65
	s_mov_b32 s16, 0xa000
	s_addc_u32 s25, s87, 0
	s_add_u32 s26, s24, 0xaf1a000
	s_addc_u32 s27, s25, 0
	v_cmp_eq_u32_e64 s[36:37], 0, v97
	v_readlane_b32 s70, v250, 43
	v_readlane_b32 s71, v250, 44
	v_readlane_b32 s74, v250, 47
	v_readlane_b32 s75, v250, 48
	v_readlane_b32 s76, v250, 49
	v_readlane_b32 s77, v250, 50
	v_readlane_b32 s78, v250, 51
	v_readlane_b32 s79, v250, 52
	v_readlane_b32 s80, v250, 53
	v_readlane_b32 s81, v250, 54
	v_readlane_b32 s82, v250, 55
	v_readlane_b32 s83, v250, 56
	s_waitcnt vmcnt(4)
	v_pk_fma_f32 v[68:69], v[94:95], v[118:119], v[192:193]
	v_pk_fma_f32 v[66:67], v[92:93], v[116:117], v[190:191]
	global_store_dwordx4 v[84:85], v[66:69], off
	global_load_dwordx4 v[136:139], v[56:57], off
	global_load_dwordx4 v[140:143], v[56:57], off offset:64
	global_load_dwordx4 v[144:147], v[56:57], off offset:128
	global_load_dwordx4 v[148:151], v[56:57], off offset:192
	global_load_dwordx4 v[152:155], v[86:87], off
	global_load_dwordx4 v[156:159], v[86:87], off offset:64
	global_load_dwordx4 v[160:163], v[86:87], off offset:128
	global_load_dwordx4 v[180:183], v[86:87], off offset:192
	v_lshl_add_u64 v[92:93], v[58:59], 1, v[78:79]
	s_waitcnt vmcnt(0)
	v_pk_mul_f32 v[72:73], v[68:69], v[138:139]
	v_pk_mul_f32 v[70:71], v[66:67], v[136:137]
	s_waitcnt vmcnt(0)
	v_pk_add_f32 v[76:77], v[154:155], 1.0 op_sel_hi:[1,0]
	v_pk_add_f32 v[74:75], v[152:153], 1.0 op_sel_hi:[1,0]
	v_pk_mul_f32 v[72:73], v[72:73], v[76:77]
	v_pk_mul_f32 v[70:71], v[70:71], v[74:75]
	v_and_b32_sdwa v76, v73, v170 dst_sel:DWORD dst_unused:UNUSED_PAD src0_sel:WORD_1 src1_sel:DWORD
	v_and_b32_sdwa v77, v71, v170 dst_sel:DWORD dst_unused:UNUSED_PAD src0_sel:WORD_1 src1_sel:DWORD
	v_and_b32_sdwa v74, v72, v170 dst_sel:DWORD dst_unused:UNUSED_PAD src0_sel:WORD_1 src1_sel:DWORD
	v_and_b32_sdwa v75, v70, v170 dst_sel:DWORD dst_unused:UNUSED_PAD src0_sel:WORD_1 src1_sel:DWORD
	v_add3_u32 v73, v73, v76, s56
	v_add3_u32 v71, v71, v77, s56
	v_add3_u32 v70, v70, v75, s56
	v_add3_u32 v72, v72, v74, s56
	v_and_b32_e32 v73, 0xffff0000, v73
	v_and_b32_e32 v74, 0xffff0000, v71
	v_or_b32_sdwa v71, v73, v72 dst_sel:DWORD dst_unused:UNUSED_PAD src0_sel:DWORD src1_sel:WORD_1
	v_or_b32_sdwa v70, v74, v70 dst_sel:DWORD dst_unused:UNUSED_PAD src0_sel:DWORD src1_sel:WORD_1
	global_store_dwordx2 v[92:93], v[70:71], off
	s_nop 0
	s_waitcnt vmcnt(0)
	v_pk_fma_f32 v[72:73], v[90:91], v[122:123], v[196:197]
	v_pk_fma_f32 v[70:71], v[88:89], v[120:121], v[194:195]
	global_store_dwordx4 v[84:85], v[70:73], off offset:64
	v_pk_mul_f32 v[76:77], v[72:73], v[142:143]
	v_pk_mul_f32 v[74:75], v[70:71], v[140:141]
	v_pk_add_f32 v[80:81], v[158:159], 1.0 op_sel_hi:[1,0]
	v_pk_add_f32 v[78:79], v[156:157], 1.0 op_sel_hi:[1,0]
	v_pk_mul_f32 v[76:77], v[76:77], v[80:81]
	v_pk_mul_f32 v[74:75], v[74:75], v[78:79]
	v_and_b32_sdwa v80, v77, v170 dst_sel:DWORD dst_unused:UNUSED_PAD src0_sel:WORD_1 src1_sel:DWORD
	v_and_b32_sdwa v81, v75, v170 dst_sel:DWORD dst_unused:UNUSED_PAD src0_sel:WORD_1 src1_sel:DWORD
	v_and_b32_sdwa v78, v76, v170 dst_sel:DWORD dst_unused:UNUSED_PAD src0_sel:WORD_1 src1_sel:DWORD
	v_and_b32_sdwa v79, v74, v170 dst_sel:DWORD dst_unused:UNUSED_PAD src0_sel:WORD_1 src1_sel:DWORD
	v_add3_u32 v77, v77, v80, s56
	v_add3_u32 v75, v75, v81, s56
	v_add3_u32 v74, v74, v79, s56
	v_add3_u32 v76, v76, v78, s56
	v_and_b32_e32 v77, 0xffff0000, v77
	v_and_b32_e32 v78, 0xffff0000, v75
	v_or_b32_sdwa v75, v77, v76 dst_sel:DWORD dst_unused:UNUSED_PAD src0_sel:DWORD src1_sel:WORD_1
	v_or_b32_sdwa v74, v78, v74 dst_sel:DWORD dst_unused:UNUSED_PAD src0_sel:DWORD src1_sel:WORD_1
	global_store_dwordx2 v[92:93], v[74:75], off offset:32
	s_nop 0
	v_pk_fma_f32 v[54:55], v[54:55], v[126:127], v[200:201]
	v_pk_fma_f32 v[52:53], v[52:53], v[124:125], v[198:199]
	global_store_dwordx4 v[84:85], v[52:55], off offset:128
	v_pk_mul_f32 v[76:77], v[54:55], v[146:147]
	v_pk_mul_f32 v[74:75], v[52:53], v[144:145]
	v_pk_add_f32 v[80:81], v[162:163], 1.0 op_sel_hi:[1,0]
	v_pk_add_f32 v[78:79], v[160:161], 1.0 op_sel_hi:[1,0]
	v_pk_mul_f32 v[76:77], v[76:77], v[80:81]
	v_pk_mul_f32 v[74:75], v[74:75], v[78:79]
	v_and_b32_sdwa v80, v77, v170 dst_sel:DWORD dst_unused:UNUSED_PAD src0_sel:WORD_1 src1_sel:DWORD
	v_and_b32_sdwa v81, v75, v170 dst_sel:DWORD dst_unused:UNUSED_PAD src0_sel:WORD_1 src1_sel:DWORD
	v_and_b32_sdwa v78, v76, v170 dst_sel:DWORD dst_unused:UNUSED_PAD src0_sel:WORD_1 src1_sel:DWORD
	v_and_b32_sdwa v79, v74, v170 dst_sel:DWORD dst_unused:UNUSED_PAD src0_sel:WORD_1 src1_sel:DWORD
	v_add3_u32 v77, v77, v80, s56
	v_add3_u32 v75, v75, v81, s56
	v_add3_u32 v74, v74, v79, s56
	v_add3_u32 v76, v76, v78, s56
	v_and_b32_e32 v77, 0xffff0000, v77
	v_and_b32_e32 v78, 0xffff0000, v75
	v_or_b32_sdwa v75, v77, v76 dst_sel:DWORD dst_unused:UNUSED_PAD src0_sel:DWORD src1_sel:WORD_1
	v_or_b32_sdwa v74, v78, v74 dst_sel:DWORD dst_unused:UNUSED_PAD src0_sel:DWORD src1_sel:WORD_1
	global_store_dwordx2 v[92:93], v[74:75], off offset:64
	s_nop 0
	v_pk_fma_f32 v[76:77], v[50:51], v[134:135], v[204:205]
	v_pk_fma_f32 v[74:75], v[48:49], v[132:133], v[202:203]
	global_store_dwordx4 v[84:85], v[74:77], off offset:192
	s_nop 0
	v_mbcnt_lo_u32_b32 v48, -1, 0
	v_mbcnt_hi_u32_b32 v48, -1, v48
	v_and_b32_e32 v50, 64, v48
	v_xor_b32_e32 v49, 16, v48
	v_add_u32_e32 v50, 64, v50
	v_xor_b32_e32 v51, 32, v48
	v_cmp_lt_i32_e32 vcc, v49, v50
	s_nop 1
	v_cndmask_b32_e32 v49, v48, v49, vcc
	v_cmp_lt_i32_e32 vcc, v51, v50
	v_lshlrev_b32_e32 v105, 2, v49
	s_nop 0
	v_cndmask_b32_e32 v50, v48, v51, vcc
	v_lshlrev_b32_e32 v104, 2, v50
	v_mul_f32_e32 v50, v67, v67
	v_mul_f32_e32 v51, v71, v71
	v_fmac_f32_e32 v50, v66, v66
	v_fmac_f32_e32 v51, v70, v70
	v_fmac_f32_e32 v50, v68, v68
	v_fmac_f32_e32 v51, v72, v72
	v_fmac_f32_e32 v50, v69, v69
	v_fmac_f32_e32 v51, v73, v73
	v_add_f32_e32 v50, v50, v51
	v_mul_f32_e32 v51, v53, v53
	v_fmac_f32_e32 v51, v52, v52
	v_fmac_f32_e32 v51, v54, v54
	v_fmac_f32_e32 v51, v55, v55
	v_add_f32_e32 v50, v50, v51
	v_mul_f32_e32 v51, v75, v75
	v_fmac_f32_e32 v51, v74, v74
	v_fmac_f32_e32 v51, v76, v76
	v_fmac_f32_e32 v51, v77, v77
	v_add_f32_e32 v50, v50, v51
	ds_bpermute_b32 v51, v105, v50
	v_mul_lo_u32 v48, v65, s16
	v_ashrrev_i32_e32 v49, 31, v48
	v_lshl_add_u64 v[48:49], s[26:27], 0, v[48:49]
	v_lshl_add_u64 v[48:49], v[62:63], 2, v[48:49]
	s_waitcnt lgkmcnt(0)
	v_add_f32_e32 v50, v50, v51
	ds_bpermute_b32 v51, v104, v50
	v_pk_mul_f32 v[52:53], v[76:77], v[150:151]
	v_pk_mul_f32 v[54:55], v[74:75], v[148:149]
	v_pk_add_f32 v[66:67], v[182:183], 1.0 op_sel_hi:[1,0]
	v_pk_add_f32 v[68:69], v[180:181], 1.0 op_sel_hi:[1,0]
	v_pk_mul_f32 v[52:53], v[52:53], v[66:67]
	v_pk_mul_f32 v[54:55], v[54:55], v[68:69]
	v_cvt_pk_bf16_f32 v53, v52, v53
	v_cvt_pk_bf16_f32 v52, v54, v55
	global_store_dwordx2 v[92:93], v[52:53], off offset:96
	s_and_saveexec_b64 s[24:25], s[36:37]
	s_cbranch_execz .LBB0_95
	s_waitcnt lgkmcnt(0)
	v_add_f32_e32 v50, v50, v51
	global_store_dword v[48:49], v50, off
.LBB0_95:
	s_or_b64 exec, exec, s[24:25]
	v_add_u32_e32 v50, 0xffffe010, v64
	v_or_b32_e32 v54, 16, v62
	v_lshrrev_b32_e32 v50, 10, v50
	s_movk_i32 s5, 0x1800
	s_movk_i32 s13, 0x1fff
	v_mad_u32_u24 v50, v50, s5, s5
	v_cmp_lt_i32_e32 vcc, s13, v54
	v_ashrrev_i32_e32 v55, 31, v54
	v_readlane_b32 s16, v250, 15
	v_cndmask_b32_e32 v50, 0, v50, vcc
	s_waitcnt lgkmcnt(0)
	v_ashrrev_i32_e32 v51, 31, v50
	v_lshlrev_b64 v[70:71], 2, v[50:51]
	v_lshl_add_u64 v[50:51], s[40:41], 0, v[70:71]
	v_lshl_add_u64 v[72:73], v[50:51], 0, v[60:61]
	v_lshlrev_b64 v[50:51], 12, v[54:55]
	v_readlane_b32 s17, v250, 16
	v_lshl_add_u64 v[70:71], s[42:43], 0, v[70:71]
	v_lshl_add_u64 v[70:71], v[70:71], 0, v[60:61]
	v_lshl_add_u64 v[50:51], s[16:17], 0, v[50:51]
	v_lshl_add_u64 v[74:75], v[50:51], 0, v[60:61]
	v_readlane_b32 s16, v250, 21
	v_lshlrev_b64 v[54:55], 11, v[54:55]
	v_readlane_b32 s17, v250, 22
	global_load_dwordx4 v[190:193], v[222:223], off
	global_load_dwordx4 v[194:197], v[222:223], off offset:64
	global_load_dwordx4 v[198:201], v[222:223], off offset:128
	global_load_dwordx4 v[202:205], v[222:223], off offset:192
	s_waitcnt vmcnt(20)
	v_pk_fma_f32 v[46:47], v[46:47], v[118:119], v[208:209]
	v_pk_fma_f32 v[44:45], v[44:45], v[116:117], v[206:207]
	global_store_dwordx4 v[74:75], v[44:47], off
	v_lshl_add_u64 v[54:55], s[16:17], 0, v[54:55]
	v_lshl_add_u64 v[54:55], v[58:59], 1, v[54:55]
	v_pk_mul_f32 v[52:53], v[46:47], v[138:139]
	v_pk_mul_f32 v[50:51], v[44:45], v[136:137]
	v_pk_add_f32 v[68:69], v[154:155], 1.0 op_sel_hi:[1,0]
	v_pk_add_f32 v[66:67], v[152:153], 1.0 op_sel_hi:[1,0]
	v_pk_mul_f32 v[52:53], v[52:53], v[68:69]
	v_pk_mul_f32 v[50:51], v[50:51], v[66:67]
	v_and_b32_sdwa v66, v53, v170 dst_sel:DWORD dst_unused:UNUSED_PAD src0_sel:WORD_1 src1_sel:DWORD
	v_and_b32_sdwa v67, v51, v170 dst_sel:DWORD dst_unused:UNUSED_PAD src0_sel:WORD_1 src1_sel:DWORD
	v_and_b32_sdwa v63, v52, v170 dst_sel:DWORD dst_unused:UNUSED_PAD src0_sel:WORD_1 src1_sel:DWORD
	v_and_b32_sdwa v65, v50, v170 dst_sel:DWORD dst_unused:UNUSED_PAD src0_sel:WORD_1 src1_sel:DWORD
	v_add3_u32 v53, v53, v66, s56
	v_add3_u32 v51, v51, v67, s56
	v_add3_u32 v50, v50, v65, s56
	v_add3_u32 v52, v52, v63, s56
	v_and_b32_e32 v53, 0xffff0000, v53
	v_and_b32_e32 v63, 0xffff0000, v51
	v_or_b32_sdwa v51, v53, v52 dst_sel:DWORD dst_unused:UNUSED_PAD src0_sel:DWORD src1_sel:WORD_1
	v_or_b32_sdwa v50, v63, v50 dst_sel:DWORD dst_unused:UNUSED_PAD src0_sel:DWORD src1_sel:WORD_1
	global_store_dwordx2 v[54:55], v[50:51], off
	s_nop 0
	v_pk_fma_f32 v[42:43], v[42:43], v[122:123], v[212:213]
	v_pk_fma_f32 v[40:41], v[40:41], v[120:121], v[210:211]
	global_store_dwordx4 v[74:75], v[40:43], off offset:64
	v_pk_mul_f32 v[52:53], v[42:43], v[142:143]
	v_pk_mul_f32 v[50:51], v[40:41], v[140:141]
	v_pk_add_f32 v[68:69], v[158:159], 1.0 op_sel_hi:[1,0]
	v_pk_add_f32 v[66:67], v[156:157], 1.0 op_sel_hi:[1,0]
	v_pk_mul_f32 v[52:53], v[52:53], v[68:69]
	v_pk_mul_f32 v[50:51], v[50:51], v[66:67]
	v_and_b32_sdwa v66, v53, v170 dst_sel:DWORD dst_unused:UNUSED_PAD src0_sel:WORD_1 src1_sel:DWORD
	v_and_b32_sdwa v67, v51, v170 dst_sel:DWORD dst_unused:UNUSED_PAD src0_sel:WORD_1 src1_sel:DWORD
	v_and_b32_sdwa v63, v52, v170 dst_sel:DWORD dst_unused:UNUSED_PAD src0_sel:WORD_1 src1_sel:DWORD
	v_and_b32_sdwa v65, v50, v170 dst_sel:DWORD dst_unused:UNUSED_PAD src0_sel:WORD_1 src1_sel:DWORD
	v_add3_u32 v53, v53, v66, s56
	v_add3_u32 v51, v51, v67, s56
	v_add3_u32 v50, v50, v65, s56
	v_add3_u32 v52, v52, v63, s56
	v_and_b32_e32 v53, 0xffff0000, v53
	v_and_b32_e32 v63, 0xffff0000, v51
	v_or_b32_sdwa v51, v53, v52 dst_sel:DWORD dst_unused:UNUSED_PAD src0_sel:DWORD src1_sel:WORD_1
	v_or_b32_sdwa v50, v63, v50 dst_sel:DWORD dst_unused:UNUSED_PAD src0_sel:DWORD src1_sel:WORD_1
	global_store_dwordx2 v[54:55], v[50:51], off offset:32
	s_nop 0
	v_pk_fma_f32 v[38:39], v[38:39], v[126:127], v[216:217]
	v_pk_fma_f32 v[36:37], v[36:37], v[124:125], v[214:215]
	global_store_dwordx4 v[74:75], v[36:39], off offset:128
	v_pk_mul_f32 v[52:53], v[38:39], v[146:147]
	v_pk_mul_f32 v[50:51], v[36:37], v[144:145]
	v_pk_add_f32 v[68:69], v[162:163], 1.0 op_sel_hi:[1,0]
	v_pk_add_f32 v[66:67], v[160:161], 1.0 op_sel_hi:[1,0]
	v_pk_mul_f32 v[52:53], v[52:53], v[68:69]
	v_pk_mul_f32 v[50:51], v[50:51], v[66:67]
	v_and_b32_sdwa v66, v53, v170 dst_sel:DWORD dst_unused:UNUSED_PAD src0_sel:WORD_1 src1_sel:DWORD
	v_and_b32_sdwa v67, v51, v170 dst_sel:DWORD dst_unused:UNUSED_PAD src0_sel:WORD_1 src1_sel:DWORD
	v_and_b32_sdwa v63, v52, v170 dst_sel:DWORD dst_unused:UNUSED_PAD src0_sel:WORD_1 src1_sel:DWORD
	v_and_b32_sdwa v65, v50, v170 dst_sel:DWORD dst_unused:UNUSED_PAD src0_sel:WORD_1 src1_sel:DWORD
	v_add3_u32 v53, v53, v66, s56
	v_add3_u32 v51, v51, v67, s56
	v_add3_u32 v50, v50, v65, s56
	v_add3_u32 v52, v52, v63, s56
	v_and_b32_e32 v53, 0xffff0000, v53
	v_and_b32_e32 v63, 0xffff0000, v51
	v_or_b32_sdwa v51, v53, v52 dst_sel:DWORD dst_unused:UNUSED_PAD src0_sel:DWORD src1_sel:WORD_1
	v_or_b32_sdwa v50, v63, v50 dst_sel:DWORD dst_unused:UNUSED_PAD src0_sel:DWORD src1_sel:WORD_1
	global_store_dwordx2 v[54:55], v[50:51], off offset:64
	s_nop 0
	v_pk_fma_f32 v[52:53], v[34:35], v[134:135], v[220:221]
	v_pk_fma_f32 v[50:51], v[32:33], v[132:133], v[218:219]
	global_store_dwordx4 v[74:75], v[50:53], off offset:192
	s_nop 0
	v_mul_f32_e32 v32, v45, v45
	v_mul_f32_e32 v33, v41, v41
	v_fmac_f32_e32 v32, v44, v44
	v_fmac_f32_e32 v33, v40, v40
	v_fmac_f32_e32 v32, v46, v46
	v_fmac_f32_e32 v33, v42, v42
	v_fmac_f32_e32 v32, v47, v47
	v_fmac_f32_e32 v33, v43, v43
	v_add_f32_e32 v32, v32, v33
	v_mul_f32_e32 v33, v37, v37
	v_fmac_f32_e32 v33, v36, v36
	v_fmac_f32_e32 v33, v38, v38
	v_fmac_f32_e32 v33, v39, v39
	v_add_f32_e32 v32, v32, v33
	v_mul_f32_e32 v33, v51, v51
	v_fmac_f32_e32 v33, v50, v50
	v_fmac_f32_e32 v33, v52, v52
	v_fmac_f32_e32 v33, v53, v53
	v_add_f32_e32 v32, v32, v33
	ds_bpermute_b32 v33, v105, v32
	s_waitcnt lgkmcnt(0)
	v_add_f32_e32 v32, v32, v33
	ds_bpermute_b32 v33, v104, v32
	v_pk_mul_f32 v[34:35], v[52:53], v[150:151]
	v_pk_mul_f32 v[36:37], v[50:51], v[148:149]
	v_pk_add_f32 v[38:39], v[182:183], 1.0 op_sel_hi:[1,0]
	v_pk_add_f32 v[40:41], v[180:181], 1.0 op_sel_hi:[1,0]
	v_pk_mul_f32 v[34:35], v[34:35], v[38:39]
	v_pk_mul_f32 v[36:37], v[36:37], v[40:41]
	v_cvt_pk_bf16_f32 v35, v34, v35
	v_cvt_pk_bf16_f32 v34, v36, v37
	global_store_dwordx2 v[54:55], v[34:35], off offset:96
	s_and_saveexec_b64 s[24:25], s[36:37]
	s_cbranch_execz .LBB0_97
	s_waitcnt lgkmcnt(0)
	v_add_f32_e32 v32, v32, v33
	global_store_dword v[48:49], v32, off offset:64
.LBB0_97:
	s_or_b64 exec, exec, s[24:25]
	v_add_u32_e32 v32, 0xffffe020, v64
	v_or_b32_e32 v40, 32, v62
	v_lshrrev_b32_e32 v32, 10, v32
	v_mad_u32_u24 v32, v32, s5, s5
	v_cmp_lt_i32_e32 vcc, s13, v40
	v_ashrrev_i32_e32 v41, 31, v40
	v_readlane_b32 s16, v250, 15
	v_cndmask_b32_e32 v32, 0, v32, vcc
	s_waitcnt lgkmcnt(0)
	v_ashrrev_i32_e32 v33, 31, v32
	v_lshlrev_b64 v[42:43], 2, v[32:33]
	v_lshl_add_u64 v[32:33], s[40:41], 0, v[42:43]
	v_lshl_add_u64 v[44:45], v[32:33], 0, v[60:61]
	v_lshlrev_b64 v[32:33], 12, v[40:41]
	v_readlane_b32 s17, v250, 16
	v_lshl_add_u64 v[42:43], s[42:43], 0, v[42:43]
	v_lshl_add_u64 v[42:43], v[42:43], 0, v[60:61]
	v_lshl_add_u64 v[32:33], s[16:17], 0, v[32:33]
	v_lshl_add_u64 v[46:47], v[32:33], 0, v[60:61]
	v_readlane_b32 s16, v250, 21
	v_lshlrev_b64 v[40:41], 11, v[40:41]
	v_readlane_b32 s17, v250, 22
	global_load_dwordx4 v[206:209], v[224:225], off
	global_load_dwordx4 v[210:213], v[224:225], off offset:64
	global_load_dwordx4 v[214:217], v[224:225], off offset:128
	global_load_dwordx4 v[218:221], v[224:225], off offset:192
	s_waitcnt vmcnt(12)
	v_pk_fma_f32 v[30:31], v[30:31], v[118:119], v[192:193]
	v_pk_fma_f32 v[28:29], v[28:29], v[116:117], v[190:191]
	global_store_dwordx4 v[46:47], v[28:31], off
	v_lshl_add_u64 v[40:41], s[16:17], 0, v[40:41]
	v_lshl_add_u64 v[50:51], v[58:59], 1, v[40:41]
	v_pk_mul_f32 v[34:35], v[30:31], v[138:139]
	v_pk_mul_f32 v[32:33], v[28:29], v[136:137]
	v_pk_add_f32 v[38:39], v[154:155], 1.0 op_sel_hi:[1,0]
	v_pk_add_f32 v[36:37], v[152:153], 1.0 op_sel_hi:[1,0]
	v_pk_mul_f32 v[34:35], v[34:35], v[38:39]
	v_pk_mul_f32 v[32:33], v[32:33], v[36:37]
	v_and_b32_sdwa v38, v35, v170 dst_sel:DWORD dst_unused:UNUSED_PAD src0_sel:WORD_1 src1_sel:DWORD
	v_and_b32_sdwa v39, v33, v170 dst_sel:DWORD dst_unused:UNUSED_PAD src0_sel:WORD_1 src1_sel:DWORD
	v_and_b32_sdwa v36, v34, v170 dst_sel:DWORD dst_unused:UNUSED_PAD src0_sel:WORD_1 src1_sel:DWORD
	v_and_b32_sdwa v37, v32, v170 dst_sel:DWORD dst_unused:UNUSED_PAD src0_sel:WORD_1 src1_sel:DWORD
	v_add3_u32 v35, v35, v38, s56
	v_add3_u32 v33, v33, v39, s56
	v_add3_u32 v32, v32, v37, s56
	v_add3_u32 v34, v34, v36, s56
	v_and_b32_e32 v35, 0xffff0000, v35
	v_and_b32_e32 v36, 0xffff0000, v33
	v_or_b32_sdwa v33, v35, v34 dst_sel:DWORD dst_unused:UNUSED_PAD src0_sel:DWORD src1_sel:WORD_1
	v_or_b32_sdwa v32, v36, v32 dst_sel:DWORD dst_unused:UNUSED_PAD src0_sel:DWORD src1_sel:WORD_1
	global_store_dwordx2 v[50:51], v[32:33], off
	s_nop 0
	v_pk_fma_f32 v[26:27], v[26:27], v[122:123], v[196:197]
	v_pk_fma_f32 v[24:25], v[24:25], v[120:121], v[194:195]
	global_store_dwordx4 v[46:47], v[24:27], off offset:64
	v_pk_mul_f32 v[34:35], v[26:27], v[142:143]
	v_pk_mul_f32 v[32:33], v[24:25], v[140:141]
	v_pk_add_f32 v[38:39], v[158:159], 1.0 op_sel_hi:[1,0]
	v_pk_add_f32 v[36:37], v[156:157], 1.0 op_sel_hi:[1,0]
	v_pk_mul_f32 v[34:35], v[34:35], v[38:39]
	v_pk_mul_f32 v[32:33], v[32:33], v[36:37]
	v_and_b32_sdwa v38, v35, v170 dst_sel:DWORD dst_unused:UNUSED_PAD src0_sel:WORD_1 src1_sel:DWORD
	v_and_b32_sdwa v39, v33, v170 dst_sel:DWORD dst_unused:UNUSED_PAD src0_sel:WORD_1 src1_sel:DWORD
	v_and_b32_sdwa v36, v34, v170 dst_sel:DWORD dst_unused:UNUSED_PAD src0_sel:WORD_1 src1_sel:DWORD
	v_and_b32_sdwa v37, v32, v170 dst_sel:DWORD dst_unused:UNUSED_PAD src0_sel:WORD_1 src1_sel:DWORD
	v_add3_u32 v35, v35, v38, s56
	v_add3_u32 v33, v33, v39, s56
	v_add3_u32 v32, v32, v37, s56
	v_add3_u32 v34, v34, v36, s56
	v_and_b32_e32 v35, 0xffff0000, v35
	v_and_b32_e32 v36, 0xffff0000, v33
	v_or_b32_sdwa v33, v35, v34 dst_sel:DWORD dst_unused:UNUSED_PAD src0_sel:DWORD src1_sel:WORD_1
	v_or_b32_sdwa v32, v36, v32 dst_sel:DWORD dst_unused:UNUSED_PAD src0_sel:DWORD src1_sel:WORD_1
	global_store_dwordx2 v[50:51], v[32:33], off offset:32
	s_nop 0
	v_pk_fma_f32 v[22:23], v[22:23], v[126:127], v[200:201]
	v_pk_fma_f32 v[20:21], v[20:21], v[124:125], v[198:199]
	global_store_dwordx4 v[46:47], v[20:23], off offset:128
	v_pk_mul_f32 v[34:35], v[22:23], v[146:147]
	v_pk_mul_f32 v[32:33], v[20:21], v[144:145]
	v_pk_add_f32 v[38:39], v[162:163], 1.0 op_sel_hi:[1,0]
	v_pk_add_f32 v[36:37], v[160:161], 1.0 op_sel_hi:[1,0]
	v_pk_mul_f32 v[34:35], v[34:35], v[38:39]
	v_pk_mul_f32 v[32:33], v[32:33], v[36:37]
	v_and_b32_sdwa v38, v35, v170 dst_sel:DWORD dst_unused:UNUSED_PAD src0_sel:WORD_1 src1_sel:DWORD
	v_and_b32_sdwa v39, v33, v170 dst_sel:DWORD dst_unused:UNUSED_PAD src0_sel:WORD_1 src1_sel:DWORD
	v_and_b32_sdwa v36, v34, v170 dst_sel:DWORD dst_unused:UNUSED_PAD src0_sel:WORD_1 src1_sel:DWORD
	v_and_b32_sdwa v37, v32, v170 dst_sel:DWORD dst_unused:UNUSED_PAD src0_sel:WORD_1 src1_sel:DWORD
	v_add3_u32 v35, v35, v38, s56
	v_add3_u32 v33, v33, v39, s56
	v_add3_u32 v32, v32, v37, s56
	v_add3_u32 v34, v34, v36, s56
	v_and_b32_e32 v35, 0xffff0000, v35
	v_and_b32_e32 v36, 0xffff0000, v33
	v_or_b32_sdwa v33, v35, v34 dst_sel:DWORD dst_unused:UNUSED_PAD src0_sel:DWORD src1_sel:WORD_1
	v_or_b32_sdwa v32, v36, v32 dst_sel:DWORD dst_unused:UNUSED_PAD src0_sel:DWORD src1_sel:WORD_1
	global_store_dwordx2 v[50:51], v[32:33], off offset:64
	s_nop 0
	v_pk_fma_f32 v[34:35], v[18:19], v[134:135], v[204:205]
	v_pk_fma_f32 v[32:33], v[16:17], v[132:133], v[202:203]
	global_store_dwordx4 v[46:47], v[32:35], off offset:192
	s_nop 0
	v_mul_f32_e32 v16, v29, v29
	v_mul_f32_e32 v17, v25, v25
	v_fmac_f32_e32 v16, v28, v28
	v_fmac_f32_e32 v17, v24, v24
	v_fmac_f32_e32 v16, v30, v30
	v_fmac_f32_e32 v17, v26, v26
	v_fmac_f32_e32 v16, v31, v31
	v_fmac_f32_e32 v17, v27, v27
	v_add_f32_e32 v16, v16, v17
	v_mul_f32_e32 v17, v21, v21
	v_fmac_f32_e32 v17, v20, v20
	v_fmac_f32_e32 v17, v22, v22
	v_fmac_f32_e32 v17, v23, v23
	v_add_f32_e32 v16, v16, v17
	v_mul_f32_e32 v17, v33, v33
	v_fmac_f32_e32 v17, v32, v32
	v_fmac_f32_e32 v17, v34, v34
	v_fmac_f32_e32 v17, v35, v35
	v_add_f32_e32 v16, v16, v17
	ds_bpermute_b32 v17, v105, v16
	s_waitcnt lgkmcnt(0)
	v_add_f32_e32 v16, v16, v17
	ds_bpermute_b32 v17, v104, v16
	v_pk_mul_f32 v[18:19], v[34:35], v[150:151]
	v_pk_mul_f32 v[20:21], v[32:33], v[148:149]
	v_pk_add_f32 v[22:23], v[182:183], 1.0 op_sel_hi:[1,0]
	v_pk_add_f32 v[24:25], v[180:181], 1.0 op_sel_hi:[1,0]
	v_pk_mul_f32 v[18:19], v[18:19], v[22:23]
	v_pk_mul_f32 v[20:21], v[20:21], v[24:25]
	v_cvt_pk_bf16_f32 v19, v18, v19
	v_cvt_pk_bf16_f32 v18, v20, v21
	global_store_dwordx2 v[50:51], v[18:19], off offset:96
	s_and_saveexec_b64 s[24:25], s[36:37]
	s_movk_i32 s8, 0x400
	s_mov_b32 s5, 0xffff0000
	s_mov_b32 s9, 0x12000
	s_movk_i32 s89, 0xff
	s_mov_b64 s[78:79], s[50:51]
	s_cbranch_execz .LBB0_99
	s_waitcnt lgkmcnt(0)
	v_add_f32_e32 v16, v16, v17
	global_store_dword v[48:49], v16, off offset:128
.LBB0_99:
	s_or_b64 exec, exec, s[24:25]
	v_add_u32_e32 v16, 0xffffe030, v64
	v_or_b32_e32 v24, 48, v62
	v_lshrrev_b32_e32 v16, 10, v16
	s_movk_i32 s16, 0x1800
	v_mad_u32_u24 v16, v16, s16, s16
	v_cmp_lt_i32_e32 vcc, s13, v24
	v_ashrrev_i32_e32 v25, 31, v24
	v_readlane_b32 s16, v250, 15
	v_cndmask_b32_e32 v16, 0, v16, vcc
	s_waitcnt lgkmcnt(0)
	v_ashrrev_i32_e32 v17, 31, v16
	v_lshlrev_b64 v[26:27], 2, v[16:17]
	v_lshl_add_u64 v[16:17], s[40:41], 0, v[26:27]
	v_lshl_add_u64 v[28:29], v[16:17], 0, v[60:61]
	v_lshlrev_b64 v[16:17], 12, v[24:25]
	v_readlane_b32 s17, v250, 16
	v_lshl_add_u64 v[26:27], s[42:43], 0, v[26:27]
	v_lshl_add_u64 v[26:27], v[26:27], 0, v[60:61]
	v_lshl_add_u64 v[16:17], s[16:17], 0, v[16:17]
	v_lshl_add_u64 v[30:31], v[16:17], 0, v[60:61]
	v_readlane_b32 s16, v250, 21
	v_lshlrev_b64 v[24:25], 11, v[24:25]
	v_readlane_b32 s17, v250, 22
	s_waitcnt vmcnt(8)
	v_pk_fma_f32 v[14:15], v[14:15], v[118:119], v[208:209]
	v_pk_fma_f32 v[12:13], v[12:13], v[116:117], v[206:207]
	global_store_dwordx4 v[30:31], v[12:15], off
	v_lshl_add_u64 v[24:25], s[16:17], 0, v[24:25]
	v_lshl_add_u64 v[32:33], v[58:59], 1, v[24:25]
	v_pk_mul_f32 v[18:19], v[14:15], v[138:139]
	v_pk_mul_f32 v[16:17], v[12:13], v[136:137]
	v_pk_add_f32 v[22:23], v[154:155], 1.0 op_sel_hi:[1,0]
	v_pk_add_f32 v[20:21], v[152:153], 1.0 op_sel_hi:[1,0]
	v_pk_mul_f32 v[18:19], v[18:19], v[22:23]
	v_pk_mul_f32 v[16:17], v[16:17], v[20:21]
	v_and_b32_sdwa v22, v19, v170 dst_sel:DWORD dst_unused:UNUSED_PAD src0_sel:WORD_1 src1_sel:DWORD
	v_and_b32_sdwa v23, v17, v170 dst_sel:DWORD dst_unused:UNUSED_PAD src0_sel:WORD_1 src1_sel:DWORD
	v_and_b32_sdwa v20, v18, v170 dst_sel:DWORD dst_unused:UNUSED_PAD src0_sel:WORD_1 src1_sel:DWORD
	v_and_b32_sdwa v21, v16, v170 dst_sel:DWORD dst_unused:UNUSED_PAD src0_sel:WORD_1 src1_sel:DWORD
	v_add3_u32 v19, v19, v22, s56
	v_add3_u32 v17, v17, v23, s56
	v_add3_u32 v16, v16, v21, s56
	v_add3_u32 v18, v18, v20, s56
	v_and_b32_e32 v19, 0xffff0000, v19
	v_and_b32_e32 v20, 0xffff0000, v17
	v_or_b32_sdwa v17, v19, v18 dst_sel:DWORD dst_unused:UNUSED_PAD src0_sel:DWORD src1_sel:WORD_1
	v_or_b32_sdwa v16, v20, v16 dst_sel:DWORD dst_unused:UNUSED_PAD src0_sel:DWORD src1_sel:WORD_1
	global_store_dwordx2 v[32:33], v[16:17], off
	s_nop 0
	v_pk_fma_f32 v[10:11], v[10:11], v[122:123], v[212:213]
	v_pk_fma_f32 v[8:9], v[8:9], v[120:121], v[210:211]
	global_store_dwordx4 v[30:31], v[8:11], off offset:64
	v_pk_mul_f32 v[18:19], v[10:11], v[142:143]
	v_pk_mul_f32 v[16:17], v[8:9], v[140:141]
	v_pk_add_f32 v[22:23], v[158:159], 1.0 op_sel_hi:[1,0]
	v_pk_add_f32 v[20:21], v[156:157], 1.0 op_sel_hi:[1,0]
	v_pk_mul_f32 v[18:19], v[18:19], v[22:23]
	v_pk_mul_f32 v[16:17], v[16:17], v[20:21]
	v_and_b32_sdwa v22, v19, v170 dst_sel:DWORD dst_unused:UNUSED_PAD src0_sel:WORD_1 src1_sel:DWORD
	v_and_b32_sdwa v23, v17, v170 dst_sel:DWORD dst_unused:UNUSED_PAD src0_sel:WORD_1 src1_sel:DWORD
	v_and_b32_sdwa v20, v18, v170 dst_sel:DWORD dst_unused:UNUSED_PAD src0_sel:WORD_1 src1_sel:DWORD
	v_and_b32_sdwa v21, v16, v170 dst_sel:DWORD dst_unused:UNUSED_PAD src0_sel:WORD_1 src1_sel:DWORD
	v_add3_u32 v19, v19, v22, s56
	v_add3_u32 v17, v17, v23, s56
	v_add3_u32 v16, v16, v21, s56
	v_add3_u32 v18, v18, v20, s56
	v_and_b32_e32 v19, 0xffff0000, v19
	v_and_b32_e32 v20, 0xffff0000, v17
	v_or_b32_sdwa v17, v19, v18 dst_sel:DWORD dst_unused:UNUSED_PAD src0_sel:DWORD src1_sel:WORD_1
	v_or_b32_sdwa v16, v20, v16 dst_sel:DWORD dst_unused:UNUSED_PAD src0_sel:DWORD src1_sel:WORD_1
	global_store_dwordx2 v[32:33], v[16:17], off offset:32
	s_nop 0
	v_pk_fma_f32 v[6:7], v[6:7], v[126:127], v[216:217]
	v_pk_fma_f32 v[4:5], v[4:5], v[124:125], v[214:215]
	global_store_dwordx4 v[30:31], v[4:7], off offset:128
	v_pk_mul_f32 v[18:19], v[6:7], v[146:147]
	v_pk_mul_f32 v[16:17], v[4:5], v[144:145]
	v_pk_add_f32 v[22:23], v[162:163], 1.0 op_sel_hi:[1,0]
	v_pk_add_f32 v[20:21], v[160:161], 1.0 op_sel_hi:[1,0]
	v_pk_mul_f32 v[18:19], v[18:19], v[22:23]
	v_pk_mul_f32 v[16:17], v[16:17], v[20:21]
	v_and_b32_sdwa v22, v19, v170 dst_sel:DWORD dst_unused:UNUSED_PAD src0_sel:WORD_1 src1_sel:DWORD
	v_and_b32_sdwa v23, v17, v170 dst_sel:DWORD dst_unused:UNUSED_PAD src0_sel:WORD_1 src1_sel:DWORD
	v_and_b32_sdwa v20, v18, v170 dst_sel:DWORD dst_unused:UNUSED_PAD src0_sel:WORD_1 src1_sel:DWORD
	v_and_b32_sdwa v21, v16, v170 dst_sel:DWORD dst_unused:UNUSED_PAD src0_sel:WORD_1 src1_sel:DWORD
	v_add3_u32 v19, v19, v22, s56
	v_add3_u32 v17, v17, v23, s56
	v_add3_u32 v16, v16, v21, s56
	v_add3_u32 v18, v18, v20, s56
	v_and_b32_e32 v19, 0xffff0000, v19
	v_and_b32_e32 v20, 0xffff0000, v17
	v_or_b32_sdwa v17, v19, v18 dst_sel:DWORD dst_unused:UNUSED_PAD src0_sel:DWORD src1_sel:WORD_1
	v_or_b32_sdwa v16, v20, v16 dst_sel:DWORD dst_unused:UNUSED_PAD src0_sel:DWORD src1_sel:WORD_1
	global_store_dwordx2 v[32:33], v[16:17], off offset:64
	s_nop 0
	v_pk_fma_f32 v[18:19], v[2:3], v[134:135], v[220:221]
	v_pk_fma_f32 v[16:17], v[0:1], v[132:133], v[218:219]
	global_store_dwordx4 v[30:31], v[16:19], off offset:192
	s_nop 0
	v_mul_f32_e32 v0, v13, v13
	v_mul_f32_e32 v1, v9, v9
	v_fmac_f32_e32 v0, v12, v12
	v_fmac_f32_e32 v1, v8, v8
	v_fmac_f32_e32 v0, v14, v14
	v_fmac_f32_e32 v1, v10, v10
	v_fmac_f32_e32 v0, v15, v15
	v_fmac_f32_e32 v1, v11, v11
	v_add_f32_e32 v0, v0, v1
	v_mul_f32_e32 v1, v5, v5
	v_fmac_f32_e32 v1, v4, v4
	v_fmac_f32_e32 v1, v6, v6
	v_fmac_f32_e32 v1, v7, v7
	v_add_f32_e32 v0, v0, v1
	v_mul_f32_e32 v1, v17, v17
	v_fmac_f32_e32 v1, v16, v16
	v_fmac_f32_e32 v1, v18, v18
	v_fmac_f32_e32 v1, v19, v19
	v_add_f32_e32 v0, v0, v1
	ds_bpermute_b32 v1, v105, v0
	s_waitcnt lgkmcnt(0)
	v_add_f32_e32 v0, v0, v1
	ds_bpermute_b32 v1, v104, v0
	v_pk_mul_f32 v[2:3], v[18:19], v[150:151]
	v_pk_mul_f32 v[4:5], v[16:17], v[148:149]
	v_pk_add_f32 v[6:7], v[182:183], 1.0 op_sel_hi:[1,0]
	v_pk_add_f32 v[8:9], v[180:181], 1.0 op_sel_hi:[1,0]
	v_pk_mul_f32 v[2:3], v[2:3], v[6:7]
	v_pk_mul_f32 v[4:5], v[4:5], v[8:9]
	v_cvt_pk_bf16_f32 v3, v2, v3
	v_cvt_pk_bf16_f32 v2, v4, v5
	global_store_dwordx2 v[32:33], v[2:3], off offset:96
	s_and_saveexec_b64 s[24:25], s[36:37]
	s_cbranch_execz .LBB0_101
	s_waitcnt lgkmcnt(0)
	v_add_f32_e32 v0, v0, v1
	global_store_dword v[48:49], v0, off offset:192

.Ltail106:
	s_add_i32 s29, s44, 2
	ds_read_b128 v[136:139], v111 offset:16384
	ds_read_b128 v[140:143], v111 offset:18432
	ds_read_b128 v[144:147], v111 offset:20480
	ds_read_b128 v[148:151], v111 offset:22528
	ds_read_b128 v[116:119], v110
	s_add_i32 s44, s44, 4
	ds_read_b128 v[120:123], v110 offset:2048
	s_min_u32 s44, s44, 15
	s_lshl_b32 s92, s44, 7
	ds_read_b128 v[124:127], v110 offset:4096
	ds_read_b128 v[194:197], v113 offset:16384
	ds_read_b128 v[198:201], v113 offset:18432
	ds_read_b128 v[202:205], v113 offset:20480
	ds_read_b128 v[206:209], v113 offset:22528
	v_lshl_add_u64 v[164:165], v[100:101], 0, s[92:93]
	ds_read_b128 v[132:135], v110 offset:6144
	ds_read_b128 v[152:155], v112
	ds_read_b128 v[156:159], v112 offset:2048
	ds_read_b128 v[160:163], v112 offset:4096
	ds_read_b128 v[190:193], v112 offset:6144
	s_waitcnt lgkmcnt(11)
	v_mfma_f32_16x16x32_bf16 v[92:95], v[136:139], v[116:119], v[92:95]
	v_mfma_f32_16x16x32_bf16 v[88:91], v[140:143], v[116:119], v[88:91]
	v_mfma_f32_16x16x32_bf16 v[56:59], v[144:147], v[116:119], v[56:59]
	v_mfma_f32_16x16x32_bf16 v[48:51], v[148:151], v[116:119], v[48:51]
	s_waitcnt vmcnt(7)
	ds_write_b128 v109, v[52:55] offset:32768
	v_add_co_u32_e32 v52, vcc, s11, v164
	s_waitcnt lgkmcnt(11)
	v_mfma_f32_16x16x32_bf16 v[44:47], v[136:139], v[120:123], v[44:47]
	v_addc_co_u32_e32 v53, vcc, 0, v165, vcc
	v_mfma_f32_16x16x32_bf16 v[40:43], v[140:143], v[120:123], v[40:43]
	v_mfma_f32_16x16x32_bf16 v[36:39], v[144:147], v[120:123], v[36:39]
	v_mfma_f32_16x16x32_bf16 v[32:35], v[148:151], v[120:123], v[32:35]
	v_add_co_u32_e32 v52, vcc, s33, v164
	s_waitcnt vmcnt(6)
	ds_write_b128 v109, v[60:63] offset:36864
	s_nop 0
	v_addc_co_u32_e32 v53, vcc, 0, v165, vcc
	s_waitcnt lgkmcnt(11)
	v_mfma_f32_16x16x32_bf16 v[28:31], v[136:139], v[124:127], v[28:31]
	v_mfma_f32_16x16x32_bf16 v[24:27], v[140:143], v[124:127], v[24:27]
	v_mfma_f32_16x16x32_bf16 v[20:23], v[144:147], v[124:127], v[20:23]
	v_mfma_f32_16x16x32_bf16 v[16:19], v[148:151], v[124:127], v[16:19]
	v_add_co_u32_e32 v52, vcc, s59, v164
	s_waitcnt vmcnt(5)
	ds_write_b128 v109, v[64:67] offset:40960
	s_nop 0
	v_addc_co_u32_e32 v53, vcc, 0, v165, vcc
	v_lshl_add_u64 v[64:65], v[102:103], 0, s[92:93]
	v_add_co_u32_e32 v66, vcc, s11, v64
	s_waitcnt lgkmcnt(7)
	v_mfma_f32_16x16x32_bf16 v[12:15], v[136:139], v[132:135], v[12:15]
	v_addc_co_u32_e32 v67, vcc, 0, v65, vcc
	v_mfma_f32_16x16x32_bf16 v[8:11], v[140:143], v[132:135], v[8:11]
	v_mfma_f32_16x16x32_bf16 v[4:7], v[144:147], v[132:135], v[4:7]
	v_mfma_f32_16x16x32_bf16 v[0:3], v[148:151], v[132:135], v[0:3]
	s_waitcnt vmcnt(4)
	ds_write_b128 v109, v[72:75] offset:45056
	s_waitcnt lgkmcnt(7)
	v_mfma_f32_16x16x32_bf16 v[52:55], v[194:197], v[152:155], v[92:95]
	v_mfma_f32_16x16x32_bf16 v[60:63], v[198:201], v[152:155], v[88:91]
	v_mfma_f32_16x16x32_bf16 v[56:59], v[202:205], v[152:155], v[56:59]
	v_mfma_f32_16x16x32_bf16 v[48:51], v[206:209], v[152:155], v[48:51]
	s_waitcnt vmcnt(3)
	ds_write_b128 v109, v[68:71] offset:49152
	s_waitcnt lgkmcnt(7)
	v_mfma_f32_16x16x32_bf16 v[44:47], v[194:197], v[156:159], v[44:47]
	v_mfma_f32_16x16x32_bf16 v[40:43], v[198:201], v[156:159], v[40:43]
	v_mfma_f32_16x16x32_bf16 v[36:39], v[202:205], v[156:159], v[36:39]
	v_mfma_f32_16x16x32_bf16 v[32:35], v[206:209], v[156:159], v[32:35]
	v_add_co_u32_e32 v66, vcc, s33, v64
	s_waitcnt vmcnt(2)
	ds_write_b128 v109, v[76:79] offset:53248
	v_addc_co_u32_e32 v67, vcc, 0, v65, vcc
	v_add_co_u32_e32 v64, vcc, s59, v64
	s_waitcnt lgkmcnt(7)
	v_mfma_f32_16x16x32_bf16 v[28:31], v[194:197], v[160:163], v[28:31]
	v_addc_co_u32_e32 v65, vcc, 0, v65, vcc
	v_mfma_f32_16x16x32_bf16 v[24:27], v[198:201], v[160:163], v[24:27]
	v_mfma_f32_16x16x32_bf16 v[20:23], v[202:205], v[160:163], v[20:23]
	v_mfma_f32_16x16x32_bf16 v[16:19], v[206:209], v[160:163], v[16:19]
	s_waitcnt vmcnt(1)
	ds_write_b128 v109, v[80:83] offset:57344
	s_waitcnt lgkmcnt(7)
	v_mfma_f32_16x16x32_bf16 v[12:15], v[194:197], v[190:193], v[12:15]
	v_mfma_f32_16x16x32_bf16 v[8:11], v[198:201], v[190:193], v[8:11]
	v_mfma_f32_16x16x32_bf16 v[4:7], v[202:205], v[190:193], v[4:7]
	v_mfma_f32_16x16x32_bf16 v[0:3], v[206:209], v[190:193], v[0:3]
	s_waitcnt vmcnt(0)
	ds_write_b128 v109, v[84:87] offset:61440
	s_waitcnt lgkmcnt(0)
	s_barrier
	ds_read_b128 v[84:87], v111 offset:51200
	ds_read_b128 v[80:83], v111 offset:49152
	ds_read_b128 v[88:91], v111 offset:53248
	ds_read_b128 v[92:95], v111 offset:55296
	ds_read_b128 v[64:67], v110 offset:32768
	s_min_u32 s44, s29, 12
	s_lshl_b32 s92, s44, 7
	ds_read_b128 v[68:71], v110 offset:34816
	v_lshl_add_u64 v[164:165], v[100:101], 0, s[92:93]
	ds_read_b128 v[72:75], v110 offset:36864
	ds_read_b128 v[76:79], v110 offset:38912
	ds_read_b128 v[152:155], v112 offset:32768
	ds_read_b128 v[156:159], v112 offset:34816
	ds_read_b128 v[160:163], v112 offset:36864
	ds_read_b128 v[190:193], v112 offset:38912
	ds_read_b128 v[194:197], v113 offset:49152
	ds_read_b128 v[198:201], v113 offset:51200
	ds_read_b128 v[202:205], v113 offset:53248
	ds_read_b128 v[206:209], v113 offset:55296
	s_waitcnt lgkmcnt(11)
	v_mfma_f32_16x16x32_bf16 v[214:217], v[84:87], v[64:67], v[60:63]
	v_mfma_f32_16x16x32_bf16 v[210:213], v[80:83], v[64:67], v[52:55]
	s_nop 1
	v_add_co_u32_e32 v60, vcc, s11, v164
	s_nop 1
	v_addc_co_u32_e32 v61, vcc, 0, v165, vcc
	v_mfma_f32_16x16x32_bf16 v[56:59], v[88:91], v[64:67], v[56:59]
	v_mfma_f32_16x16x32_bf16 v[48:51], v[92:95], v[64:67], v[48:51]
	v_add_co_u32_e32 v64, vcc, s33, v164
	s_nop 0
	v_addc_co_u32_e32 v65, vcc, 0, v165, vcc
	s_waitcnt lgkmcnt(10)
	v_mfma_f32_16x16x32_bf16 v[44:47], v[80:83], v[68:71], v[44:47]
	v_mfma_f32_16x16x32_bf16 v[40:43], v[84:87], v[68:71], v[40:43]
	v_mfma_f32_16x16x32_bf16 v[36:39], v[88:91], v[68:71], v[36:39]
	v_mfma_f32_16x16x32_bf16 v[32:35], v[92:95], v[68:71], v[32:35]
	v_add_co_u32_e32 v68, vcc, s59, v164
	s_waitcnt lgkmcnt(9)
	v_mfma_f32_16x16x32_bf16 v[28:31], v[80:83], v[72:75], v[28:31]
	v_addc_co_u32_e32 v69, vcc, 0, v165, vcc
	v_mfma_f32_16x16x32_bf16 v[24:27], v[84:87], v[72:75], v[24:27]
	v_mfma_f32_16x16x32_bf16 v[20:23], v[88:91], v[72:75], v[20:23]
	v_mfma_f32_16x16x32_bf16 v[16:19], v[92:95], v[72:75], v[16:19]
	s_waitcnt lgkmcnt(8)
	v_mfma_f32_16x16x32_bf16 v[8:11], v[84:87], v[76:79], v[8:11]
	v_lshl_add_u64 v[84:85], v[102:103], 0, s[92:93]
	v_mfma_f32_16x16x32_bf16 v[12:15], v[80:83], v[76:79], v[12:15]
	v_mfma_f32_16x16x32_bf16 v[4:7], v[88:91], v[76:79], v[4:7]
	v_mfma_f32_16x16x32_bf16 v[0:3], v[92:95], v[76:79], v[0:3]
	v_add_co_u32_e32 v76, vcc, s11, v84
	s_nop 0
	v_addc_co_u32_e32 v77, vcc, 0, v85, vcc
	v_add_co_u32_e32 v80, vcc, s33, v84
	v_addc_co_u32_e32 v81, vcc, 0, v85, vcc
	s_waitcnt lgkmcnt(3)
	v_mfma_f32_16x16x32_bf16 v[92:95], v[194:197], v[152:155], v[210:213]
	s_waitcnt lgkmcnt(2)
	v_mfma_f32_16x16x32_bf16 v[88:91], v[198:201], v[152:155], v[214:217]
	s_waitcnt lgkmcnt(1)
	v_mfma_f32_16x16x32_bf16 v[56:59], v[202:205], v[152:155], v[56:59]
	s_waitcnt lgkmcnt(0)
	v_mfma_f32_16x16x32_bf16 v[48:51], v[206:209], v[152:155], v[48:51]
	v_add_co_u32_e32 v84, vcc, s59, v84
	v_addc_co_u32_e32 v85, vcc, 0, v85, vcc
	v_mfma_f32_16x16x32_bf16 v[44:47], v[194:197], v[156:159], v[44:47]
	v_mfma_f32_16x16x32_bf16 v[40:43], v[198:201], v[156:159], v[40:43]
	v_mfma_f32_16x16x32_bf16 v[36:39], v[202:205], v[156:159], v[36:39]
	v_mfma_f32_16x16x32_bf16 v[32:35], v[206:209], v[156:159], v[32:35]
	v_mfma_f32_16x16x32_bf16 v[28:31], v[194:197], v[160:163], v[28:31]
	v_mfma_f32_16x16x32_bf16 v[24:27], v[198:201], v[160:163], v[24:27]
	v_mfma_f32_16x16x32_bf16 v[20:23], v[202:205], v[160:163], v[20:23]
	v_mfma_f32_16x16x32_bf16 v[16:19], v[206:209], v[160:163], v[16:19]
	v_mfma_f32_16x16x32_bf16 v[12:15], v[194:197], v[190:193], v[12:15]
	v_mfma_f32_16x16x32_bf16 v[8:11], v[198:201], v[190:193], v[8:11]
	v_mfma_f32_16x16x32_bf16 v[4:7], v[202:205], v[190:193], v[4:7]
	v_mfma_f32_16x16x32_bf16 v[0:3], v[206:209], v[190:193], v[0:3]
	s_mov_b32 s44, s29
	s_waitcnt lgkmcnt(0)
	s_barrier
	s_waitcnt vmcnt(5)
	v_add_u32_e32 v64, s24, v108
	v_add_u32_e32 v52, 0xffffe000, v64
	v_or_b32_e32 v62, v64, v107
	v_lshrrev_b32_e32 v52, 10, v52
	s_movk_i32 s16, 0x1800
	v_mad_u32_u24 v52, v52, s16, s16
	v_cmp_lt_i32_e32 vcc, s13, v62
	v_or_b32_e32 v65, s25, v114
	v_or_b32_e32 v54, v65, v115
	v_cndmask_b32_e32 v52, 0, v52, vcc
	v_ashrrev_i32_e32 v53, 31, v52
	s_waitcnt vmcnt(4)
	v_lshlrev_b64 v[74:75], 2, v[52:53]
	v_ashrrev_i32_e32 v55, 31, v54
	v_ashrrev_i32_e32 v63, 31, v62
	v_lshl_add_u64 v[52:53], s[40:41], 0, v[74:75]
	v_lshlrev_b64 v[60:61], 2, v[54:55]
	v_readlane_b32 s16, v250, 15
	s_waitcnt vmcnt(1)
	v_lshl_add_u64 v[82:83], v[52:53], 0, v[60:61]
	v_lshlrev_b64 v[52:53], 12, v[62:63]
	v_readlane_b32 s17, v250, 16
	v_lshl_add_u64 v[74:75], s[42:43], 0, v[74:75]
	s_waitcnt vmcnt(0)
	v_lshl_add_u64 v[86:87], v[74:75], 0, v[60:61]
	v_lshl_add_u64 v[52:53], s[16:17], 0, v[52:53]
	v_lshl_add_u64 v[84:85], v[52:53], 0, v[60:61]
	global_load_dwordx4 v[66:69], v[82:83], off
	global_load_dwordx4 v[70:73], v[84:85], off
	v_lshl_add_u64 v[52:53], s[0:1], 0, v[60:61]
	v_readlane_b32 s16, v250, 21
	v_lshlrev_b64 v[78:79], 11, v[62:63]
	v_readlane_b32 s17, v250, 22
	s_waitcnt vmcnt(0)
	v_pk_fma_f32 v[68:69], v[94:95], v[68:69], v[72:73]
	v_pk_fma_f32 v[66:67], v[92:93], v[66:67], v[70:71]
	global_store_dwordx4 v[84:85], v[66:69], off
	global_load_dwordx4 v[70:73], v[52:53], off
	global_load_dwordx4 v[74:77], v[86:87], off
	v_lshl_add_u64 v[78:79], s[16:17], 0, v[78:79]
	v_lshl_add_u64 v[92:93], v[54:55], 1, v[78:79]
	s_mov_b32 s16, 0xa000
	s_waitcnt vmcnt(1)
	v_pk_mul_f32 v[72:73], v[68:69], v[72:73]
	v_pk_mul_f32 v[70:71], v[66:67], v[70:71]
	s_waitcnt vmcnt(0)
	v_pk_add_f32 v[76:77], v[76:77], 1.0 op_sel_hi:[1,0]
	v_pk_add_f32 v[74:75], v[74:75], 1.0 op_sel_hi:[1,0]
	v_pk_mul_f32 v[72:73], v[72:73], v[76:77]
	v_pk_mul_f32 v[70:71], v[70:71], v[74:75]
	v_and_b32_sdwa v76, v73, v170 dst_sel:DWORD dst_unused:UNUSED_PAD src0_sel:WORD_1 src1_sel:DWORD
	v_and_b32_sdwa v77, v71, v170 dst_sel:DWORD dst_unused:UNUSED_PAD src0_sel:WORD_1 src1_sel:DWORD
	v_and_b32_sdwa v74, v72, v170 dst_sel:DWORD dst_unused:UNUSED_PAD src0_sel:WORD_1 src1_sel:DWORD
	v_and_b32_sdwa v75, v70, v170 dst_sel:DWORD dst_unused:UNUSED_PAD src0_sel:WORD_1 src1_sel:DWORD
	v_add3_u32 v73, v73, v76, s56
	v_add3_u32 v71, v71, v77, s56
	v_add3_u32 v70, v70, v75, s56
	v_add3_u32 v72, v72, v74, s56
	v_and_b32_e32 v73, 0xffff0000, v73
	v_and_b32_e32 v74, 0xffff0000, v71
	v_or_b32_sdwa v71, v73, v72 dst_sel:DWORD dst_unused:UNUSED_PAD src0_sel:DWORD src1_sel:WORD_1
	v_or_b32_sdwa v70, v74, v70 dst_sel:DWORD dst_unused:UNUSED_PAD src0_sel:DWORD src1_sel:WORD_1
	global_store_dwordx2 v[92:93], v[70:71], off
	global_load_dwordx4 v[70:73], v[82:83], off offset:64
	s_nop 0
	global_load_dwordx4 v[74:77], v[84:85], off offset:64
	s_waitcnt vmcnt(0)
	v_pk_fma_f32 v[72:73], v[90:91], v[72:73], v[76:77]
	v_pk_fma_f32 v[70:71], v[88:89], v[70:71], v[74:75]
	global_store_dwordx4 v[84:85], v[70:73], off offset:64
	global_load_dwordx4 v[74:77], v[52:53], off offset:64
	global_load_dwordx4 v[78:81], v[86:87], off offset:64
	s_waitcnt vmcnt(1)
	v_pk_mul_f32 v[76:77], v[72:73], v[76:77]
	v_pk_mul_f32 v[74:75], v[70:71], v[74:75]
	s_waitcnt vmcnt(0)
	v_pk_add_f32 v[80:81], v[80:81], 1.0 op_sel_hi:[1,0]
	v_pk_add_f32 v[78:79], v[78:79], 1.0 op_sel_hi:[1,0]
	v_pk_mul_f32 v[76:77], v[76:77], v[80:81]
	v_pk_mul_f32 v[74:75], v[74:75], v[78:79]
	v_and_b32_sdwa v80, v77, v170 dst_sel:DWORD dst_unused:UNUSED_PAD src0_sel:WORD_1 src1_sel:DWORD
	v_and_b32_sdwa v81, v75, v170 dst_sel:DWORD dst_unused:UNUSED_PAD src0_sel:WORD_1 src1_sel:DWORD
	v_and_b32_sdwa v78, v76, v170 dst_sel:DWORD dst_unused:UNUSED_PAD src0_sel:WORD_1 src1_sel:DWORD
	v_and_b32_sdwa v79, v74, v170 dst_sel:DWORD dst_unused:UNUSED_PAD src0_sel:WORD_1 src1_sel:DWORD
	v_add3_u32 v77, v77, v80, s56
	v_add3_u32 v75, v75, v81, s56
	v_add3_u32 v74, v74, v79, s56
	v_add3_u32 v76, v76, v78, s56
	v_and_b32_e32 v77, 0xffff0000, v77
	v_and_b32_e32 v78, 0xffff0000, v75
	v_or_b32_sdwa v75, v77, v76 dst_sel:DWORD dst_unused:UNUSED_PAD src0_sel:DWORD src1_sel:WORD_1
	v_or_b32_sdwa v74, v78, v74 dst_sel:DWORD dst_unused:UNUSED_PAD src0_sel:DWORD src1_sel:WORD_1
	global_store_dwordx2 v[92:93], v[74:75], off offset:32
	global_load_dwordx4 v[74:77], v[82:83], off offset:128
	s_nop 0
	global_load_dwordx4 v[78:81], v[84:85], off offset:128
	s_waitcnt vmcnt(0)
	v_pk_fma_f32 v[58:59], v[58:59], v[76:77], v[80:81]
	v_pk_fma_f32 v[56:57], v[56:57], v[74:75], v[78:79]
	global_store_dwordx4 v[84:85], v[56:59], off offset:128
	global_load_dwordx4 v[74:77], v[52:53], off offset:128
	global_load_dwordx4 v[78:81], v[86:87], off offset:128
	s_waitcnt vmcnt(1)
	v_pk_mul_f32 v[76:77], v[58:59], v[76:77]
	v_pk_mul_f32 v[74:75], v[56:57], v[74:75]
	s_waitcnt vmcnt(0)
	v_pk_add_f32 v[80:81], v[80:81], 1.0 op_sel_hi:[1,0]
	v_pk_add_f32 v[78:79], v[78:79], 1.0 op_sel_hi:[1,0]
	v_pk_mul_f32 v[76:77], v[76:77], v[80:81]
	v_pk_mul_f32 v[74:75], v[74:75], v[78:79]
	v_and_b32_sdwa v80, v77, v170 dst_sel:DWORD dst_unused:UNUSED_PAD src0_sel:WORD_1 src1_sel:DWORD
	v_and_b32_sdwa v81, v75, v170 dst_sel:DWORD dst_unused:UNUSED_PAD src0_sel:WORD_1 src1_sel:DWORD
	v_and_b32_sdwa v78, v76, v170 dst_sel:DWORD dst_unused:UNUSED_PAD src0_sel:WORD_1 src1_sel:DWORD
	v_and_b32_sdwa v79, v74, v170 dst_sel:DWORD dst_unused:UNUSED_PAD src0_sel:WORD_1 src1_sel:DWORD
	v_add3_u32 v77, v77, v80, s56
	v_add3_u32 v75, v75, v81, s56
	v_add3_u32 v74, v74, v79, s56
	v_add3_u32 v76, v76, v78, s56
	v_and_b32_e32 v77, 0xffff0000, v77
	v_and_b32_e32 v78, 0xffff0000, v75
	v_or_b32_sdwa v75, v77, v76 dst_sel:DWORD dst_unused:UNUSED_PAD src0_sel:DWORD src1_sel:WORD_1
	v_or_b32_sdwa v74, v78, v74 dst_sel:DWORD dst_unused:UNUSED_PAD src0_sel:DWORD src1_sel:WORD_1
	global_store_dwordx2 v[92:93], v[74:75], off offset:64
	global_load_dwordx4 v[74:77], v[82:83], off offset:192
	s_nop 0
	global_load_dwordx4 v[78:81], v[84:85], off offset:192
	s_waitcnt vmcnt(0)
	v_pk_fma_f32 v[76:77], v[50:51], v[76:77], v[80:81]
	v_pk_fma_f32 v[74:75], v[48:49], v[74:75], v[78:79]
	global_store_dwordx4 v[84:85], v[74:77], off offset:192
	global_load_dwordx4 v[78:81], v[52:53], off offset:192
	s_nop 0
	global_load_dwordx4 v[82:85], v[86:87], off offset:192
	v_mul_f32_e32 v48, v67, v67
	v_mul_f32_e32 v49, v71, v71
	v_fmac_f32_e32 v48, v66, v66
	v_fmac_f32_e32 v49, v70, v70
	v_fmac_f32_e32 v48, v68, v68
	v_fmac_f32_e32 v49, v72, v72
	v_fmac_f32_e32 v48, v69, v69
	v_fmac_f32_e32 v49, v73, v73
	v_add_f32_e32 v48, v48, v49
	v_mul_f32_e32 v49, v57, v57
	v_fmac_f32_e32 v49, v56, v56
	v_fmac_f32_e32 v49, v58, v58
	v_fmac_f32_e32 v49, v59, v59
	v_add_f32_e32 v48, v48, v49
	v_mul_f32_e32 v49, v75, v75
	v_fmac_f32_e32 v49, v74, v74
	v_fmac_f32_e32 v49, v76, v76
	v_fmac_f32_e32 v49, v77, v77
	v_add_f32_e32 v50, v48, v49
	ds_bpermute_b32 v51, v105, v50
	v_lshrrev_b32_e32 v48, 6, v65
	v_mul_lo_u32 v48, v48, s16
	v_ashrrev_i32_e32 v49, 31, v48
	v_lshl_add_u64 v[48:49], s[26:27], 0, v[48:49]
	s_waitcnt lgkmcnt(0)
	v_add_f32_e32 v50, v50, v51
	ds_bpermute_b32 v51, v104, v50
	v_lshl_add_u64 v[48:49], v[62:63], 2, v[48:49]
	s_waitcnt vmcnt(1)
	v_pk_mul_f32 v[56:57], v[76:77], v[80:81]
	v_pk_mul_f32 v[58:59], v[74:75], v[78:79]
	s_waitcnt vmcnt(0)
	v_pk_add_f32 v[66:67], v[84:85], 1.0 op_sel_hi:[1,0]
	v_pk_add_f32 v[68:69], v[82:83], 1.0 op_sel_hi:[1,0]
	v_pk_mul_f32 v[56:57], v[56:57], v[66:67]
	v_pk_mul_f32 v[58:59], v[58:59], v[68:69]
	v_cvt_pk_bf16_f32 v57, v56, v57
	v_cvt_pk_bf16_f32 v56, v58, v59
	global_store_dwordx2 v[92:93], v[56:57], off offset:96
	s_and_saveexec_b64 s[24:25], s[36:37]
	s_cbranch_execz .LBB0_109
	s_waitcnt lgkmcnt(0)
	v_add_f32_e32 v50, v50, v51
	global_store_dword v[48:49], v50, off
.LBB0_109:
	s_or_b64 exec, exec, s[24:25]
	s_waitcnt lgkmcnt(0)
	v_add_u32_e32 v51, 0xffffe010, v64
	v_or_b32_e32 v50, 16, v62
	v_lshrrev_b32_e32 v51, 10, v51
	s_movk_i32 s16, 0x1800
	v_mad_u32_u24 v51, v51, s16, s16
	v_cmp_lt_i32_e32 vcc, s13, v50
	v_readlane_b32 s16, v250, 15
	v_readlane_b32 s17, v250, 16
	v_cndmask_b32_e32 v56, 0, v51, vcc
	v_ashrrev_i32_e32 v57, 31, v56
	v_lshlrev_b64 v[70:71], 2, v[56:57]
	v_ashrrev_i32_e32 v51, 31, v50
	v_lshl_add_u64 v[56:57], s[40:41], 0, v[70:71]
	v_lshl_add_u64 v[72:73], v[56:57], 0, v[60:61]
	v_lshlrev_b64 v[56:57], 12, v[50:51]
	v_lshl_add_u64 v[56:57], s[16:17], 0, v[56:57]
	v_lshl_add_u64 v[74:75], v[56:57], 0, v[60:61]
	global_load_dwordx4 v[56:59], v[72:73], off
	global_load_dwordx4 v[66:69], v[74:75], off
	v_lshl_add_u64 v[70:71], s[42:43], 0, v[70:71]
	v_lshl_add_u64 v[70:71], v[70:71], 0, v[60:61]
	v_readlane_b32 s16, v250, 21
	v_lshlrev_b64 v[50:51], 11, v[50:51]
	v_readlane_b32 s17, v250, 22
	s_waitcnt vmcnt(0)
	v_pk_fma_f32 v[46:47], v[46:47], v[58:59], v[68:69]
	v_pk_fma_f32 v[44:45], v[44:45], v[56:57], v[66:67]
	global_store_dwordx4 v[74:75], v[44:47], off
	global_load_dwordx4 v[56:59], v[52:53], off
	global_load_dwordx4 v[66:69], v[70:71], off
	v_lshl_add_u64 v[50:51], s[16:17], 0, v[50:51]
	v_lshl_add_u64 v[50:51], v[54:55], 1, v[50:51]
	s_waitcnt vmcnt(1)
	v_pk_mul_f32 v[58:59], v[46:47], v[58:59]
	v_pk_mul_f32 v[56:57], v[44:45], v[56:57]
	s_waitcnt vmcnt(0)
	v_pk_add_f32 v[68:69], v[68:69], 1.0 op_sel_hi:[1,0]
	v_pk_add_f32 v[66:67], v[66:67], 1.0 op_sel_hi:[1,0]
	v_pk_mul_f32 v[58:59], v[58:59], v[68:69]
	v_pk_mul_f32 v[56:57], v[56:57], v[66:67]
	v_and_b32_sdwa v66, v59, v170 dst_sel:DWORD dst_unused:UNUSED_PAD src0_sel:WORD_1 src1_sel:DWORD
	v_and_b32_sdwa v67, v57, v170 dst_sel:DWORD dst_unused:UNUSED_PAD src0_sel:WORD_1 src1_sel:DWORD
	v_and_b32_sdwa v63, v58, v170 dst_sel:DWORD dst_unused:UNUSED_PAD src0_sel:WORD_1 src1_sel:DWORD
	v_and_b32_sdwa v65, v56, v170 dst_sel:DWORD dst_unused:UNUSED_PAD src0_sel:WORD_1 src1_sel:DWORD
	v_add3_u32 v59, v59, v66, s56
	v_add3_u32 v57, v57, v67, s56
	v_add3_u32 v56, v56, v65, s56
	v_add3_u32 v58, v58, v63, s56
	v_and_b32_e32 v59, 0xffff0000, v59
	v_and_b32_e32 v63, 0xffff0000, v57
	v_or_b32_sdwa v57, v59, v58 dst_sel:DWORD dst_unused:UNUSED_PAD src0_sel:DWORD src1_sel:WORD_1
	v_or_b32_sdwa v56, v63, v56 dst_sel:DWORD dst_unused:UNUSED_PAD src0_sel:DWORD src1_sel:WORD_1
	global_store_dwordx2 v[50:51], v[56:57], off
	global_load_dwordx4 v[56:59], v[72:73], off offset:64
	s_nop 0
	global_load_dwordx4 v[66:69], v[74:75], off offset:64
	s_waitcnt vmcnt(0)
	v_pk_fma_f32 v[42:43], v[42:43], v[58:59], v[68:69]
	v_pk_fma_f32 v[40:41], v[40:41], v[56:57], v[66:67]
	global_store_dwordx4 v[74:75], v[40:43], off offset:64
	global_load_dwordx4 v[56:59], v[52:53], off offset:64
	global_load_dwordx4 v[66:69], v[70:71], off offset:64
	s_waitcnt vmcnt(1)
	v_pk_mul_f32 v[58:59], v[42:43], v[58:59]
	v_pk_mul_f32 v[56:57], v[40:41], v[56:57]
	s_waitcnt vmcnt(0)
	v_pk_add_f32 v[68:69], v[68:69], 1.0 op_sel_hi:[1,0]
	v_pk_add_f32 v[66:67], v[66:67], 1.0 op_sel_hi:[1,0]
	v_pk_mul_f32 v[58:59], v[58:59], v[68:69]
	v_pk_mul_f32 v[56:57], v[56:57], v[66:67]
	v_and_b32_sdwa v66, v59, v170 dst_sel:DWORD dst_unused:UNUSED_PAD src0_sel:WORD_1 src1_sel:DWORD
	v_and_b32_sdwa v67, v57, v170 dst_sel:DWORD dst_unused:UNUSED_PAD src0_sel:WORD_1 src1_sel:DWORD
	v_and_b32_sdwa v63, v58, v170 dst_sel:DWORD dst_unused:UNUSED_PAD src0_sel:WORD_1 src1_sel:DWORD
	v_and_b32_sdwa v65, v56, v170 dst_sel:DWORD dst_unused:UNUSED_PAD src0_sel:WORD_1 src1_sel:DWORD
	v_add3_u32 v59, v59, v66, s56
	v_add3_u32 v57, v57, v67, s56
	v_add3_u32 v56, v56, v65, s56
	v_add3_u32 v58, v58, v63, s56
	v_and_b32_e32 v59, 0xffff0000, v59
	v_and_b32_e32 v63, 0xffff0000, v57
	v_or_b32_sdwa v57, v59, v58 dst_sel:DWORD dst_unused:UNUSED_PAD src0_sel:DWORD src1_sel:WORD_1
	v_or_b32_sdwa v56, v63, v56 dst_sel:DWORD dst_unused:UNUSED_PAD src0_sel:DWORD src1_sel:WORD_1
	global_store_dwordx2 v[50:51], v[56:57], off offset:32
	global_load_dwordx4 v[56:59], v[72:73], off offset:128
	s_nop 0
	global_load_dwordx4 v[66:69], v[74:75], off offset:128
	s_waitcnt vmcnt(0)
	v_pk_fma_f32 v[38:39], v[38:39], v[58:59], v[68:69]
	v_pk_fma_f32 v[36:37], v[36:37], v[56:57], v[66:67]
	global_store_dwordx4 v[74:75], v[36:39], off offset:128
	global_load_dwordx4 v[56:59], v[52:53], off offset:128
	global_load_dwordx4 v[66:69], v[70:71], off offset:128
	s_waitcnt vmcnt(1)
	v_pk_mul_f32 v[58:59], v[38:39], v[58:59]
	v_pk_mul_f32 v[56:57], v[36:37], v[56:57]
	s_waitcnt vmcnt(0)
	v_pk_add_f32 v[68:69], v[68:69], 1.0 op_sel_hi:[1,0]
	v_pk_add_f32 v[66:67], v[66:67], 1.0 op_sel_hi:[1,0]
	v_pk_mul_f32 v[58:59], v[58:59], v[68:69]
	v_pk_mul_f32 v[56:57], v[56:57], v[66:67]
	v_and_b32_sdwa v66, v59, v170 dst_sel:DWORD dst_unused:UNUSED_PAD src0_sel:WORD_1 src1_sel:DWORD
	v_and_b32_sdwa v67, v57, v170 dst_sel:DWORD dst_unused:UNUSED_PAD src0_sel:WORD_1 src1_sel:DWORD
	v_and_b32_sdwa v63, v58, v170 dst_sel:DWORD dst_unused:UNUSED_PAD src0_sel:WORD_1 src1_sel:DWORD
	v_and_b32_sdwa v65, v56, v170 dst_sel:DWORD dst_unused:UNUSED_PAD src0_sel:WORD_1 src1_sel:DWORD
	v_add3_u32 v59, v59, v66, s56
	v_add3_u32 v57, v57, v67, s56
	v_add3_u32 v56, v56, v65, s56
	v_add3_u32 v58, v58, v63, s56
	v_and_b32_e32 v59, 0xffff0000, v59
	v_and_b32_e32 v63, 0xffff0000, v57
	v_or_b32_sdwa v57, v59, v58 dst_sel:DWORD dst_unused:UNUSED_PAD src0_sel:DWORD src1_sel:WORD_1
	v_or_b32_sdwa v56, v63, v56 dst_sel:DWORD dst_unused:UNUSED_PAD src0_sel:DWORD src1_sel:WORD_1
	global_store_dwordx2 v[50:51], v[56:57], off offset:64
	global_load_dwordx4 v[56:59], v[72:73], off offset:192
	s_nop 0
	global_load_dwordx4 v[66:69], v[74:75], off offset:192
	s_waitcnt vmcnt(0)
	v_pk_fma_f32 v[58:59], v[34:35], v[58:59], v[68:69]
	v_pk_fma_f32 v[56:57], v[32:33], v[56:57], v[66:67]
	global_store_dwordx4 v[74:75], v[56:59], off offset:192
	global_load_dwordx4 v[66:69], v[52:53], off offset:192
	s_nop 0
	global_load_dwordx4 v[70:73], v[70:71], off offset:192
	v_mul_f32_e32 v32, v45, v45
	v_mul_f32_e32 v33, v41, v41
	v_fmac_f32_e32 v32, v44, v44
	v_fmac_f32_e32 v33, v40, v40
	v_fmac_f32_e32 v32, v46, v46
	v_fmac_f32_e32 v33, v42, v42
	v_fmac_f32_e32 v32, v47, v47
	v_fmac_f32_e32 v33, v43, v43
	v_add_f32_e32 v32, v32, v33
	v_mul_f32_e32 v33, v37, v37
	v_fmac_f32_e32 v33, v36, v36
	v_fmac_f32_e32 v33, v38, v38
	v_fmac_f32_e32 v33, v39, v39
	v_add_f32_e32 v32, v32, v33
	v_mul_f32_e32 v33, v57, v57
	v_fmac_f32_e32 v33, v56, v56
	v_fmac_f32_e32 v33, v58, v58
	v_fmac_f32_e32 v33, v59, v59
	v_add_f32_e32 v32, v32, v33
	ds_bpermute_b32 v33, v105, v32
	s_waitcnt lgkmcnt(0)
	v_add_f32_e32 v32, v32, v33
	ds_bpermute_b32 v33, v104, v32
	s_waitcnt vmcnt(1)
	v_pk_mul_f32 v[34:35], v[58:59], v[68:69]
	v_pk_mul_f32 v[36:37], v[56:57], v[66:67]
	s_waitcnt vmcnt(0)
	v_pk_add_f32 v[38:39], v[72:73], 1.0 op_sel_hi:[1,0]
	v_pk_add_f32 v[40:41], v[70:71], 1.0 op_sel_hi:[1,0]
	v_pk_mul_f32 v[34:35], v[34:35], v[38:39]
	v_pk_mul_f32 v[36:37], v[36:37], v[40:41]
	v_cvt_pk_bf16_f32 v35, v34, v35
	v_cvt_pk_bf16_f32 v34, v36, v37
	global_store_dwordx2 v[50:51], v[34:35], off offset:96
	s_and_saveexec_b64 s[24:25], s[36:37]
	s_cbranch_execz .LBB0_111
	s_waitcnt lgkmcnt(0)
	v_add_f32_e32 v32, v32, v33
	global_store_dword v[48:49], v32, off offset:64
.LBB0_111:
	s_or_b64 exec, exec, s[24:25]
	v_add_u32_e32 v32, 0xffffe020, v64
	v_or_b32_e32 v40, 32, v62
	v_lshrrev_b32_e32 v32, 10, v32
	s_movk_i32 s16, 0x1800
	v_mad_u32_u24 v32, v32, s16, s16
	v_cmp_lt_i32_e32 vcc, s13, v40
	v_ashrrev_i32_e32 v41, 31, v40
	v_readlane_b32 s16, v250, 15
	v_cndmask_b32_e32 v32, 0, v32, vcc
	s_waitcnt lgkmcnt(0)
	v_ashrrev_i32_e32 v33, 31, v32
	v_lshlrev_b64 v[42:43], 2, v[32:33]
	v_lshl_add_u64 v[32:33], s[40:41], 0, v[42:43]
	v_lshl_add_u64 v[44:45], v[32:33], 0, v[60:61]
	v_lshlrev_b64 v[32:33], 12, v[40:41]
	v_readlane_b32 s17, v250, 16
	v_lshl_add_u64 v[42:43], s[42:43], 0, v[42:43]
	v_lshl_add_u64 v[42:43], v[42:43], 0, v[60:61]
	v_lshl_add_u64 v[32:33], s[16:17], 0, v[32:33]
	v_lshl_add_u64 v[46:47], v[32:33], 0, v[60:61]
	global_load_dwordx4 v[32:35], v[44:45], off
	global_load_dwordx4 v[36:39], v[46:47], off
	v_readlane_b32 s16, v250, 21
	v_lshlrev_b64 v[40:41], 11, v[40:41]
	v_readlane_b32 s17, v250, 22
	s_waitcnt vmcnt(0)
	v_pk_fma_f32 v[30:31], v[30:31], v[34:35], v[38:39]
	v_pk_fma_f32 v[28:29], v[28:29], v[32:33], v[36:37]
	global_store_dwordx4 v[46:47], v[28:31], off
	global_load_dwordx4 v[32:35], v[52:53], off
	global_load_dwordx4 v[36:39], v[42:43], off
	v_lshl_add_u64 v[40:41], s[16:17], 0, v[40:41]
	v_lshl_add_u64 v[50:51], v[54:55], 1, v[40:41]
	s_waitcnt vmcnt(1)
	v_pk_mul_f32 v[34:35], v[30:31], v[34:35]
	v_pk_mul_f32 v[32:33], v[28:29], v[32:33]
	s_waitcnt vmcnt(0)
	v_pk_add_f32 v[38:39], v[38:39], 1.0 op_sel_hi:[1,0]
	v_pk_add_f32 v[36:37], v[36:37], 1.0 op_sel_hi:[1,0]
	v_pk_mul_f32 v[34:35], v[34:35], v[38:39]
	v_pk_mul_f32 v[32:33], v[32:33], v[36:37]
	v_and_b32_sdwa v38, v35, v170 dst_sel:DWORD dst_unused:UNUSED_PAD src0_sel:WORD_1 src1_sel:DWORD
	v_and_b32_sdwa v39, v33, v170 dst_sel:DWORD dst_unused:UNUSED_PAD src0_sel:WORD_1 src1_sel:DWORD
	v_and_b32_sdwa v36, v34, v170 dst_sel:DWORD dst_unused:UNUSED_PAD src0_sel:WORD_1 src1_sel:DWORD
	v_and_b32_sdwa v37, v32, v170 dst_sel:DWORD dst_unused:UNUSED_PAD src0_sel:WORD_1 src1_sel:DWORD
	v_add3_u32 v35, v35, v38, s56
	v_add3_u32 v33, v33, v39, s56
	v_add3_u32 v32, v32, v37, s56
	v_add3_u32 v34, v34, v36, s56
	v_and_b32_e32 v35, 0xffff0000, v35
	v_and_b32_e32 v36, 0xffff0000, v33
	v_or_b32_sdwa v33, v35, v34 dst_sel:DWORD dst_unused:UNUSED_PAD src0_sel:DWORD src1_sel:WORD_1
	v_or_b32_sdwa v32, v36, v32 dst_sel:DWORD dst_unused:UNUSED_PAD src0_sel:DWORD src1_sel:WORD_1
	global_store_dwordx2 v[50:51], v[32:33], off
	global_load_dwordx4 v[32:35], v[44:45], off offset:64
	s_nop 0
	global_load_dwordx4 v[36:39], v[46:47], off offset:64
	s_waitcnt vmcnt(0)
	v_pk_fma_f32 v[26:27], v[26:27], v[34:35], v[38:39]
	v_pk_fma_f32 v[24:25], v[24:25], v[32:33], v[36:37]
	global_store_dwordx4 v[46:47], v[24:27], off offset:64
	global_load_dwordx4 v[32:35], v[52:53], off offset:64
	global_load_dwordx4 v[36:39], v[42:43], off offset:64
	s_waitcnt vmcnt(1)
	v_pk_mul_f32 v[34:35], v[26:27], v[34:35]
	v_pk_mul_f32 v[32:33], v[24:25], v[32:33]
	s_waitcnt vmcnt(0)
	v_pk_add_f32 v[38:39], v[38:39], 1.0 op_sel_hi:[1,0]
	v_pk_add_f32 v[36:37], v[36:37], 1.0 op_sel_hi:[1,0]
	v_pk_mul_f32 v[34:35], v[34:35], v[38:39]
	v_pk_mul_f32 v[32:33], v[32:33], v[36:37]
	v_and_b32_sdwa v38, v35, v170 dst_sel:DWORD dst_unused:UNUSED_PAD src0_sel:WORD_1 src1_sel:DWORD
	v_and_b32_sdwa v39, v33, v170 dst_sel:DWORD dst_unused:UNUSED_PAD src0_sel:WORD_1 src1_sel:DWORD
	v_and_b32_sdwa v36, v34, v170 dst_sel:DWORD dst_unused:UNUSED_PAD src0_sel:WORD_1 src1_sel:DWORD
	v_and_b32_sdwa v37, v32, v170 dst_sel:DWORD dst_unused:UNUSED_PAD src0_sel:WORD_1 src1_sel:DWORD
	v_add3_u32 v35, v35, v38, s56
	v_add3_u32 v33, v33, v39, s56
	v_add3_u32 v32, v32, v37, s56
	v_add3_u32 v34, v34, v36, s56
	v_and_b32_e32 v35, 0xffff0000, v35
	v_and_b32_e32 v36, 0xffff0000, v33
	v_or_b32_sdwa v33, v35, v34 dst_sel:DWORD dst_unused:UNUSED_PAD src0_sel:DWORD src1_sel:WORD_1
	v_or_b32_sdwa v32, v36, v32 dst_sel:DWORD dst_unused:UNUSED_PAD src0_sel:DWORD src1_sel:WORD_1
	global_store_dwordx2 v[50:51], v[32:33], off offset:32
	global_load_dwordx4 v[32:35], v[44:45], off offset:128
	s_nop 0
	global_load_dwordx4 v[36:39], v[46:47], off offset:128
	s_waitcnt vmcnt(0)
	v_pk_fma_f32 v[22:23], v[22:23], v[34:35], v[38:39]
	v_pk_fma_f32 v[20:21], v[20:21], v[32:33], v[36:37]
	global_store_dwordx4 v[46:47], v[20:23], off offset:128
	global_load_dwordx4 v[32:35], v[52:53], off offset:128
	global_load_dwordx4 v[36:39], v[42:43], off offset:128
	s_waitcnt vmcnt(1)
	v_pk_mul_f32 v[34:35], v[22:23], v[34:35]
	v_pk_mul_f32 v[32:33], v[20:21], v[32:33]
	s_waitcnt vmcnt(0)
	v_pk_add_f32 v[38:39], v[38:39], 1.0 op_sel_hi:[1,0]
	v_pk_add_f32 v[36:37], v[36:37], 1.0 op_sel_hi:[1,0]
	v_pk_mul_f32 v[34:35], v[34:35], v[38:39]
	v_pk_mul_f32 v[32:33], v[32:33], v[36:37]
	v_and_b32_sdwa v38, v35, v170 dst_sel:DWORD dst_unused:UNUSED_PAD src0_sel:WORD_1 src1_sel:DWORD
	v_and_b32_sdwa v39, v33, v170 dst_sel:DWORD dst_unused:UNUSED_PAD src0_sel:WORD_1 src1_sel:DWORD
	v_and_b32_sdwa v36, v34, v170 dst_sel:DWORD dst_unused:UNUSED_PAD src0_sel:WORD_1 src1_sel:DWORD
	v_and_b32_sdwa v37, v32, v170 dst_sel:DWORD dst_unused:UNUSED_PAD src0_sel:WORD_1 src1_sel:DWORD
	v_add3_u32 v35, v35, v38, s56
	v_add3_u32 v33, v33, v39, s56
	v_add3_u32 v32, v32, v37, s56
	v_add3_u32 v34, v34, v36, s56
	v_and_b32_e32 v35, 0xffff0000, v35
	v_and_b32_e32 v36, 0xffff0000, v33
	v_or_b32_sdwa v33, v35, v34 dst_sel:DWORD dst_unused:UNUSED_PAD src0_sel:DWORD src1_sel:WORD_1
	v_or_b32_sdwa v32, v36, v32 dst_sel:DWORD dst_unused:UNUSED_PAD src0_sel:DWORD src1_sel:WORD_1
	global_store_dwordx2 v[50:51], v[32:33], off offset:64
	global_load_dwordx4 v[32:35], v[44:45], off offset:192
	s_nop 0
	global_load_dwordx4 v[36:39], v[46:47], off offset:192
	s_waitcnt vmcnt(0)
	v_pk_fma_f32 v[34:35], v[18:19], v[34:35], v[38:39]
	v_pk_fma_f32 v[32:33], v[16:17], v[32:33], v[36:37]
	global_store_dwordx4 v[46:47], v[32:35], off offset:192
	global_load_dwordx4 v[36:39], v[52:53], off offset:192
	s_nop 0
	global_load_dwordx4 v[40:43], v[42:43], off offset:192
	v_mul_f32_e32 v16, v29, v29
	v_mul_f32_e32 v17, v25, v25
	v_fmac_f32_e32 v16, v28, v28
	v_fmac_f32_e32 v17, v24, v24
	v_fmac_f32_e32 v16, v30, v30
	v_fmac_f32_e32 v17, v26, v26
	v_fmac_f32_e32 v16, v31, v31
	v_fmac_f32_e32 v17, v27, v27
	v_add_f32_e32 v16, v16, v17
	v_mul_f32_e32 v17, v21, v21
	v_fmac_f32_e32 v17, v20, v20
	v_fmac_f32_e32 v17, v22, v22
	v_fmac_f32_e32 v17, v23, v23
	v_add_f32_e32 v16, v16, v17
	v_mul_f32_e32 v17, v33, v33
	v_fmac_f32_e32 v17, v32, v32
	v_fmac_f32_e32 v17, v34, v34
	v_fmac_f32_e32 v17, v35, v35
	v_add_f32_e32 v16, v16, v17
	ds_bpermute_b32 v17, v105, v16
	s_waitcnt lgkmcnt(0)
	v_add_f32_e32 v16, v16, v17
	ds_bpermute_b32 v17, v104, v16
	s_waitcnt vmcnt(1)
	v_pk_mul_f32 v[18:19], v[34:35], v[38:39]
	v_pk_mul_f32 v[20:21], v[32:33], v[36:37]
	s_waitcnt vmcnt(0)
	v_pk_add_f32 v[22:23], v[42:43], 1.0 op_sel_hi:[1,0]
	v_pk_add_f32 v[24:25], v[40:41], 1.0 op_sel_hi:[1,0]
	v_pk_mul_f32 v[18:19], v[18:19], v[22:23]
	v_pk_mul_f32 v[20:21], v[20:21], v[24:25]
	v_cvt_pk_bf16_f32 v19, v18, v19
	v_cvt_pk_bf16_f32 v18, v20, v21
	global_store_dwordx2 v[50:51], v[18:19], off offset:96
	s_and_saveexec_b64 s[24:25], s[36:37]
	s_movk_i32 s89, 0xff
	s_cbranch_execz .LBB0_113
	s_waitcnt lgkmcnt(0)
	v_add_f32_e32 v16, v16, v17
	global_store_dword v[48:49], v16, off offset:128
.LBB0_113:
	s_or_b64 exec, exec, s[24:25]
	v_add_u32_e32 v16, 0xffffe030, v64
	v_or_b32_e32 v24, 48, v62
	v_lshrrev_b32_e32 v16, 10, v16
	s_movk_i32 s16, 0x1800
	v_mad_u32_u24 v16, v16, s16, s16
	v_cmp_lt_i32_e32 vcc, s13, v24
	v_ashrrev_i32_e32 v25, 31, v24
	v_readlane_b32 s16, v250, 15
	v_cndmask_b32_e32 v16, 0, v16, vcc
	s_waitcnt lgkmcnt(0)
	v_ashrrev_i32_e32 v17, 31, v16
	v_lshlrev_b64 v[26:27], 2, v[16:17]
	v_lshl_add_u64 v[16:17], s[40:41], 0, v[26:27]
	v_lshl_add_u64 v[28:29], v[16:17], 0, v[60:61]
	v_lshlrev_b64 v[16:17], 12, v[24:25]
	v_readlane_b32 s17, v250, 16
	v_lshl_add_u64 v[26:27], s[42:43], 0, v[26:27]
	v_lshl_add_u64 v[26:27], v[26:27], 0, v[60:61]
	v_lshl_add_u64 v[16:17], s[16:17], 0, v[16:17]
	v_lshl_add_u64 v[30:31], v[16:17], 0, v[60:61]
	global_load_dwordx4 v[16:19], v[28:29], off
	global_load_dwordx4 v[20:23], v[30:31], off
	v_readlane_b32 s16, v250, 21
	v_lshlrev_b64 v[24:25], 11, v[24:25]
	v_readlane_b32 s17, v250, 22
	s_waitcnt vmcnt(0)
	v_pk_fma_f32 v[14:15], v[14:15], v[18:19], v[22:23]
	v_pk_fma_f32 v[12:13], v[12:13], v[16:17], v[20:21]
	global_store_dwordx4 v[30:31], v[12:15], off
	global_load_dwordx4 v[16:19], v[52:53], off
	global_load_dwordx4 v[20:23], v[26:27], off
	v_lshl_add_u64 v[24:25], s[16:17], 0, v[24:25]
	v_lshl_add_u64 v[32:33], v[54:55], 1, v[24:25]
	s_waitcnt vmcnt(1)
	v_pk_mul_f32 v[18:19], v[14:15], v[18:19]
	v_pk_mul_f32 v[16:17], v[12:13], v[16:17]
	s_waitcnt vmcnt(0)
	v_pk_add_f32 v[22:23], v[22:23], 1.0 op_sel_hi:[1,0]
	v_pk_add_f32 v[20:21], v[20:21], 1.0 op_sel_hi:[1,0]
	v_pk_mul_f32 v[18:19], v[18:19], v[22:23]
	v_pk_mul_f32 v[16:17], v[16:17], v[20:21]
	v_and_b32_sdwa v22, v19, v170 dst_sel:DWORD dst_unused:UNUSED_PAD src0_sel:WORD_1 src1_sel:DWORD
	v_and_b32_sdwa v23, v17, v170 dst_sel:DWORD dst_unused:UNUSED_PAD src0_sel:WORD_1 src1_sel:DWORD
	v_and_b32_sdwa v20, v18, v170 dst_sel:DWORD dst_unused:UNUSED_PAD src0_sel:WORD_1 src1_sel:DWORD
	v_and_b32_sdwa v21, v16, v170 dst_sel:DWORD dst_unused:UNUSED_PAD src0_sel:WORD_1 src1_sel:DWORD
	v_add3_u32 v19, v19, v22, s56
	v_add3_u32 v17, v17, v23, s56
	v_add3_u32 v16, v16, v21, s56
	v_add3_u32 v18, v18, v20, s56
	v_and_b32_e32 v19, 0xffff0000, v19
	v_and_b32_e32 v20, 0xffff0000, v17
	v_or_b32_sdwa v17, v19, v18 dst_sel:DWORD dst_unused:UNUSED_PAD src0_sel:DWORD src1_sel:WORD_1
	v_or_b32_sdwa v16, v20, v16 dst_sel:DWORD dst_unused:UNUSED_PAD src0_sel:DWORD src1_sel:WORD_1
	global_store_dwordx2 v[32:33], v[16:17], off
	global_load_dwordx4 v[16:19], v[28:29], off offset:64
	s_nop 0
	global_load_dwordx4 v[20:23], v[30:31], off offset:64
	s_waitcnt vmcnt(0)
	v_pk_fma_f32 v[10:11], v[10:11], v[18:19], v[22:23]
	v_pk_fma_f32 v[8:9], v[8:9], v[16:17], v[20:21]
	global_store_dwordx4 v[30:31], v[8:11], off offset:64
	global_load_dwordx4 v[16:19], v[52:53], off offset:64
	global_load_dwordx4 v[20:23], v[26:27], off offset:64
	s_waitcnt vmcnt(1)
	v_pk_mul_f32 v[18:19], v[10:11], v[18:19]
	v_pk_mul_f32 v[16:17], v[8:9], v[16:17]
	s_waitcnt vmcnt(0)
	v_pk_add_f32 v[22:23], v[22:23], 1.0 op_sel_hi:[1,0]
	v_pk_add_f32 v[20:21], v[20:21], 1.0 op_sel_hi:[1,0]
	v_pk_mul_f32 v[18:19], v[18:19], v[22:23]
	v_pk_mul_f32 v[16:17], v[16:17], v[20:21]
	v_and_b32_sdwa v22, v19, v170 dst_sel:DWORD dst_unused:UNUSED_PAD src0_sel:WORD_1 src1_sel:DWORD
	v_and_b32_sdwa v23, v17, v170 dst_sel:DWORD dst_unused:UNUSED_PAD src0_sel:WORD_1 src1_sel:DWORD
	v_and_b32_sdwa v20, v18, v170 dst_sel:DWORD dst_unused:UNUSED_PAD src0_sel:WORD_1 src1_sel:DWORD
	v_and_b32_sdwa v21, v16, v170 dst_sel:DWORD dst_unused:UNUSED_PAD src0_sel:WORD_1 src1_sel:DWORD
	v_add3_u32 v19, v19, v22, s56
	v_add3_u32 v17, v17, v23, s56
	v_add3_u32 v16, v16, v21, s56
	v_add3_u32 v18, v18, v20, s56
	v_and_b32_e32 v19, 0xffff0000, v19
	v_and_b32_e32 v20, 0xffff0000, v17
	v_or_b32_sdwa v17, v19, v18 dst_sel:DWORD dst_unused:UNUSED_PAD src0_sel:DWORD src1_sel:WORD_1
	v_or_b32_sdwa v16, v20, v16 dst_sel:DWORD dst_unused:UNUSED_PAD src0_sel:DWORD src1_sel:WORD_1
	global_store_dwordx2 v[32:33], v[16:17], off offset:32
	global_load_dwordx4 v[16:19], v[28:29], off offset:128
	s_nop 0
	global_load_dwordx4 v[20:23], v[30:31], off offset:128
	s_waitcnt vmcnt(0)
	v_pk_fma_f32 v[6:7], v[6:7], v[18:19], v[22:23]
	v_pk_fma_f32 v[4:5], v[4:5], v[16:17], v[20:21]
	global_store_dwordx4 v[30:31], v[4:7], off offset:128
	global_load_dwordx4 v[16:19], v[52:53], off offset:128
	global_load_dwordx4 v[20:23], v[26:27], off offset:128
	s_waitcnt vmcnt(1)
	v_pk_mul_f32 v[18:19], v[6:7], v[18:19]
	v_pk_mul_f32 v[16:17], v[4:5], v[16:17]
	s_waitcnt vmcnt(0)
	v_pk_add_f32 v[22:23], v[22:23], 1.0 op_sel_hi:[1,0]
	v_pk_add_f32 v[20:21], v[20:21], 1.0 op_sel_hi:[1,0]
	v_pk_mul_f32 v[18:19], v[18:19], v[22:23]
	v_pk_mul_f32 v[16:17], v[16:17], v[20:21]
	v_and_b32_sdwa v22, v19, v170 dst_sel:DWORD dst_unused:UNUSED_PAD src0_sel:WORD_1 src1_sel:DWORD
	v_and_b32_sdwa v23, v17, v170 dst_sel:DWORD dst_unused:UNUSED_PAD src0_sel:WORD_1 src1_sel:DWORD
	v_and_b32_sdwa v20, v18, v170 dst_sel:DWORD dst_unused:UNUSED_PAD src0_sel:WORD_1 src1_sel:DWORD
	v_and_b32_sdwa v21, v16, v170 dst_sel:DWORD dst_unused:UNUSED_PAD src0_sel:WORD_1 src1_sel:DWORD
	v_add3_u32 v19, v19, v22, s56
	v_add3_u32 v17, v17, v23, s56
	v_add3_u32 v16, v16, v21, s56
	v_add3_u32 v18, v18, v20, s56
	v_and_b32_e32 v19, 0xffff0000, v19
	v_and_b32_e32 v20, 0xffff0000, v17
	v_or_b32_sdwa v17, v19, v18 dst_sel:DWORD dst_unused:UNUSED_PAD src0_sel:DWORD src1_sel:WORD_1
	v_or_b32_sdwa v16, v20, v16 dst_sel:DWORD dst_unused:UNUSED_PAD src0_sel:DWORD src1_sel:WORD_1
	global_store_dwordx2 v[32:33], v[16:17], off offset:64
	global_load_dwordx4 v[16:19], v[28:29], off offset:192
	s_nop 0
	global_load_dwordx4 v[20:23], v[30:31], off offset:192
	s_waitcnt vmcnt(0)
	v_pk_fma_f32 v[18:19], v[2:3], v[18:19], v[22:23]
	v_pk_fma_f32 v[16:17], v[0:1], v[16:17], v[20:21]
	global_store_dwordx4 v[30:31], v[16:19], off offset:192
	global_load_dwordx4 v[20:23], v[52:53], off offset:192
	s_nop 0
	global_load_dwordx4 v[24:27], v[26:27], off offset:192
	v_mul_f32_e32 v0, v13, v13
	v_mul_f32_e32 v1, v9, v9
	v_fmac_f32_e32 v0, v12, v12
	v_fmac_f32_e32 v1, v8, v8
	v_fmac_f32_e32 v0, v14, v14
	v_fmac_f32_e32 v1, v10, v10
	v_fmac_f32_e32 v0, v15, v15
	v_fmac_f32_e32 v1, v11, v11
	v_add_f32_e32 v0, v0, v1
	v_mul_f32_e32 v1, v5, v5
	v_fmac_f32_e32 v1, v4, v4
	v_fmac_f32_e32 v1, v6, v6
	v_fmac_f32_e32 v1, v7, v7
	v_add_f32_e32 v0, v0, v1
	v_mul_f32_e32 v1, v17, v17
	v_fmac_f32_e32 v1, v16, v16
	v_fmac_f32_e32 v1, v18, v18
	v_fmac_f32_e32 v1, v19, v19
	v_add_f32_e32 v0, v0, v1
	ds_bpermute_b32 v1, v105, v0
	s_waitcnt lgkmcnt(0)
	v_add_f32_e32 v0, v0, v1
	ds_bpermute_b32 v1, v104, v0
	s_waitcnt vmcnt(1)
	v_pk_mul_f32 v[2:3], v[18:19], v[22:23]
	v_pk_mul_f32 v[4:5], v[16:17], v[20:21]
	s_waitcnt vmcnt(0)
	v_pk_add_f32 v[6:7], v[26:27], 1.0 op_sel_hi:[1,0]
	v_pk_add_f32 v[8:9], v[24:25], 1.0 op_sel_hi:[1,0]
	v_pk_mul_f32 v[2:3], v[2:3], v[6:7]
	v_pk_mul_f32 v[4:5], v[4:5], v[8:9]
	v_cvt_pk_bf16_f32 v3, v2, v3
	v_cvt_pk_bf16_f32 v2, v4, v5
	global_store_dwordx2 v[32:33], v[2:3], off offset:96
	s_and_saveexec_b64 s[24:25], s[36:37]
	s_cbranch_execz .LBB0_104
	s_waitcnt lgkmcnt(0)
	v_add_f32_e32 v0, v0, v1
	global_store_dword v[48:49], v0, off offset:192
	s_branch .LBB0_104

.LBB0_122:
	s_or_b64 exec, exec, s[2:3]
	v_add_u32_e32 v13, 0xffffe010, v18
	s_waitcnt lgkmcnt(0)
	v_lshl_add_u64 v[14:15], s[0:1], 0, v[128:129]
	v_or_b32_e32 v12, 16, v12
	v_lshrrev_b32_e32 v13, 10, v13
	s_movk_i32 s0, 0x1800
	v_mad_u32_u24 v13, v13, s0, s0
	v_cmp_lt_i32_e64 s[0:1], s13, v12
	s_nop 1
	v_cndmask_b32_e64 v18, 0, v13, s[0:1]
	v_ashrrev_i32_e32 v19, 31, v18
	v_lshlrev_b64 v[34:35], 2, v[18:19]
	v_ashrrev_i32_e32 v13, 31, v12
	v_lshl_add_u64 v[18:19], s[40:41], 0, v[34:35]
	v_readlane_b32 s0, v250, 15
	v_lshl_add_u64 v[20:21], v[18:19], 0, v[128:129]
	v_lshlrev_b64 v[18:19], 12, v[12:13]
	v_readlane_b32 s1, v250, 16
	s_nop 0
	v_lshl_add_u64 v[18:19], s[0:1], 0, v[18:19]
	v_lshl_add_u64 v[18:19], v[18:19], 0, v[128:129]
	v_readlane_b32 s0, v250, 21
	v_readlane_b32 s1, v250, 22
	s_waitcnt vmcnt(16)
	v_pk_fma_f32 v[28:29], v[38:39], v[74:75], v[212:213]
	v_pk_fma_f32 v[26:27], v[36:37], v[72:73], v[210:211]
	v_lshl_add_u64 v[22:23], s[42:43], 0, v[34:35]
	global_store_dwordx4 v[18:19], v[26:29], off
	v_lshl_add_u64 v[22:23], v[22:23], 0, v[128:129]
	v_mul_f32_e32 v38, v27, v27
	v_fmac_f32_e32 v38, v26, v26
	v_fmac_f32_e32 v38, v28, v28
	v_fmac_f32_e32 v38, v29, v29
	v_pk_mul_f32 v[24:25], v[28:29], v[142:143]
	v_pk_add_f32 v[28:29], v[158:159], 1.0 op_sel_hi:[1,0]
	v_pk_mul_f32 v[26:27], v[26:27], v[140:141]
	v_pk_add_f32 v[30:31], v[156:157], 1.0 op_sel_hi:[1,0]
	v_pk_mul_f32 v[24:25], v[24:25], v[28:29]
	v_lshlrev_b64 v[28:29], 11, v[12:13]
	v_pk_mul_f32 v[26:27], v[26:27], v[30:31]
	v_lshl_add_u64 v[28:29], s[0:1], 0, v[28:29]
	v_lshl_add_u64 v[16:17], v[28:29], 0, v[16:17]
	v_cvt_pk_bf16_f32 v25, v24, v25
	v_cvt_pk_bf16_f32 v24, v26, v27
	global_store_dwordx2 v[16:17], v[24:25], off
	s_nop 0
	v_pk_fma_f32 v[8:9], v[8:9], v[80:81], v[214:215]
	s_nop 0
	v_mul_f32_e32 v24, v9, v9
	v_pk_fma_f32 v[10:11], v[10:11], v[82:83], v[216:217]
	v_fmac_f32_e32 v24, v8, v8
	v_fmac_f32_e32 v24, v10, v10
	global_store_dwordx4 v[18:19], v[8:11], off offset:64
	v_fmac_f32_e32 v24, v11, v11
	v_add_f32_e32 v32, v38, v24
	v_pk_mul_f32 v[10:11], v[10:11], v[146:147]
	v_pk_mul_f32 v[8:9], v[8:9], v[144:145]
	v_pk_add_f32 v[24:25], v[162:163], 1.0 op_sel_hi:[1,0]
	v_pk_add_f32 v[26:27], v[160:161], 1.0 op_sel_hi:[1,0]
	v_pk_mul_f32 v[10:11], v[10:11], v[24:25]
	v_pk_mul_f32 v[8:9], v[8:9], v[26:27]
	v_and_b32_sdwa v24, v10, v170 dst_sel:DWORD dst_unused:UNUSED_PAD src0_sel:WORD_1 src1_sel:DWORD
	v_and_b32_sdwa v25, v8, v170 dst_sel:DWORD dst_unused:UNUSED_PAD src0_sel:WORD_1 src1_sel:DWORD
	v_add3_u32 v8, v8, v25, s56
	v_add3_u32 v10, v10, v24, s56
	v_and_b32_sdwa v24, v11, v170 dst_sel:DWORD dst_unused:UNUSED_PAD src0_sel:WORD_1 src1_sel:DWORD
	v_and_b32_sdwa v25, v9, v170 dst_sel:DWORD dst_unused:UNUSED_PAD src0_sel:WORD_1 src1_sel:DWORD
	v_add3_u32 v11, v11, v24, s56
	v_add3_u32 v9, v9, v25, s56
	v_and_b32_e32 v11, 0xffff0000, v11
	v_and_b32_e32 v24, 0xffff0000, v9
	v_or_b32_sdwa v9, v11, v10 dst_sel:DWORD dst_unused:UNUSED_PAD src0_sel:DWORD src1_sel:WORD_1
	v_or_b32_sdwa v8, v24, v8 dst_sel:DWORD dst_unused:UNUSED_PAD src0_sel:DWORD src1_sel:WORD_1
	global_store_dwordx2 v[16:17], v[8:9], off offset:32
	s_nop 0
	v_pk_fma_f32 v[4:5], v[4:5], v[88:89], v[218:219]
	s_nop 0
	v_mul_f32_e32 v8, v5, v5
	v_pk_fma_f32 v[6:7], v[6:7], v[90:91], v[220:221]
	v_fmac_f32_e32 v8, v4, v4
	v_fmac_f32_e32 v8, v6, v6
	global_store_dwordx4 v[18:19], v[4:7], off offset:128
	v_fmac_f32_e32 v8, v7, v7
	v_add_f32_e32 v28, v32, v8
	v_pk_mul_f32 v[6:7], v[6:7], v[150:151]
	v_pk_mul_f32 v[4:5], v[4:5], v[148:149]
	v_pk_add_f32 v[8:9], v[182:183], 1.0 op_sel_hi:[1,0]
	v_pk_add_f32 v[10:11], v[180:181], 1.0 op_sel_hi:[1,0]
	v_pk_mul_f32 v[6:7], v[6:7], v[8:9]
	v_pk_mul_f32 v[4:5], v[4:5], v[10:11]
	v_and_b32_sdwa v8, v6, v170 dst_sel:DWORD dst_unused:UNUSED_PAD src0_sel:WORD_1 src1_sel:DWORD
	v_and_b32_sdwa v9, v4, v170 dst_sel:DWORD dst_unused:UNUSED_PAD src0_sel:WORD_1 src1_sel:DWORD
	v_add3_u32 v4, v4, v9, s56
	v_add3_u32 v6, v6, v8, s56
	v_and_b32_sdwa v8, v7, v170 dst_sel:DWORD dst_unused:UNUSED_PAD src0_sel:WORD_1 src1_sel:DWORD
	v_and_b32_sdwa v9, v5, v170 dst_sel:DWORD dst_unused:UNUSED_PAD src0_sel:WORD_1 src1_sel:DWORD
	v_add3_u32 v7, v7, v8, s56
	v_add3_u32 v5, v5, v9, s56
	v_and_b32_e32 v7, 0xffff0000, v7
	v_and_b32_e32 v8, 0xffff0000, v5
	v_or_b32_sdwa v5, v7, v6 dst_sel:DWORD dst_unused:UNUSED_PAD src0_sel:DWORD src1_sel:WORD_1
	v_or_b32_sdwa v4, v8, v4 dst_sel:DWORD dst_unused:UNUSED_PAD src0_sel:DWORD src1_sel:WORD_1
	global_store_dwordx2 v[16:17], v[4:5], off offset:64
	s_nop 0
	v_pk_fma_f32 v[0:1], v[0:1], v[136:137], v[222:223]
	s_nop 0
	v_mul_f32_e32 v4, v1, v1
	v_pk_fma_f32 v[2:3], v[2:3], v[138:139], v[224:225]
	v_fmac_f32_e32 v4, v0, v0
	v_fmac_f32_e32 v4, v2, v2
	global_store_dwordx4 v[18:19], v[0:3], off offset:192
	v_fmac_f32_e32 v4, v3, v3
	v_add_f32_e32 v18, v28, v4
	v_pk_mul_f32 v[2:3], v[2:3], v[154:155]
	v_pk_mul_f32 v[0:1], v[0:1], v[152:153]
	v_pk_add_f32 v[4:5], v[192:193], 1.0 op_sel_hi:[1,0]
	v_pk_add_f32 v[6:7], v[190:191], 1.0 op_sel_hi:[1,0]
	v_pk_mul_f32 v[2:3], v[2:3], v[4:5]
	v_pk_mul_f32 v[0:1], v[0:1], v[6:7]
	v_and_b32_sdwa v4, v2, v170 dst_sel:DWORD dst_unused:UNUSED_PAD src0_sel:WORD_1 src1_sel:DWORD
	v_and_b32_sdwa v5, v0, v170 dst_sel:DWORD dst_unused:UNUSED_PAD src0_sel:WORD_1 src1_sel:DWORD
	v_add3_u32 v0, v0, v5, s56
	v_add3_u32 v2, v2, v4, s56
	v_and_b32_sdwa v4, v3, v170 dst_sel:DWORD dst_unused:UNUSED_PAD src0_sel:WORD_1 src1_sel:DWORD
	v_and_b32_sdwa v5, v1, v170 dst_sel:DWORD dst_unused:UNUSED_PAD src0_sel:WORD_1 src1_sel:DWORD
	v_add3_u32 v3, v3, v4, s56
	v_add3_u32 v1, v1, v5, s56
	v_and_b32_e32 v3, 0xffff0000, v3
	v_and_b32_e32 v4, 0xffff0000, v1
	v_or_b32_sdwa v1, v3, v2 dst_sel:DWORD dst_unused:UNUSED_PAD src0_sel:DWORD src1_sel:WORD_1
	v_or_b32_sdwa v0, v4, v0 dst_sel:DWORD dst_unused:UNUSED_PAD src0_sel:DWORD src1_sel:WORD_1
	global_store_dwordx2 v[16:17], v[0:1], off offset:96
	ds_bpermute_b32 v0, v105, v18
	s_waitcnt lgkmcnt(0)
	v_add_f32_e32 v0, v18, v0
	ds_bpermute_b32 v1, v104, v0
	s_and_saveexec_b64 s[0:1], vcc
	s_movk_i32 s89, 0xff
	s_cbranch_execz .LBB0_124
	v_readlane_b32 s2, v253, 20
	s_add_u32 s2, s26, s2
	s_addc_u32 s3, s27, 0
	v_lshl_add_u64 v[2:3], v[12:13], 2, s[2:3]
	s_waitcnt lgkmcnt(0)
	v_add_f32_e32 v0, v0, v1
	global_store_dword v[2:3], v0, off

.LBB0_139:
	v_add_u32_e32 v160, v140, v141
	v_add_u32_e32 v143, v139, v141
	ds_read_b128 v[96:99], v160 offset:16384
	ds_read_b128 v[100:103], v160 offset:18432
	ds_read_b128 v[104:107], v143
	ds_read_b128 v[108:111], v143 offset:2048
	ds_read_b128 v[112:115], v160 offset:20480
	ds_read_b128 v[116:119], v160 offset:22528
	s_waitcnt lgkmcnt(3)
	v_mfma_f32_16x16x32_bf16 v[92:95], v[96:99], v[104:107], v[92:95]
	s_add_i32 s29, s28, 2
	s_cmp_lt_u32 s28, 6
	s_cselect_b64 s[0:1], -1, 0
	v_mfma_f32_16x16x32_bf16 v[88:91], v[100:103], v[104:107], v[88:91]
	s_and_b64 vcc, s[0:1], exec
	v_add_u32_e32 v161, v139, v142
	v_add_u32_e32 v162, v140, v142
	s_waitcnt lgkmcnt(1)
	v_mfma_f32_16x16x32_bf16 v[84:87], v[112:115], v[104:107], v[84:87]
	s_cselect_b32 s92, s27, 0x380
	s_addk_i32 s27, 0x100
	s_waitcnt lgkmcnt(0)
	v_mfma_f32_16x16x32_bf16 v[80:83], v[116:119], v[104:107], v[80:83]
	v_mfma_f32_16x16x32_bf16 v[76:79], v[96:99], v[108:111], v[76:79]
	v_mfma_f32_16x16x32_bf16 v[72:75], v[100:103], v[108:111], v[72:75]
	v_mfma_f32_16x16x32_bf16 v[52:55], v[112:115], v[108:111], v[52:55]
	v_mfma_f32_16x16x32_bf16 v[36:39], v[116:119], v[108:111], v[36:39]
	ds_read_b128 v[104:107], v143 offset:4096
	ds_read_b128 v[108:111], v143 offset:6144
	s_waitcnt lgkmcnt(1)
	v_mfma_f32_16x16x32_bf16 v[32:35], v[96:99], v[104:107], v[32:35]
	v_mfma_f32_16x16x32_bf16 v[24:27], v[100:103], v[104:107], v[24:27]
	v_mfma_f32_16x16x32_bf16 v[20:23], v[112:115], v[104:107], v[20:23]
	v_mfma_f32_16x16x32_bf16 v[16:19], v[116:119], v[104:107], v[16:19]
	s_waitcnt lgkmcnt(0)
	v_mfma_f32_16x16x32_bf16 v[8:11], v[96:99], v[108:111], v[8:11]
	v_mfma_f32_16x16x32_bf16 v[4:7], v[100:103], v[108:111], v[4:7]
	ds_read_b128 v[96:99], v161
	ds_read_b128 v[100:103], v161 offset:2048
	ds_read_b128 v[120:123], v162 offset:16384
	ds_read_b128 v[104:107], v161 offset:4096
	ds_read_b128 v[144:147], v161 offset:6144
	ds_read_b128 v[148:151], v162 offset:18432
	ds_read_b128 v[152:155], v162 offset:20480
	ds_read_b128 v[156:159], v162 offset:22528
	s_waitcnt vmcnt(6)
	ds_write_b128 v138, v[40:43] offset:32768
	s_waitcnt vmcnt(5)
	ds_write_b128 v138, v[44:47] offset:36864
	s_waitcnt vmcnt(4)
	ds_write_b128 v138, v[48:51] offset:40960
	s_waitcnt vmcnt(3)
	ds_write_b128 v138, v[60:63] offset:45056
	ds_write_b128 v138, v[28:31] offset:49152
	s_waitcnt vmcnt(2)
	ds_write_b128 v138, v[56:59] offset:53248
	s_waitcnt vmcnt(1)
	ds_write_b128 v138, v[64:67] offset:57344
	v_lshl_add_u64 v[64:65], v[132:133], 0, s[92:93]
	s_waitcnt vmcnt(0)
	ds_write_b128 v138, v[68:71] offset:61440
	v_add_co_u32_e64 v68, s[0:1], s16, v64
	s_waitcnt lgkmcnt(13)
	v_mfma_f32_16x16x32_bf16 v[40:43], v[120:123], v[96:99], v[92:95]
	v_addc_co_u32_e64 v69, s[0:1], 0, v65, s[0:1]
	v_add_co_u32_e64 v70, s[0:1], s11, v64
	s_waitcnt lgkmcnt(10)
	v_mfma_f32_16x16x32_bf16 v[44:47], v[148:151], v[96:99], v[88:91]
	v_addc_co_u32_e64 v71, s[0:1], 0, v65, s[0:1]
	v_lshl_add_u64 v[66:67], v[134:135], 0, s[92:93]
	s_waitcnt lgkmcnt(9)
	v_mfma_f32_16x16x32_bf16 v[28:31], v[152:155], v[96:99], v[84:87]
	s_waitcnt lgkmcnt(8)
	v_mfma_f32_16x16x32_bf16 v[48:51], v[156:159], v[96:99], v[80:83]
	global_load_dwordx4 v[96:99], v[64:65], off
	v_add_co_u32_e64 v64, s[0:1], s60, v64
	v_mfma_f32_16x16x32_bf16 v[60:63], v[148:151], v[100:103], v[72:75]
	s_nop 0
	v_addc_co_u32_e64 v65, s[0:1], 0, v65, s[0:1]
	s_nop 0
	v_add_co_u32_e64 v72, s[0:1], s16, v66
	v_mfma_f32_16x16x32_bf16 v[56:59], v[120:123], v[100:103], v[76:79]
	s_nop 0
	v_addc_co_u32_e64 v73, s[0:1], 0, v67, s[0:1]
	v_add_co_u32_e64 v74, s[0:1], s11, v66
	v_mfma_f32_16x16x32_bf16 v[52:55], v[152:155], v[100:103], v[52:55]
	s_nop 0
	v_addc_co_u32_e64 v75, s[0:1], 0, v67, s[0:1]
	v_mfma_f32_16x16x32_bf16 v[36:39], v[156:159], v[100:103], v[36:39]
	global_load_dwordx4 v[100:103], v[66:67], off
	v_add_co_u32_e64 v66, s[0:1], s60, v66
	v_mfma_f32_16x16x32_bf16 v[0:3], v[112:115], v[108:111], v[0:3]
	s_nop 0
	v_addc_co_u32_e64 v67, s[0:1], 0, v67, s[0:1]
	s_min_u32 s0, s28, 4
	v_mfma_f32_16x16x32_bf16 v[12:15], v[116:119], v[108:111], v[12:15]
	s_lshl_b32 s92, s0, 7
	s_mov_b32 s28, s29
	v_mfma_f32_16x16x32_bf16 v[32:35], v[120:123], v[104:107], v[32:35]
	v_mfma_f32_16x16x32_bf16 v[24:27], v[148:151], v[104:107], v[24:27]
	v_mfma_f32_16x16x32_bf16 v[20:23], v[152:155], v[104:107], v[20:23]
	v_mfma_f32_16x16x32_bf16 v[16:19], v[156:159], v[104:107], v[16:19]
	global_load_dwordx4 v[104:107], v[68:69], off
	global_load_dwordx4 v[108:111], v[70:71], off
	global_load_dwordx4 v[112:115], v[64:65], off
	v_mfma_f32_16x16x32_bf16 v[8:11], v[120:123], v[144:147], v[8:11]
	global_load_dwordx4 v[116:119], v[72:73], off
	global_load_dwordx4 v[120:123], v[74:75], off
	global_load_dwordx4 v[124:127], v[66:67], off
	s_waitcnt lgkmcnt(0)
	s_barrier
	ds_read_b128 v[64:67], v160 offset:49152
	ds_read_b128 v[68:71], v160 offset:51200
	ds_read_b128 v[72:75], v143 offset:32768
	ds_read_b128 v[76:79], v143 offset:34816
	ds_read_b128 v[80:83], v160 offset:53248
	ds_read_b128 v[84:87], v160 offset:55296
	s_waitcnt lgkmcnt(3)
	v_mfma_f32_16x16x32_bf16 v[40:43], v[64:67], v[72:75], v[40:43]
	v_mfma_f32_16x16x32_bf16 v[44:47], v[68:71], v[72:75], v[44:47]
	s_waitcnt lgkmcnt(1)
	v_mfma_f32_16x16x32_bf16 v[28:31], v[80:83], v[72:75], v[28:31]
	s_waitcnt lgkmcnt(0)
	v_mfma_f32_16x16x32_bf16 v[48:51], v[84:87], v[72:75], v[48:51]
	v_mfma_f32_16x16x32_bf16 v[56:59], v[64:67], v[76:79], v[56:59]
	v_mfma_f32_16x16x32_bf16 v[60:63], v[68:71], v[76:79], v[60:63]
	v_mfma_f32_16x16x32_bf16 v[52:55], v[80:83], v[76:79], v[52:55]
	v_mfma_f32_16x16x32_bf16 v[36:39], v[84:87], v[76:79], v[36:39]
	ds_read_b128 v[72:75], v143 offset:36864
	ds_read_b128 v[76:79], v143 offset:38912
	v_mfma_f32_16x16x32_bf16 v[4:7], v[148:151], v[144:147], v[4:7]
	v_mfma_f32_16x16x32_bf16 v[0:3], v[152:155], v[144:147], v[0:3]
	v_mfma_f32_16x16x32_bf16 v[12:15], v[156:159], v[144:147], v[12:15]
	s_waitcnt lgkmcnt(1)
	v_mfma_f32_16x16x32_bf16 v[32:35], v[64:67], v[72:75], v[32:35]
	v_mfma_f32_16x16x32_bf16 v[24:27], v[68:71], v[72:75], v[24:27]
	v_mfma_f32_16x16x32_bf16 v[20:23], v[80:83], v[72:75], v[20:23]
	v_mfma_f32_16x16x32_bf16 v[16:19], v[84:87], v[72:75], v[16:19]
	s_waitcnt lgkmcnt(0)
	v_mfma_f32_16x16x32_bf16 v[8:11], v[64:67], v[76:79], v[8:11]
	v_mfma_f32_16x16x32_bf16 v[4:7], v[68:71], v[76:79], v[4:7]
	ds_read_b128 v[64:67], v162 offset:49152
	ds_read_b128 v[68:71], v162 offset:51200
	ds_read_b128 v[72:75], v161 offset:32768
	ds_read_b128 v[144:147], v161 offset:34816
	ds_read_b128 v[152:155], v162 offset:55296
	ds_read_b128 v[148:151], v162 offset:53248
	s_waitcnt lgkmcnt(3)
	v_mfma_f32_16x16x32_bf16 v[88:91], v[68:71], v[72:75], v[44:47]
	s_nop 2
	v_lshl_add_u64 v[44:45], v[132:133], 0, s[92:93]
	v_mfma_f32_16x16x32_bf16 v[0:3], v[80:83], v[76:79], v[0:3]
	v_lshl_add_u64 v[46:47], v[134:135], 0, s[92:93]
	s_waitcnt lgkmcnt(1)
	v_mfma_f32_16x16x32_bf16 v[80:83], v[152:155], v[72:75], v[48:51]
	s_nop 2
	v_add_co_u32_e64 v48, s[0:1], s16, v44
	v_mfma_f32_16x16x32_bf16 v[12:15], v[84:87], v[76:79], v[12:15]
	s_nop 0
	v_addc_co_u32_e64 v49, s[0:1], 0, v45, s[0:1]
	v_add_co_u32_e64 v50, s[0:1], s11, v44
	v_mfma_f32_16x16x32_bf16 v[76:79], v[64:67], v[144:147], v[56:59]
	s_nop 0
	v_addc_co_u32_e64 v51, s[0:1], 0, v45, s[0:1]
	s_nop 0
	v_add_co_u32_e64 v56, s[0:1], s60, v44
	v_mfma_f32_16x16x32_bf16 v[92:95], v[64:67], v[72:75], v[40:43]
	s_nop 0
	v_addc_co_u32_e64 v57, s[0:1], 0, v45, s[0:1]
	v_add_co_u32_e64 v58, s[0:1], s16, v46
	s_waitcnt lgkmcnt(0)
	v_mfma_f32_16x16x32_bf16 v[84:87], v[148:151], v[72:75], v[28:31]
	ds_read_b128 v[40:43], v161 offset:36864
	v_addc_co_u32_e64 v59, s[0:1], 0, v47, s[0:1]
	v_mfma_f32_16x16x32_bf16 v[72:75], v[68:71], v[144:147], v[60:63]
	v_add_co_u32_e64 v156, s[0:1], s11, v46
	global_load_dwordx4 v[28:31], v[46:47], off offset:384
	v_mfma_f32_16x16x32_bf16 v[52:55], v[148:151], v[144:147], v[52:55]
	v_addc_co_u32_e64 v157, s[0:1], 0, v47, s[0:1]
	v_add_co_u32_e64 v158, s[0:1], s60, v46
	v_mfma_f32_16x16x32_bf16 v[36:39], v[152:155], v[144:147], v[36:39]
	ds_read_b128 v[144:147], v161 offset:38912
	v_addc_co_u32_e64 v159, s[0:1], 0, v47, s[0:1]
	s_waitcnt lgkmcnt(1)
	v_mfma_f32_16x16x32_bf16 v[32:35], v[64:67], v[40:43], v[32:35]
	v_mfma_f32_16x16x32_bf16 v[24:27], v[68:71], v[40:43], v[24:27]
	v_mfma_f32_16x16x32_bf16 v[20:23], v[148:151], v[40:43], v[20:23]
	v_mfma_f32_16x16x32_bf16 v[16:19], v[152:155], v[40:43], v[16:19]
	global_load_dwordx4 v[40:43], v[44:45], off offset:384
	s_nop 0
	global_load_dwordx4 v[44:47], v[48:49], off offset:384
	s_nop 0
	global_load_dwordx4 v[48:51], v[50:51], off offset:384
	s_waitcnt lgkmcnt(0)
	v_mfma_f32_16x16x32_bf16 v[8:11], v[64:67], v[144:147], v[8:11]
	global_load_dwordx4 v[60:63], v[56:57], off offset:384
	s_nop 0
	global_load_dwordx4 v[56:59], v[58:59], off offset:384
	s_nop 0
	global_load_dwordx4 v[64:67], v[156:157], off offset:384
	v_mfma_f32_16x16x32_bf16 v[4:7], v[68:71], v[144:147], v[4:7]
	global_load_dwordx4 v[68:71], v[158:159], off offset:384
	s_waitcnt vmcnt(15)
	ds_write_b128 v138, v[96:99]
	s_waitcnt vmcnt(14)
	ds_write_b128 v138, v[100:103] offset:16384
	s_waitcnt vmcnt(13)
	ds_write_b128 v138, v[104:107] offset:4096
	s_waitcnt vmcnt(12)
	ds_write_b128 v138, v[108:111] offset:8192
	s_waitcnt vmcnt(11)
	ds_write_b128 v138, v[112:115] offset:12288
	s_waitcnt vmcnt(10)
	ds_write_b128 v138, v[116:119] offset:20480
	s_waitcnt vmcnt(9)
	ds_write_b128 v138, v[120:123] offset:24576
	s_waitcnt vmcnt(8)
	ds_write_b128 v138, v[124:127] offset:28672
	s_waitcnt lgkmcnt(0)
	v_mfma_f32_16x16x32_bf16 v[0:3], v[148:151], v[144:147], v[0:3]
	s_barrier
	v_mfma_f32_16x16x32_bf16 v[12:15], v[152:155], v[144:147], v[12:15]
	s_cbranch_vccnz .LBB0_139
	s_lshl_b32 s0, s2, 8
	s_waitcnt vmcnt(7)
	v_or_b32_e32 v28, s26, v136
	v_lshlrev_b32_e32 v29, 6, v137
	v_lshlrev_b32_e32 v30, 2, v128
	v_add3_u32 v28, v28, v130, s0
	s_waitcnt vmcnt(6)
	v_or3_b32 v40, v29, v30, s3
	v_ashrrev_i32_e32 v29, 31, v28
	v_readlane_b32 s0, v251, 20
	v_and_b32_sdwa v41, v95, v170 dst_sel:DWORD dst_unused:UNUSED_PAD src0_sel:WORD_1 src1_sel:DWORD
	v_and_b32_sdwa v42, v93, v170 dst_sel:DWORD dst_unused:UNUSED_PAD src0_sel:WORD_1 src1_sel:DWORD
	v_lshlrev_b64 v[30:31], 11, v[28:29]
	v_readlane_b32 s1, v251, 21
	v_lshlrev_b32_e32 v128, 1, v40
	v_and_b32_sdwa v29, v94, v170 dst_sel:DWORD dst_unused:UNUSED_PAD src0_sel:WORD_1 src1_sel:DWORD
	v_and_b32_sdwa v40, v92, v170 dst_sel:DWORD dst_unused:UNUSED_PAD src0_sel:WORD_1 src1_sel:DWORD
	v_add3_u32 v41, v95, v41, s56
	v_add3_u32 v42, v93, v42, s56
	v_lshl_add_u64 v[30:31], s[0:1], 0, v[30:31]
	v_add3_u32 v40, v92, v40, s56
	v_add3_u32 v29, v94, v29, s56
	v_and_b32_e32 v41, 0xffff0000, v41
	v_and_b32_e32 v42, 0xffff0000, v42
	v_lshl_add_u64 v[30:31], v[30:31], 0, v[128:129]
	v_or_b32_sdwa v41, v41, v29 dst_sel:DWORD dst_unused:UNUSED_PAD src0_sel:DWORD src1_sel:WORD_1
	v_or_b32_sdwa v40, v42, v40 dst_sel:DWORD dst_unused:UNUSED_PAD src0_sel:DWORD src1_sel:WORD_1
	global_store_dwordx2 v[30:31], v[40:41], off
	v_cvt_pk_bf16_f32 v41, v90, v91
	v_cvt_pk_bf16_f32 v40, v88, v89
	global_store_dwordx2 v[30:31], v[40:41], off offset:32
	v_cvt_pk_bf16_f32 v41, v86, v87
	v_cvt_pk_bf16_f32 v40, v84, v85
	global_store_dwordx2 v[30:31], v[40:41], off offset:64
	v_cvt_pk_bf16_f32 v41, v82, v83
	v_cvt_pk_bf16_f32 v40, v80, v81
	global_store_dwordx2 v[30:31], v[40:41], off offset:96
	v_add_u32_e32 v30, 16, v28
	v_ashrrev_i32_e32 v31, 31, v30
	v_lshlrev_b64 v[30:31], 11, v[30:31]
	v_lshl_add_u64 v[30:31], s[0:1], 0, v[30:31]
	v_lshl_add_u64 v[30:31], v[30:31], 0, v[128:129]
	v_cvt_pk_bf16_f32 v41, v78, v79
	v_cvt_pk_bf16_f32 v40, v76, v77
	global_store_dwordx2 v[30:31], v[40:41], off
	v_cvt_pk_bf16_f32 v41, v74, v75
	v_cvt_pk_bf16_f32 v40, v72, v73
	global_store_dwordx2 v[30:31], v[40:41], off offset:32
	v_cvt_pk_bf16_f32 v41, v54, v55
	v_cvt_pk_bf16_f32 v40, v52, v53
	global_store_dwordx2 v[30:31], v[40:41], off offset:64
	v_and_b32_sdwa v29, v38, v170 dst_sel:DWORD dst_unused:UNUSED_PAD src0_sel:WORD_1 src1_sel:DWORD
	v_and_b32_sdwa v40, v36, v170 dst_sel:DWORD dst_unused:UNUSED_PAD src0_sel:WORD_1 src1_sel:DWORD
	v_add3_u32 v36, v36, v40, s56
	v_add3_u32 v29, v38, v29, s56
	v_and_b32_sdwa v38, v39, v170 dst_sel:DWORD dst_unused:UNUSED_PAD src0_sel:WORD_1 src1_sel:DWORD
	v_and_b32_sdwa v40, v37, v170 dst_sel:DWORD dst_unused:UNUSED_PAD src0_sel:WORD_1 src1_sel:DWORD
	v_add3_u32 v38, v39, v38, s56
	v_add3_u32 v37, v37, v40, s56
	v_and_b32_e32 v38, 0xffff0000, v38
	v_and_b32_e32 v39, 0xffff0000, v37
	v_or_b32_sdwa v37, v38, v29 dst_sel:DWORD dst_unused:UNUSED_PAD src0_sel:DWORD src1_sel:WORD_1
	v_or_b32_sdwa v36, v39, v36 dst_sel:DWORD dst_unused:UNUSED_PAD src0_sel:DWORD src1_sel:WORD_1
	global_store_dwordx2 v[30:31], v[36:37], off offset:96
	v_add_u32_e32 v30, 32, v28
	v_and_b32_sdwa v29, v34, v170 dst_sel:DWORD dst_unused:UNUSED_PAD src0_sel:WORD_1 src1_sel:DWORD
	v_and_b32_sdwa v36, v32, v170 dst_sel:DWORD dst_unused:UNUSED_PAD src0_sel:WORD_1 src1_sel:DWORD
	v_ashrrev_i32_e32 v31, 31, v30
	v_add3_u32 v32, v32, v36, s56
	v_add3_u32 v29, v34, v29, s56
	v_and_b32_sdwa v34, v35, v170 dst_sel:DWORD dst_unused:UNUSED_PAD src0_sel:WORD_1 src1_sel:DWORD
	v_and_b32_sdwa v36, v33, v170 dst_sel:DWORD dst_unused:UNUSED_PAD src0_sel:WORD_1 src1_sel:DWORD
	v_lshlrev_b64 v[30:31], 11, v[30:31]
	v_add3_u32 v34, v35, v34, s56
	v_add3_u32 v33, v33, v36, s56
	v_lshl_add_u64 v[30:31], s[0:1], 0, v[30:31]
	v_and_b32_e32 v34, 0xffff0000, v34
	v_and_b32_e32 v35, 0xffff0000, v33
	v_lshl_add_u64 v[30:31], v[30:31], 0, v[128:129]
	v_or_b32_sdwa v33, v34, v29 dst_sel:DWORD dst_unused:UNUSED_PAD src0_sel:DWORD src1_sel:WORD_1
	v_or_b32_sdwa v32, v35, v32 dst_sel:DWORD dst_unused:UNUSED_PAD src0_sel:DWORD src1_sel:WORD_1
	global_store_dwordx2 v[30:31], v[32:33], off
	v_and_b32_sdwa v29, v26, v170 dst_sel:DWORD dst_unused:UNUSED_PAD src0_sel:WORD_1 src1_sel:DWORD
	v_and_b32_sdwa v32, v24, v170 dst_sel:DWORD dst_unused:UNUSED_PAD src0_sel:WORD_1 src1_sel:DWORD
	v_add3_u32 v24, v24, v32, s56
	v_add3_u32 v26, v26, v29, s56
	v_and_b32_sdwa v29, v27, v170 dst_sel:DWORD dst_unused:UNUSED_PAD src0_sel:WORD_1 src1_sel:DWORD
	v_and_b32_sdwa v32, v25, v170 dst_sel:DWORD dst_unused:UNUSED_PAD src0_sel:WORD_1 src1_sel:DWORD
	v_add3_u32 v27, v27, v29, s56
	v_add3_u32 v25, v25, v32, s56
	v_and_b32_e32 v27, 0xffff0000, v27
	v_and_b32_e32 v29, 0xffff0000, v25
	v_or_b32_sdwa v25, v27, v26 dst_sel:DWORD dst_unused:UNUSED_PAD src0_sel:DWORD src1_sel:WORD_1
	v_or_b32_sdwa v24, v29, v24 dst_sel:DWORD dst_unused:UNUSED_PAD src0_sel:DWORD src1_sel:WORD_1
	global_store_dwordx2 v[30:31], v[24:25], off offset:32
	v_and_b32_sdwa v24, v22, v170 dst_sel:DWORD dst_unused:UNUSED_PAD src0_sel:WORD_1 src1_sel:DWORD
	v_and_b32_sdwa v25, v20, v170 dst_sel:DWORD dst_unused:UNUSED_PAD src0_sel:WORD_1 src1_sel:DWORD
	v_add3_u32 v20, v20, v25, s56
	v_add3_u32 v22, v22, v24, s56
	v_and_b32_sdwa v24, v23, v170 dst_sel:DWORD dst_unused:UNUSED_PAD src0_sel:WORD_1 src1_sel:DWORD
	v_and_b32_sdwa v25, v21, v170 dst_sel:DWORD dst_unused:UNUSED_PAD src0_sel:WORD_1 src1_sel:DWORD
	v_add3_u32 v23, v23, v24, s56
	v_add3_u32 v21, v21, v25, s56
	v_and_b32_e32 v23, 0xffff0000, v23
	v_and_b32_e32 v24, 0xffff0000, v21
	v_or_b32_sdwa v21, v23, v22 dst_sel:DWORD dst_unused:UNUSED_PAD src0_sel:DWORD src1_sel:WORD_1
	v_or_b32_sdwa v20, v24, v20 dst_sel:DWORD dst_unused:UNUSED_PAD src0_sel:DWORD src1_sel:WORD_1
	global_store_dwordx2 v[30:31], v[20:21], off offset:64
	v_and_b32_sdwa v20, v18, v170 dst_sel:DWORD dst_unused:UNUSED_PAD src0_sel:WORD_1 src1_sel:DWORD
	v_and_b32_sdwa v21, v16, v170 dst_sel:DWORD dst_unused:UNUSED_PAD src0_sel:WORD_1 src1_sel:DWORD
	v_add3_u32 v16, v16, v21, s56
	v_add3_u32 v18, v18, v20, s56
	v_and_b32_sdwa v20, v19, v170 dst_sel:DWORD dst_unused:UNUSED_PAD src0_sel:WORD_1 src1_sel:DWORD
	v_and_b32_sdwa v21, v17, v170 dst_sel:DWORD dst_unused:UNUSED_PAD src0_sel:WORD_1 src1_sel:DWORD
	v_add3_u32 v19, v19, v20, s56
	v_add3_u32 v17, v17, v21, s56
	v_and_b32_e32 v19, 0xffff0000, v19
	v_and_b32_e32 v20, 0xffff0000, v17
	v_or_b32_sdwa v17, v19, v18 dst_sel:DWORD dst_unused:UNUSED_PAD src0_sel:DWORD src1_sel:WORD_1
	v_or_b32_sdwa v16, v20, v16 dst_sel:DWORD dst_unused:UNUSED_PAD src0_sel:DWORD src1_sel:WORD_1
	global_store_dwordx2 v[30:31], v[16:17], off offset:96
	v_add_u32_e32 v16, 48, v28
	v_and_b32_sdwa v18, v10, v170 dst_sel:DWORD dst_unused:UNUSED_PAD src0_sel:WORD_1 src1_sel:DWORD
	v_and_b32_sdwa v19, v8, v170 dst_sel:DWORD dst_unused:UNUSED_PAD src0_sel:WORD_1 src1_sel:DWORD
	v_ashrrev_i32_e32 v17, 31, v16
	v_add3_u32 v8, v8, v19, s56
	v_add3_u32 v10, v10, v18, s56
	v_and_b32_sdwa v18, v11, v170 dst_sel:DWORD dst_unused:UNUSED_PAD src0_sel:WORD_1 src1_sel:DWORD
	v_and_b32_sdwa v19, v9, v170 dst_sel:DWORD dst_unused:UNUSED_PAD src0_sel:WORD_1 src1_sel:DWORD
	v_lshlrev_b64 v[16:17], 11, v[16:17]
	v_add3_u32 v11, v11, v18, s56
	v_add3_u32 v9, v9, v19, s56
	v_lshl_add_u64 v[16:17], s[0:1], 0, v[16:17]
	v_and_b32_e32 v11, 0xffff0000, v11
	v_and_b32_e32 v18, 0xffff0000, v9
	v_lshl_add_u64 v[16:17], v[16:17], 0, v[128:129]
	v_or_b32_sdwa v9, v11, v10 dst_sel:DWORD dst_unused:UNUSED_PAD src0_sel:DWORD src1_sel:WORD_1
	v_or_b32_sdwa v8, v18, v8 dst_sel:DWORD dst_unused:UNUSED_PAD src0_sel:DWORD src1_sel:WORD_1
	global_store_dwordx2 v[16:17], v[8:9], off
	v_and_b32_sdwa v8, v6, v170 dst_sel:DWORD dst_unused:UNUSED_PAD src0_sel:WORD_1 src1_sel:DWORD
	v_and_b32_sdwa v9, v4, v170 dst_sel:DWORD dst_unused:UNUSED_PAD src0_sel:WORD_1 src1_sel:DWORD
	v_add3_u32 v4, v4, v9, s56
	v_add3_u32 v6, v6, v8, s56
	v_and_b32_sdwa v8, v7, v170 dst_sel:DWORD dst_unused:UNUSED_PAD src0_sel:WORD_1 src1_sel:DWORD
	v_and_b32_sdwa v9, v5, v170 dst_sel:DWORD dst_unused:UNUSED_PAD src0_sel:WORD_1 src1_sel:DWORD
	v_add3_u32 v7, v7, v8, s56
	v_add3_u32 v5, v5, v9, s56
	v_and_b32_e32 v7, 0xffff0000, v7
	v_and_b32_e32 v8, 0xffff0000, v5
	v_or_b32_sdwa v5, v7, v6 dst_sel:DWORD dst_unused:UNUSED_PAD src0_sel:DWORD src1_sel:WORD_1
	v_or_b32_sdwa v4, v8, v4 dst_sel:DWORD dst_unused:UNUSED_PAD src0_sel:DWORD src1_sel:WORD_1
	global_store_dwordx2 v[16:17], v[4:5], off offset:32
	v_and_b32_sdwa v4, v2, v170 dst_sel:DWORD dst_unused:UNUSED_PAD src0_sel:WORD_1 src1_sel:DWORD
	v_and_b32_sdwa v5, v0, v170 dst_sel:DWORD dst_unused:UNUSED_PAD src0_sel:WORD_1 src1_sel:DWORD
	v_add3_u32 v0, v0, v5, s56
	v_add3_u32 v2, v2, v4, s56
	v_and_b32_sdwa v4, v3, v170 dst_sel:DWORD dst_unused:UNUSED_PAD src0_sel:WORD_1 src1_sel:DWORD
	v_and_b32_sdwa v5, v1, v170 dst_sel:DWORD dst_unused:UNUSED_PAD src0_sel:WORD_1 src1_sel:DWORD
	v_add3_u32 v3, v3, v4, s56
	v_add3_u32 v1, v1, v5, s56
	v_and_b32_e32 v3, 0xffff0000, v3
	v_and_b32_e32 v4, 0xffff0000, v1
	v_or_b32_sdwa v1, v3, v2 dst_sel:DWORD dst_unused:UNUSED_PAD src0_sel:DWORD src1_sel:WORD_1
	v_or_b32_sdwa v0, v4, v0 dst_sel:DWORD dst_unused:UNUSED_PAD src0_sel:DWORD src1_sel:WORD_1
	global_store_dwordx2 v[16:17], v[0:1], off offset:64
	v_and_b32_sdwa v1, v12, v170 dst_sel:DWORD dst_unused:UNUSED_PAD src0_sel:WORD_1 src1_sel:DWORD
	v_add3_u32 v2, v12, v1, s56
	v_and_b32_sdwa v3, v13, v170 dst_sel:DWORD dst_unused:UNUSED_PAD src0_sel:WORD_1 src1_sel:DWORD
	v_add3_u32 v3, v13, v3, s56
	v_and_b32_e32 v3, 0xffff0000, v3
	v_cvt_pk_bf16_f32 v1, v14, v15
	v_or_b32_sdwa v0, v3, v2 dst_sel:DWORD dst_unused:UNUSED_PAD src0_sel:DWORD src1_sel:WORD_1
	global_store_dwordx2 v[16:17], v[0:1], off offset:96
	s_mov_b64 s[0:1], 0
	s_movk_i32 s89, 0xff

.LBB0_143:
	s_add_i32 s29, s28, 2
	v_add_u32_e32 v117, v87, v88
	v_add_u32_e32 v116, v91, v88
	ds_read_b128 v[56:59], v117 offset:16384
	ds_read_b128 v[60:63], v116
	ds_read_b128 v[64:67], v117 offset:18432
	ds_read_b128 v[68:71], v116 offset:2048
	s_cmp_lt_u32 s28, 30
	s_cselect_b64 s[0:1], -1, 0
	s_and_b64 vcc, s[0:1], exec
	v_add_u32_e32 v118, v91, v89
	v_add_u32_e32 v119, v87, v89
	s_cselect_b32 s92, s27, 0xf80
	ds_read_b128 v[72:75], v117 offset:20480
	ds_read_b128 v[76:79], v117 offset:22528
	ds_read_b128 v[92:95], v118
	ds_read_b128 v[96:99], v118 offset:2048
	ds_read_b128 v[100:103], v119 offset:16384
	ds_read_b128 v[104:107], v119 offset:18432
	ds_read_b128 v[108:111], v119 offset:20480
	ds_read_b128 v[112:115], v119 offset:22528
	s_waitcnt vmcnt(5)
	ds_write_b128 v90, v[4:7] offset:32768
	s_waitcnt vmcnt(3)
	ds_write_b128 v90, v[32:35] offset:36864
	v_lshl_add_u64 v[32:33], v[80:81], 0, s[92:93]
	s_waitcnt lgkmcnt(12)
	v_mfma_f32_16x16x32_bf16 v[44:47], v[56:59], v[60:63], v[44:47]
	s_waitcnt vmcnt(2)
	ds_write_b128 v90, v[28:31] offset:40960
	s_waitcnt vmcnt(1)
	ds_write_b128 v90, v[24:27] offset:45056
	s_waitcnt vmcnt(1)
	ds_write_b128 v90, v[16:19] offset:49152
	v_lshl_add_u64 v[34:35], v[82:83], 0, s[92:93]
	s_waitcnt vmcnt(0)
	ds_write_b128 v90, v[20:23] offset:53248
	s_waitcnt lgkmcnt(14)
	v_mfma_f32_16x16x32_bf16 v[4:7], v[56:59], v[68:71], v[36:39]
	global_load_dwordx4 v[56:59], v[34:35], off
	s_addk_i32 s27, 0x100
	s_nop 0
	v_add_co_u32_e64 v36, s[0:1], s33, v32
	v_mfma_f32_16x16x32_bf16 v[52:55], v[64:67], v[60:63], v[52:55]
	s_nop 0
	v_addc_co_u32_e64 v37, s[0:1], 0, v33, s[0:1]
	v_add_co_u32_e64 v38, s[0:1], s7, v32
	s_waitcnt lgkmcnt(13)
	v_mfma_f32_16x16x32_bf16 v[48:51], v[72:75], v[60:63], v[48:51]
	v_addc_co_u32_e64 v39, s[0:1], 0, v33, s[0:1]
	s_waitcnt lgkmcnt(12)
	v_mfma_f32_16x16x32_bf16 v[40:43], v[76:79], v[60:63], v[40:43]
	s_waitcnt lgkmcnt(9)
	v_mfma_f32_16x16x32_bf16 v[16:19], v[100:103], v[92:95], v[44:47]
	s_nop 2
	v_add_co_u32_e64 v44, s[0:1], s90, v32
	v_mfma_f32_16x16x32_bf16 v[8:11], v[64:67], v[68:71], v[8:11]
	s_nop 0
	v_addc_co_u32_e64 v45, s[0:1], 0, v33, s[0:1]
	v_add_co_u32_e64 v34, s[0:1], s33, v34
	v_mfma_f32_16x16x32_bf16 v[0:3], v[72:75], v[68:71], v[0:3]
	s_nop 0
	v_addc_co_u32_e64 v35, s[0:1], 0, v35, s[0:1]
	global_load_dwordx4 v[64:67], v[32:33], off
	global_load_dwordx4 v[60:63], v[36:37], off
	v_mfma_f32_16x16x32_bf16 v[12:15], v[76:79], v[68:71], v[12:15]
	global_load_dwordx4 v[68:71], v[38:39], off
	global_load_dwordx4 v[72:75], v[44:45], off
	global_load_dwordx4 v[76:79], v[34:35], off
	s_waitcnt lgkmcnt(0)
	s_barrier
	v_mfma_f32_16x16x32_bf16 v[20:23], v[104:107], v[92:95], v[52:55]
	ds_read_b128 v[32:35], v117 offset:49152
	ds_read_b128 v[36:39], v117 offset:51200
	s_min_u32 s0, s28, 28
	v_mfma_f32_16x16x32_bf16 v[24:27], v[108:111], v[92:95], v[48:51]
	s_lshl_b32 s92, s0, 7
	s_mov_b32 s28, s29
	v_mfma_f32_16x16x32_bf16 v[28:31], v[112:115], v[92:95], v[40:43]
	s_nop 2
	ds_read_b128 v[40:43], v116 offset:32768
	ds_read_b128 v[44:47], v116 offset:34816
	ds_read_b128 v[48:51], v117 offset:53248
	ds_read_b128 v[52:55], v117 offset:55296
	v_mfma_f32_16x16x32_bf16 v[8:11], v[104:107], v[96:99], v[8:11]
	v_mfma_f32_16x16x32_bf16 v[4:7], v[100:103], v[96:99], v[4:7]
	v_mfma_f32_16x16x32_bf16 v[0:3], v[108:111], v[96:99], v[0:3]
	v_lshl_add_u64 v[108:109], v[80:81], 0, s[92:93]
	v_lshl_add_u64 v[110:111], v[82:83], 0, s[92:93]
	s_waitcnt lgkmcnt(3)
	v_mfma_f32_16x16x32_bf16 v[16:19], v[32:35], v[40:43], v[16:19]
	v_mfma_f32_16x16x32_bf16 v[20:23], v[36:39], v[40:43], v[20:23]
	s_waitcnt lgkmcnt(1)
	v_mfma_f32_16x16x32_bf16 v[24:27], v[48:51], v[40:43], v[24:27]
	s_waitcnt lgkmcnt(0)
	v_mfma_f32_16x16x32_bf16 v[28:31], v[52:55], v[40:43], v[28:31]
	v_mfma_f32_16x16x32_bf16 v[8:11], v[36:39], v[44:47], v[8:11]
	ds_read_b128 v[36:39], v119 offset:49152
	ds_read_b128 v[40:43], v118 offset:32768
	ds_read_b128 v[92:95], v119 offset:51200
	v_mfma_f32_16x16x32_bf16 v[12:15], v[112:115], v[96:99], v[12:15]
	v_add_co_u32_e64 v112, s[0:1], s33, v108
	v_mfma_f32_16x16x32_bf16 v[32:35], v[32:35], v[44:47], v[4:7]
	s_nop 0
	v_addc_co_u32_e64 v113, s[0:1], 0, v109, s[0:1]
	s_nop 0
	global_load_dwordx4 v[4:7], v[108:109], off offset:384
	ds_read_b128 v[96:99], v118 offset:34816
	ds_read_b128 v[100:103], v119 offset:53248
	ds_read_b128 v[104:107], v119 offset:55296
	v_mfma_f32_16x16x32_bf16 v[12:15], v[52:55], v[44:47], v[12:15]
	s_waitcnt lgkmcnt(3)
	v_mfma_f32_16x16x32_bf16 v[52:55], v[92:95], v[40:43], v[20:23]
	s_nop 2
	v_add_co_u32_e64 v20, s[0:1], s7, v108
	v_mfma_f32_16x16x32_bf16 v[0:3], v[48:51], v[44:47], v[0:3]
	s_nop 0
	v_addc_co_u32_e64 v21, s[0:1], 0, v109, s[0:1]
	v_add_co_u32_e64 v22, s[0:1], s90, v108
	v_mfma_f32_16x16x32_bf16 v[44:47], v[36:39], v[40:43], v[16:19]
	s_nop 0
	v_addc_co_u32_e64 v23, s[0:1], 0, v109, s[0:1]
	v_add_co_u32_e64 v108, s[0:1], s33, v110
	s_waitcnt lgkmcnt(1)
	v_mfma_f32_16x16x32_bf16 v[48:51], v[100:103], v[40:43], v[24:27]
	global_load_dwordx4 v[16:19], v[110:111], off offset:384
	v_addc_co_u32_e64 v109, s[0:1], 0, v111, s[0:1]
	s_waitcnt lgkmcnt(0)
	v_mfma_f32_16x16x32_bf16 v[40:43], v[104:107], v[40:43], v[28:31]
	v_mfma_f32_16x16x32_bf16 v[36:39], v[36:39], v[96:99], v[32:35]
	s_nop 2
	global_load_dwordx4 v[32:35], v[112:113], off offset:384
	global_load_dwordx4 v[28:31], v[20:21], off offset:384
	global_load_dwordx4 v[24:27], v[22:23], off offset:384
	s_nop 0
	global_load_dwordx4 v[20:23], v[108:109], off offset:384
	v_mfma_f32_16x16x32_bf16 v[8:11], v[92:95], v[96:99], v[8:11]
	s_waitcnt vmcnt(10)
	ds_write_b128 v90, v[64:67]
	ds_write_b128 v90, v[56:59] offset:16384
	s_waitcnt vmcnt(9)
	ds_write_b128 v90, v[60:63] offset:4096
	s_waitcnt vmcnt(8)
	ds_write_b128 v90, v[68:71] offset:8192
	s_waitcnt vmcnt(7)
	ds_write_b128 v90, v[72:75] offset:12288
	s_waitcnt vmcnt(6)
	ds_write_b128 v90, v[76:79] offset:20480
	s_waitcnt lgkmcnt(0)
	s_barrier
	v_mfma_f32_16x16x32_bf16 v[0:3], v[100:103], v[96:99], v[0:3]
	v_mfma_f32_16x16x32_bf16 v[12:15], v[104:107], v[96:99], v[12:15]
	s_cbranch_vccnz .LBB0_143
	s_lshl_b32 s0, s2, 10
	s_waitcnt vmcnt(5)
	v_or_b32_e32 v4, s26, v85
	s_waitcnt vmcnt(4)
	v_add3_u32 v16, v4, v86, s0
	v_add_u32_e32 v4, 0x2000, v16
	v_and_b32_sdwa v7, v44, v170 dst_sel:DWORD dst_unused:UNUSED_PAD src0_sel:WORD_1 src1_sel:DWORD
	v_ashrrev_i32_e32 v5, 31, v4
	v_readlane_b32 s16, v251, 20
	v_add3_u32 v17, v44, v7, s56
	v_and_b32_sdwa v18, v45, v170 dst_sel:DWORD dst_unused:UNUSED_PAD src0_sel:WORD_1 src1_sel:DWORD
	v_lshlrev_b64 v[4:5], 11, v[4:5]
	v_readlane_b32 s17, v251, 21
	s_lshl_b32 s0, s3, 1
	v_add3_u32 v18, v45, v18, s56
	v_lshl_add_u64 v[4:5], s[16:17], 0, v[4:5]
	v_lshl_or_b32 v128, v84, 3, s0
	v_and_b32_e32 v18, 0xffff0000, v18
	v_lshl_add_u64 v[4:5], v[4:5], 0, v[128:129]
	v_cvt_pk_bf16_f32 v7, v46, v47
	v_or_b32_sdwa v6, v18, v17 dst_sel:DWORD dst_unused:UNUSED_PAD src0_sel:DWORD src1_sel:WORD_1
	global_store_dwordx2 v[4:5], v[6:7], off
	v_and_b32_sdwa v7, v52, v170 dst_sel:DWORD dst_unused:UNUSED_PAD src0_sel:WORD_1 src1_sel:DWORD
	v_add3_u32 v17, v52, v7, s56
	v_and_b32_sdwa v18, v53, v170 dst_sel:DWORD dst_unused:UNUSED_PAD src0_sel:WORD_1 src1_sel:DWORD
	v_add3_u32 v18, v53, v18, s56
	v_and_b32_e32 v18, 0xffff0000, v18
	v_cvt_pk_bf16_f32 v7, v54, v55
	v_or_b32_sdwa v6, v18, v17 dst_sel:DWORD dst_unused:UNUSED_PAD src0_sel:DWORD src1_sel:WORD_1
	global_store_dwordx2 v[4:5], v[6:7], off offset:32
	v_and_b32_sdwa v7, v48, v170 dst_sel:DWORD dst_unused:UNUSED_PAD src0_sel:WORD_1 src1_sel:DWORD
	v_add3_u32 v17, v48, v7, s56
	v_and_b32_sdwa v18, v49, v170 dst_sel:DWORD dst_unused:UNUSED_PAD src0_sel:WORD_1 src1_sel:DWORD
	v_add3_u32 v18, v49, v18, s56
	v_and_b32_e32 v18, 0xffff0000, v18
	v_cvt_pk_bf16_f32 v7, v50, v51
	v_or_b32_sdwa v6, v18, v17 dst_sel:DWORD dst_unused:UNUSED_PAD src0_sel:DWORD src1_sel:WORD_1
	global_store_dwordx2 v[4:5], v[6:7], off offset:64
	v_and_b32_sdwa v7, v40, v170 dst_sel:DWORD dst_unused:UNUSED_PAD src0_sel:WORD_1 src1_sel:DWORD
	v_add3_u32 v17, v40, v7, s56
	v_and_b32_sdwa v18, v41, v170 dst_sel:DWORD dst_unused:UNUSED_PAD src0_sel:WORD_1 src1_sel:DWORD
	v_add3_u32 v18, v41, v18, s56
	v_and_b32_e32 v18, 0xffff0000, v18
	v_cvt_pk_bf16_f32 v7, v42, v43
	v_or_b32_sdwa v6, v18, v17 dst_sel:DWORD dst_unused:UNUSED_PAD src0_sel:DWORD src1_sel:WORD_1
	global_store_dwordx2 v[4:5], v[6:7], off offset:96
	v_add_u32_e32 v4, 0x2010, v16
	v_and_b32_sdwa v7, v36, v170 dst_sel:DWORD dst_unused:UNUSED_PAD src0_sel:WORD_1 src1_sel:DWORD
	v_ashrrev_i32_e32 v5, 31, v4
	v_add3_u32 v16, v36, v7, s56
	v_and_b32_sdwa v17, v37, v170 dst_sel:DWORD dst_unused:UNUSED_PAD src0_sel:WORD_1 src1_sel:DWORD
	v_lshlrev_b64 v[4:5], 11, v[4:5]
	v_add3_u32 v17, v37, v17, s56
	v_lshl_add_u64 v[4:5], s[16:17], 0, v[4:5]
	v_and_b32_e32 v17, 0xffff0000, v17
	v_lshl_add_u64 v[4:5], v[4:5], 0, v[128:129]
	v_cvt_pk_bf16_f32 v7, v38, v39
	v_or_b32_sdwa v6, v17, v16 dst_sel:DWORD dst_unused:UNUSED_PAD src0_sel:DWORD src1_sel:WORD_1
	global_store_dwordx2 v[4:5], v[6:7], off
	v_and_b32_sdwa v6, v10, v170 dst_sel:DWORD dst_unused:UNUSED_PAD src0_sel:WORD_1 src1_sel:DWORD
	v_and_b32_sdwa v7, v8, v170 dst_sel:DWORD dst_unused:UNUSED_PAD src0_sel:WORD_1 src1_sel:DWORD
	v_add3_u32 v8, v8, v7, s56
	v_add3_u32 v6, v10, v6, s56
	v_and_b32_sdwa v7, v11, v170 dst_sel:DWORD dst_unused:UNUSED_PAD src0_sel:WORD_1 src1_sel:DWORD
	v_and_b32_sdwa v10, v9, v170 dst_sel:DWORD dst_unused:UNUSED_PAD src0_sel:WORD_1 src1_sel:DWORD
	v_add3_u32 v7, v11, v7, s56
	v_add3_u32 v9, v9, v10, s56
	v_and_b32_e32 v7, 0xffff0000, v7
	v_and_b32_e32 v9, 0xffff0000, v9
	v_or_b32_sdwa v7, v7, v6 dst_sel:DWORD dst_unused:UNUSED_PAD src0_sel:DWORD src1_sel:WORD_1
	v_or_b32_sdwa v6, v9, v8 dst_sel:DWORD dst_unused:UNUSED_PAD src0_sel:DWORD src1_sel:WORD_1
	global_store_dwordx2 v[4:5], v[6:7], off offset:32
	v_and_b32_sdwa v6, v2, v170 dst_sel:DWORD dst_unused:UNUSED_PAD src0_sel:WORD_1 src1_sel:DWORD
	v_and_b32_sdwa v7, v0, v170 dst_sel:DWORD dst_unused:UNUSED_PAD src0_sel:WORD_1 src1_sel:DWORD
	v_add3_u32 v0, v0, v7, s56
	v_add3_u32 v2, v2, v6, s56
	v_and_b32_sdwa v6, v3, v170 dst_sel:DWORD dst_unused:UNUSED_PAD src0_sel:WORD_1 src1_sel:DWORD
	v_and_b32_sdwa v7, v1, v170 dst_sel:DWORD dst_unused:UNUSED_PAD src0_sel:WORD_1 src1_sel:DWORD
	v_add3_u32 v3, v3, v6, s56
	v_add3_u32 v1, v1, v7, s56
	v_and_b32_e32 v3, 0xffff0000, v3
	v_and_b32_e32 v6, 0xffff0000, v1
	v_or_b32_sdwa v1, v3, v2 dst_sel:DWORD dst_unused:UNUSED_PAD src0_sel:DWORD src1_sel:WORD_1
	v_or_b32_sdwa v0, v6, v0 dst_sel:DWORD dst_unused:UNUSED_PAD src0_sel:DWORD src1_sel:WORD_1
	global_store_dwordx2 v[4:5], v[0:1], off offset:64
	v_and_b32_sdwa v1, v12, v170 dst_sel:DWORD dst_unused:UNUSED_PAD src0_sel:WORD_1 src1_sel:DWORD
	v_add3_u32 v2, v12, v1, s56
	v_and_b32_sdwa v3, v13, v170 dst_sel:DWORD dst_unused:UNUSED_PAD src0_sel:WORD_1 src1_sel:DWORD
	v_add3_u32 v3, v13, v3, s56
	v_and_b32_e32 v3, 0xffff0000, v3
	v_cvt_pk_bf16_f32 v1, v14, v15
	v_or_b32_sdwa v0, v3, v2 dst_sel:DWORD dst_unused:UNUSED_PAD src0_sel:DWORD src1_sel:WORD_1
	s_movk_i32 s89, 0xff
	global_store_dwordx2 v[4:5], v[0:1], off offset:96

.LBB0_163:
	s_or_b64 exec, exec, s[0:1]
	s_mov_b64 s[0:1], src_shared_base
	s_add_i32 s0, 0, 0x11fe0
	s_cmp_lg_u32 s0, -1
	s_cselect_b32 s0, s0, 0
	s_cselect_b32 s1, s1, 0
	v_mov_b32_e32 v0, s0
	v_mov_b32_e32 v1, s1
	s_waitcnt lgkmcnt(0)
	s_barrier
	flat_load_dword v8, v[0:1] sc0 sc1
	s_waitcnt vmcnt(0)
	s_movk_i32 s0, 0x880
	s_waitcnt lgkmcnt(0)
	v_cmp_gt_i32_e32 vcc, s0, v8
	s_mov_b64 s[0:1], -1
	s_and_saveexec_b64 s[26:27], vcc
	s_cbranch_execz .LBB0_158
	s_movk_i32 s0, 0x1ff
	v_cmp_lt_i32_e32 vcc, s0, v8
	s_and_saveexec_b64 s[0:1], vcc
	s_xor_b64 s[48:49], exec, s[0:1]
	s_cbranch_execz .LBB0_197
	s_movk_i32 s0, 0x5ff
	v_cmp_lt_u32_e32 vcc, s0, v8
	s_and_saveexec_b64 s[0:1], vcc
	s_xor_b64 s[2:3], exec, s[0:1]
	s_cbranch_execz .LBB0_167
	s_movk_i32 s0, 0x67f
	v_cmp_lt_u32_e32 vcc, s0, v8
	v_mov_b32_e32 v0, 0xfffffa00
	v_mov_b32_e32 v1, 0xfffff980
	v_cndmask_b32_e32 v0, v0, v1, vcc
	v_cndmask_b32_e64 v2, 4, 2, vcc
	v_cndmask_b32_e64 v1, 6, 4, vcc
	v_cndmask_b32_e64 v3, 3, 1, vcc
	v_add_u32_e32 v0, v0, v8
	v_lshrrev_b32_e32 v2, v2, v8
	v_lshrrev_b32_e32 v128, v1, v0
	v_lshrrev_b32_e32 v3, v3, v8
	v_mov_b32_e32 v0, 0x2000
	v_lshlrev_b32_e32 v2, 7, v2
	v_lshl_add_u32 v0, v128, 10, v0
	v_lshlrev_b32_e32 v1, 8, v128
	v_and_b32_e32 v130, 0x180, v2
	v_lshlrev_b32_e32 v2, 7, v3
	v_mov_b32_e32 v104, v166
	v_cndmask_b32_e64 v4, 7, 1, vcc
	v_cndmask_b32_e32 v0, v0, v1, vcc
	s_barrier
	v_mov_b32_e32 v1, v129
	v_readlane_b32 s0, v251, 32
	v_and_b32_e32 v132, 0x80, v2
	v_and_b32_e32 v4, v4, v8
	v_ashrrev_i32_e32 v6, 3, v104
	v_lshlrev_b64 v[0:1], 10, v[0:1]
	v_readlane_b32 s1, v251, 33
	v_add_u32_e32 v2, v6, v132
	v_lshlrev_b32_e32 v133, 7, v4
	v_lshl_add_u64 v[0:1], s[0:1], 0, v[0:1]
	v_ashrrev_i32_e32 v3, 31, v2
	v_readlane_b32 s0, v250, 37
	v_lshlrev_b64 v[34:35], 20, v[128:129]
	v_lshlrev_b64 v[32:33], 18, v[128:129]
	v_lshlrev_b32_e32 v128, 1, v130
	v_lshlrev_b64 v[2:3], 8, v[2:3]
	v_readlane_b32 s1, v250, 38
	v_lshlrev_b32_e32 v7, 4, v104
	v_add_u32_e32 v4, v6, v133
	v_lshl_add_u64 v[0:1], v[0:1], 0, v[128:129]
	v_lshl_add_u64 v[2:3], s[0:1], 0, v[2:3]
	v_and_b32_e32 v128, 0x70, v7
	v_ashrrev_i32_e32 v5, 31, v4
	v_lshl_add_u64 v[2:3], v[2:3], 0, v[128:129]
	v_lshlrev_b64 v[4:5], 10, v[4:5]
	s_movk_i32 s0, 0x2000
	v_lshl_add_u64 v[0:1], v[0:1], 0, v[4:5]
	v_add_co_u32_e64 v4, s[0:1], s0, v2
	global_load_dwordx4 v[12:15], v[2:3], off
	s_nop 0
	v_addc_co_u32_e64 v5, s[0:1], 0, v3, s[0:1]
	s_movk_i32 s0, 0x4000
	s_nop 0
	v_add_co_u32_e64 v8, s[0:1], s0, v2
	global_load_dwordx4 v[16:19], v[4:5], off
	s_nop 0
	v_addc_co_u32_e64 v9, s[0:1], 0, v3, s[0:1]
	global_load_dwordx4 v[20:23], v[8:9], off
	v_add_co_u32_e64 v50, s[0:1], s58, v2
	v_lshl_add_u64 v[48:49], v[0:1], 0, v[128:129]
	s_nop 0
	v_addc_co_u32_e64 v51, s[0:1], 0, v3, s[0:1]
	global_load_dwordx4 v[24:27], v[50:51], off
	global_load_dwordx4 v[28:31], v[48:49], off
	s_mov_b32 s0, 0x8000
	v_add_co_u32_e64 v52, s[0:1], s0, v48
	v_ashrrev_i32_e32 v0, 1, v104
	s_nop 0
	v_addc_co_u32_e64 v53, s[0:1], 0, v49, s[0:1]
	v_add_co_u32_e64 v54, s[0:1], s11, v48
	global_load_dwordx4 v[36:39], v[52:53], off
	s_nop 0
	v_addc_co_u32_e64 v55, s[0:1], 0, v49, s[0:1]
	global_load_dwordx4 v[40:43], v[54:55], off
	v_add_co_u32_e64 v56, s[0:1], s60, v48
	v_and_b32_e32 v134, 15, v104
	s_nop 0
	v_addc_co_u32_e64 v57, s[0:1], 0, v49, s[0:1]
	global_load_dwordx4 v[44:47], v[56:57], off
	v_and_b32_e32 v135, 0xffffffc0, v0
	v_lshlrev_b32_e32 v0, 7, v6
	v_xor_b32_e32 v1, v7, v104
	s_movk_i32 s0, 0x70
	v_bfe_u32 v128, v104, 6, 1
	v_lshlrev_b32_e32 v6, 7, v134
	v_and_or_b32 v0, v1, s0, v0
	v_lshl_or_b32 v59, v128, 13, v6
	v_add_u32_e32 v136, 0, v0
	global_load_dwordx4 v[0:3], v[2:3], off offset:128
	s_nop 0
	global_load_dwordx4 v[4:7], v[4:5], off offset:128
	s_nop 0
	global_load_dwordx4 v[8:11], v[8:9], off offset:128
	s_waitcnt vmcnt(10)
	ds_write_b128 v136, v[12:15]
	s_waitcnt vmcnt(9)
	ds_write_b128 v136, v[16:19] offset:4096
	s_waitcnt vmcnt(8)
	ds_write_b128 v136, v[20:23] offset:8192
	global_load_dwordx4 v[12:15], v[50:51], off offset:128
	global_load_dwordx4 v[16:19], v[48:49], off offset:128
	global_load_dwordx4 v[20:23], v[52:53], off offset:128
	v_lshrrev_b32_e32 v58, 4, v104
	v_bfe_u32 v105, v104, 1, 3
	v_add_u32_e32 v106, 0, v59
	s_waitcnt vmcnt(10)
	ds_write_b128 v136, v[24:27] offset:12288
	global_load_dwordx4 v[24:27], v[54:55], off offset:128
	s_waitcnt vmcnt(10)
	ds_write_b128 v136, v[28:31] offset:16384
	global_load_dwordx4 v[28:31], v[56:57], off offset:128
	v_bfe_u32 v137, v104, 4, 2
	v_bitop3_b32 v104, v137, v105, 4 bitop3:0x36
	v_lshlrev_b32_e32 v109, 4, v104
	v_add_u32_e32 v122, v106, v109
	s_mov_b64 s[0:1], 0x800000
	v_lshl_add_u64 v[34:35], v[34:35], 0, s[0:1]
	s_waitcnt vmcnt(10)
	ds_write_b128 v136, v[36:39] offset:20480
	v_bitop3_b32 v36, v58, v105, 3 bitop3:0x6c
	v_readlane_b32 s0, v251, 26
	s_waitcnt vmcnt(9)
	ds_write_b128 v136, v[40:43] offset:24576
	v_lshlrev_b32_e32 v40, 4, v36
	v_add_u32_e32 v120, v106, v40
	v_or_b32_e32 v41, v135, v134
	v_lshl_add_u32 v108, v41, 7, 0
	v_add_u32_e32 v121, v108, v40
	s_waitcnt vmcnt(8)
	ds_write_b128 v136, v[44:47] offset:28672
	s_waitcnt lgkmcnt(0)
	s_barrier
	ds_read_b128 v[36:39], v120 offset:16384
	ds_read_b128 v[48:51], v120 offset:18432
	ds_read_b128 v[56:59], v120 offset:20480
	ds_read_b128 v[64:67], v120 offset:22528
	ds_read_b128 v[40:43], v121
	ds_read_b128 v[68:71], v121 offset:2048
	ds_read_b128 v[84:87], v121 offset:4096
	ds_read_b128 v[100:103], v121 offset:6144
	ds_read_b128 v[104:107], v122 offset:16384
	v_add_u32_e32 v124, v108, v109
	ds_read_b128 v[108:111], v122 offset:18432
	ds_read_b128 v[112:115], v122 offset:20480
	ds_read_b128 v[116:119], v122 offset:22528
	s_waitcnt lgkmcnt(7)
	v_mfma_f32_16x16x32_bf16 v[44:47], v[36:39], v[40:43], 0
	v_cndmask_b32_e32 v33, v35, v33, vcc
	v_cndmask_b32_e32 v32, v34, v32, vcc
	v_readlane_b32 s1, v251, 27
	v_mfma_f32_16x16x32_bf16 v[52:55], v[48:51], v[40:43], 0
	s_nop 0
	v_lshl_add_u64 v[32:33], v[32:33], 1, s[0:1]
	s_movk_i32 s0, 0x4f
	v_mfma_f32_16x16x32_bf16 v[60:63], v[56:59], v[40:43], 0
	v_mfma_f32_16x16x32_bf16 v[40:43], v[64:67], v[40:43], 0
	s_waitcnt lgkmcnt(6)
	v_mfma_f32_16x16x32_bf16 v[72:75], v[36:39], v[68:71], 0
	v_mfma_f32_16x16x32_bf16 v[76:79], v[48:51], v[68:71], 0
	v_mfma_f32_16x16x32_bf16 v[80:83], v[56:59], v[68:71], 0
	v_mfma_f32_16x16x32_bf16 v[68:71], v[64:67], v[68:71], 0
	s_waitcnt lgkmcnt(5)
	v_mfma_f32_16x16x32_bf16 v[88:91], v[36:39], v[84:87], 0
	v_mfma_f32_16x16x32_bf16 v[92:95], v[48:51], v[84:87], 0
	v_mfma_f32_16x16x32_bf16 v[96:99], v[56:59], v[84:87], 0
	v_mfma_f32_16x16x32_bf16 v[84:87], v[64:67], v[84:87], 0
	s_waitcnt lgkmcnt(4)
	v_mfma_f32_16x16x32_bf16 v[36:39], v[36:39], v[100:103], 0
	v_mfma_f32_16x16x32_bf16 v[48:51], v[48:51], v[100:103], 0
	v_mfma_f32_16x16x32_bf16 v[56:59], v[56:59], v[100:103], 0
	v_mfma_f32_16x16x32_bf16 v[64:67], v[64:67], v[100:103], 0
	ds_read_b128 v[100:103], v124
	s_waitcnt lgkmcnt(0)
	v_mfma_f32_16x16x32_bf16 v[44:47], v[104:107], v[100:103], v[44:47]
	v_mfma_f32_16x16x32_bf16 v[52:55], v[108:111], v[100:103], v[52:55]
	v_mfma_f32_16x16x32_bf16 v[60:63], v[112:115], v[100:103], v[60:63]
	v_mfma_f32_16x16x32_bf16 v[40:43], v[116:119], v[100:103], v[40:43]
	ds_read_b128 v[100:103], v124 offset:2048
	s_waitcnt lgkmcnt(0)
	v_mfma_f32_16x16x32_bf16 v[72:75], v[104:107], v[100:103], v[72:75]
	v_mfma_f32_16x16x32_bf16 v[76:79], v[108:111], v[100:103], v[76:79]
	v_mfma_f32_16x16x32_bf16 v[80:83], v[112:115], v[100:103], v[80:83]
	v_mfma_f32_16x16x32_bf16 v[68:71], v[116:119], v[100:103], v[68:71]
	ds_read_b128 v[100:103], v124 offset:4096
	s_waitcnt lgkmcnt(0)
	v_mfma_f32_16x16x32_bf16 v[88:91], v[104:107], v[100:103], v[88:91]
	v_mfma_f32_16x16x32_bf16 v[92:95], v[108:111], v[100:103], v[92:95]
	v_mfma_f32_16x16x32_bf16 v[96:99], v[112:115], v[100:103], v[96:99]
	v_mfma_f32_16x16x32_bf16 v[84:87], v[116:119], v[100:103], v[84:87]
	ds_read_b128 v[100:103], v124 offset:6144
	s_waitcnt vmcnt(7)
	ds_write_b128 v136, v[0:3] offset:32768
	s_waitcnt vmcnt(6)
	ds_write_b128 v136, v[4:7] offset:36864
	s_waitcnt vmcnt(5)
	ds_write_b128 v136, v[8:11] offset:40960
	s_waitcnt vmcnt(4)
	ds_write_b128 v136, v[12:15] offset:45056
	s_waitcnt vmcnt(3)
	ds_write_b128 v136, v[16:19] offset:49152
	s_waitcnt vmcnt(2)
	ds_write_b128 v136, v[20:23] offset:53248
	s_waitcnt vmcnt(1)
	ds_write_b128 v136, v[24:27] offset:57344
	s_waitcnt vmcnt(0)
	ds_write_b128 v136, v[28:31] offset:61440
	s_waitcnt lgkmcnt(0)
	v_mfma_f32_16x16x32_bf16 v[36:39], v[104:107], v[100:103], v[36:39]
	s_barrier
	ds_read_b128 v[104:107], v120 offset:49152
	v_mfma_f32_16x16x32_bf16 v[48:51], v[108:111], v[100:103], v[48:51]
	ds_read_b128 v[108:111], v120 offset:51200
	v_mfma_f32_16x16x32_bf16 v[56:59], v[112:115], v[100:103], v[56:59]
	ds_read_b128 v[112:115], v120 offset:53248
	v_mfma_f32_16x16x32_bf16 v[64:67], v[116:119], v[100:103], v[64:67]
	ds_read_b128 v[116:119], v120 offset:55296
	ds_read_b128 v[100:103], v121 offset:32768
	s_waitcnt lgkmcnt(0)
	v_mfma_f32_16x16x32_bf16 v[44:47], v[104:107], v[100:103], v[44:47]
	v_mfma_f32_16x16x32_bf16 v[52:55], v[108:111], v[100:103], v[52:55]
	v_mfma_f32_16x16x32_bf16 v[60:63], v[112:115], v[100:103], v[60:63]
	v_mfma_f32_16x16x32_bf16 v[40:43], v[116:119], v[100:103], v[40:43]
	ds_read_b128 v[100:103], v121 offset:34816
	s_waitcnt lgkmcnt(0)
	v_mfma_f32_16x16x32_bf16 v[72:75], v[104:107], v[100:103], v[72:75]
	v_mfma_f32_16x16x32_bf16 v[76:79], v[108:111], v[100:103], v[76:79]
	v_mfma_f32_16x16x32_bf16 v[80:83], v[112:115], v[100:103], v[80:83]
	v_mfma_f32_16x16x32_bf16 v[68:71], v[116:119], v[100:103], v[68:71]
	ds_read_b128 v[100:103], v121 offset:36864
	s_waitcnt lgkmcnt(0)
	v_mfma_f32_16x16x32_bf16 v[88:91], v[104:107], v[100:103], v[88:91]
	v_mfma_f32_16x16x32_bf16 v[92:95], v[108:111], v[100:103], v[92:95]
	v_mfma_f32_16x16x32_bf16 v[96:99], v[112:115], v[100:103], v[96:99]
	v_mfma_f32_16x16x32_bf16 v[84:87], v[116:119], v[100:103], v[84:87]
	ds_read_b128 v[100:103], v121 offset:38912
	s_waitcnt lgkmcnt(0)
	v_mfma_f32_16x16x32_bf16 v[36:39], v[104:107], v[100:103], v[36:39]
	ds_read_b128 v[104:107], v122 offset:49152
	v_mfma_f32_16x16x32_bf16 v[48:51], v[108:111], v[100:103], v[48:51]
	ds_read_b128 v[108:111], v122 offset:51200
	v_mfma_f32_16x16x32_bf16 v[56:59], v[112:115], v[100:103], v[56:59]
	ds_read_b128 v[112:115], v122 offset:53248
	v_mfma_f32_16x16x32_bf16 v[64:67], v[116:119], v[100:103], v[64:67]
	ds_read_b128 v[116:119], v122 offset:55296
	ds_read_b128 v[100:103], v124 offset:32768
	s_waitcnt lgkmcnt(0)
	v_mfma_f32_16x16x32_bf16 v[44:47], v[104:107], v[100:103], v[44:47]
	v_mfma_f32_16x16x32_bf16 v[52:55], v[108:111], v[100:103], v[52:55]
	v_mfma_f32_16x16x32_bf16 v[60:63], v[112:115], v[100:103], v[60:63]
	v_mfma_f32_16x16x32_bf16 v[40:43], v[116:119], v[100:103], v[40:43]
	ds_read_b128 v[100:103], v124 offset:34816
	ds_read_b128 v[120:123], v124 offset:36864
	ds_read_b128 v[124:127], v124 offset:38912
	ds_write_b128 v136, v[0:3]
	v_or_b32_e32 v0, v134, v132
	v_add_u32_e32 v0, v0, v135
	ds_write_b128 v136, v[4:7] offset:4096
	ds_write_b128 v136, v[8:11] offset:8192
	ds_write_b128 v136, v[12:15] offset:12288
	ds_write_b128 v136, v[16:19] offset:16384
	ds_write_b128 v136, v[20:23] offset:20480
	ds_write_b128 v136, v[24:27] offset:24576
	s_waitcnt lgkmcnt(8)
	v_mfma_f32_16x16x32_bf16 v[20:23], v[116:119], v[120:123], v[84:87]
	v_lshlrev_b32_e32 v1, 6, v128
	v_lshlrev_b32_e32 v2, 2, v137
	ds_write_b128 v136, v[28:31] offset:28672
	v_and_or_b32 v85, v0, s0, v130
	v_cndmask_b32_e64 v86, 11, 9, vcc
	v_or3_b32 v84, v1, v2, v133
	v_lshlrev_b32_e32 v1, v86, v85
	v_lshlrev_b32_e32 v128, 1, v1
	v_ashrrev_i32_e32 v0, 7, v0
	v_cndmask_b32_e64 v1, 10, 8, vcc
	s_waitcnt lgkmcnt(8)
	v_mfma_f32_16x16x32_bf16 v[24:27], v[104:107], v[124:127], v[36:39]
	v_lshl_add_u64 v[34:35], v[32:33], 0, v[128:129]
	v_lshlrev_b32_e32 v128, 1, v84
	s_waitcnt lgkmcnt(0)
	v_lshlrev_b32_e32 v36, v1, v0
	v_and_b32_sdwa v38, v46, v170 dst_sel:DWORD dst_unused:UNUSED_PAD src0_sel:WORD_1 src1_sel:DWORD
	v_and_b32_sdwa v39, v44, v170 dst_sel:DWORD dst_unused:UNUSED_PAD src0_sel:WORD_1 src1_sel:DWORD
	v_ashrrev_i32_e32 v37, 31, v36
	v_add3_u32 v44, v44, v39, s56
	v_add3_u32 v38, v46, v38, s56
	v_and_b32_sdwa v39, v47, v170 dst_sel:DWORD dst_unused:UNUSED_PAD src0_sel:WORD_1 src1_sel:DWORD
	v_and_b32_sdwa v46, v45, v170 dst_sel:DWORD dst_unused:UNUSED_PAD src0_sel:WORD_1 src1_sel:DWORD
	v_lshlrev_b64 v[36:37], 1, v[36:37]
	v_add3_u32 v39, v47, v39, s56
	v_add3_u32 v45, v45, v46, s56
	v_lshl_add_u64 v[34:35], v[34:35], 0, v[36:37]
	v_and_b32_e32 v39, 0xffff0000, v39
	v_and_b32_e32 v45, 0xffff0000, v45
	v_lshl_add_u64 v[34:35], v[34:35], 0, v[128:129]
	v_or_b32_sdwa v39, v39, v38 dst_sel:DWORD dst_unused:UNUSED_PAD src0_sel:DWORD src1_sel:WORD_1
	v_or_b32_sdwa v38, v45, v44 dst_sel:DWORD dst_unused:UNUSED_PAD src0_sel:DWORD src1_sel:WORD_1
	s_barrier
	global_store_dwordx2 v[34:35], v[38:39], off
	v_and_b32_sdwa v39, v52, v170 dst_sel:DWORD dst_unused:UNUSED_PAD src0_sel:WORD_1 src1_sel:DWORD
	v_add3_u32 v44, v52, v39, s56
	v_and_b32_sdwa v45, v53, v170 dst_sel:DWORD dst_unused:UNUSED_PAD src0_sel:WORD_1 src1_sel:DWORD
	v_add3_u32 v45, v53, v45, s56
	v_and_b32_e32 v45, 0xffff0000, v45
	v_cvt_pk_bf16_f32 v39, v54, v55
	v_or_b32_sdwa v38, v45, v44 dst_sel:DWORD dst_unused:UNUSED_PAD src0_sel:DWORD src1_sel:WORD_1
	global_store_dwordx2 v[34:35], v[38:39], off offset:32
	v_and_b32_sdwa v39, v60, v170 dst_sel:DWORD dst_unused:UNUSED_PAD src0_sel:WORD_1 src1_sel:DWORD
	v_add3_u32 v44, v60, v39, s56
	v_and_b32_sdwa v45, v61, v170 dst_sel:DWORD dst_unused:UNUSED_PAD src0_sel:WORD_1 src1_sel:DWORD
	v_add3_u32 v45, v61, v45, s56
	v_and_b32_e32 v45, 0xffff0000, v45
	v_cvt_pk_bf16_f32 v39, v62, v63
	v_or_b32_sdwa v38, v45, v44 dst_sel:DWORD dst_unused:UNUSED_PAD src0_sel:DWORD src1_sel:WORD_1
	global_store_dwordx2 v[34:35], v[38:39], off offset:64
	v_and_b32_sdwa v38, v42, v170 dst_sel:DWORD dst_unused:UNUSED_PAD src0_sel:WORD_1 src1_sel:DWORD
	v_and_b32_sdwa v39, v40, v170 dst_sel:DWORD dst_unused:UNUSED_PAD src0_sel:WORD_1 src1_sel:DWORD
	v_add3_u32 v40, v40, v39, s56
	v_add3_u32 v38, v42, v38, s56
	v_and_b32_sdwa v39, v43, v170 dst_sel:DWORD dst_unused:UNUSED_PAD src0_sel:WORD_1 src1_sel:DWORD
	v_and_b32_sdwa v42, v41, v170 dst_sel:DWORD dst_unused:UNUSED_PAD src0_sel:WORD_1 src1_sel:DWORD
	v_mfma_f32_16x16x32_bf16 v[72:75], v[104:107], v[100:103], v[72:75]
	v_add3_u32 v39, v43, v39, s56
	v_add3_u32 v41, v41, v42, s56
	v_and_b32_e32 v39, 0xffff0000, v39
	v_and_b32_e32 v41, 0xffff0000, v41
	v_or_b32_sdwa v39, v39, v38 dst_sel:DWORD dst_unused:UNUSED_PAD src0_sel:DWORD src1_sel:WORD_1
	v_or_b32_sdwa v38, v41, v40 dst_sel:DWORD dst_unused:UNUSED_PAD src0_sel:DWORD src1_sel:WORD_1
	global_store_dwordx2 v[34:35], v[38:39], off offset:96
	v_or_b32_e32 v34, 16, v85
	v_lshlrev_b32_e32 v34, v86, v34
	v_and_b32_sdwa v39, v72, v170 dst_sel:DWORD dst_unused:UNUSED_PAD src0_sel:WORD_1 src1_sel:DWORD
	v_mfma_f32_16x16x32_bf16 v[76:79], v[108:111], v[100:103], v[76:79]
	v_lshlrev_b32_e32 v34, 1, v34
	v_mov_b32_e32 v35, v129
	v_add3_u32 v40, v72, v39, s56
	v_and_b32_sdwa v41, v73, v170 dst_sel:DWORD dst_unused:UNUSED_PAD src0_sel:WORD_1 src1_sel:DWORD
	v_lshl_add_u64 v[34:35], v[32:33], 0, v[34:35]
	v_add3_u32 v41, v73, v41, s56
	v_lshl_add_u64 v[34:35], v[34:35], 0, v[36:37]
	v_and_b32_e32 v41, 0xffff0000, v41
	v_lshl_add_u64 v[34:35], v[34:35], 0, v[128:129]
	v_cvt_pk_bf16_f32 v39, v74, v75
	v_or_b32_sdwa v38, v41, v40 dst_sel:DWORD dst_unused:UNUSED_PAD src0_sel:DWORD src1_sel:WORD_1
	global_store_dwordx2 v[34:35], v[38:39], off
	v_and_b32_sdwa v39, v76, v170 dst_sel:DWORD dst_unused:UNUSED_PAD src0_sel:WORD_1 src1_sel:DWORD
	v_mfma_f32_16x16x32_bf16 v[80:83], v[112:115], v[100:103], v[80:83]
	v_add3_u32 v40, v76, v39, s56
	v_and_b32_sdwa v41, v77, v170 dst_sel:DWORD dst_unused:UNUSED_PAD src0_sel:WORD_1 src1_sel:DWORD
	v_add3_u32 v41, v77, v41, s56
	v_and_b32_e32 v41, 0xffff0000, v41
	v_cvt_pk_bf16_f32 v39, v78, v79
	v_or_b32_sdwa v38, v41, v40 dst_sel:DWORD dst_unused:UNUSED_PAD src0_sel:DWORD src1_sel:WORD_1
	global_store_dwordx2 v[34:35], v[38:39], off offset:32
	v_and_b32_sdwa v39, v80, v170 dst_sel:DWORD dst_unused:UNUSED_PAD src0_sel:WORD_1 src1_sel:DWORD
	v_mfma_f32_16x16x32_bf16 v[68:71], v[116:119], v[100:103], v[68:71]
	v_add3_u32 v40, v80, v39, s56
	v_and_b32_sdwa v41, v81, v170 dst_sel:DWORD dst_unused:UNUSED_PAD src0_sel:WORD_1 src1_sel:DWORD
	v_add3_u32 v41, v81, v41, s56
	v_and_b32_e32 v41, 0xffff0000, v41
	v_cvt_pk_bf16_f32 v39, v82, v83
	v_or_b32_sdwa v38, v41, v40 dst_sel:DWORD dst_unused:UNUSED_PAD src0_sel:DWORD src1_sel:WORD_1
	global_store_dwordx2 v[34:35], v[38:39], off offset:64
	v_and_b32_sdwa v39, v68, v170 dst_sel:DWORD dst_unused:UNUSED_PAD src0_sel:WORD_1 src1_sel:DWORD
	v_add3_u32 v40, v68, v39, s56
	v_and_b32_sdwa v41, v69, v170 dst_sel:DWORD dst_unused:UNUSED_PAD src0_sel:WORD_1 src1_sel:DWORD
	v_mfma_f32_16x16x32_bf16 v[8:11], v[104:107], v[120:123], v[88:91]
	v_add3_u32 v41, v69, v41, s56
	v_and_b32_e32 v41, 0xffff0000, v41
	v_cvt_pk_bf16_f32 v39, v70, v71
	v_or_b32_sdwa v38, v41, v40 dst_sel:DWORD dst_unused:UNUSED_PAD src0_sel:DWORD src1_sel:WORD_1
	global_store_dwordx2 v[34:35], v[38:39], off offset:96
	v_or_b32_e32 v34, 32, v85
	v_lshlrev_b32_e32 v34, v86, v34
	v_and_b32_sdwa v38, v10, v170 dst_sel:DWORD dst_unused:UNUSED_PAD src0_sel:WORD_1 src1_sel:DWORD
	v_and_b32_sdwa v39, v8, v170 dst_sel:DWORD dst_unused:UNUSED_PAD src0_sel:WORD_1 src1_sel:DWORD
	v_mfma_f32_16x16x32_bf16 v[12:15], v[108:111], v[120:123], v[92:95]
	v_lshlrev_b32_e32 v34, 1, v34
	v_mov_b32_e32 v35, v129
	v_add3_u32 v8, v8, v39, s56
	v_add3_u32 v10, v10, v38, s56
	v_and_b32_sdwa v38, v11, v170 dst_sel:DWORD dst_unused:UNUSED_PAD src0_sel:WORD_1 src1_sel:DWORD
	v_and_b32_sdwa v39, v9, v170 dst_sel:DWORD dst_unused:UNUSED_PAD src0_sel:WORD_1 src1_sel:DWORD
	v_lshl_add_u64 v[34:35], v[32:33], 0, v[34:35]
	v_add3_u32 v11, v11, v38, s56
	v_add3_u32 v9, v9, v39, s56
	v_lshl_add_u64 v[34:35], v[34:35], 0, v[36:37]
	v_and_b32_e32 v11, 0xffff0000, v11
	v_and_b32_e32 v38, 0xffff0000, v9
	v_lshl_add_u64 v[34:35], v[34:35], 0, v[128:129]
	v_or_b32_sdwa v9, v11, v10 dst_sel:DWORD dst_unused:UNUSED_PAD src0_sel:DWORD src1_sel:WORD_1
	v_or_b32_sdwa v8, v38, v8 dst_sel:DWORD dst_unused:UNUSED_PAD src0_sel:DWORD src1_sel:WORD_1
	global_store_dwordx2 v[34:35], v[8:9], off
	v_and_b32_sdwa v9, v12, v170 dst_sel:DWORD dst_unused:UNUSED_PAD src0_sel:WORD_1 src1_sel:DWORD
	v_mfma_f32_16x16x32_bf16 v[16:19], v[112:115], v[120:123], v[96:99]
	v_add3_u32 v10, v12, v9, s56
	v_and_b32_sdwa v11, v13, v170 dst_sel:DWORD dst_unused:UNUSED_PAD src0_sel:WORD_1 src1_sel:DWORD
	v_add3_u32 v11, v13, v11, s56
	v_and_b32_e32 v11, 0xffff0000, v11
	v_cvt_pk_bf16_f32 v9, v14, v15
	v_or_b32_sdwa v8, v11, v10 dst_sel:DWORD dst_unused:UNUSED_PAD src0_sel:DWORD src1_sel:WORD_1
	global_store_dwordx2 v[34:35], v[8:9], off offset:32
	v_and_b32_sdwa v9, v16, v170 dst_sel:DWORD dst_unused:UNUSED_PAD src0_sel:WORD_1 src1_sel:DWORD
	v_add3_u32 v10, v16, v9, s56
	v_and_b32_sdwa v11, v17, v170 dst_sel:DWORD dst_unused:UNUSED_PAD src0_sel:WORD_1 src1_sel:DWORD
	v_add3_u32 v11, v17, v11, s56
	v_and_b32_e32 v11, 0xffff0000, v11
	v_cvt_pk_bf16_f32 v9, v18, v19
	v_or_b32_sdwa v8, v11, v10 dst_sel:DWORD dst_unused:UNUSED_PAD src0_sel:DWORD src1_sel:WORD_1
	global_store_dwordx2 v[34:35], v[8:9], off offset:64
	v_and_b32_sdwa v9, v20, v170 dst_sel:DWORD dst_unused:UNUSED_PAD src0_sel:WORD_1 src1_sel:DWORD
	v_add3_u32 v10, v20, v9, s56
	v_and_b32_sdwa v11, v21, v170 dst_sel:DWORD dst_unused:UNUSED_PAD src0_sel:WORD_1 src1_sel:DWORD
	v_add3_u32 v11, v21, v11, s56
	v_and_b32_e32 v11, 0xffff0000, v11
	v_cvt_pk_bf16_f32 v9, v22, v23
	v_or_b32_sdwa v8, v11, v10 dst_sel:DWORD dst_unused:UNUSED_PAD src0_sel:DWORD src1_sel:WORD_1
	global_store_dwordx2 v[34:35], v[8:9], off offset:96
	v_or_b32_e32 v8, 48, v85
	v_lshlrev_b32_e32 v8, v86, v8
	v_and_b32_sdwa v11, v24, v170 dst_sel:DWORD dst_unused:UNUSED_PAD src0_sel:WORD_1 src1_sel:DWORD
	v_mfma_f32_16x16x32_bf16 v[28:31], v[108:111], v[124:127], v[48:51]
	v_lshlrev_b32_e32 v8, 1, v8
	v_mov_b32_e32 v9, v129
	v_add3_u32 v12, v24, v11, s56
	v_and_b32_sdwa v13, v25, v170 dst_sel:DWORD dst_unused:UNUSED_PAD src0_sel:WORD_1 src1_sel:DWORD
	v_lshl_add_u64 v[8:9], v[32:33], 0, v[8:9]
	v_add3_u32 v13, v25, v13, s56
	v_lshl_add_u64 v[8:9], v[8:9], 0, v[36:37]
	v_and_b32_e32 v13, 0xffff0000, v13
	v_lshl_add_u64 v[8:9], v[8:9], 0, v[128:129]
	v_cvt_pk_bf16_f32 v11, v26, v27
	v_or_b32_sdwa v10, v13, v12 dst_sel:DWORD dst_unused:UNUSED_PAD src0_sel:DWORD src1_sel:WORD_1
	global_store_dwordx2 v[8:9], v[10:11], off
	v_and_b32_sdwa v11, v28, v170 dst_sel:DWORD dst_unused:UNUSED_PAD src0_sel:WORD_1 src1_sel:DWORD
	v_mfma_f32_16x16x32_bf16 v[4:7], v[112:115], v[124:127], v[56:59]
	v_add3_u32 v12, v28, v11, s56
	v_and_b32_sdwa v13, v29, v170 dst_sel:DWORD dst_unused:UNUSED_PAD src0_sel:WORD_1 src1_sel:DWORD
	v_add3_u32 v13, v29, v13, s56
	v_and_b32_e32 v13, 0xffff0000, v13
	v_cvt_pk_bf16_f32 v11, v30, v31
	v_or_b32_sdwa v10, v13, v12 dst_sel:DWORD dst_unused:UNUSED_PAD src0_sel:DWORD src1_sel:WORD_1
	global_store_dwordx2 v[8:9], v[10:11], off offset:32
	v_and_b32_sdwa v10, v6, v170 dst_sel:DWORD dst_unused:UNUSED_PAD src0_sel:WORD_1 src1_sel:DWORD
	v_and_b32_sdwa v11, v4, v170 dst_sel:DWORD dst_unused:UNUSED_PAD src0_sel:WORD_1 src1_sel:DWORD
	v_mfma_f32_16x16x32_bf16 v[0:3], v[116:119], v[124:127], v[64:67]
	v_add3_u32 v4, v4, v11, s56
	v_add3_u32 v6, v6, v10, s56
	v_and_b32_sdwa v10, v7, v170 dst_sel:DWORD dst_unused:UNUSED_PAD src0_sel:WORD_1 src1_sel:DWORD
	v_and_b32_sdwa v11, v5, v170 dst_sel:DWORD dst_unused:UNUSED_PAD src0_sel:WORD_1 src1_sel:DWORD
	v_add3_u32 v7, v7, v10, s56
	v_add3_u32 v5, v5, v11, s56
	v_and_b32_e32 v7, 0xffff0000, v7
	v_and_b32_e32 v10, 0xffff0000, v5
	v_or_b32_sdwa v5, v7, v6 dst_sel:DWORD dst_unused:UNUSED_PAD src0_sel:DWORD src1_sel:WORD_1
	v_or_b32_sdwa v4, v10, v4 dst_sel:DWORD dst_unused:UNUSED_PAD src0_sel:DWORD src1_sel:WORD_1
	global_store_dwordx2 v[8:9], v[4:5], off offset:64
	v_bfe_u32 v4, v0, 16, 1
	v_add3_u32 v0, v0, v4, s56
	v_bfe_u32 v4, v1, 16, 1
	v_lshrrev_b32_e32 v0, 16, v0
	v_add3_u32 v1, v1, v4, s56
	v_and_or_b32 v4, v1, s5, v0
	v_bfe_u32 v0, v2, 16, 1
	v_add3_u32 v0, v2, v0, s56
	v_bfe_u32 v1, v3, 16, 1
	v_lshrrev_b32_e32 v0, 16, v0
	v_add3_u32 v1, v3, v1, s56
	s_mov_b64 s[0:1], 0x60
	v_and_or_b32 v2, v1, s5, v0
	v_lshl_add_u64 v[0:1], v[8:9], 0, s[0:1]
	global_store_dword v[8:9], v4, off offset:96

.LBB0_180:
	s_or_b64 exec, exec, s[36:37]
	s_waitcnt vmcnt(1)
	v_lshlrev_b32_e32 v36, 16, v0
	v_and_b32_e32 v40, 0xffff0000, v0
	s_waitcnt vmcnt(0)
	v_lshlrev_b32_e32 v25, 16, v25
	v_lshlrev_b32_e32 v35, 16, v1
	v_and_b32_e32 v39, 0xffff0000, v1
	v_and_b32_e32 v38, 16, v0
	v_mov_b32_e32 v0, v36
	v_mov_b32_e32 v1, v40
	v_cndmask_b32_e64 v27, v25, 0, vcc
	v_mov_b32_e32 v34, v40
	v_pk_fma_f32 v[0:1], v[20:21], v[0:1], v[10:11]
	v_mov_b32_e32 v25, v35
	v_mov_b32_e32 v37, v39
	v_mov_b32_e32 v42, v35
	v_mov_b32_e32 v43, v39
	v_pk_fma_f32 v[0:1], v[14:15], v[34:35], v[0:1]
	v_pk_fma_f32 v[24:25], v[20:21], v[24:25], v[10:11]
	v_lshlrev_b32_e32 v41, 16, v2
	v_pk_fma_f32 v[0:1], v[12:13], v[42:43], v[0:1]
	v_pk_fma_f32 v[24:25], v[14:15], v[36:37], v[24:25]
	v_and_b32_sdwa v33, v1, v170 dst_sel:DWORD dst_unused:UNUSED_PAD src0_sel:WORD_1 src1_sel:DWORD
	v_pk_fma_f32 v[24:25], v[12:13], v[40:41], v[24:25]
	v_and_b32_sdwa v34, v0, v170 dst_sel:DWORD dst_unused:UNUSED_PAD src0_sel:WORD_1 src1_sel:DWORD
	v_add3_u32 v1, v1, v33, s56
	v_and_b32_sdwa v33, v25, v170 dst_sel:DWORD dst_unused:UNUSED_PAD src0_sel:WORD_1 src1_sel:DWORD
	v_add3_u32 v0, v0, v34, s56
	v_and_b32_sdwa v34, v24, v170 dst_sel:DWORD dst_unused:UNUSED_PAD src0_sel:WORD_1 src1_sel:DWORD
	v_add3_u32 v25, v25, v33, s56
	v_lshlrev_b32_e32 v26, 16, v3
	v_and_b32_e32 v0, 0xffff0000, v0
	v_add3_u32 v24, v24, v34, s56
	v_and_b32_e32 v25, 0xffff0000, v25
	v_and_b32_e32 v3, 0xffff0000, v3
	v_and_b32_e32 v2, 0xffff0000, v2
	v_or_b32_sdwa v1, v25, v1 dst_sel:DWORD dst_unused:UNUSED_PAD src0_sel:DWORD src1_sel:WORD_1
	v_or_b32_sdwa v0, v24, v0 dst_sel:DWORD dst_unused:UNUSED_PAD src0_sel:WORD_1 src1_sel:DWORD
	v_pk_mov_b32 v[24:25], v[38:39], v[2:3] op_sel:[1,0]
	v_mov_b32_e32 v34, v41
	v_pk_fma_f32 v[24:25], v[20:21], v[24:25], v[10:11]
	v_mov_b32_e32 v35, v26
	v_pk_fma_f32 v[24:25], v[14:15], v[34:35], v[24:25]
	v_pk_fma_f32 v[34:35], v[20:21], v[34:35], v[10:11]
	v_pk_fma_f32 v[24:25], v[12:13], v[2:3], v[24:25]
	v_pk_fma_f32 v[2:3], v[14:15], v[2:3], v[34:35]
	v_cmp_lt_i32_e32 vcc, s89, v19
	v_pk_fma_f32 v[2:3], v[12:13], v[26:27], v[2:3]
	v_cvt_pk_bf16_f32 v3, v25, v3
	v_cvt_pk_bf16_f32 v2, v24, v2
	v_lshl_add_u32 v24, v32, 4, v17
	ds_write_b128 v24, v[0:3]
	v_add_u32_e32 v0, 0x100, v19
	v_add_u32_e32 v31, 0x800, v31
	v_add_u32_e32 v17, 0x1000, v17
	s_or_b64 s[28:29], vcc, s[28:29]
	v_mov_b32_e32 v19, v0
	s_andn2_b64 exec, exec, s[28:29]
	s_cbranch_execz .LBB0_183

.LBB0_184:
	s_or_b64 exec, exec, s[36:37]
	s_waitcnt vmcnt(1)
	v_lshlrev_b32_e32 v32, 16, v0
	v_and_b32_e32 v36, 0xffff0000, v0
	s_waitcnt vmcnt(0)
	v_lshlrev_b32_e32 v21, 16, v21
	v_lshlrev_b32_e32 v27, 16, v1
	v_and_b32_e32 v35, 0xffff0000, v1
	v_and_b32_e32 v34, 16, v0
	v_mov_b32_e32 v0, v32
	v_mov_b32_e32 v1, v36
	v_cndmask_b32_e64 v23, v21, 0, vcc
	v_mov_b32_e32 v26, v36
	v_pk_fma_f32 v[0:1], v[8:9], v[0:1], v[6:7]
	v_mov_b32_e32 v21, v27
	v_mov_b32_e32 v33, v35
	v_mov_b32_e32 v38, v27
	v_mov_b32_e32 v39, v35
	v_pk_fma_f32 v[0:1], v[10:11], v[26:27], v[0:1]
	v_pk_fma_f32 v[20:21], v[8:9], v[20:21], v[6:7]
	v_lshlrev_b32_e32 v37, 16, v2
	v_pk_fma_f32 v[0:1], v[12:13], v[38:39], v[0:1]
	v_pk_fma_f32 v[20:21], v[10:11], v[32:33], v[20:21]
	v_and_b32_sdwa v26, v1, v170 dst_sel:DWORD dst_unused:UNUSED_PAD src0_sel:WORD_1 src1_sel:DWORD
	v_pk_fma_f32 v[20:21], v[12:13], v[36:37], v[20:21]
	v_and_b32_sdwa v27, v0, v170 dst_sel:DWORD dst_unused:UNUSED_PAD src0_sel:WORD_1 src1_sel:DWORD
	v_add3_u32 v1, v1, v26, s56
	v_and_b32_sdwa v26, v21, v170 dst_sel:DWORD dst_unused:UNUSED_PAD src0_sel:WORD_1 src1_sel:DWORD
	v_add3_u32 v0, v0, v27, s56
	v_and_b32_sdwa v27, v20, v170 dst_sel:DWORD dst_unused:UNUSED_PAD src0_sel:WORD_1 src1_sel:DWORD
	v_add3_u32 v21, v21, v26, s56
	v_lshlrev_b32_e32 v22, 16, v3
	v_and_b32_e32 v0, 0xffff0000, v0
	v_add3_u32 v20, v20, v27, s56
	v_and_b32_e32 v21, 0xffff0000, v21
	v_and_b32_e32 v3, 0xffff0000, v3
	v_and_b32_e32 v2, 0xffff0000, v2
	v_or_b32_sdwa v1, v21, v1 dst_sel:DWORD dst_unused:UNUSED_PAD src0_sel:DWORD src1_sel:WORD_1
	v_or_b32_sdwa v0, v20, v0 dst_sel:DWORD dst_unused:UNUSED_PAD src0_sel:WORD_1 src1_sel:DWORD
	v_pk_mov_b32 v[20:21], v[34:35], v[2:3] op_sel:[1,0]
	v_mov_b32_e32 v26, v37
	v_pk_fma_f32 v[20:21], v[8:9], v[20:21], v[6:7]
	v_mov_b32_e32 v27, v22
	v_pk_fma_f32 v[20:21], v[10:11], v[26:27], v[20:21]
	v_pk_fma_f32 v[26:27], v[8:9], v[26:27], v[6:7]
	v_pk_fma_f32 v[20:21], v[12:13], v[2:3], v[20:21]
	v_pk_fma_f32 v[2:3], v[10:11], v[2:3], v[26:27]
	v_cmp_lt_i32_e32 vcc, s89, v24
	v_pk_fma_f32 v[2:3], v[12:13], v[22:23], v[2:3]
	v_cvt_pk_bf16_f32 v3, v21, v3
	v_cvt_pk_bf16_f32 v2, v20, v2
	v_lshl_add_u32 v20, v25, 4, v17
	ds_write_b128 v20, v[0:3]
	v_add_u32_e32 v0, 0x100, v24
	v_add_u32_e32 v19, 0x800, v19
	v_add_u32_e32 v17, 0x1000, v17
	s_or_b64 s[28:29], vcc, s[28:29]
	v_mov_b32_e32 v24, v0
	s_andn2_b64 exec, exec, s[28:29]
	s_cbranch_execz .LBB0_187

.LBB0_188:
	s_or_b64 exec, exec, s[36:37]
	s_waitcnt vmcnt(1)
	v_lshlrev_b32_e32 v26, 16, v0
	v_and_b32_e32 v32, 0xffff0000, v0
	s_waitcnt vmcnt(0)
	v_lshlrev_b32_e32 v15, 16, v15
	v_lshlrev_b32_e32 v25, 16, v1
	v_and_b32_e32 v31, 0xffff0000, v1
	v_and_b32_e32 v30, 16, v0
	v_mov_b32_e32 v0, v26
	v_mov_b32_e32 v1, v32
	v_cndmask_b32_e64 v21, v15, 0, vcc
	v_mov_b32_e32 v24, v32
	v_pk_fma_f32 v[0:1], v[6:7], v[0:1], v[12:13]
	v_mov_b32_e32 v15, v25
	v_mov_b32_e32 v27, v31
	v_mov_b32_e32 v34, v25
	v_mov_b32_e32 v35, v31
	v_pk_fma_f32 v[0:1], v[8:9], v[24:25], v[0:1]
	v_pk_fma_f32 v[14:15], v[6:7], v[14:15], v[12:13]
	v_lshlrev_b32_e32 v33, 16, v2
	v_pk_fma_f32 v[0:1], v[10:11], v[34:35], v[0:1]
	v_pk_fma_f32 v[14:15], v[8:9], v[26:27], v[14:15]
	v_and_b32_sdwa v23, v1, v170 dst_sel:DWORD dst_unused:UNUSED_PAD src0_sel:WORD_1 src1_sel:DWORD
	v_pk_fma_f32 v[14:15], v[10:11], v[32:33], v[14:15]
	v_and_b32_sdwa v24, v0, v170 dst_sel:DWORD dst_unused:UNUSED_PAD src0_sel:WORD_1 src1_sel:DWORD
	v_add3_u32 v1, v1, v23, s56
	v_and_b32_sdwa v23, v15, v170 dst_sel:DWORD dst_unused:UNUSED_PAD src0_sel:WORD_1 src1_sel:DWORD
	v_add3_u32 v0, v0, v24, s56
	v_and_b32_sdwa v24, v14, v170 dst_sel:DWORD dst_unused:UNUSED_PAD src0_sel:WORD_1 src1_sel:DWORD
	v_add3_u32 v15, v15, v23, s56
	v_lshlrev_b32_e32 v20, 16, v3
	v_and_b32_e32 v0, 0xffff0000, v0
	v_add3_u32 v14, v14, v24, s56
	v_and_b32_e32 v15, 0xffff0000, v15
	v_and_b32_e32 v3, 0xffff0000, v3
	v_and_b32_e32 v2, 0xffff0000, v2
	v_or_b32_sdwa v1, v15, v1 dst_sel:DWORD dst_unused:UNUSED_PAD src0_sel:DWORD src1_sel:WORD_1
	v_or_b32_sdwa v0, v14, v0 dst_sel:DWORD dst_unused:UNUSED_PAD src0_sel:WORD_1 src1_sel:DWORD
	v_pk_mov_b32 v[14:15], v[30:31], v[2:3] op_sel:[1,0]
	v_mov_b32_e32 v24, v33
	v_pk_fma_f32 v[14:15], v[6:7], v[14:15], v[12:13]
	v_mov_b32_e32 v25, v20
	v_pk_fma_f32 v[14:15], v[8:9], v[24:25], v[14:15]
	v_pk_fma_f32 v[24:25], v[6:7], v[24:25], v[12:13]
	v_pk_fma_f32 v[14:15], v[10:11], v[2:3], v[14:15]
	v_pk_fma_f32 v[2:3], v[8:9], v[2:3], v[24:25]
	v_cmp_lt_i32_e32 vcc, s89, v19
	v_pk_fma_f32 v[2:3], v[10:11], v[20:21], v[2:3]
	v_cvt_pk_bf16_f32 v3, v15, v3
	v_cvt_pk_bf16_f32 v2, v14, v2
	v_lshl_add_u32 v14, v22, 4, v17
	ds_write_b128 v14, v[0:3]
	v_add_u32_e32 v0, 0x100, v19
	v_add_u32_e32 v29, 0x800, v29
	v_add_u32_e32 v17, 0x1000, v17
	s_or_b64 s[28:29], vcc, s[28:29]
	v_mov_b32_e32 v19, v0
	s_andn2_b64 exec, exec, s[28:29]
	s_cbranch_execz .LBB0_191

.LBB0_192:
	v_add_u32_e32 v22, s0, v20
	ds_read_b128 v[30:33], v22 offset:96
	ds_read_b128 v[38:41], v22 offset:64
	ds_read_b128 v[42:45], v22
	ds_read_b128 v[46:49], v22 offset:32
	v_add_u32_e32 v21, s0, v19
	ds_read_b128 v[34:37], v21
	s_addk_i32 s0, 0x80
	s_cmpk_lg_i32 s0, 0x200
	s_waitcnt lgkmcnt(0)
	v_mfma_f32_16x16x32_bf16 v[12:15], v[30:33], v[34:37], v[12:15]
	v_mfma_f32_16x16x32_bf16 v[8:11], v[38:41], v[34:37], v[8:11]
	v_mfma_f32_16x16x32_bf16 v[4:7], v[46:49], v[34:37], v[4:7]
	v_mfma_f32_16x16x32_bf16 v[0:3], v[42:45], v[34:37], v[0:3]
	ds_read_b128 v[30:33], v22 offset:160
	ds_read_b128 v[38:41], v22 offset:128
	ds_read_b128 v[42:45], v22 offset:64
	ds_read_b128 v[46:49], v22 offset:96
	ds_read_b128 v[34:37], v21 offset:64
	s_waitcnt lgkmcnt(0)
	v_mfma_f32_16x16x32_bf16 v[12:15], v[30:33], v[34:37], v[12:15]
	v_mfma_f32_16x16x32_bf16 v[8:11], v[38:41], v[34:37], v[8:11]
	v_mfma_f32_16x16x32_bf16 v[4:7], v[46:49], v[34:37], v[4:7]
	v_mfma_f32_16x16x32_bf16 v[0:3], v[42:45], v[34:37], v[0:3]
	s_cbranch_scc1 .LBB0_192
	v_readlane_b32 s36, v250, 0
	v_add_u32_e32 v128, s75, v16
	v_readlane_b32 s42, v250, 6
	v_readlane_b32 s43, v250, 7
	v_and_b32_e32 v27, 0xffffffc0, v28
	v_lshlrev_b32_e32 v24, 1, v27
	v_lshl_add_u64 v[20:21], v[128:129], 2, s[42:43]
	global_load_dword v22, v[20:21], off
	v_lshl_or_b32 v24, v23, 3, v24
	v_add_u32_e32 v28, v17, v24
	v_add_u32_e32 v42, 0x2000, v28
	s_barrier
	ds_read2_b64 v[30:33], v42 offset0:32 offset1:36
	ds_read2_b64 v[34:37], v28 offset1:4
	v_mov_b32_e32 v40, v12
	v_mov_b32_e32 v41, v14
	v_mov_b32_e32 v14, v13
	s_waitcnt lgkmcnt(1)
	v_lshlrev_b32_e32 v39, 16, v31
	s_waitcnt lgkmcnt(0)
	v_lshlrev_b32_e32 v25, 16, v35
	v_lshlrev_b32_e32 v24, 16, v34
	v_and_b32_e32 v35, 0xffff0000, v35
	v_and_b32_e32 v34, 0xffff0000, v34
	v_lshlrev_b32_e32 v38, 16, v30
	v_and_b32_e32 v31, 0xffff0000, v31
	v_and_b32_e32 v30, 0xffff0000, v30
	v_readlane_b32 s0, v253, 46
	v_readlane_b32 s37, v250, 1
	v_readlane_b32 s38, v250, 2
	v_readlane_b32 s39, v250, 3
	v_readlane_b32 s40, v250, 4
	v_readlane_b32 s41, v250, 5
	s_waitcnt vmcnt(0)
	v_pk_fma_f32 v[24:25], v[22:23], v[24:25], v[40:41] op_sel_hi:[0,1,1]
	v_pk_mul_f32 v[24:25], v[24:25], v[38:39]
	v_pk_fma_f32 v[12:13], v[22:23], v[34:35], v[14:15] op_sel_hi:[0,1,1]
	v_pk_mul_f32 v[12:13], v[12:13], v[30:31]
	v_and_b32_sdwa v14, v25, v170 dst_sel:DWORD dst_unused:UNUSED_PAD src0_sel:WORD_1 src1_sel:DWORD
	v_and_b32_sdwa v15, v24, v170 dst_sel:DWORD dst_unused:UNUSED_PAD src0_sel:WORD_1 src1_sel:DWORD
	v_add3_u32 v15, v24, v15, s56
	v_add3_u32 v14, v25, v14, s56
	v_and_b32_sdwa v24, v13, v170 dst_sel:DWORD dst_unused:UNUSED_PAD src0_sel:WORD_1 src1_sel:DWORD
	v_and_b32_sdwa v25, v12, v170 dst_sel:DWORD dst_unused:UNUSED_PAD src0_sel:WORD_1 src1_sel:DWORD
	v_add3_u32 v13, v13, v24, s56
	v_add3_u32 v12, v12, v25, s56
	v_and_b32_e32 v13, 0xffff0000, v13
	v_and_b32_e32 v12, 0xffff0000, v12
	v_or_b32_sdwa v13, v13, v14 dst_sel:DWORD dst_unused:UNUSED_PAD src0_sel:DWORD src1_sel:WORD_1
	v_or_b32_sdwa v12, v12, v15 dst_sel:DWORD dst_unused:UNUSED_PAD src0_sel:DWORD src1_sel:WORD_1
	v_lshlrev_b32_e32 v15, 16, v37
	v_lshlrev_b32_e32 v14, 16, v36
	v_mov_b32_e32 v34, v8
	v_mov_b32_e32 v35, v10
	v_and_b32_e32 v25, 0xffff0000, v37
	v_and_b32_e32 v24, 0xffff0000, v36
	v_lshlrev_b32_e32 v31, 16, v33
	v_lshlrev_b32_e32 v30, 16, v32
	v_pk_fma_f32 v[14:15], v[22:23], v[14:15], v[34:35] op_sel_hi:[0,1,1]
	v_mov_b32_e32 v10, v9
	v_and_b32_e32 v33, 0xffff0000, v33
	v_and_b32_e32 v32, 0xffff0000, v32
	v_pk_mul_f32 v[14:15], v[14:15], v[30:31]
	v_pk_fma_f32 v[8:9], v[22:23], v[24:25], v[10:11] op_sel_hi:[0,1,1]
	v_pk_mul_f32 v[8:9], v[8:9], v[32:33]
	v_and_b32_sdwa v10, v15, v170 dst_sel:DWORD dst_unused:UNUSED_PAD src0_sel:WORD_1 src1_sel:DWORD
	v_and_b32_sdwa v11, v14, v170 dst_sel:DWORD dst_unused:UNUSED_PAD src0_sel:WORD_1 src1_sel:DWORD
	v_add3_u32 v11, v14, v11, s56
	v_add3_u32 v10, v15, v10, s56
	v_and_b32_sdwa v14, v9, v170 dst_sel:DWORD dst_unused:UNUSED_PAD src0_sel:WORD_1 src1_sel:DWORD
	v_and_b32_sdwa v15, v8, v170 dst_sel:DWORD dst_unused:UNUSED_PAD src0_sel:WORD_1 src1_sel:DWORD
	v_add3_u32 v9, v9, v14, s56
	v_add3_u32 v8, v8, v15, s56
	v_and_b32_e32 v9, 0xffff0000, v9
	v_and_b32_e32 v8, 0xffff0000, v8
	v_or_b32_sdwa v9, v9, v10 dst_sel:DWORD dst_unused:UNUSED_PAD src0_sel:DWORD src1_sel:WORD_1
	v_or_b32_sdwa v8, v8, v11 dst_sel:DWORD dst_unused:UNUSED_PAD src0_sel:DWORD src1_sel:WORD_1
	ds_write2_b64 v28, v[12:13], v[8:9] offset1:4
	ds_read2_b64 v[12:15], v28 offset0:8 offset1:12
	ds_read2_b64 v[8:11], v42 offset0:40 offset1:44
	v_mov_b32_e32 v33, v6
	v_mov_b32_e32 v6, v5
	v_mov_b32_e32 v32, v4
	s_waitcnt lgkmcnt(1)
	v_lshlrev_b32_e32 v25, 16, v13
	v_lshlrev_b32_e32 v24, 16, v12
	v_and_b32_e32 v13, 0xffff0000, v13
	v_and_b32_e32 v12, 0xffff0000, v12
	s_waitcnt lgkmcnt(0)
	v_lshlrev_b32_e32 v31, 16, v9
	v_lshlrev_b32_e32 v30, 16, v8
	v_and_b32_e32 v9, 0xffff0000, v9
	v_and_b32_e32 v8, 0xffff0000, v8
	v_pk_fma_f32 v[4:5], v[22:23], v[12:13], v[6:7] op_sel_hi:[0,1,1]
	v_pk_fma_f32 v[24:25], v[22:23], v[24:25], v[32:33] op_sel_hi:[0,1,1]
	v_pk_mul_f32 v[4:5], v[4:5], v[8:9]
	v_pk_mul_f32 v[24:25], v[24:25], v[30:31]
	v_cvt_pk_bf16_f32 v5, v25, v5
	v_cvt_pk_bf16_f32 v4, v24, v4
	v_lshlrev_b32_e32 v7, 16, v15
	v_lshlrev_b32_e32 v6, 16, v14
	v_and_b32_e32 v9, 0xffff0000, v15
	v_and_b32_e32 v8, 0xffff0000, v14
	v_mov_b32_e32 v14, v0
	v_mov_b32_e32 v15, v2
	v_lshlrev_b32_e32 v13, 16, v11
	v_lshlrev_b32_e32 v12, 16, v10
	v_pk_fma_f32 v[6:7], v[22:23], v[6:7], v[14:15] op_sel_hi:[0,1,1]
	v_mov_b32_e32 v2, v1
	v_and_b32_e32 v11, 0xffff0000, v11
	v_and_b32_e32 v10, 0xffff0000, v10
	v_pk_mul_f32 v[6:7], v[6:7], v[12:13]
	v_pk_fma_f32 v[0:1], v[22:23], v[8:9], v[2:3] op_sel_hi:[0,1,1]
	v_pk_mul_f32 v[0:1], v[0:1], v[10:11]
	v_and_b32_sdwa v2, v7, v170 dst_sel:DWORD dst_unused:UNUSED_PAD src0_sel:WORD_1 src1_sel:DWORD
	v_and_b32_sdwa v3, v6, v170 dst_sel:DWORD dst_unused:UNUSED_PAD src0_sel:WORD_1 src1_sel:DWORD
	v_add3_u32 v3, v6, v3, s56
	v_add3_u32 v2, v7, v2, s56
	v_and_b32_sdwa v6, v1, v170 dst_sel:DWORD dst_unused:UNUSED_PAD src0_sel:WORD_1 src1_sel:DWORD
	v_and_b32_sdwa v7, v0, v170 dst_sel:DWORD dst_unused:UNUSED_PAD src0_sel:WORD_1 src1_sel:DWORD
	v_add3_u32 v1, v1, v6, s56
	v_add3_u32 v0, v0, v7, s56
	v_and_b32_e32 v1, 0xffff0000, v1
	v_and_b32_e32 v0, 0xffff0000, v0
	v_or_b32_sdwa v1, v1, v2 dst_sel:DWORD dst_unused:UNUSED_PAD src0_sel:DWORD src1_sel:WORD_1
	v_or_b32_sdwa v0, v0, v3 dst_sel:DWORD dst_unused:UNUSED_PAD src0_sel:DWORD src1_sel:WORD_1
	ds_write2_b64 v28, v[4:5], v[0:1] offset0:8 offset1:12
	v_mov_b32_e32 v0, 0
	v_add_u32_e32 v22, s0, v29
	s_mov_b32 s0, 0
	v_mov_b32_e32 v1, v0
	v_mov_b32_e32 v2, v0
	v_mov_b32_e32 v3, v0
	v_mov_b32_e32 v4, v0
	v_mov_b32_e32 v5, v0
	v_mov_b32_e32 v6, v0
	v_mov_b32_e32 v7, v0
	v_mov_b32_e32 v8, v0
	v_mov_b32_e32 v9, v0
	v_mov_b32_e32 v10, v0
	v_mov_b32_e32 v11, v0
	v_mov_b32_e32 v12, v0
	v_mov_b32_e32 v13, v0
	v_mov_b32_e32 v14, v0
	v_mov_b32_e32 v15, v0
	s_waitcnt lgkmcnt(0)
	s_barrier
.LBB0_194:
	v_add_u32_e32 v25, s0, v22
	ds_read_b128 v[28:31], v25 offset:96
	ds_read_b128 v[36:39], v25 offset:64
	ds_read_b128 v[40:43], v25
	ds_read_b128 v[44:47], v25 offset:32
	v_add_u32_e32 v24, s0, v19
	ds_read_b128 v[32:35], v24
	s_addk_i32 s0, 0x80
	s_cmpk_lg_i32 s0, 0x200
	s_waitcnt lgkmcnt(0)
	v_mfma_f32_16x16x32_bf16 v[12:15], v[28:31], v[32:35], v[12:15]
	v_mfma_f32_16x16x32_bf16 v[8:11], v[36:39], v[32:35], v[8:11]
	v_mfma_f32_16x16x32_bf16 v[4:7], v[44:47], v[32:35], v[4:7]
	v_mfma_f32_16x16x32_bf16 v[0:3], v[40:43], v[32:35], v[0:3]
	ds_read_b128 v[28:31], v25 offset:160
	ds_read_b128 v[36:39], v25 offset:128
	ds_read_b128 v[40:43], v25 offset:64
	ds_read_b128 v[44:47], v25 offset:96
	ds_read_b128 v[32:35], v24 offset:64
	s_waitcnt lgkmcnt(0)
	v_mfma_f32_16x16x32_bf16 v[12:15], v[28:31], v[32:35], v[12:15]
	v_mfma_f32_16x16x32_bf16 v[8:11], v[36:39], v[32:35], v[8:11]
	v_mfma_f32_16x16x32_bf16 v[4:7], v[44:47], v[32:35], v[4:7]
	v_mfma_f32_16x16x32_bf16 v[0:3], v[40:43], v[32:35], v[0:3]
	s_cbranch_scc1 .LBB0_194
	v_readlane_b32 s0, v250, 21
	v_readlane_b32 s1, v250, 22
	v_mov_b32_e32 v19, v129
	v_lshlrev_b32_e32 v128, 9, v26
	v_mov_b64_e32 v[24:25], s[0:1]
	s_movk_i32 s0, 0x5000
	v_mad_u64_u32 v[24:25], s[0:1], v16, s0, v[24:25]
	v_lshl_add_u64 v[18:19], v[24:25], 0, v[18:19]
	v_lshl_add_u64 v[24:25], v[18:19], 0, v[128:129]
	global_load_dword v18, v[20:21], off offset:2048
	v_lshl_or_b32 v16, v23, 2, v27
	v_lshl_add_u32 v19, v16, 1, v17
	v_ashrrev_i32_e32 v17, 31, v16
	v_add_u32_e32 v34, 0x4000, v19
	v_lshl_add_u64 v[16:17], v[16:17], 1, v[24:25]
	ds_read2_b64 v[20:23], v34 offset0:64 offset1:68
	ds_read2_b64 v[24:27], v19 offset1:4
	v_mov_b32_e32 v33, v14
	v_mov_b32_e32 v14, v13
	v_mov_b32_e32 v32, v12
	s_waitcnt lgkmcnt(1)
	v_lshlrev_b32_e32 v31, 16, v21
	s_waitcnt lgkmcnt(0)
	v_lshlrev_b32_e32 v29, 16, v25
	v_lshlrev_b32_e32 v28, 16, v24
	v_and_b32_e32 v25, 0xffff0000, v25
	v_and_b32_e32 v24, 0xffff0000, v24
	v_lshlrev_b32_e32 v30, 16, v20
	v_and_b32_e32 v21, 0xffff0000, v21
	v_and_b32_e32 v20, 0xffff0000, v20
	s_mov_b64 s[0:1], 0x60
	s_waitcnt vmcnt(0)
	v_pk_fma_f32 v[12:13], v[18:19], v[24:25], v[14:15] op_sel_hi:[0,1,1]
	v_pk_fma_f32 v[28:29], v[18:19], v[28:29], v[32:33] op_sel_hi:[0,1,1]
	v_pk_mul_f32 v[12:13], v[12:13], v[20:21]
	v_pk_mul_f32 v[28:29], v[28:29], v[30:31]
	v_cvt_pk_bf16_f32 v13, v29, v13
	v_cvt_pk_bf16_f32 v12, v28, v12
	global_store_dwordx2 v[16:17], v[12:13], off
	v_lshlrev_b32_e32 v13, 16, v27
	v_lshlrev_b32_e32 v12, 16, v26
	v_mov_b32_e32 v24, v8
	v_mov_b32_e32 v25, v10
	v_and_b32_e32 v15, 0xffff0000, v27
	v_and_b32_e32 v14, 0xffff0000, v26
	v_lshlrev_b32_e32 v21, 16, v23
	v_lshlrev_b32_e32 v20, 16, v22
	v_pk_fma_f32 v[12:13], v[18:19], v[12:13], v[24:25] op_sel_hi:[0,1,1]
	v_mov_b32_e32 v10, v9
	v_and_b32_e32 v23, 0xffff0000, v23
	v_and_b32_e32 v22, 0xffff0000, v22
	v_pk_mul_f32 v[12:13], v[12:13], v[20:21]
	v_pk_fma_f32 v[8:9], v[18:19], v[14:15], v[10:11] op_sel_hi:[0,1,1]
	v_pk_mul_f32 v[8:9], v[8:9], v[22:23]
	v_and_b32_sdwa v10, v13, v170 dst_sel:DWORD dst_unused:UNUSED_PAD src0_sel:WORD_1 src1_sel:DWORD
	v_and_b32_sdwa v11, v12, v170 dst_sel:DWORD dst_unused:UNUSED_PAD src0_sel:WORD_1 src1_sel:DWORD
	v_add3_u32 v11, v12, v11, s56
	v_add3_u32 v10, v13, v10, s56
	v_and_b32_sdwa v12, v9, v170 dst_sel:DWORD dst_unused:UNUSED_PAD src0_sel:WORD_1 src1_sel:DWORD
	v_and_b32_sdwa v13, v8, v170 dst_sel:DWORD dst_unused:UNUSED_PAD src0_sel:WORD_1 src1_sel:DWORD
	v_add3_u32 v9, v9, v12, s56
	v_add3_u32 v8, v8, v13, s56
	v_and_b32_e32 v9, 0xffff0000, v9
	v_and_b32_e32 v8, 0xffff0000, v8
	v_or_b32_sdwa v9, v9, v10 dst_sel:DWORD dst_unused:UNUSED_PAD src0_sel:DWORD src1_sel:WORD_1
	v_or_b32_sdwa v8, v8, v11 dst_sel:DWORD dst_unused:UNUSED_PAD src0_sel:DWORD src1_sel:WORD_1
	global_store_dwordx2 v[16:17], v[8:9], off offset:32
	ds_read2_b64 v[12:15], v19 offset0:8 offset1:12
	ds_read2_b64 v[8:11], v34 offset0:72 offset1:76
	v_mov_b32_e32 v25, v6
	v_mov_b32_e32 v6, v5
	v_mov_b32_e32 v24, v4
	s_waitcnt lgkmcnt(1)
	v_and_b32_e32 v21, 0xffff0000, v13
	v_and_b32_e32 v20, 0xffff0000, v12
	v_lshlrev_b32_e32 v23, 16, v13
	v_lshlrev_b32_e32 v22, 16, v12
	s_waitcnt lgkmcnt(0)
	v_lshlrev_b32_e32 v13, 16, v9
	v_lshlrev_b32_e32 v12, 16, v8
	v_and_b32_e32 v9, 0xffff0000, v9
	v_and_b32_e32 v8, 0xffff0000, v8
	v_pk_fma_f32 v[4:5], v[18:19], v[20:21], v[6:7] op_sel_hi:[0,1,1]
	v_pk_fma_f32 v[22:23], v[18:19], v[22:23], v[24:25] op_sel_hi:[0,1,1]
	v_pk_mul_f32 v[4:5], v[4:5], v[8:9]
	v_pk_mul_f32 v[12:13], v[22:23], v[12:13]
	v_and_b32_sdwa v8, v5, v170 dst_sel:DWORD dst_unused:UNUSED_PAD src0_sel:WORD_1 src1_sel:DWORD
	v_and_b32_sdwa v7, v12, v170 dst_sel:DWORD dst_unused:UNUSED_PAD src0_sel:WORD_1 src1_sel:DWORD
	v_and_b32_sdwa v9, v4, v170 dst_sel:DWORD dst_unused:UNUSED_PAD src0_sel:WORD_1 src1_sel:DWORD
	v_add3_u32 v5, v5, v8, s56
	v_lshlrev_b32_e32 v8, 16, v14
	v_add3_u32 v7, v12, v7, s56
	v_add3_u32 v4, v4, v9, s56
	v_and_b32_e32 v9, 0xffff0000, v14
	v_lshlrev_b32_e32 v12, 16, v10
	v_fma_f32 v0, v18, v8, v0
	v_and_b32_sdwa v6, v13, v170 dst_sel:DWORD dst_unused:UNUSED_PAD src0_sel:WORD_1 src1_sel:DWORD
	v_and_b32_e32 v10, 0xffff0000, v10
	v_mul_f32_e32 v0, v0, v12
	v_fma_f32 v1, v18, v9, v1
	v_add3_u32 v6, v13, v6, s56
	v_and_b32_e32 v5, 0xffff0000, v5
	v_and_b32_e32 v4, 0xffff0000, v4
	v_mul_f32_e32 v1, v1, v10
	v_bfe_u32 v8, v0, 16, 1
	v_or_b32_sdwa v5, v5, v6 dst_sel:DWORD dst_unused:UNUSED_PAD src0_sel:DWORD src1_sel:WORD_1
	v_or_b32_sdwa v4, v4, v7 dst_sel:DWORD dst_unused:UNUSED_PAD src0_sel:DWORD src1_sel:WORD_1
	v_add3_u32 v0, v0, v8, s56
	v_bfe_u32 v8, v1, 16, 1
	global_store_dwordx2 v[16:17], v[4:5], off offset:64
	v_lshlrev_b32_e32 v4, 16, v15
	v_and_b32_e32 v5, 0xffff0000, v15
	v_lshrrev_b32_e32 v0, 16, v0
	v_add3_u32 v1, v1, v8, s56
	v_lshlrev_b32_e32 v6, 16, v11
	v_and_b32_e32 v7, 0xffff0000, v11
	v_and_or_b32 v8, v1, s5, v0
	v_pk_fma_f32 v[0:1], v[18:19], v[4:5], v[2:3] op_sel_hi:[0,1,1]
	v_pk_mul_f32 v[0:1], v[0:1], v[6:7]
	global_store_dword v[16:17], v8, off offset:96
	v_and_b32_sdwa v3, v0, v170 dst_sel:DWORD dst_unused:UNUSED_PAD src0_sel:WORD_1 src1_sel:DWORD
	v_and_b32_sdwa v2, v1, v170 dst_sel:DWORD dst_unused:UNUSED_PAD src0_sel:WORD_1 src1_sel:DWORD
	v_add3_u32 v0, v0, v3, s56
	v_add3_u32 v1, v1, v2, s56
	v_lshrrev_b32_e32 v0, 16, v0
	v_and_or_b32 v2, v1, s5, v0
	v_lshl_add_u64 v[0:1], v[16:17], 0, s[0:1]

.LBB0_208:
	s_or_b64 exec, exec, s[40:41]
	s_waitcnt vmcnt(1)
	v_lshlrev_b32_e32 v40, 16, v0
	v_and_b32_e32 v44, 0xffff0000, v0
	s_waitcnt vmcnt(0)
	v_lshlrev_b32_e32 v27, 16, v27
	v_lshlrev_b32_e32 v39, 16, v1
	v_and_b32_e32 v43, 0xffff0000, v1
	v_and_b32_e32 v42, 16, v0
	v_mov_b32_e32 v0, v40
	v_mov_b32_e32 v1, v44
	v_cndmask_b32_e64 v29, v27, 0, vcc
	v_mov_b32_e32 v38, v44
	v_pk_fma_f32 v[0:1], v[20:21], v[0:1], v[14:15]
	v_mov_b32_e32 v27, v39
	v_mov_b32_e32 v41, v43
	v_mov_b32_e32 v46, v39
	v_mov_b32_e32 v47, v43
	v_pk_fma_f32 v[0:1], v[18:19], v[38:39], v[0:1]
	v_pk_fma_f32 v[26:27], v[20:21], v[26:27], v[14:15]
	v_lshlrev_b32_e32 v45, 16, v2
	v_pk_fma_f32 v[0:1], v[16:17], v[46:47], v[0:1]
	v_pk_fma_f32 v[26:27], v[18:19], v[40:41], v[26:27]
	v_and_b32_sdwa v37, v1, v170 dst_sel:DWORD dst_unused:UNUSED_PAD src0_sel:WORD_1 src1_sel:DWORD
	v_pk_fma_f32 v[26:27], v[16:17], v[44:45], v[26:27]
	v_and_b32_sdwa v38, v0, v170 dst_sel:DWORD dst_unused:UNUSED_PAD src0_sel:WORD_1 src1_sel:DWORD
	v_add3_u32 v1, v1, v37, s56
	v_and_b32_sdwa v37, v27, v170 dst_sel:DWORD dst_unused:UNUSED_PAD src0_sel:WORD_1 src1_sel:DWORD
	v_add3_u32 v0, v0, v38, s56
	v_and_b32_sdwa v38, v26, v170 dst_sel:DWORD dst_unused:UNUSED_PAD src0_sel:WORD_1 src1_sel:DWORD
	v_add3_u32 v27, v27, v37, s56
	v_lshlrev_b32_e32 v28, 16, v3
	v_and_b32_e32 v0, 0xffff0000, v0
	v_add3_u32 v26, v26, v38, s56
	v_and_b32_e32 v27, 0xffff0000, v27
	v_and_b32_e32 v3, 0xffff0000, v3
	v_and_b32_e32 v2, 0xffff0000, v2
	v_or_b32_sdwa v1, v27, v1 dst_sel:DWORD dst_unused:UNUSED_PAD src0_sel:DWORD src1_sel:WORD_1
	v_or_b32_sdwa v0, v26, v0 dst_sel:DWORD dst_unused:UNUSED_PAD src0_sel:WORD_1 src1_sel:DWORD
	v_pk_mov_b32 v[26:27], v[42:43], v[2:3] op_sel:[1,0]
	v_mov_b32_e32 v38, v45
	v_pk_fma_f32 v[26:27], v[20:21], v[26:27], v[14:15]
	v_mov_b32_e32 v39, v28
	v_pk_fma_f32 v[26:27], v[18:19], v[38:39], v[26:27]
	v_pk_fma_f32 v[38:39], v[20:21], v[38:39], v[14:15]
	v_pk_fma_f32 v[26:27], v[16:17], v[2:3], v[26:27]
	v_pk_fma_f32 v[2:3], v[18:19], v[2:3], v[38:39]
	v_cmp_lt_i32_e32 vcc, -1, v35
	v_pk_fma_f32 v[2:3], v[16:17], v[28:29], v[2:3]
	v_cvt_pk_bf16_f32 v3, v27, v3
	v_cvt_pk_bf16_f32 v2, v26, v2
	v_mad_u64_u32 v[26:27], s[0:1], v36, s23, v[24:25]
	ds_write_b128 v26, v[0:3]
	v_add_u32_e32 v0, 0x100, v35
	v_add_u32_e32 v25, 0x800, v25
	v_add_u32_e32 v24, 0x1000, v24
	s_or_b64 s[28:29], vcc, s[28:29]
	v_mov_b32_e32 v35, v0
	s_andn2_b64 exec, exec, s[28:29]
	s_cbranch_execz .LBB0_211

.LBB0_212:
	s_or_b64 exec, exec, s[40:41]
	s_waitcnt vmcnt(1)
	v_lshlrev_b32_e32 v40, 16, v0
	v_and_b32_e32 v44, 0xffff0000, v0
	s_waitcnt vmcnt(0)
	v_lshlrev_b32_e32 v27, 16, v27
	v_lshlrev_b32_e32 v39, 16, v1
	v_and_b32_e32 v43, 0xffff0000, v1
	v_and_b32_e32 v42, 16, v0
	v_mov_b32_e32 v0, v40
	v_mov_b32_e32 v1, v44
	v_cndmask_b32_e64 v29, v27, 0, vcc
	v_mov_b32_e32 v38, v44
	v_pk_fma_f32 v[0:1], v[14:15], v[0:1], v[20:21]
	v_mov_b32_e32 v27, v39
	v_mov_b32_e32 v41, v43
	v_mov_b32_e32 v46, v39
	v_mov_b32_e32 v47, v43
	v_pk_fma_f32 v[0:1], v[16:17], v[38:39], v[0:1]
	v_pk_fma_f32 v[26:27], v[14:15], v[26:27], v[20:21]
	v_lshlrev_b32_e32 v45, 16, v2
	v_pk_fma_f32 v[0:1], v[18:19], v[46:47], v[0:1]
	v_pk_fma_f32 v[26:27], v[16:17], v[40:41], v[26:27]
	v_and_b32_sdwa v37, v1, v170 dst_sel:DWORD dst_unused:UNUSED_PAD src0_sel:WORD_1 src1_sel:DWORD
	v_pk_fma_f32 v[26:27], v[18:19], v[44:45], v[26:27]
	v_and_b32_sdwa v38, v0, v170 dst_sel:DWORD dst_unused:UNUSED_PAD src0_sel:WORD_1 src1_sel:DWORD
	v_add3_u32 v1, v1, v37, s56
	v_and_b32_sdwa v37, v27, v170 dst_sel:DWORD dst_unused:UNUSED_PAD src0_sel:WORD_1 src1_sel:DWORD
	v_add3_u32 v0, v0, v38, s56
	v_and_b32_sdwa v38, v26, v170 dst_sel:DWORD dst_unused:UNUSED_PAD src0_sel:WORD_1 src1_sel:DWORD
	v_add3_u32 v27, v27, v37, s56
	v_lshlrev_b32_e32 v28, 16, v3
	v_and_b32_e32 v0, 0xffff0000, v0
	v_add3_u32 v26, v26, v38, s56
	v_and_b32_e32 v27, 0xffff0000, v27
	v_and_b32_e32 v3, 0xffff0000, v3
	v_and_b32_e32 v2, 0xffff0000, v2
	v_or_b32_sdwa v1, v27, v1 dst_sel:DWORD dst_unused:UNUSED_PAD src0_sel:DWORD src1_sel:WORD_1
	v_or_b32_sdwa v0, v26, v0 dst_sel:DWORD dst_unused:UNUSED_PAD src0_sel:WORD_1 src1_sel:DWORD
	v_pk_mov_b32 v[26:27], v[42:43], v[2:3] op_sel:[1,0]
	v_mov_b32_e32 v38, v45
	v_pk_fma_f32 v[26:27], v[14:15], v[26:27], v[20:21]
	v_mov_b32_e32 v39, v28
	v_pk_fma_f32 v[26:27], v[16:17], v[38:39], v[26:27]
	v_pk_fma_f32 v[38:39], v[14:15], v[38:39], v[20:21]
	v_pk_fma_f32 v[26:27], v[18:19], v[2:3], v[26:27]
	v_pk_fma_f32 v[2:3], v[16:17], v[2:3], v[38:39]
	v_cmp_lt_i32_e32 vcc, -1, v35
	v_pk_fma_f32 v[2:3], v[18:19], v[28:29], v[2:3]
	v_cvt_pk_bf16_f32 v3, v27, v3
	v_cvt_pk_bf16_f32 v2, v26, v2
	v_mad_u64_u32 v[26:27], s[0:1], v36, s23, v[24:25]
	ds_write_b128 v26, v[0:3]
	v_add_u32_e32 v0, 0x100, v35
	v_add_u32_e32 v25, 0x800, v25
	v_add_u32_e32 v24, 0x1000, v24
	s_or_b64 s[28:29], vcc, s[28:29]
	v_mov_b32_e32 v35, v0
	s_andn2_b64 exec, exec, s[28:29]
	s_cbranch_execz .LBB0_215

.LBB0_216:
	s_or_b64 exec, exec, s[40:41]
	s_waitcnt vmcnt(1)
	v_lshlrev_b32_e32 v28, 16, v0
	v_and_b32_e32 v38, 0xffff0000, v0
	s_waitcnt vmcnt(0)
	v_lshlrev_b32_e32 v23, 16, v23
	v_lshlrev_b32_e32 v27, 16, v1
	v_and_b32_e32 v37, 0xffff0000, v1
	v_and_b32_e32 v36, 16, v0
	v_mov_b32_e32 v0, v28
	v_mov_b32_e32 v1, v38
	v_cndmask_b32_e64 v25, v23, 0, vcc
	v_mov_b32_e32 v26, v38
	v_pk_fma_f32 v[0:1], v[14:15], v[0:1], v[4:5]
	v_mov_b32_e32 v23, v27
	v_mov_b32_e32 v29, v37
	v_mov_b32_e32 v40, v27
	v_mov_b32_e32 v41, v37
	v_pk_fma_f32 v[0:1], v[16:17], v[26:27], v[0:1]
	v_pk_fma_f32 v[22:23], v[14:15], v[22:23], v[4:5]
	v_lshlrev_b32_e32 v39, 16, v2
	v_pk_fma_f32 v[0:1], v[6:7], v[40:41], v[0:1]
	v_pk_fma_f32 v[22:23], v[16:17], v[28:29], v[22:23]
	v_and_b32_sdwa v26, v1, v170 dst_sel:DWORD dst_unused:UNUSED_PAD src0_sel:WORD_1 src1_sel:DWORD
	v_pk_fma_f32 v[22:23], v[6:7], v[38:39], v[22:23]
	v_and_b32_sdwa v27, v0, v170 dst_sel:DWORD dst_unused:UNUSED_PAD src0_sel:WORD_1 src1_sel:DWORD
	v_add3_u32 v1, v1, v26, s56
	v_and_b32_sdwa v26, v23, v170 dst_sel:DWORD dst_unused:UNUSED_PAD src0_sel:WORD_1 src1_sel:DWORD
	v_add3_u32 v0, v0, v27, s56
	v_and_b32_sdwa v27, v22, v170 dst_sel:DWORD dst_unused:UNUSED_PAD src0_sel:WORD_1 src1_sel:DWORD
	v_add3_u32 v23, v23, v26, s56
	v_lshlrev_b32_e32 v24, 16, v3
	v_and_b32_e32 v0, 0xffff0000, v0
	v_add3_u32 v22, v22, v27, s56
	v_and_b32_e32 v23, 0xffff0000, v23
	v_and_b32_e32 v3, 0xffff0000, v3
	v_and_b32_e32 v2, 0xffff0000, v2
	v_or_b32_sdwa v1, v23, v1 dst_sel:DWORD dst_unused:UNUSED_PAD src0_sel:DWORD src1_sel:WORD_1
	v_or_b32_sdwa v0, v22, v0 dst_sel:DWORD dst_unused:UNUSED_PAD src0_sel:WORD_1 src1_sel:DWORD
	v_pk_mov_b32 v[22:23], v[36:37], v[2:3] op_sel:[1,0]
	v_mov_b32_e32 v26, v39
	v_pk_fma_f32 v[22:23], v[14:15], v[22:23], v[4:5]
	v_mov_b32_e32 v27, v24
	v_pk_fma_f32 v[22:23], v[16:17], v[26:27], v[22:23]
	v_pk_fma_f32 v[26:27], v[14:15], v[26:27], v[4:5]
	v_pk_fma_f32 v[22:23], v[6:7], v[2:3], v[22:23]
	v_pk_fma_f32 v[2:3], v[16:17], v[2:3], v[26:27]
	v_cmp_lt_i32_e32 vcc, -1, v11
	v_pk_fma_f32 v[2:3], v[6:7], v[24:25], v[2:3]
	v_cvt_pk_bf16_f32 v3, v23, v3
	v_cvt_pk_bf16_f32 v2, v22, v2
	v_mad_u64_u32 v[22:23], s[0:1], v21, s23, v[20:21]
	ds_write_b128 v22, v[0:3]
	v_add_u32_e32 v0, 0x100, v11
	v_add_u32_e32 v9, 0x800, v9
	v_add_u32_e32 v20, 0x1000, v20
	s_or_b64 s[28:29], vcc, s[28:29]
	v_mov_b32_e32 v11, v0
	s_andn2_b64 exec, exec, s[28:29]
	s_cbranch_execz .LBB0_219

.LBB0_220:
	v_add_u32_e32 v16, s0, v18
	ds_read_b128 v[20:23], v16 offset:256
	ds_read_b128 v[36:39], v16
	v_add_u32_e32 v15, s0, v19
	ds_read_b128 v[24:27], v15
	s_addk_i32 s0, 0x80
	s_cmpk_eq_i32 s0, 0x900
	s_waitcnt lgkmcnt(0)
	v_mfma_f32_16x16x32_bf16 v[4:7], v[20:23], v[24:27], v[4:7]
	v_mfma_f32_16x16x32_bf16 v[0:3], v[36:39], v[24:27], v[0:3]
	ds_read_b128 v[20:23], v16 offset:320
	ds_read_b128 v[24:27], v16 offset:64
	ds_read_b128 v[36:39], v15 offset:64
	s_waitcnt lgkmcnt(0)
	v_mfma_f32_16x16x32_bf16 v[4:7], v[20:23], v[36:39], v[4:7]
	v_mfma_f32_16x16x32_bf16 v[0:3], v[24:27], v[36:39], v[0:3]
	s_cbranch_scc0 .LBB0_220
	v_and_b32_e32 v20, 0xffffff00, v10
	v_or_b32_e32 v15, 0x70, v20
	v_add_u32_e32 v22, 0, v14
	v_lshlrev_b32_e32 v21, 4, v11
	v_add_u32_e32 v14, s75, v8
	v_readlane_b32 s40, v250, 0
	v_sub_u32_e32 v23, v15, v21
	v_ashrrev_i32_e32 v15, 31, v14
	v_readlane_b32 s46, v250, 6
	v_readlane_b32 s47, v250, 7
	v_lshlrev_b32_e32 v24, 3, v9
	v_lshl_or_b32 v11, v23, 1, v24
	v_lshl_add_u64 v[14:15], v[14:15], 2, s[46:47]
	global_load_dword v16, v[14:15], off
	v_add_u32_e32 v11, v22, v11
	s_barrier
	ds_read2_b64 v[24:27], v11 offset0:32 offset1:64
	v_add_u32_e32 v28, 0x1000, v11
	ds_read2_b64 v[36:39], v28 offset0:164 offset1:196
	v_mov_b32_e32 v43, v6
	v_mov_b32_e32 v6, v5
	s_waitcnt lgkmcnt(1)
	v_lshlrev_b32_e32 v29, 16, v25
	v_lshlrev_b32_e32 v28, 16, v24
	v_and_b32_e32 v25, 0xffff0000, v25
	v_and_b32_e32 v24, 0xffff0000, v24
	s_waitcnt lgkmcnt(0)
	v_lshlrev_b32_e32 v41, 16, v37
	v_lshlrev_b32_e32 v40, 16, v36
	v_and_b32_e32 v37, 0xffff0000, v37
	v_and_b32_e32 v36, 0xffff0000, v36
	v_mov_b32_e32 v42, v4
	v_readlane_b32 s41, v250, 1
	v_readlane_b32 s42, v250, 2
	v_readlane_b32 s43, v250, 3
	v_readlane_b32 s44, v250, 4
	v_readlane_b32 s45, v250, 5
	s_waitcnt vmcnt(0)
	v_pk_fma_f32 v[4:5], v[16:17], v[24:25], v[6:7] op_sel_hi:[0,1,1]
	v_pk_fma_f32 v[28:29], v[16:17], v[28:29], v[42:43] op_sel_hi:[0,1,1]
	v_pk_mul_f32 v[4:5], v[4:5], v[36:37]
	v_pk_mul_f32 v[28:29], v[28:29], v[40:41]
	v_cvt_pk_bf16_f32 v5, v29, v5
	v_cvt_pk_bf16_f32 v4, v28, v4
	v_lshlrev_b32_e32 v7, 16, v27
	v_lshlrev_b32_e32 v6, 16, v26
	v_mov_b32_e32 v36, v0
	v_mov_b32_e32 v37, v2
	v_and_b32_e32 v25, 0xffff0000, v27
	v_and_b32_e32 v24, 0xffff0000, v26
	v_lshlrev_b32_e32 v27, 16, v39
	v_lshlrev_b32_e32 v26, 16, v38
	v_pk_fma_f32 v[6:7], v[16:17], v[6:7], v[36:37] op_sel_hi:[0,1,1]
	v_mov_b32_e32 v2, v1
	v_and_b32_e32 v29, 0xffff0000, v39
	v_and_b32_e32 v28, 0xffff0000, v38
	v_pk_mul_f32 v[6:7], v[6:7], v[26:27]
	v_pk_fma_f32 v[0:1], v[16:17], v[24:25], v[2:3] op_sel_hi:[0,1,1]
	v_pk_mul_f32 v[0:1], v[0:1], v[28:29]
	v_and_b32_sdwa v2, v7, v170 dst_sel:DWORD dst_unused:UNUSED_PAD src0_sel:WORD_1 src1_sel:DWORD
	v_and_b32_sdwa v3, v6, v170 dst_sel:DWORD dst_unused:UNUSED_PAD src0_sel:WORD_1 src1_sel:DWORD
	v_add3_u32 v3, v6, v3, s56
	v_add3_u32 v2, v7, v2, s56
	v_and_b32_sdwa v6, v1, v170 dst_sel:DWORD dst_unused:UNUSED_PAD src0_sel:WORD_1 src1_sel:DWORD
	v_and_b32_sdwa v7, v0, v170 dst_sel:DWORD dst_unused:UNUSED_PAD src0_sel:WORD_1 src1_sel:DWORD
	v_add3_u32 v1, v1, v6, s56
	v_add3_u32 v0, v0, v7, s56
	v_and_b32_e32 v1, 0xffff0000, v1
	v_and_b32_e32 v0, 0xffff0000, v0
	v_or_b32_sdwa v1, v1, v2 dst_sel:DWORD dst_unused:UNUSED_PAD src0_sel:DWORD src1_sel:WORD_1
	v_or_b32_sdwa v0, v0, v3 dst_sel:DWORD dst_unused:UNUSED_PAD src0_sel:DWORD src1_sel:WORD_1
	ds_write2_b64 v11, v[4:5], v[0:1] offset0:32 offset1:64
	s_and_saveexec_b64 s[0:1], s[36:37]
	s_cbranch_execz .LBB0_224
	v_readlane_b32 s16, v255, 8
	s_mov_b64 s[24:25], 0x400000
	v_lshl_add_u64 v[2:3], v[12:13], 0, s[24:25]
	v_add_u32_e32 v0, s16, v8
	v_readlane_b32 s16, v251, 36
	v_ashrrev_i32_e32 v1, 31, v0
	v_readlane_b32 s17, v251, 37
	s_mov_b64 s[24:25], 0
	s_nop 0
	v_lshl_add_u64 v[0:1], v[0:1], 2, s[16:17]
	global_load_dword v0, v[0:1], off
	s_waitcnt vmcnt(0)
	v_mov_b32_e32 v1, v0
	v_mov_b32_e32 v4, v0
	v_mov_b32_e32 v5, v0

.LBB0_228:
	v_add_u32_e32 v32, s0, v18
	ds_read_b128 v[10:13], v32 offset:256
	ds_read_b128 v[28:31], v32
	v_add_u32_e32 v16, s0, v19
	ds_read_b128 v[24:27], v16
	s_addk_i32 s0, 0x80
	s_cmpk_lg_i32 s0, 0x900
	s_waitcnt lgkmcnt(0)
	v_mfma_f32_16x16x32_bf16 v[4:7], v[10:13], v[24:27], v[4:7]
	v_mfma_f32_16x16x32_bf16 v[0:3], v[28:31], v[24:27], v[0:3]
	ds_read_b128 v[10:13], v32 offset:320
	ds_read_b128 v[24:27], v32 offset:64
	ds_read_b128 v[28:31], v16 offset:64
	s_waitcnt lgkmcnt(0)
	v_mfma_f32_16x16x32_bf16 v[4:7], v[10:13], v[28:31], v[4:7]
	v_mfma_f32_16x16x32_bf16 v[0:3], v[24:27], v[28:31], v[0:3]
	s_cbranch_scc1 .LBB0_228
	global_load_dword v18, v[14:15], off offset:2048
	v_mov_b64_e32 v[10:11], s[86:87]
	s_movk_i32 s0, 0x5000
	v_mad_i64_i32 v[10:11], s[0:1], v8, s0, v[10:11]
	v_lshlrev_b32_e32 v128, 11, v17
	v_lshl_add_u64 v[10:11], v[10:11], 0, v[128:129]
	v_lshlrev_b32_e32 v128, 2, v9
	v_or_b32_e32 v8, v23, v128
	v_lshl_add_u32 v14, v8, 1, v22
	v_ashrrev_i32_e32 v9, 31, v20
	v_sub_co_u32_e32 v8, vcc, v20, v21
	v_mov_b32_e32 v25, v6
	s_nop 0
	v_subbrev_co_u32_e32 v9, vcc, 0, v9, vcc
	v_lshl_add_u64 v[8:9], v[8:9], 0, v[128:129]
	v_lshl_add_u64 v[8:9], v[8:9], 1, v[10:11]
	ds_read2_b64 v[10:13], v14 offset0:32 offset1:64
	v_add_u32_e32 v14, 0x2800, v14
	ds_read2_b64 v[14:17], v14 offset0:40 offset1:72
	v_mov_b32_e32 v6, v5
	v_mov_b32_e32 v24, v4
	s_waitcnt lgkmcnt(1)
	v_lshlrev_b32_e32 v21, 16, v11
	v_lshlrev_b32_e32 v20, 16, v10
	v_and_b32_e32 v11, 0xffff0000, v11
	v_and_b32_e32 v10, 0xffff0000, v10
	s_waitcnt lgkmcnt(0)
	v_lshlrev_b32_e32 v23, 16, v15
	v_lshlrev_b32_e32 v22, 16, v14
	v_and_b32_e32 v15, 0xffff0000, v15
	v_and_b32_e32 v14, 0xffff0000, v14
	s_mov_b64 s[0:1], 0x9a7e000
	v_lshl_add_u64 v[8:9], v[8:9], 0, s[0:1]
	s_mov_b64 s[0:1], 0x1e0
	s_waitcnt vmcnt(0)
	v_pk_fma_f32 v[4:5], v[18:19], v[10:11], v[6:7] op_sel_hi:[0,1,1]
	v_pk_fma_f32 v[20:21], v[18:19], v[20:21], v[24:25] op_sel_hi:[0,1,1]
	v_pk_mul_f32 v[4:5], v[4:5], v[14:15]
	v_pk_mul_f32 v[20:21], v[20:21], v[22:23]
	v_and_b32_sdwa v10, v5, v170 dst_sel:DWORD dst_unused:UNUSED_PAD src0_sel:WORD_1 src1_sel:DWORD
	v_and_b32_sdwa v6, v21, v170 dst_sel:DWORD dst_unused:UNUSED_PAD src0_sel:WORD_1 src1_sel:DWORD
	v_add3_u32 v5, v5, v10, s56
	v_add3_u32 v6, v21, v6, s56
	v_and_b32_e32 v5, 0xffff0000, v5
	v_lshlrev_b32_e32 v10, 16, v12
	v_or_b32_sdwa v5, v5, v6 dst_sel:DWORD dst_unused:UNUSED_PAD src0_sel:DWORD src1_sel:WORD_1
	v_cvt_pk_bf16_f32 v4, v20, v4
	v_and_b32_e32 v11, 0xffff0000, v12
	v_lshlrev_b32_e32 v12, 16, v16
	v_fma_f32 v0, v18, v10, v0
	global_store_dwordx2 v[8:9], v[4:5], off offset:224
	v_lshlrev_b32_e32 v4, 16, v13
	v_and_b32_e32 v5, 0xffff0000, v13
	v_and_b32_e32 v13, 0xffff0000, v16
	v_mul_f32_e32 v0, v0, v12
	v_fma_f32 v1, v18, v11, v1
	v_mul_f32_e32 v1, v1, v13
	v_bfe_u32 v10, v0, 16, 1
	v_add3_u32 v0, v0, v10, s56
	v_bfe_u32 v10, v1, 16, 1
	v_lshrrev_b32_e32 v0, 16, v0
	v_add3_u32 v1, v1, v10, s56
	v_lshlrev_b32_e32 v6, 16, v17
	v_and_b32_e32 v7, 0xffff0000, v17
	v_and_or_b32 v10, v1, s5, v0
	v_pk_fma_f32 v[0:1], v[18:19], v[4:5], v[2:3] op_sel_hi:[0,1,1]
	v_pk_mul_f32 v[0:1], v[0:1], v[6:7]
	global_store_dword v[8:9], v10, off offset:480
	v_and_b32_sdwa v3, v0, v170 dst_sel:DWORD dst_unused:UNUSED_PAD src0_sel:WORD_1 src1_sel:DWORD
	v_and_b32_sdwa v2, v1, v170 dst_sel:DWORD dst_unused:UNUSED_PAD src0_sel:WORD_1 src1_sel:DWORD
	v_add3_u32 v0, v0, v3, s56
	v_add3_u32 v1, v1, v2, s56
	v_lshrrev_b32_e32 v0, 16, v0
	v_and_or_b32 v2, v1, s5, v0
	v_lshl_add_u64 v[0:1], v[8:9], 0, s[0:1]
	s_branch .LBB0_157

.LBB0_253:
	s_nop 0
	s_and_b64 vcc, exec, s[36:37]
	v_pk_fma_f32 v[34:35], v[34:35], v[134:135], v[220:221]
	v_pk_fma_f32 v[32:33], v[32:33], v[132:133], v[218:219]
	global_store_dwordx4 v[50:51], v[32:35], off offset:192
	s_cbranch_vccnz .LBB0_255
	v_lshl_add_u64 v[50:51], v[56:57], 0, v[66:67]
	v_lshl_add_u64 v[50:51], v[64:65], 1, v[52:53]
	v_pk_mul_f32 v[52:53], v[34:35], v[150:151]
	v_pk_mul_f32 v[58:59], v[32:33], v[148:149]
	v_pk_add_f32 v[56:57], v[182:183], 1.0 op_sel_hi:[1,0]
	v_pk_add_f32 v[54:55], v[180:181], 1.0 op_sel_hi:[1,0]
	v_pk_mul_f32 v[52:53], v[52:53], v[56:57]
	v_pk_mul_f32 v[54:55], v[58:59], v[54:55]
	v_cvt_pk_bf16_f32 v53, v52, v53
	v_cvt_pk_bf16_f32 v52, v54, v55
	global_store_dwordx2 v[50:51], v[52:53], off offset:96

.LBB0_263:
	s_nop 0
	s_and_b64 vcc, exec, s[36:37]
	v_pk_fma_f32 v[18:19], v[18:19], v[134:135], v[204:205]
	v_pk_fma_f32 v[16:17], v[16:17], v[132:133], v[202:203]
	global_store_dwordx4 v[32:33], v[16:19], off offset:192
	s_cbranch_vccnz .LBB0_265
	v_lshl_add_u64 v[32:33], v[38:39], 0, v[66:67]
	v_lshl_add_u64 v[32:33], v[64:65], 1, v[34:35]
	v_pk_mul_f32 v[34:35], v[18:19], v[150:151]
	v_pk_mul_f32 v[40:41], v[16:17], v[148:149]
	v_pk_add_f32 v[38:39], v[182:183], 1.0 op_sel_hi:[1,0]
	v_pk_add_f32 v[36:37], v[180:181], 1.0 op_sel_hi:[1,0]
	v_pk_mul_f32 v[34:35], v[34:35], v[38:39]
	v_pk_mul_f32 v[36:37], v[40:41], v[36:37]
	v_cvt_pk_bf16_f32 v35, v34, v35
	v_cvt_pk_bf16_f32 v34, v36, v37
	global_store_dwordx2 v[32:33], v[34:35], off offset:96

.LBB0_273:
	s_nop 0
	s_and_b64 vcc, exec, s[36:37]
	v_pk_fma_f32 v[2:3], v[2:3], v[134:135], v[220:221]
	v_pk_fma_f32 v[0:1], v[0:1], v[132:133], v[218:219]
	global_store_dwordx4 v[16:17], v[0:3], off offset:192
	s_cbranch_vccnz .LBB0_275
	v_lshl_add_u64 v[16:17], v[22:23], 0, v[66:67]
	v_lshl_add_u64 v[16:17], v[64:65], 1, v[18:19]
	v_pk_mul_f32 v[18:19], v[2:3], v[150:151]
	v_pk_mul_f32 v[24:25], v[0:1], v[148:149]
	v_pk_add_f32 v[22:23], v[182:183], 1.0 op_sel_hi:[1,0]
	v_pk_add_f32 v[20:21], v[180:181], 1.0 op_sel_hi:[1,0]
	v_pk_mul_f32 v[18:19], v[18:19], v[22:23]
	v_pk_mul_f32 v[20:21], v[24:25], v[20:21]
	v_cvt_pk_bf16_f32 v19, v18, v19
	v_cvt_pk_bf16_f32 v18, v20, v21
	global_store_dwordx2 v[16:17], v[18:19], off offset:96

.LBB0_299:
	global_load_dwordx4 v[58:61], v[54:55], off offset:192
	s_nop 0
	global_load_dwordx4 v[72:75], v[50:51], off offset:192
	s_and_b64 vcc, exec, s[36:37]
	s_waitcnt vmcnt(0)
	v_pk_fma_f32 v[34:35], v[34:35], v[60:61], v[74:75]
	v_pk_fma_f32 v[32:33], v[32:33], v[58:59], v[72:73]
	global_store_dwordx4 v[50:51], v[32:35], off offset:192
	s_cbranch_vccnz .LBB0_301
	v_lshl_add_u64 v[50:51], v[56:57], 0, v[66:67]
	global_load_dwordx4 v[58:61], v[68:69], off offset:192
	global_load_dwordx4 v[54:57], v[50:51], off offset:192
	v_lshl_add_u64 v[50:51], v[64:65], 1, v[52:53]
	s_waitcnt vmcnt(1)
	v_pk_mul_f32 v[52:53], v[34:35], v[60:61]
	v_pk_mul_f32 v[58:59], v[32:33], v[58:59]
	s_waitcnt vmcnt(0)
	v_pk_add_f32 v[56:57], v[56:57], 1.0 op_sel_hi:[1,0]
	v_pk_add_f32 v[54:55], v[54:55], 1.0 op_sel_hi:[1,0]
	v_pk_mul_f32 v[52:53], v[52:53], v[56:57]
	v_pk_mul_f32 v[54:55], v[58:59], v[54:55]
	v_cvt_pk_bf16_f32 v53, v52, v53
	v_cvt_pk_bf16_f32 v52, v54, v55
	global_store_dwordx2 v[50:51], v[52:53], off offset:96

.LBB0_309:
	global_load_dwordx4 v[40:43], v[36:37], off offset:192
	s_nop 0
	global_load_dwordx4 v[44:47], v[32:33], off offset:192
	s_and_b64 vcc, exec, s[36:37]
	s_waitcnt vmcnt(0)
	v_pk_fma_f32 v[18:19], v[18:19], v[42:43], v[46:47]
	v_pk_fma_f32 v[16:17], v[16:17], v[40:41], v[44:45]
	global_store_dwordx4 v[32:33], v[16:19], off offset:192
	s_cbranch_vccnz .LBB0_311
	v_lshl_add_u64 v[32:33], v[38:39], 0, v[66:67]
	global_load_dwordx4 v[40:43], v[68:69], off offset:192
	global_load_dwordx4 v[36:39], v[32:33], off offset:192
	v_lshl_add_u64 v[32:33], v[64:65], 1, v[34:35]
	s_waitcnt vmcnt(1)
	v_pk_mul_f32 v[34:35], v[18:19], v[42:43]
	v_pk_mul_f32 v[40:41], v[16:17], v[40:41]
	s_waitcnt vmcnt(0)
	v_pk_add_f32 v[38:39], v[38:39], 1.0 op_sel_hi:[1,0]
	v_pk_add_f32 v[36:37], v[36:37], 1.0 op_sel_hi:[1,0]
	v_pk_mul_f32 v[34:35], v[34:35], v[38:39]
	v_pk_mul_f32 v[36:37], v[40:41], v[36:37]
	v_cvt_pk_bf16_f32 v35, v34, v35
	v_cvt_pk_bf16_f32 v34, v36, v37
	global_store_dwordx2 v[32:33], v[34:35], off offset:96

.LBB0_319:
	global_load_dwordx4 v[24:27], v[20:21], off offset:192
	s_nop 0
	global_load_dwordx4 v[28:31], v[16:17], off offset:192
	s_and_b64 vcc, exec, s[36:37]
	s_waitcnt vmcnt(0)
	v_pk_fma_f32 v[2:3], v[2:3], v[26:27], v[30:31]
	v_pk_fma_f32 v[0:1], v[0:1], v[24:25], v[28:29]
	global_store_dwordx4 v[16:17], v[0:3], off offset:192
	s_cbranch_vccnz .LBB0_321
	v_lshl_add_u64 v[16:17], v[22:23], 0, v[66:67]
	global_load_dwordx4 v[24:27], v[68:69], off offset:192
	global_load_dwordx4 v[20:23], v[16:17], off offset:192
	v_lshl_add_u64 v[16:17], v[64:65], 1, v[18:19]
	s_waitcnt vmcnt(1)
	v_pk_mul_f32 v[18:19], v[2:3], v[26:27]
	v_pk_mul_f32 v[24:25], v[0:1], v[24:25]
	s_waitcnt vmcnt(0)
	v_pk_add_f32 v[22:23], v[22:23], 1.0 op_sel_hi:[1,0]
	v_pk_add_f32 v[20:21], v[20:21], 1.0 op_sel_hi:[1,0]
	v_pk_mul_f32 v[18:19], v[18:19], v[22:23]
	v_pk_mul_f32 v[20:21], v[24:25], v[20:21]
	v_cvt_pk_bf16_f32 v19, v18, v19
	v_cvt_pk_bf16_f32 v18, v20, v21
	global_store_dwordx2 v[16:17], v[18:19], off offset:96

.LBB0_382:
	s_or_b64 exec, exec, s[24:25]
	v_add_u32_e32 v66, s2, v142
	v_lshlrev_b32_e32 v65, 2, v66
	v_and_b32_e32 v65, 0xfffff000, v65
	v_or_b32_e32 v64, s29, v147
	v_add_u32_e32 v65, 0xffff9000, v65
	v_cmp_lt_i32_e32 vcc, s13, v66
	s_waitcnt lgkmcnt(0)
	s_barrier
	v_cndmask_b32_e32 v128, 0, v65, vcc
	v_ashrrev_i32_e32 v65, 31, v64
	v_lshl_add_u64 v[68:69], v[128:129], 2, s[0:1]
	s_waitcnt vmcnt(6)
	v_lshlrev_b64 v[100:101], 2, v[64:65]
	s_waitcnt vmcnt(3)
	v_lshl_add_u64 v[110:111], v[68:69], 0, v[100:101]
	global_load_dwordx4 v[96:99], v[110:111], off
	v_readlane_b32 s3, v250, 8
	s_add_i32 s3, s28, s3
	s_cmpk_lt_i32 s3, 0xa00
	s_cselect_b32 s24, s3, s28
	s_ashr_i32 s25, s24, 31
	s_lshr_b32 s25, s25, 25
	s_add_i32 s25, s24, s25
	v_ashrrev_i32_e32 v67, 31, v66
	s_ashr_i32 s28, s25, 7
	s_and_b32 s25, s25, 0xffffff80
	v_lshlrev_b64 v[66:67], 13, v[66:67]
	s_sub_i32 s24, s24, s25
	v_lshlrev_b64 v[108:109], 1, v[64:65]
	v_lshl_add_u64 v[64:65], s[30:31], 0, v[66:67]
	s_lshl_b32 s25, s28, 2
	s_and_b32 s28, s24, 3
	s_ashr_i32 s24, s24, 2
	v_lshl_add_u64 v[114:115], v[64:65], 0, v[108:109]
	v_lshl_add_u32 v64, s24, 7, v130
	v_ashrrev_i32_e32 v65, 31, v64
	v_lshlrev_b64 v[64:65], 11, v[64:65]
	v_lshl_add_u64 v[64:65], v[136:137], 0, v[64:65]
	v_add_co_u32_e32 v84, vcc, s11, v64
	s_or_b32 s25, s28, s25
	s_nop 0
	v_addc_co_u32_e32 v85, vcc, 0, v65, vcc
	v_lshl_add_u32 v66, s25, 7, v130
	v_add_co_u32_e32 v72, vcc, s33, v64
	ds_read_b32 v106, v148
	ds_read_b32 v112, v150
	ds_read_b32 v102, v152
	ds_read_b32 v104, v154
	v_ashrrev_i32_e32 v67, 31, v66
	v_addc_co_u32_e32 v73, vcc, 0, v65, vcc
	v_lshlrev_b64 v[66:67], 11, v[66:67]
	v_add_co_u32_e32 v74, vcc, s59, v64
	v_lshl_add_u64 v[66:67], v[134:135], 0, v[66:67]
	s_nop 0
	v_addc_co_u32_e32 v75, vcc, 0, v65, vcc
	v_add_co_u32_e32 v80, vcc, s11, v66
	s_cmpk_gt_i32 s3, 0x9ff
	s_nop 0
	v_addc_co_u32_e32 v81, vcc, 0, v67, vcc
	v_add_co_u32_e32 v82, vcc, s33, v66
	s_mov_b32 s28, s3
	s_nop 0
	v_addc_co_u32_e32 v83, vcc, 0, v67, vcc
	v_add_co_u32_e32 v86, vcc, s59, v66
	s_waitcnt vmcnt(0) lgkmcnt(3)
	v_pk_fma_f32 v[62:63], v[62:63], v[106:107], v[98:99] op_sel_hi:[1,0,1]
	v_pk_fma_f32 v[60:61], v[60:61], v[106:107], v[96:97] op_sel_hi:[1,0,1]
	v_max_f32_e32 v97, 0, v63
	v_max_f32_e32 v96, 0, v61
	v_max_f32_e32 v60, 0, v60
	v_max_f32_e32 v61, 0, v62
	v_pk_mul_f32 v[62:63], v[96:97], v[96:97]
	v_pk_mul_f32 v[60:61], v[60:61], v[60:61]
	v_addc_co_u32_e32 v87, vcc, 0, v67, vcc
	v_cvt_pk_bf16_f32 v61, v61, v63
	v_cvt_pk_bf16_f32 v60, v60, v62
	global_load_dwordx4 v[68:71], v[66:67], off
	global_load_dwordx4 v[76:79], v[64:65], off
	global_load_dwordx4 v[88:91], v[72:73], off
	global_load_dwordx4 v[92:95], v[74:75], off
	s_nop 0
	global_load_dwordx4 v[64:67], v[80:81], off
	global_load_dwordx4 v[72:75], v[82:83], off
	s_nop 0
	global_load_dwordx4 v[80:83], v[86:87], off
	s_nop 0
	global_load_dwordx4 v[84:87], v[84:85], off
	s_nop 0
	global_store_dwordx2 v[114:115], v[60:61], off
	global_load_dwordx4 v[60:63], v[110:111], off offset:64
	s_waitcnt vmcnt(0)
	v_pk_fma_f32 v[58:59], v[58:59], v[106:107], v[62:63] op_sel_hi:[1,0,1]
	v_pk_fma_f32 v[56:57], v[56:57], v[106:107], v[60:61] op_sel_hi:[1,0,1]
	v_max_f32_e32 v61, 0, v59
	v_max_f32_e32 v60, 0, v57
	v_max_f32_e32 v56, 0, v56
	v_max_f32_e32 v57, 0, v58
	v_pk_mul_f32 v[58:59], v[60:61], v[60:61]
	v_pk_mul_f32 v[56:57], v[56:57], v[56:57]
	v_cvt_pk_bf16_f32 v57, v57, v59
	v_cvt_pk_bf16_f32 v56, v56, v58
	global_store_dwordx2 v[114:115], v[56:57], off offset:32
	global_load_dwordx4 v[56:59], v[110:111], off offset:128
	s_waitcnt vmcnt(0)
	v_pk_fma_f32 v[54:55], v[54:55], v[106:107], v[58:59] op_sel_hi:[1,0,1]
	v_pk_fma_f32 v[52:53], v[52:53], v[106:107], v[56:57] op_sel_hi:[1,0,1]
	v_max_f32_e32 v57, 0, v55
	v_max_f32_e32 v56, 0, v53
	v_max_f32_e32 v52, 0, v52
	v_max_f32_e32 v53, 0, v54
	v_pk_mul_f32 v[54:55], v[56:57], v[56:57]
	v_pk_mul_f32 v[52:53], v[52:53], v[52:53]
	v_cvt_pk_bf16_f32 v53, v53, v55
	v_cvt_pk_bf16_f32 v52, v52, v54
	global_store_dwordx2 v[114:115], v[52:53], off offset:64
	global_load_dwordx4 v[52:55], v[110:111], off offset:192
	v_add_u32_e32 v56, s2, v149
	v_lshlrev_b32_e32 v57, 2, v56
	v_and_b32_e32 v57, 0xfffff000, v57
	v_add_u32_e32 v57, 0xffff9000, v57
	v_cmp_lt_i32_e32 vcc, s13, v56
	s_waitcnt vmcnt(0)
	v_pk_fma_f32 v[50:51], v[50:51], v[106:107], v[54:55] op_sel_hi:[1,0,1]
	v_pk_fma_f32 v[48:49], v[48:49], v[106:107], v[52:53] op_sel_hi:[1,0,1]
	v_max_f32_e32 v53, 0, v51
	v_max_f32_e32 v52, 0, v49
	v_max_f32_e32 v48, 0, v48
	v_max_f32_e32 v49, 0, v50
	v_pk_mul_f32 v[50:51], v[52:53], v[52:53]
	v_pk_mul_f32 v[48:49], v[48:49], v[48:49]
	v_cndmask_b32_e32 v128, 0, v57, vcc
	v_lshl_add_u64 v[58:59], v[128:129], 2, s[0:1]
	v_cvt_pk_bf16_f32 v49, v49, v51
	v_cvt_pk_bf16_f32 v48, v48, v50
	v_lshl_add_u64 v[58:59], v[58:59], 0, v[100:101]
	global_store_dwordx2 v[114:115], v[48:49], off offset:96
	global_load_dwordx4 v[48:51], v[58:59], off
	v_ashrrev_i32_e32 v57, 31, v56
	v_lshlrev_b64 v[52:53], 13, v[56:57]
	v_lshl_add_u64 v[52:53], s[30:31], 0, v[52:53]
	v_lshl_add_u64 v[52:53], v[52:53], 0, v[108:109]
	s_waitcnt vmcnt(0) lgkmcnt(2)
	v_pk_fma_f32 v[46:47], v[46:47], v[112:113], v[50:51] op_sel_hi:[1,0,1]
	v_pk_fma_f32 v[44:45], v[44:45], v[112:113], v[48:49] op_sel_hi:[1,0,1]
	v_max_f32_e32 v49, 0, v47
	v_max_f32_e32 v48, 0, v45
	v_max_f32_e32 v44, 0, v44
	v_max_f32_e32 v45, 0, v46
	v_pk_mul_f32 v[46:47], v[48:49], v[48:49]
	v_pk_mul_f32 v[44:45], v[44:45], v[44:45]
	v_cvt_pk_bf16_f32 v45, v45, v47
	v_cvt_pk_bf16_f32 v44, v44, v46
	global_store_dwordx2 v[52:53], v[44:45], off
	global_load_dwordx4 v[44:47], v[58:59], off offset:64
	s_waitcnt vmcnt(0)
	v_pk_fma_f32 v[42:43], v[42:43], v[112:113], v[46:47] op_sel_hi:[1,0,1]
	v_pk_fma_f32 v[40:41], v[40:41], v[112:113], v[44:45] op_sel_hi:[1,0,1]
	v_max_f32_e32 v45, 0, v43
	v_max_f32_e32 v44, 0, v41
	v_max_f32_e32 v40, 0, v40
	v_max_f32_e32 v41, 0, v42
	v_pk_mul_f32 v[42:43], v[44:45], v[44:45]
	v_pk_mul_f32 v[40:41], v[40:41], v[40:41]
	v_cvt_pk_bf16_f32 v41, v41, v43
	v_cvt_pk_bf16_f32 v40, v40, v42
	global_store_dwordx2 v[52:53], v[40:41], off offset:32
	global_load_dwordx4 v[40:43], v[58:59], off offset:128
	s_waitcnt vmcnt(0)
	v_pk_fma_f32 v[38:39], v[38:39], v[112:113], v[42:43] op_sel_hi:[1,0,1]
	v_pk_fma_f32 v[36:37], v[36:37], v[112:113], v[40:41] op_sel_hi:[1,0,1]
	v_max_f32_e32 v41, 0, v39
	v_max_f32_e32 v40, 0, v37
	v_max_f32_e32 v36, 0, v36
	v_max_f32_e32 v37, 0, v38
	v_pk_mul_f32 v[38:39], v[40:41], v[40:41]
	v_pk_mul_f32 v[36:37], v[36:37], v[36:37]
	v_cvt_pk_bf16_f32 v37, v37, v39
	v_cvt_pk_bf16_f32 v36, v36, v38
	global_store_dwordx2 v[52:53], v[36:37], off offset:64
	global_load_dwordx4 v[36:39], v[58:59], off offset:192
	v_add_u32_e32 v40, s2, v151
	v_lshlrev_b32_e32 v41, 2, v40
	v_and_b32_e32 v41, 0xfffff000, v41
	v_add_u32_e32 v41, 0xffff9000, v41
	v_cmp_lt_i32_e32 vcc, s13, v40
	s_waitcnt vmcnt(0)
	v_pk_fma_f32 v[34:35], v[34:35], v[112:113], v[38:39] op_sel_hi:[1,0,1]
	v_pk_fma_f32 v[32:33], v[32:33], v[112:113], v[36:37] op_sel_hi:[1,0,1]
	v_max_f32_e32 v37, 0, v35
	v_max_f32_e32 v36, 0, v33
	v_max_f32_e32 v32, 0, v32
	v_max_f32_e32 v33, 0, v34
	v_pk_mul_f32 v[34:35], v[36:37], v[36:37]
	v_pk_mul_f32 v[32:33], v[32:33], v[32:33]
	v_cndmask_b32_e32 v128, 0, v41, vcc
	v_lshl_add_u64 v[42:43], v[128:129], 2, s[0:1]
	v_cvt_pk_bf16_f32 v33, v33, v35
	v_cvt_pk_bf16_f32 v32, v32, v34
	v_lshl_add_u64 v[42:43], v[42:43], 0, v[100:101]
	global_store_dwordx2 v[52:53], v[32:33], off offset:96
	global_load_dwordx4 v[34:37], v[42:43], off
	v_ashrrev_i32_e32 v41, 31, v40
	v_lshlrev_b64 v[32:33], 13, v[40:41]
	v_lshl_add_u64 v[32:33], s[30:31], 0, v[32:33]
	v_lshl_add_u64 v[32:33], v[32:33], 0, v[108:109]
	s_waitcnt vmcnt(0) lgkmcnt(1)
	v_pk_fma_f32 v[30:31], v[30:31], v[102:103], v[36:37] op_sel_hi:[1,0,1]
	v_pk_fma_f32 v[28:29], v[28:29], v[102:103], v[34:35] op_sel_hi:[1,0,1]
	v_max_f32_e32 v35, 0, v31
	v_max_f32_e32 v34, 0, v29
	v_max_f32_e32 v28, 0, v28
	v_max_f32_e32 v29, 0, v30
	v_pk_mul_f32 v[30:31], v[34:35], v[34:35]
	v_pk_mul_f32 v[28:29], v[28:29], v[28:29]
	v_cvt_pk_bf16_f32 v29, v29, v31
	v_cvt_pk_bf16_f32 v28, v28, v30
	global_store_dwordx2 v[32:33], v[28:29], off
	global_load_dwordx4 v[28:31], v[42:43], off offset:64
	s_waitcnt vmcnt(0)
	v_pk_fma_f32 v[26:27], v[26:27], v[102:103], v[30:31] op_sel_hi:[1,0,1]
	v_pk_fma_f32 v[24:25], v[24:25], v[102:103], v[28:29] op_sel_hi:[1,0,1]
	v_max_f32_e32 v29, 0, v27
	v_max_f32_e32 v28, 0, v25
	v_max_f32_e32 v24, 0, v24
	v_max_f32_e32 v25, 0, v26
	v_pk_mul_f32 v[26:27], v[28:29], v[28:29]
	v_pk_mul_f32 v[24:25], v[24:25], v[24:25]
	v_cvt_pk_bf16_f32 v25, v25, v27
	v_cvt_pk_bf16_f32 v24, v24, v26
	global_store_dwordx2 v[32:33], v[24:25], off offset:32
	global_load_dwordx4 v[24:27], v[42:43], off offset:128
	s_waitcnt vmcnt(0)
	v_pk_fma_f32 v[22:23], v[22:23], v[102:103], v[26:27] op_sel_hi:[1,0,1]
	v_pk_fma_f32 v[20:21], v[20:21], v[102:103], v[24:25] op_sel_hi:[1,0,1]
	v_max_f32_e32 v25, 0, v23
	v_max_f32_e32 v24, 0, v21
	v_max_f32_e32 v20, 0, v20
	v_max_f32_e32 v21, 0, v22
	v_pk_mul_f32 v[22:23], v[24:25], v[24:25]
	v_pk_mul_f32 v[20:21], v[20:21], v[20:21]
	v_cvt_pk_bf16_f32 v21, v21, v23
	v_cvt_pk_bf16_f32 v20, v20, v22
	global_store_dwordx2 v[32:33], v[20:21], off offset:64
	global_load_dwordx4 v[20:23], v[42:43], off offset:192
	v_add_u32_e32 v24, s2, v153
	v_lshlrev_b32_e32 v25, 2, v24
	v_and_b32_e32 v25, 0xfffff000, v25
	v_add_u32_e32 v25, 0xffff9000, v25
	v_cmp_lt_i32_e32 vcc, s13, v24
	s_waitcnt vmcnt(0)
	v_pk_fma_f32 v[18:19], v[18:19], v[102:103], v[22:23] op_sel_hi:[1,0,1]
	v_pk_fma_f32 v[16:17], v[16:17], v[102:103], v[20:21] op_sel_hi:[1,0,1]
	v_max_f32_e32 v21, 0, v19
	v_max_f32_e32 v20, 0, v17
	v_max_f32_e32 v16, 0, v16
	v_max_f32_e32 v17, 0, v18
	v_pk_mul_f32 v[18:19], v[20:21], v[20:21]
	v_pk_mul_f32 v[16:17], v[16:17], v[16:17]
	v_cndmask_b32_e32 v128, 0, v25, vcc
	v_lshl_add_u64 v[26:27], v[128:129], 2, s[0:1]
	v_cvt_pk_bf16_f32 v17, v17, v19
	v_cvt_pk_bf16_f32 v16, v16, v18
	v_lshl_add_u64 v[26:27], v[26:27], 0, v[100:101]
	global_store_dwordx2 v[32:33], v[16:17], off offset:96
	global_load_dwordx4 v[16:19], v[26:27], off
	v_ashrrev_i32_e32 v25, 31, v24
	v_lshlrev_b64 v[20:21], 13, v[24:25]
	v_lshl_add_u64 v[20:21], s[30:31], 0, v[20:21]
	v_lshl_add_u64 v[20:21], v[20:21], 0, v[108:109]
	s_waitcnt vmcnt(0) lgkmcnt(0)
	v_pk_fma_f32 v[14:15], v[14:15], v[104:105], v[18:19] op_sel_hi:[1,0,1]
	v_pk_fma_f32 v[12:13], v[12:13], v[104:105], v[16:17] op_sel_hi:[1,0,1]
	v_max_f32_e32 v17, 0, v15
	v_max_f32_e32 v16, 0, v13
	v_max_f32_e32 v12, 0, v12
	v_max_f32_e32 v13, 0, v14
	v_pk_mul_f32 v[14:15], v[16:17], v[16:17]
	v_pk_mul_f32 v[12:13], v[12:13], v[12:13]
	v_cvt_pk_bf16_f32 v13, v13, v15
	v_cvt_pk_bf16_f32 v12, v12, v14
	global_store_dwordx2 v[20:21], v[12:13], off
	global_load_dwordx4 v[12:15], v[26:27], off offset:64
	s_waitcnt vmcnt(0)
	v_pk_fma_f32 v[10:11], v[10:11], v[104:105], v[14:15] op_sel_hi:[1,0,1]
	v_pk_fma_f32 v[8:9], v[8:9], v[104:105], v[12:13] op_sel_hi:[1,0,1]
	v_max_f32_e32 v13, 0, v11
	v_max_f32_e32 v12, 0, v9
	v_max_f32_e32 v8, 0, v8
	v_max_f32_e32 v9, 0, v10
	v_pk_mul_f32 v[10:11], v[12:13], v[12:13]
	v_pk_mul_f32 v[8:9], v[8:9], v[8:9]
	v_cvt_pk_bf16_f32 v9, v9, v11
	v_cvt_pk_bf16_f32 v8, v8, v10
	global_store_dwordx2 v[20:21], v[8:9], off offset:32
	global_load_dwordx4 v[8:11], v[26:27], off offset:128
	s_waitcnt vmcnt(0)
	v_pk_fma_f32 v[6:7], v[6:7], v[104:105], v[10:11] op_sel_hi:[1,0,1]
	v_pk_fma_f32 v[4:5], v[4:5], v[104:105], v[8:9] op_sel_hi:[1,0,1]
	v_max_f32_e32 v9, 0, v7
	v_max_f32_e32 v8, 0, v5
	v_max_f32_e32 v4, 0, v4
	v_max_f32_e32 v5, 0, v6
	v_pk_mul_f32 v[6:7], v[8:9], v[8:9]
	v_pk_mul_f32 v[4:5], v[4:5], v[4:5]
	v_cvt_pk_bf16_f32 v5, v5, v7
	v_cvt_pk_bf16_f32 v4, v4, v6
	global_store_dwordx2 v[20:21], v[4:5], off offset:64
	global_load_dwordx4 v[4:7], v[26:27], off offset:192
	s_waitcnt vmcnt(0)
	v_pk_fma_f32 v[2:3], v[2:3], v[104:105], v[6:7] op_sel_hi:[1,0,1]
	v_pk_fma_f32 v[0:1], v[0:1], v[104:105], v[4:5] op_sel_hi:[1,0,1]
	v_max_f32_e32 v5, 0, v3
	v_max_f32_e32 v4, 0, v1
	v_max_f32_e32 v0, 0, v0
	v_max_f32_e32 v1, 0, v2
	v_pk_mul_f32 v[2:3], v[4:5], v[4:5]
	v_pk_mul_f32 v[0:1], v[0:1], v[0:1]
	v_cvt_pk_bf16_f32 v1, v1, v3
	v_cvt_pk_bf16_f32 v0, v0, v2
	global_store_dwordx2 v[20:21], v[0:1], off offset:96
	s_cbranch_scc1 .LBB0_388

.Ltail392:
	s_add_i32 s0, s1, 2
	v_add_u32_e32 v111, v104, v105
	ds_read_b128 v[136:139], v111 offset:16384
	ds_read_b128 v[140:143], v111 offset:18432
	ds_read_b128 v[144:147], v111 offset:20480
	ds_read_b128 v[148:151], v111 offset:22528
	v_add_u32_e32 v110, v103, v105
	ds_read_b128 v[116:119], v110
	s_add_i32 s1, s1, 4
	ds_read_b128 v[120:123], v110 offset:2048
	s_min_u32 s1, s1, 15
	v_add_u32_e32 v113, v104, v114
	s_lshl_b32 s92, s1, 7
	ds_read_b128 v[124:127], v110 offset:4096
	v_add_u32_e32 v112, v103, v114
	ds_read_b128 v[194:197], v113 offset:16384
	ds_read_b128 v[198:201], v113 offset:18432
	ds_read_b128 v[202:205], v113 offset:20480
	ds_read_b128 v[206:209], v113 offset:22528
	v_lshl_add_u64 v[164:165], v[98:99], 0, s[92:93]
	ds_read_b128 v[132:135], v110 offset:6144
	ds_read_b128 v[152:155], v112
	ds_read_b128 v[156:159], v112 offset:2048
	ds_read_b128 v[160:163], v112 offset:4096
	ds_read_b128 v[190:193], v112 offset:6144
	s_waitcnt lgkmcnt(11)
	v_mfma_f32_16x16x32_bf16 v[92:95], v[136:139], v[116:119], v[92:95]
	v_mfma_f32_16x16x32_bf16 v[88:91], v[140:143], v[116:119], v[88:91]
	v_mfma_f32_16x16x32_bf16 v[52:55], v[144:147], v[116:119], v[52:55]
	v_mfma_f32_16x16x32_bf16 v[48:51], v[148:151], v[116:119], v[48:51]
	s_waitcnt vmcnt(7)
	ds_write_b128 v109, v[56:59] offset:32768
	v_add_co_u32_e32 v56, vcc, s11, v164
	s_waitcnt lgkmcnt(11)
	v_mfma_f32_16x16x32_bf16 v[44:47], v[136:139], v[120:123], v[44:47]
	v_addc_co_u32_e32 v57, vcc, 0, v165, vcc
	v_mfma_f32_16x16x32_bf16 v[40:43], v[140:143], v[120:123], v[40:43]
	v_mfma_f32_16x16x32_bf16 v[36:39], v[144:147], v[120:123], v[36:39]
	v_mfma_f32_16x16x32_bf16 v[32:35], v[148:151], v[120:123], v[32:35]
	v_add_co_u32_e32 v56, vcc, s33, v164
	s_waitcnt vmcnt(6)
	ds_write_b128 v109, v[60:63] offset:36864
	s_nop 0
	v_addc_co_u32_e32 v57, vcc, 0, v165, vcc
	s_waitcnt lgkmcnt(11)
	v_mfma_f32_16x16x32_bf16 v[28:31], v[136:139], v[124:127], v[28:31]
	v_mfma_f32_16x16x32_bf16 v[24:27], v[140:143], v[124:127], v[24:27]
	v_mfma_f32_16x16x32_bf16 v[20:23], v[144:147], v[124:127], v[20:23]
	v_mfma_f32_16x16x32_bf16 v[16:19], v[148:151], v[124:127], v[16:19]
	v_add_co_u32_e32 v56, vcc, s59, v164
	s_waitcnt vmcnt(5)
	ds_write_b128 v109, v[64:67] offset:40960
	s_nop 0
	v_addc_co_u32_e32 v57, vcc, 0, v165, vcc
	v_lshl_add_u64 v[64:65], v[100:101], 0, s[92:93]
	v_add_co_u32_e32 v66, vcc, s11, v64
	s_waitcnt lgkmcnt(7)
	v_mfma_f32_16x16x32_bf16 v[12:15], v[136:139], v[132:135], v[12:15]
	v_addc_co_u32_e32 v67, vcc, 0, v65, vcc
	v_mfma_f32_16x16x32_bf16 v[8:11], v[140:143], v[132:135], v[8:11]
	v_mfma_f32_16x16x32_bf16 v[4:7], v[144:147], v[132:135], v[4:7]
	v_mfma_f32_16x16x32_bf16 v[0:3], v[148:151], v[132:135], v[0:3]
	s_waitcnt vmcnt(4)
	ds_write_b128 v109, v[72:75] offset:45056
	s_waitcnt lgkmcnt(7)
	v_mfma_f32_16x16x32_bf16 v[56:59], v[194:197], v[152:155], v[92:95]
	v_mfma_f32_16x16x32_bf16 v[60:63], v[198:201], v[152:155], v[88:91]
	v_mfma_f32_16x16x32_bf16 v[52:55], v[202:205], v[152:155], v[52:55]
	v_mfma_f32_16x16x32_bf16 v[48:51], v[206:209], v[152:155], v[48:51]
	s_waitcnt vmcnt(3)
	ds_write_b128 v109, v[68:71] offset:49152
	s_waitcnt lgkmcnt(7)
	v_mfma_f32_16x16x32_bf16 v[44:47], v[194:197], v[156:159], v[44:47]
	v_mfma_f32_16x16x32_bf16 v[40:43], v[198:201], v[156:159], v[40:43]
	v_mfma_f32_16x16x32_bf16 v[36:39], v[202:205], v[156:159], v[36:39]
	v_mfma_f32_16x16x32_bf16 v[32:35], v[206:209], v[156:159], v[32:35]
	v_add_co_u32_e32 v66, vcc, s33, v64
	s_waitcnt vmcnt(2)
	ds_write_b128 v109, v[76:79] offset:53248
	v_addc_co_u32_e32 v67, vcc, 0, v65, vcc
	v_add_co_u32_e32 v64, vcc, s59, v64
	s_waitcnt lgkmcnt(7)
	v_mfma_f32_16x16x32_bf16 v[28:31], v[194:197], v[160:163], v[28:31]
	v_addc_co_u32_e32 v65, vcc, 0, v65, vcc
	v_mfma_f32_16x16x32_bf16 v[24:27], v[198:201], v[160:163], v[24:27]
	v_mfma_f32_16x16x32_bf16 v[20:23], v[202:205], v[160:163], v[20:23]
	v_mfma_f32_16x16x32_bf16 v[16:19], v[206:209], v[160:163], v[16:19]
	s_waitcnt vmcnt(1)
	ds_write_b128 v109, v[80:83] offset:57344
	s_waitcnt lgkmcnt(7)
	v_mfma_f32_16x16x32_bf16 v[12:15], v[194:197], v[190:193], v[12:15]
	v_mfma_f32_16x16x32_bf16 v[8:11], v[198:201], v[190:193], v[8:11]
	v_mfma_f32_16x16x32_bf16 v[4:7], v[202:205], v[190:193], v[4:7]
	v_mfma_f32_16x16x32_bf16 v[0:3], v[206:209], v[190:193], v[0:3]
	s_waitcnt vmcnt(0)
	ds_write_b128 v109, v[84:87] offset:61440
	s_waitcnt lgkmcnt(0)
	s_barrier
	ds_read_b128 v[84:87], v111 offset:51200
	ds_read_b128 v[80:83], v111 offset:49152
	ds_read_b128 v[88:91], v111 offset:53248
	ds_read_b128 v[92:95], v111 offset:55296
	ds_read_b128 v[64:67], v110 offset:32768
	s_min_u32 s1, s0, 12
	s_lshl_b32 s92, s1, 7
	ds_read_b128 v[68:71], v110 offset:34816
	v_lshl_add_u64 v[164:165], v[98:99], 0, s[92:93]
	ds_read_b128 v[72:75], v110 offset:36864
	ds_read_b128 v[76:79], v110 offset:38912
	ds_read_b128 v[152:155], v112 offset:32768
	ds_read_b128 v[156:159], v112 offset:34816
	ds_read_b128 v[160:163], v112 offset:36864
	ds_read_b128 v[190:193], v112 offset:38912
	ds_read_b128 v[194:197], v113 offset:49152
	ds_read_b128 v[198:201], v113 offset:51200
	ds_read_b128 v[202:205], v113 offset:53248
	ds_read_b128 v[206:209], v113 offset:55296
	s_waitcnt lgkmcnt(11)
	v_mfma_f32_16x16x32_bf16 v[214:217], v[84:87], v[64:67], v[60:63]
	v_mfma_f32_16x16x32_bf16 v[210:213], v[80:83], v[64:67], v[56:59]
	s_nop 1
	v_add_co_u32_e32 v60, vcc, s11, v164
	s_nop 1
	v_addc_co_u32_e32 v61, vcc, 0, v165, vcc
	v_mfma_f32_16x16x32_bf16 v[52:55], v[88:91], v[64:67], v[52:55]
	v_mfma_f32_16x16x32_bf16 v[48:51], v[92:95], v[64:67], v[48:51]
	v_add_co_u32_e32 v64, vcc, s33, v164
	s_nop 0
	v_addc_co_u32_e32 v65, vcc, 0, v165, vcc
	s_waitcnt lgkmcnt(10)
	v_mfma_f32_16x16x32_bf16 v[44:47], v[80:83], v[68:71], v[44:47]
	v_mfma_f32_16x16x32_bf16 v[40:43], v[84:87], v[68:71], v[40:43]
	v_mfma_f32_16x16x32_bf16 v[36:39], v[88:91], v[68:71], v[36:39]
	v_mfma_f32_16x16x32_bf16 v[32:35], v[92:95], v[68:71], v[32:35]
	v_add_co_u32_e32 v68, vcc, s59, v164
	s_waitcnt lgkmcnt(9)
	v_mfma_f32_16x16x32_bf16 v[28:31], v[80:83], v[72:75], v[28:31]
	v_addc_co_u32_e32 v69, vcc, 0, v165, vcc
	v_mfma_f32_16x16x32_bf16 v[24:27], v[84:87], v[72:75], v[24:27]
	v_mfma_f32_16x16x32_bf16 v[20:23], v[88:91], v[72:75], v[20:23]
	v_mfma_f32_16x16x32_bf16 v[16:19], v[92:95], v[72:75], v[16:19]
	s_waitcnt lgkmcnt(8)
	v_mfma_f32_16x16x32_bf16 v[8:11], v[84:87], v[76:79], v[8:11]
	v_lshl_add_u64 v[84:85], v[100:101], 0, s[92:93]
	v_mfma_f32_16x16x32_bf16 v[12:15], v[80:83], v[76:79], v[12:15]
	v_mfma_f32_16x16x32_bf16 v[4:7], v[88:91], v[76:79], v[4:7]
	v_mfma_f32_16x16x32_bf16 v[0:3], v[92:95], v[76:79], v[0:3]
	v_add_co_u32_e32 v76, vcc, s11, v84
	s_nop 0
	v_addc_co_u32_e32 v77, vcc, 0, v85, vcc
	v_add_co_u32_e32 v80, vcc, s33, v84
	v_addc_co_u32_e32 v81, vcc, 0, v85, vcc
	s_waitcnt lgkmcnt(3)
	v_mfma_f32_16x16x32_bf16 v[92:95], v[194:197], v[152:155], v[210:213]
	s_waitcnt lgkmcnt(2)
	v_mfma_f32_16x16x32_bf16 v[88:91], v[198:201], v[152:155], v[214:217]
	s_waitcnt lgkmcnt(1)
	v_mfma_f32_16x16x32_bf16 v[52:55], v[202:205], v[152:155], v[52:55]
	s_waitcnt lgkmcnt(0)
	v_mfma_f32_16x16x32_bf16 v[48:51], v[206:209], v[152:155], v[48:51]
	v_add_co_u32_e32 v84, vcc, s59, v84
	v_addc_co_u32_e32 v85, vcc, 0, v85, vcc
	v_mfma_f32_16x16x32_bf16 v[44:47], v[194:197], v[156:159], v[44:47]
	v_mfma_f32_16x16x32_bf16 v[40:43], v[198:201], v[156:159], v[40:43]
	v_mfma_f32_16x16x32_bf16 v[36:39], v[202:205], v[156:159], v[36:39]
	v_mfma_f32_16x16x32_bf16 v[32:35], v[206:209], v[156:159], v[32:35]
	v_mfma_f32_16x16x32_bf16 v[28:31], v[194:197], v[160:163], v[28:31]
	v_mfma_f32_16x16x32_bf16 v[24:27], v[198:201], v[160:163], v[24:27]
	v_mfma_f32_16x16x32_bf16 v[20:23], v[202:205], v[160:163], v[20:23]
	v_mfma_f32_16x16x32_bf16 v[16:19], v[206:209], v[160:163], v[16:19]
	v_mfma_f32_16x16x32_bf16 v[12:15], v[194:197], v[190:193], v[12:15]
	v_mfma_f32_16x16x32_bf16 v[8:11], v[198:201], v[190:193], v[8:11]
	v_mfma_f32_16x16x32_bf16 v[4:7], v[202:205], v[190:193], v[4:7]
	v_mfma_f32_16x16x32_bf16 v[0:3], v[206:209], v[190:193], v[0:3]
	s_mov_b32 s1, s0
	s_waitcnt lgkmcnt(0)
	s_barrier
	s_mul_i32 s0, s69, 0x12000
	v_readlane_b32 s16, v250, 25
	s_add_u32 s24, s16, s0
	v_readlane_b32 s0, v251, 5
	v_lshlrev_b32_e32 v114, 6, v102
	v_readlane_b32 s17, v250, 26
	s_waitcnt vmcnt(5)
	v_add_u32_e32 v64, s0, v108
	v_readlane_b32 s0, v251, 6
	v_add_u32_e32 v56, 0xffffe000, v64
	v_or_b32_e32 v62, v64, v107
	v_or_b32_e32 v65, s0, v114
	v_lshrrev_b32_e32 v56, 10, v56
	s_movk_i32 s0, 0x1800
	v_mad_u32_u24 v56, v56, s0, s0
	v_cmp_lt_i32_e32 vcc, s13, v62
	s_addc_u32 s25, s17, 0
	v_lshlrev_b32_e32 v115, 2, v97
	v_cndmask_b32_e32 v56, 0, v56, vcc
	s_add_u32 s40, s24, 0x2000
	v_or_b32_e32 v58, v65, v115
	v_ashrrev_i32_e32 v57, 31, v56
	s_addc_u32 s41, s25, 0
	s_waitcnt vmcnt(4)
	v_lshlrev_b64 v[74:75], 2, v[56:57]
	v_ashrrev_i32_e32 v59, 31, v58
	v_ashrrev_i32_e32 v63, 31, v62
	v_lshl_add_u64 v[56:57], s[40:41], 0, v[74:75]
	v_lshlrev_b64 v[60:61], 2, v[58:59]
	v_readlane_b32 s0, v250, 15
	s_waitcnt vmcnt(1)
	v_lshl_add_u64 v[82:83], v[56:57], 0, v[60:61]
	v_lshlrev_b64 v[56:57], 12, v[62:63]
	v_readlane_b32 s1, v250, 16
	v_readlane_b32 s16, v250, 21
	v_lshlrev_b64 v[78:79], 11, v[62:63]
	v_lshl_add_u64 v[56:57], s[0:1], 0, v[56:57]
	s_waitcnt vmcnt(0)
	v_lshl_add_u64 v[84:85], v[56:57], 0, v[60:61]
	global_load_dwordx4 v[116:119], v[82:83], off
	global_load_dwordx4 v[120:123], v[82:83], off offset:64
	global_load_dwordx4 v[124:127], v[82:83], off offset:128
	global_load_dwordx4 v[132:135], v[82:83], off offset:192
	global_load_dwordx4 v[190:193], v[84:85], off
	global_load_dwordx4 v[194:197], v[84:85], off offset:64
	global_load_dwordx4 v[198:201], v[84:85], off offset:128
	global_load_dwordx4 v[202:205], v[84:85], off offset:192
	v_add_co_u32_e32 v164, vcc, 0x10000, v84
	s_nop 1
	v_addc_co_u32_e32 v165, vcc, 0, v85, vcc
	v_add_co_u32_e32 v222, vcc, 0x20000, v84
	s_nop 1
	v_addc_co_u32_e32 v223, vcc, 0, v85, vcc
	v_add_co_u32_e32 v224, vcc, 0x30000, v84
	s_nop 1
	v_addc_co_u32_e32 v225, vcc, 0, v85, vcc
	global_load_dwordx4 v[206:209], v[164:165], off
	global_load_dwordx4 v[210:213], v[164:165], off offset:64
	global_load_dwordx4 v[214:217], v[164:165], off offset:128
	global_load_dwordx4 v[218:221], v[164:165], off offset:192
	s_lshl_b32 s0, s69, 12
	v_readlane_b32 s68, v250, 41
	v_readlane_b32 s72, v250, 45
	v_readlane_b32 s73, v250, 46
	s_add_u32 s0, s72, s0
	s_addc_u32 s1, s73, 0
	s_add_u32 s42, s24, 0x4000
	s_addc_u32 s43, s25, 0
	v_lshl_add_u64 v[74:75], s[42:43], 0, v[74:75]
	v_lshl_add_u64 v[56:57], s[0:1], 0, v[60:61]
	v_lshl_add_u64 v[86:87], v[74:75], 0, v[60:61]
	v_readlane_b32 s17, v250, 22
	v_readlane_b32 s69, v250, 42
	v_readlane_b32 s69, v254, 49
	v_lshl_add_u64 v[78:79], s[16:17], 0, v[78:79]
	s_mul_i32 s24, s69, 0x140000
	s_add_u32 s24, s86, s24
	v_lshrrev_b32_e32 v65, 6, v65
	s_mov_b32 s16, 0xa000
	s_addc_u32 s25, s87, 0
	s_add_u32 s38, s24, 0xaf1a000
	s_addc_u32 s39, s25, 0
	v_cmp_eq_u32_e64 s[36:37], 0, v97
	v_readlane_b32 s70, v250, 43
	v_readlane_b32 s71, v250, 44
	v_readlane_b32 s74, v250, 47
	v_readlane_b32 s75, v250, 48
	v_readlane_b32 s76, v250, 49
	v_readlane_b32 s77, v250, 50
	v_readlane_b32 s78, v250, 51
	v_readlane_b32 s79, v250, 52
	v_readlane_b32 s80, v250, 53
	v_readlane_b32 s81, v250, 54
	v_readlane_b32 s82, v250, 55
	v_readlane_b32 s83, v250, 56
	s_waitcnt vmcnt(4)
	v_pk_fma_f32 v[68:69], v[94:95], v[118:119], v[192:193]
	v_pk_fma_f32 v[66:67], v[92:93], v[116:117], v[190:191]
	global_store_dwordx4 v[84:85], v[66:69], off
	global_load_dwordx4 v[136:139], v[56:57], off
	global_load_dwordx4 v[140:143], v[56:57], off offset:64
	global_load_dwordx4 v[144:147], v[56:57], off offset:128
	global_load_dwordx4 v[148:151], v[56:57], off offset:192
	global_load_dwordx4 v[152:155], v[86:87], off
	global_load_dwordx4 v[156:159], v[86:87], off offset:64
	global_load_dwordx4 v[160:163], v[86:87], off offset:128
	global_load_dwordx4 v[180:183], v[86:87], off offset:192
	v_lshl_add_u64 v[92:93], v[58:59], 1, v[78:79]
	s_waitcnt vmcnt(0)
	v_pk_mul_f32 v[72:73], v[68:69], v[138:139]
	v_pk_mul_f32 v[70:71], v[66:67], v[136:137]
	s_waitcnt vmcnt(0)
	v_pk_add_f32 v[76:77], v[154:155], 1.0 op_sel_hi:[1,0]
	v_pk_add_f32 v[74:75], v[152:153], 1.0 op_sel_hi:[1,0]
	v_pk_mul_f32 v[72:73], v[72:73], v[76:77]
	v_pk_mul_f32 v[70:71], v[70:71], v[74:75]
	v_and_b32_sdwa v76, v73, v170 dst_sel:DWORD dst_unused:UNUSED_PAD src0_sel:WORD_1 src1_sel:DWORD
	v_and_b32_sdwa v77, v71, v170 dst_sel:DWORD dst_unused:UNUSED_PAD src0_sel:WORD_1 src1_sel:DWORD
	v_and_b32_sdwa v74, v72, v170 dst_sel:DWORD dst_unused:UNUSED_PAD src0_sel:WORD_1 src1_sel:DWORD
	v_and_b32_sdwa v75, v70, v170 dst_sel:DWORD dst_unused:UNUSED_PAD src0_sel:WORD_1 src1_sel:DWORD
	v_add3_u32 v73, v73, v76, s56
	v_add3_u32 v71, v71, v77, s56
	v_add3_u32 v70, v70, v75, s56
	v_add3_u32 v72, v72, v74, s56
	v_and_b32_e32 v73, 0xffff0000, v73
	v_and_b32_e32 v74, 0xffff0000, v71
	v_or_b32_sdwa v71, v73, v72 dst_sel:DWORD dst_unused:UNUSED_PAD src0_sel:DWORD src1_sel:WORD_1
	v_or_b32_sdwa v70, v74, v70 dst_sel:DWORD dst_unused:UNUSED_PAD src0_sel:DWORD src1_sel:WORD_1
	global_store_dwordx2 v[92:93], v[70:71], off
	s_nop 0
	s_waitcnt vmcnt(0)
	v_pk_fma_f32 v[72:73], v[90:91], v[122:123], v[196:197]
	v_pk_fma_f32 v[70:71], v[88:89], v[120:121], v[194:195]
	global_store_dwordx4 v[84:85], v[70:73], off offset:64
	v_pk_mul_f32 v[76:77], v[72:73], v[142:143]
	v_pk_mul_f32 v[74:75], v[70:71], v[140:141]
	v_pk_add_f32 v[80:81], v[158:159], 1.0 op_sel_hi:[1,0]
	v_pk_add_f32 v[78:79], v[156:157], 1.0 op_sel_hi:[1,0]
	v_pk_mul_f32 v[76:77], v[76:77], v[80:81]
	v_pk_mul_f32 v[74:75], v[74:75], v[78:79]
	v_and_b32_sdwa v80, v77, v170 dst_sel:DWORD dst_unused:UNUSED_PAD src0_sel:WORD_1 src1_sel:DWORD
	v_and_b32_sdwa v81, v75, v170 dst_sel:DWORD dst_unused:UNUSED_PAD src0_sel:WORD_1 src1_sel:DWORD
	v_and_b32_sdwa v78, v76, v170 dst_sel:DWORD dst_unused:UNUSED_PAD src0_sel:WORD_1 src1_sel:DWORD
	v_and_b32_sdwa v79, v74, v170 dst_sel:DWORD dst_unused:UNUSED_PAD src0_sel:WORD_1 src1_sel:DWORD
	v_add3_u32 v77, v77, v80, s56
	v_add3_u32 v75, v75, v81, s56
	v_add3_u32 v74, v74, v79, s56
	v_add3_u32 v76, v76, v78, s56
	v_and_b32_e32 v77, 0xffff0000, v77
	v_and_b32_e32 v78, 0xffff0000, v75
	v_or_b32_sdwa v75, v77, v76 dst_sel:DWORD dst_unused:UNUSED_PAD src0_sel:DWORD src1_sel:WORD_1
	v_or_b32_sdwa v74, v78, v74 dst_sel:DWORD dst_unused:UNUSED_PAD src0_sel:DWORD src1_sel:WORD_1
	global_store_dwordx2 v[92:93], v[74:75], off offset:32
	s_nop 0
	v_pk_fma_f32 v[54:55], v[54:55], v[126:127], v[200:201]
	v_pk_fma_f32 v[52:53], v[52:53], v[124:125], v[198:199]
	global_store_dwordx4 v[84:85], v[52:55], off offset:128
	v_pk_mul_f32 v[76:77], v[54:55], v[146:147]
	v_pk_mul_f32 v[74:75], v[52:53], v[144:145]
	v_pk_add_f32 v[80:81], v[162:163], 1.0 op_sel_hi:[1,0]
	v_pk_add_f32 v[78:79], v[160:161], 1.0 op_sel_hi:[1,0]
	v_pk_mul_f32 v[76:77], v[76:77], v[80:81]
	v_pk_mul_f32 v[74:75], v[74:75], v[78:79]
	v_and_b32_sdwa v80, v77, v170 dst_sel:DWORD dst_unused:UNUSED_PAD src0_sel:WORD_1 src1_sel:DWORD
	v_and_b32_sdwa v81, v75, v170 dst_sel:DWORD dst_unused:UNUSED_PAD src0_sel:WORD_1 src1_sel:DWORD
	v_and_b32_sdwa v78, v76, v170 dst_sel:DWORD dst_unused:UNUSED_PAD src0_sel:WORD_1 src1_sel:DWORD
	v_and_b32_sdwa v79, v74, v170 dst_sel:DWORD dst_unused:UNUSED_PAD src0_sel:WORD_1 src1_sel:DWORD
	v_add3_u32 v77, v77, v80, s56
	v_add3_u32 v75, v75, v81, s56
	v_add3_u32 v74, v74, v79, s56
	v_add3_u32 v76, v76, v78, s56
	v_and_b32_e32 v77, 0xffff0000, v77
	v_and_b32_e32 v78, 0xffff0000, v75
	v_or_b32_sdwa v75, v77, v76 dst_sel:DWORD dst_unused:UNUSED_PAD src0_sel:DWORD src1_sel:WORD_1
	v_or_b32_sdwa v74, v78, v74 dst_sel:DWORD dst_unused:UNUSED_PAD src0_sel:DWORD src1_sel:WORD_1
	global_store_dwordx2 v[92:93], v[74:75], off offset:64
	s_nop 0
	v_pk_fma_f32 v[76:77], v[50:51], v[134:135], v[204:205]
	v_pk_fma_f32 v[74:75], v[48:49], v[132:133], v[202:203]
	global_store_dwordx4 v[84:85], v[74:77], off offset:192
	s_nop 0
	v_mbcnt_lo_u32_b32 v48, -1, 0
	v_mbcnt_hi_u32_b32 v48, -1, v48
	v_and_b32_e32 v50, 64, v48
	v_xor_b32_e32 v49, 16, v48
	v_add_u32_e32 v50, 64, v50
	v_xor_b32_e32 v51, 32, v48
	v_cmp_lt_i32_e32 vcc, v49, v50
	s_nop 1
	v_cndmask_b32_e32 v49, v48, v49, vcc
	v_cmp_lt_i32_e32 vcc, v51, v50
	v_lshlrev_b32_e32 v105, 2, v49
	s_nop 0
	v_cndmask_b32_e32 v50, v48, v51, vcc
	v_lshlrev_b32_e32 v104, 2, v50
	v_mul_f32_e32 v50, v67, v67
	v_mul_f32_e32 v51, v71, v71
	v_fmac_f32_e32 v50, v66, v66
	v_fmac_f32_e32 v51, v70, v70
	v_fmac_f32_e32 v50, v68, v68
	v_fmac_f32_e32 v51, v72, v72
	v_fmac_f32_e32 v50, v69, v69
	v_fmac_f32_e32 v51, v73, v73
	v_add_f32_e32 v50, v50, v51
	v_mul_f32_e32 v51, v53, v53
	v_fmac_f32_e32 v51, v52, v52
	v_fmac_f32_e32 v51, v54, v54
	v_fmac_f32_e32 v51, v55, v55
	v_add_f32_e32 v50, v50, v51
	v_mul_f32_e32 v51, v75, v75
	v_fmac_f32_e32 v51, v74, v74
	v_fmac_f32_e32 v51, v76, v76
	v_fmac_f32_e32 v51, v77, v77
	v_add_f32_e32 v50, v50, v51
	ds_bpermute_b32 v51, v105, v50
	v_mul_lo_u32 v48, v65, s16
	v_ashrrev_i32_e32 v49, 31, v48
	v_lshl_add_u64 v[48:49], s[38:39], 0, v[48:49]
	v_lshl_add_u64 v[48:49], v[62:63], 2, v[48:49]
	s_waitcnt lgkmcnt(0)
	v_add_f32_e32 v50, v50, v51
	ds_bpermute_b32 v51, v104, v50
	v_pk_mul_f32 v[52:53], v[76:77], v[150:151]
	v_pk_mul_f32 v[54:55], v[74:75], v[148:149]
	v_pk_add_f32 v[66:67], v[182:183], 1.0 op_sel_hi:[1,0]
	v_pk_add_f32 v[68:69], v[180:181], 1.0 op_sel_hi:[1,0]
	v_pk_mul_f32 v[52:53], v[52:53], v[66:67]
	v_pk_mul_f32 v[54:55], v[54:55], v[68:69]
	v_cvt_pk_bf16_f32 v53, v52, v53
	v_cvt_pk_bf16_f32 v52, v54, v55
	global_store_dwordx2 v[92:93], v[52:53], off offset:96
	s_and_saveexec_b64 s[24:25], s[36:37]
	s_cbranch_execz .LBB0_395
	s_waitcnt lgkmcnt(0)
	v_add_f32_e32 v50, v50, v51
	global_store_dword v[48:49], v50, off

.LBB0_397:
	s_or_b64 exec, exec, s[24:25]
	v_add_u32_e32 v32, 0xffffe020, v64
	v_or_b32_e32 v40, 32, v62
	v_lshrrev_b32_e32 v32, 10, v32
	v_mad_u32_u24 v32, v32, s5, s5
	v_cmp_lt_i32_e32 vcc, s13, v40
	v_ashrrev_i32_e32 v41, 31, v40
	v_readlane_b32 s16, v250, 15
	v_cndmask_b32_e32 v32, 0, v32, vcc
	s_waitcnt lgkmcnt(0)
	v_ashrrev_i32_e32 v33, 31, v32
	v_lshlrev_b64 v[42:43], 2, v[32:33]
	v_lshl_add_u64 v[32:33], s[40:41], 0, v[42:43]
	v_lshl_add_u64 v[44:45], v[32:33], 0, v[60:61]
	v_lshlrev_b64 v[32:33], 12, v[40:41]
	v_readlane_b32 s17, v250, 16
	v_lshl_add_u64 v[42:43], s[42:43], 0, v[42:43]
	v_lshl_add_u64 v[42:43], v[42:43], 0, v[60:61]
	v_lshl_add_u64 v[32:33], s[16:17], 0, v[32:33]
	v_lshl_add_u64 v[46:47], v[32:33], 0, v[60:61]
	v_readlane_b32 s16, v250, 21
	v_lshlrev_b64 v[40:41], 11, v[40:41]
	v_readlane_b32 s17, v250, 22
	global_load_dwordx4 v[206:209], v[224:225], off
	global_load_dwordx4 v[210:213], v[224:225], off offset:64
	global_load_dwordx4 v[214:217], v[224:225], off offset:128
	global_load_dwordx4 v[218:221], v[224:225], off offset:192
	s_waitcnt vmcnt(12)
	v_pk_fma_f32 v[30:31], v[30:31], v[118:119], v[192:193]
	v_pk_fma_f32 v[28:29], v[28:29], v[116:117], v[190:191]
	global_store_dwordx4 v[46:47], v[28:31], off
	v_lshl_add_u64 v[40:41], s[16:17], 0, v[40:41]
	v_lshl_add_u64 v[50:51], v[58:59], 1, v[40:41]
	v_pk_mul_f32 v[34:35], v[30:31], v[138:139]
	v_pk_mul_f32 v[32:33], v[28:29], v[136:137]
	v_pk_add_f32 v[38:39], v[154:155], 1.0 op_sel_hi:[1,0]
	v_pk_add_f32 v[36:37], v[152:153], 1.0 op_sel_hi:[1,0]
	v_pk_mul_f32 v[34:35], v[34:35], v[38:39]
	v_pk_mul_f32 v[32:33], v[32:33], v[36:37]
	v_and_b32_sdwa v38, v35, v170 dst_sel:DWORD dst_unused:UNUSED_PAD src0_sel:WORD_1 src1_sel:DWORD
	v_and_b32_sdwa v39, v33, v170 dst_sel:DWORD dst_unused:UNUSED_PAD src0_sel:WORD_1 src1_sel:DWORD
	v_and_b32_sdwa v36, v34, v170 dst_sel:DWORD dst_unused:UNUSED_PAD src0_sel:WORD_1 src1_sel:DWORD
	v_and_b32_sdwa v37, v32, v170 dst_sel:DWORD dst_unused:UNUSED_PAD src0_sel:WORD_1 src1_sel:DWORD
	v_add3_u32 v35, v35, v38, s56
	v_add3_u32 v33, v33, v39, s56
	v_add3_u32 v32, v32, v37, s56
	v_add3_u32 v34, v34, v36, s56
	v_and_b32_e32 v35, 0xffff0000, v35
	v_and_b32_e32 v36, 0xffff0000, v33
	v_or_b32_sdwa v33, v35, v34 dst_sel:DWORD dst_unused:UNUSED_PAD src0_sel:DWORD src1_sel:WORD_1
	v_or_b32_sdwa v32, v36, v32 dst_sel:DWORD dst_unused:UNUSED_PAD src0_sel:DWORD src1_sel:WORD_1
	global_store_dwordx2 v[50:51], v[32:33], off
	s_nop 0
	v_pk_fma_f32 v[26:27], v[26:27], v[122:123], v[196:197]
	v_pk_fma_f32 v[24:25], v[24:25], v[120:121], v[194:195]
	global_store_dwordx4 v[46:47], v[24:27], off offset:64
	v_pk_mul_f32 v[34:35], v[26:27], v[142:143]
	v_pk_mul_f32 v[32:33], v[24:25], v[140:141]
	v_pk_add_f32 v[38:39], v[158:159], 1.0 op_sel_hi:[1,0]
	v_pk_add_f32 v[36:37], v[156:157], 1.0 op_sel_hi:[1,0]
	v_pk_mul_f32 v[34:35], v[34:35], v[38:39]
	v_pk_mul_f32 v[32:33], v[32:33], v[36:37]
	v_and_b32_sdwa v38, v35, v170 dst_sel:DWORD dst_unused:UNUSED_PAD src0_sel:WORD_1 src1_sel:DWORD
	v_and_b32_sdwa v39, v33, v170 dst_sel:DWORD dst_unused:UNUSED_PAD src0_sel:WORD_1 src1_sel:DWORD
	v_and_b32_sdwa v36, v34, v170 dst_sel:DWORD dst_unused:UNUSED_PAD src0_sel:WORD_1 src1_sel:DWORD
	v_and_b32_sdwa v37, v32, v170 dst_sel:DWORD dst_unused:UNUSED_PAD src0_sel:WORD_1 src1_sel:DWORD
	v_add3_u32 v35, v35, v38, s56
	v_add3_u32 v33, v33, v39, s56
	v_add3_u32 v32, v32, v37, s56
	v_add3_u32 v34, v34, v36, s56
	v_and_b32_e32 v35, 0xffff0000, v35
	v_and_b32_e32 v36, 0xffff0000, v33
	v_or_b32_sdwa v33, v35, v34 dst_sel:DWORD dst_unused:UNUSED_PAD src0_sel:DWORD src1_sel:WORD_1
	v_or_b32_sdwa v32, v36, v32 dst_sel:DWORD dst_unused:UNUSED_PAD src0_sel:DWORD src1_sel:WORD_1
	global_store_dwordx2 v[50:51], v[32:33], off offset:32
	s_nop 0
	v_pk_fma_f32 v[22:23], v[22:23], v[126:127], v[200:201]
	v_pk_fma_f32 v[20:21], v[20:21], v[124:125], v[198:199]
	global_store_dwordx4 v[46:47], v[20:23], off offset:128
	v_pk_mul_f32 v[34:35], v[22:23], v[146:147]
	v_pk_mul_f32 v[32:33], v[20:21], v[144:145]
	v_pk_add_f32 v[38:39], v[162:163], 1.0 op_sel_hi:[1,0]
	v_pk_add_f32 v[36:37], v[160:161], 1.0 op_sel_hi:[1,0]
	v_pk_mul_f32 v[34:35], v[34:35], v[38:39]
	v_pk_mul_f32 v[32:33], v[32:33], v[36:37]
	v_and_b32_sdwa v38, v35, v170 dst_sel:DWORD dst_unused:UNUSED_PAD src0_sel:WORD_1 src1_sel:DWORD
	v_and_b32_sdwa v39, v33, v170 dst_sel:DWORD dst_unused:UNUSED_PAD src0_sel:WORD_1 src1_sel:DWORD
	v_and_b32_sdwa v36, v34, v170 dst_sel:DWORD dst_unused:UNUSED_PAD src0_sel:WORD_1 src1_sel:DWORD
	v_and_b32_sdwa v37, v32, v170 dst_sel:DWORD dst_unused:UNUSED_PAD src0_sel:WORD_1 src1_sel:DWORD
	v_add3_u32 v35, v35, v38, s56
	v_add3_u32 v33, v33, v39, s56
	v_add3_u32 v32, v32, v37, s56
	v_add3_u32 v34, v34, v36, s56
	v_and_b32_e32 v35, 0xffff0000, v35
	v_and_b32_e32 v36, 0xffff0000, v33
	v_or_b32_sdwa v33, v35, v34 dst_sel:DWORD dst_unused:UNUSED_PAD src0_sel:DWORD src1_sel:WORD_1
	v_or_b32_sdwa v32, v36, v32 dst_sel:DWORD dst_unused:UNUSED_PAD src0_sel:DWORD src1_sel:WORD_1
	global_store_dwordx2 v[50:51], v[32:33], off offset:64
	s_nop 0
	v_pk_fma_f32 v[34:35], v[18:19], v[134:135], v[204:205]
	v_pk_fma_f32 v[32:33], v[16:17], v[132:133], v[202:203]
	global_store_dwordx4 v[46:47], v[32:35], off offset:192
	s_nop 0
	v_mul_f32_e32 v16, v29, v29
	v_mul_f32_e32 v17, v25, v25
	v_fmac_f32_e32 v16, v28, v28
	v_fmac_f32_e32 v17, v24, v24
	v_fmac_f32_e32 v16, v30, v30
	v_fmac_f32_e32 v17, v26, v26
	v_fmac_f32_e32 v16, v31, v31
	v_fmac_f32_e32 v17, v27, v27
	v_add_f32_e32 v16, v16, v17
	v_mul_f32_e32 v17, v21, v21
	v_fmac_f32_e32 v17, v20, v20
	v_fmac_f32_e32 v17, v22, v22
	v_fmac_f32_e32 v17, v23, v23
	v_add_f32_e32 v16, v16, v17
	v_mul_f32_e32 v17, v33, v33
	v_fmac_f32_e32 v17, v32, v32
	v_fmac_f32_e32 v17, v34, v34
	v_fmac_f32_e32 v17, v35, v35
	v_add_f32_e32 v16, v16, v17
	ds_bpermute_b32 v17, v105, v16
	s_waitcnt lgkmcnt(0)
	v_add_f32_e32 v16, v16, v17
	ds_bpermute_b32 v17, v104, v16
	v_pk_mul_f32 v[18:19], v[34:35], v[150:151]
	v_pk_mul_f32 v[20:21], v[32:33], v[148:149]
	v_pk_add_f32 v[22:23], v[182:183], 1.0 op_sel_hi:[1,0]
	v_pk_add_f32 v[24:25], v[180:181], 1.0 op_sel_hi:[1,0]
	v_pk_mul_f32 v[18:19], v[18:19], v[22:23]
	v_pk_mul_f32 v[20:21], v[20:21], v[24:25]
	v_cvt_pk_bf16_f32 v19, v18, v19
	v_cvt_pk_bf16_f32 v18, v20, v21
	global_store_dwordx2 v[50:51], v[18:19], off offset:96
	s_and_saveexec_b64 s[24:25], s[36:37]
	s_movk_i32 s8, 0x400
	s_mov_b32 s5, 0xffff0000
	s_mov_b32 s9, 0x12000
	s_movk_i32 s89, 0xff
	s_cbranch_execz .LBB0_399
	s_waitcnt lgkmcnt(0)
	v_add_f32_e32 v16, v16, v17
	global_store_dword v[48:49], v16, off offset:128

.Ltail406:
	s_add_i32 s29, s44, 2
	ds_read_b128 v[136:139], v111 offset:16384
	ds_read_b128 v[140:143], v111 offset:18432
	ds_read_b128 v[144:147], v111 offset:20480
	ds_read_b128 v[148:151], v111 offset:22528
	ds_read_b128 v[116:119], v110
	s_add_i32 s44, s44, 4
	ds_read_b128 v[120:123], v110 offset:2048
	s_min_u32 s44, s44, 15
	s_lshl_b32 s92, s44, 7
	ds_read_b128 v[124:127], v110 offset:4096
	ds_read_b128 v[194:197], v113 offset:16384
	ds_read_b128 v[198:201], v113 offset:18432
	ds_read_b128 v[202:205], v113 offset:20480
	ds_read_b128 v[206:209], v113 offset:22528
	v_lshl_add_u64 v[164:165], v[100:101], 0, s[92:93]
	ds_read_b128 v[132:135], v110 offset:6144
	ds_read_b128 v[152:155], v112
	ds_read_b128 v[156:159], v112 offset:2048
	ds_read_b128 v[160:163], v112 offset:4096
	ds_read_b128 v[190:193], v112 offset:6144
	s_waitcnt lgkmcnt(11)
	v_mfma_f32_16x16x32_bf16 v[92:95], v[136:139], v[116:119], v[92:95]
	v_mfma_f32_16x16x32_bf16 v[88:91], v[140:143], v[116:119], v[88:91]
	v_mfma_f32_16x16x32_bf16 v[56:59], v[144:147], v[116:119], v[56:59]
	v_mfma_f32_16x16x32_bf16 v[48:51], v[148:151], v[116:119], v[48:51]
	s_waitcnt vmcnt(7)
	ds_write_b128 v109, v[52:55] offset:32768
	v_add_co_u32_e32 v52, vcc, s11, v164
	s_waitcnt lgkmcnt(11)
	v_mfma_f32_16x16x32_bf16 v[44:47], v[136:139], v[120:123], v[44:47]
	v_addc_co_u32_e32 v53, vcc, 0, v165, vcc
	v_mfma_f32_16x16x32_bf16 v[40:43], v[140:143], v[120:123], v[40:43]
	v_mfma_f32_16x16x32_bf16 v[36:39], v[144:147], v[120:123], v[36:39]
	v_mfma_f32_16x16x32_bf16 v[32:35], v[148:151], v[120:123], v[32:35]
	v_add_co_u32_e32 v52, vcc, s33, v164
	s_waitcnt vmcnt(6)
	ds_write_b128 v109, v[60:63] offset:36864
	s_nop 0
	v_addc_co_u32_e32 v53, vcc, 0, v165, vcc
	s_waitcnt lgkmcnt(11)
	v_mfma_f32_16x16x32_bf16 v[28:31], v[136:139], v[124:127], v[28:31]
	v_mfma_f32_16x16x32_bf16 v[24:27], v[140:143], v[124:127], v[24:27]
	v_mfma_f32_16x16x32_bf16 v[20:23], v[144:147], v[124:127], v[20:23]
	v_mfma_f32_16x16x32_bf16 v[16:19], v[148:151], v[124:127], v[16:19]
	v_add_co_u32_e32 v52, vcc, s59, v164
	s_waitcnt vmcnt(5)
	ds_write_b128 v109, v[64:67] offset:40960
	s_nop 0
	v_addc_co_u32_e32 v53, vcc, 0, v165, vcc
	v_lshl_add_u64 v[64:65], v[102:103], 0, s[92:93]
	v_add_co_u32_e32 v66, vcc, s11, v64
	s_waitcnt lgkmcnt(7)
	v_mfma_f32_16x16x32_bf16 v[12:15], v[136:139], v[132:135], v[12:15]
	v_addc_co_u32_e32 v67, vcc, 0, v65, vcc
	v_mfma_f32_16x16x32_bf16 v[8:11], v[140:143], v[132:135], v[8:11]
	v_mfma_f32_16x16x32_bf16 v[4:7], v[144:147], v[132:135], v[4:7]
	v_mfma_f32_16x16x32_bf16 v[0:3], v[148:151], v[132:135], v[0:3]
	s_waitcnt vmcnt(4)
	ds_write_b128 v109, v[72:75] offset:45056
	s_waitcnt lgkmcnt(7)
	v_mfma_f32_16x16x32_bf16 v[52:55], v[194:197], v[152:155], v[92:95]
	v_mfma_f32_16x16x32_bf16 v[60:63], v[198:201], v[152:155], v[88:91]
	v_mfma_f32_16x16x32_bf16 v[56:59], v[202:205], v[152:155], v[56:59]
	v_mfma_f32_16x16x32_bf16 v[48:51], v[206:209], v[152:155], v[48:51]
	s_waitcnt vmcnt(3)
	ds_write_b128 v109, v[68:71] offset:49152
	s_waitcnt lgkmcnt(7)
	v_mfma_f32_16x16x32_bf16 v[44:47], v[194:197], v[156:159], v[44:47]
	v_mfma_f32_16x16x32_bf16 v[40:43], v[198:201], v[156:159], v[40:43]
	v_mfma_f32_16x16x32_bf16 v[36:39], v[202:205], v[156:159], v[36:39]
	v_mfma_f32_16x16x32_bf16 v[32:35], v[206:209], v[156:159], v[32:35]
	v_add_co_u32_e32 v66, vcc, s33, v64
	s_waitcnt vmcnt(2)
	ds_write_b128 v109, v[76:79] offset:53248
	v_addc_co_u32_e32 v67, vcc, 0, v65, vcc
	v_add_co_u32_e32 v64, vcc, s59, v64
	s_waitcnt lgkmcnt(7)
	v_mfma_f32_16x16x32_bf16 v[28:31], v[194:197], v[160:163], v[28:31]
	v_addc_co_u32_e32 v65, vcc, 0, v65, vcc
	v_mfma_f32_16x16x32_bf16 v[24:27], v[198:201], v[160:163], v[24:27]
	v_mfma_f32_16x16x32_bf16 v[20:23], v[202:205], v[160:163], v[20:23]
	v_mfma_f32_16x16x32_bf16 v[16:19], v[206:209], v[160:163], v[16:19]
	s_waitcnt vmcnt(1)
	ds_write_b128 v109, v[80:83] offset:57344
	s_waitcnt lgkmcnt(7)
	v_mfma_f32_16x16x32_bf16 v[12:15], v[194:197], v[190:193], v[12:15]
	v_mfma_f32_16x16x32_bf16 v[8:11], v[198:201], v[190:193], v[8:11]
	v_mfma_f32_16x16x32_bf16 v[4:7], v[202:205], v[190:193], v[4:7]
	v_mfma_f32_16x16x32_bf16 v[0:3], v[206:209], v[190:193], v[0:3]
	s_waitcnt vmcnt(0)
	ds_write_b128 v109, v[84:87] offset:61440
	s_waitcnt lgkmcnt(0)
	s_barrier
	ds_read_b128 v[84:87], v111 offset:51200
	ds_read_b128 v[80:83], v111 offset:49152
	ds_read_b128 v[88:91], v111 offset:53248
	ds_read_b128 v[92:95], v111 offset:55296
	ds_read_b128 v[64:67], v110 offset:32768
	s_min_u32 s44, s29, 12
	s_lshl_b32 s92, s44, 7
	ds_read_b128 v[68:71], v110 offset:34816
	v_lshl_add_u64 v[164:165], v[100:101], 0, s[92:93]
	ds_read_b128 v[72:75], v110 offset:36864
	ds_read_b128 v[76:79], v110 offset:38912
	ds_read_b128 v[152:155], v112 offset:32768
	ds_read_b128 v[156:159], v112 offset:34816
	ds_read_b128 v[160:163], v112 offset:36864
	ds_read_b128 v[190:193], v112 offset:38912
	ds_read_b128 v[194:197], v113 offset:49152
	ds_read_b128 v[198:201], v113 offset:51200
	ds_read_b128 v[202:205], v113 offset:53248
	ds_read_b128 v[206:209], v113 offset:55296
	s_waitcnt lgkmcnt(11)
	v_mfma_f32_16x16x32_bf16 v[214:217], v[84:87], v[64:67], v[60:63]
	v_mfma_f32_16x16x32_bf16 v[210:213], v[80:83], v[64:67], v[52:55]
	s_nop 1
	v_add_co_u32_e32 v60, vcc, s11, v164
	s_nop 1
	v_addc_co_u32_e32 v61, vcc, 0, v165, vcc
	v_mfma_f32_16x16x32_bf16 v[56:59], v[88:91], v[64:67], v[56:59]
	v_mfma_f32_16x16x32_bf16 v[48:51], v[92:95], v[64:67], v[48:51]
	v_add_co_u32_e32 v64, vcc, s33, v164
	s_nop 0
	v_addc_co_u32_e32 v65, vcc, 0, v165, vcc
	s_waitcnt lgkmcnt(10)
	v_mfma_f32_16x16x32_bf16 v[44:47], v[80:83], v[68:71], v[44:47]
	v_mfma_f32_16x16x32_bf16 v[40:43], v[84:87], v[68:71], v[40:43]
	v_mfma_f32_16x16x32_bf16 v[36:39], v[88:91], v[68:71], v[36:39]
	v_mfma_f32_16x16x32_bf16 v[32:35], v[92:95], v[68:71], v[32:35]
	v_add_co_u32_e32 v68, vcc, s59, v164
	s_waitcnt lgkmcnt(9)
	v_mfma_f32_16x16x32_bf16 v[28:31], v[80:83], v[72:75], v[28:31]
	v_addc_co_u32_e32 v69, vcc, 0, v165, vcc
	v_mfma_f32_16x16x32_bf16 v[24:27], v[84:87], v[72:75], v[24:27]
	v_mfma_f32_16x16x32_bf16 v[20:23], v[88:91], v[72:75], v[20:23]
	v_mfma_f32_16x16x32_bf16 v[16:19], v[92:95], v[72:75], v[16:19]
	s_waitcnt lgkmcnt(8)
	v_mfma_f32_16x16x32_bf16 v[8:11], v[84:87], v[76:79], v[8:11]
	v_lshl_add_u64 v[84:85], v[102:103], 0, s[92:93]
	v_mfma_f32_16x16x32_bf16 v[12:15], v[80:83], v[76:79], v[12:15]
	v_mfma_f32_16x16x32_bf16 v[4:7], v[88:91], v[76:79], v[4:7]
	v_mfma_f32_16x16x32_bf16 v[0:3], v[92:95], v[76:79], v[0:3]
	v_add_co_u32_e32 v76, vcc, s11, v84
	s_nop 0
	v_addc_co_u32_e32 v77, vcc, 0, v85, vcc
	v_add_co_u32_e32 v80, vcc, s33, v84
	v_addc_co_u32_e32 v81, vcc, 0, v85, vcc
	s_waitcnt lgkmcnt(3)
	v_mfma_f32_16x16x32_bf16 v[92:95], v[194:197], v[152:155], v[210:213]
	s_waitcnt lgkmcnt(2)
	v_mfma_f32_16x16x32_bf16 v[88:91], v[198:201], v[152:155], v[214:217]
	s_waitcnt lgkmcnt(1)
	v_mfma_f32_16x16x32_bf16 v[56:59], v[202:205], v[152:155], v[56:59]
	s_waitcnt lgkmcnt(0)
	v_mfma_f32_16x16x32_bf16 v[48:51], v[206:209], v[152:155], v[48:51]
	v_add_co_u32_e32 v84, vcc, s59, v84
	v_addc_co_u32_e32 v85, vcc, 0, v85, vcc
	v_mfma_f32_16x16x32_bf16 v[44:47], v[194:197], v[156:159], v[44:47]
	v_mfma_f32_16x16x32_bf16 v[40:43], v[198:201], v[156:159], v[40:43]
	v_mfma_f32_16x16x32_bf16 v[36:39], v[202:205], v[156:159], v[36:39]
	v_mfma_f32_16x16x32_bf16 v[32:35], v[206:209], v[156:159], v[32:35]
	v_mfma_f32_16x16x32_bf16 v[28:31], v[194:197], v[160:163], v[28:31]
	v_mfma_f32_16x16x32_bf16 v[24:27], v[198:201], v[160:163], v[24:27]
	v_mfma_f32_16x16x32_bf16 v[20:23], v[202:205], v[160:163], v[20:23]
	v_mfma_f32_16x16x32_bf16 v[16:19], v[206:209], v[160:163], v[16:19]
	v_mfma_f32_16x16x32_bf16 v[12:15], v[194:197], v[190:193], v[12:15]
	v_mfma_f32_16x16x32_bf16 v[8:11], v[198:201], v[190:193], v[8:11]
	v_mfma_f32_16x16x32_bf16 v[4:7], v[202:205], v[190:193], v[4:7]
	v_mfma_f32_16x16x32_bf16 v[0:3], v[206:209], v[190:193], v[0:3]
	s_mov_b32 s44, s29
	s_waitcnt lgkmcnt(0)
	s_barrier
	s_waitcnt vmcnt(5)
	v_add_u32_e32 v64, s24, v108
	v_add_u32_e32 v52, 0xffffe000, v64
	v_or_b32_e32 v62, v64, v107
	v_lshrrev_b32_e32 v52, 10, v52
	s_movk_i32 s16, 0x1800
	v_mad_u32_u24 v52, v52, s16, s16
	v_cmp_lt_i32_e32 vcc, s13, v62
	v_or_b32_e32 v65, s25, v114
	v_or_b32_e32 v54, v65, v115
	v_cndmask_b32_e32 v52, 0, v52, vcc
	v_ashrrev_i32_e32 v53, 31, v52
	s_waitcnt vmcnt(4)
	v_lshlrev_b64 v[74:75], 2, v[52:53]
	v_ashrrev_i32_e32 v55, 31, v54
	v_ashrrev_i32_e32 v63, 31, v62
	v_lshl_add_u64 v[52:53], s[40:41], 0, v[74:75]
	v_lshlrev_b64 v[60:61], 2, v[54:55]
	v_readlane_b32 s16, v250, 15
	s_waitcnt vmcnt(1)
	v_lshl_add_u64 v[82:83], v[52:53], 0, v[60:61]
	v_lshlrev_b64 v[52:53], 12, v[62:63]
	v_readlane_b32 s17, v250, 16
	v_lshl_add_u64 v[74:75], s[42:43], 0, v[74:75]
	s_waitcnt vmcnt(0)
	v_lshl_add_u64 v[86:87], v[74:75], 0, v[60:61]
	v_lshl_add_u64 v[52:53], s[16:17], 0, v[52:53]
	v_lshl_add_u64 v[84:85], v[52:53], 0, v[60:61]
	global_load_dwordx4 v[66:69], v[82:83], off
	global_load_dwordx4 v[70:73], v[84:85], off
	v_lshl_add_u64 v[52:53], s[0:1], 0, v[60:61]
	v_readlane_b32 s16, v250, 21
	v_lshlrev_b64 v[78:79], 11, v[62:63]
	v_readlane_b32 s17, v250, 22
	s_waitcnt vmcnt(0)
	v_pk_fma_f32 v[68:69], v[94:95], v[68:69], v[72:73]
	v_pk_fma_f32 v[66:67], v[92:93], v[66:67], v[70:71]
	global_store_dwordx4 v[84:85], v[66:69], off
	global_load_dwordx4 v[70:73], v[52:53], off
	global_load_dwordx4 v[74:77], v[86:87], off
	v_lshl_add_u64 v[78:79], s[16:17], 0, v[78:79]
	v_lshl_add_u64 v[92:93], v[54:55], 1, v[78:79]
	s_mov_b32 s16, 0xa000
	s_waitcnt vmcnt(1)
	v_pk_mul_f32 v[72:73], v[68:69], v[72:73]
	v_pk_mul_f32 v[70:71], v[66:67], v[70:71]
	s_waitcnt vmcnt(0)
	v_pk_add_f32 v[76:77], v[76:77], 1.0 op_sel_hi:[1,0]
	v_pk_add_f32 v[74:75], v[74:75], 1.0 op_sel_hi:[1,0]
	v_pk_mul_f32 v[72:73], v[72:73], v[76:77]
	v_pk_mul_f32 v[70:71], v[70:71], v[74:75]
	v_and_b32_sdwa v76, v73, v170 dst_sel:DWORD dst_unused:UNUSED_PAD src0_sel:WORD_1 src1_sel:DWORD
	v_and_b32_sdwa v77, v71, v170 dst_sel:DWORD dst_unused:UNUSED_PAD src0_sel:WORD_1 src1_sel:DWORD
	v_and_b32_sdwa v74, v72, v170 dst_sel:DWORD dst_unused:UNUSED_PAD src0_sel:WORD_1 src1_sel:DWORD
	v_and_b32_sdwa v75, v70, v170 dst_sel:DWORD dst_unused:UNUSED_PAD src0_sel:WORD_1 src1_sel:DWORD
	v_add3_u32 v73, v73, v76, s56
	v_add3_u32 v71, v71, v77, s56
	v_add3_u32 v70, v70, v75, s56
	v_add3_u32 v72, v72, v74, s56
	v_and_b32_e32 v73, 0xffff0000, v73
	v_and_b32_e32 v74, 0xffff0000, v71
	v_or_b32_sdwa v71, v73, v72 dst_sel:DWORD dst_unused:UNUSED_PAD src0_sel:DWORD src1_sel:WORD_1
	v_or_b32_sdwa v70, v74, v70 dst_sel:DWORD dst_unused:UNUSED_PAD src0_sel:DWORD src1_sel:WORD_1
	global_store_dwordx2 v[92:93], v[70:71], off
	global_load_dwordx4 v[70:73], v[82:83], off offset:64
	s_nop 0
	global_load_dwordx4 v[74:77], v[84:85], off offset:64
	s_waitcnt vmcnt(0)
	v_pk_fma_f32 v[72:73], v[90:91], v[72:73], v[76:77]
	v_pk_fma_f32 v[70:71], v[88:89], v[70:71], v[74:75]
	global_store_dwordx4 v[84:85], v[70:73], off offset:64
	global_load_dwordx4 v[74:77], v[52:53], off offset:64
	global_load_dwordx4 v[78:81], v[86:87], off offset:64
	s_waitcnt vmcnt(1)
	v_pk_mul_f32 v[76:77], v[72:73], v[76:77]
	v_pk_mul_f32 v[74:75], v[70:71], v[74:75]
	s_waitcnt vmcnt(0)
	v_pk_add_f32 v[80:81], v[80:81], 1.0 op_sel_hi:[1,0]
	v_pk_add_f32 v[78:79], v[78:79], 1.0 op_sel_hi:[1,0]
	v_pk_mul_f32 v[76:77], v[76:77], v[80:81]
	v_pk_mul_f32 v[74:75], v[74:75], v[78:79]
	v_and_b32_sdwa v80, v77, v170 dst_sel:DWORD dst_unused:UNUSED_PAD src0_sel:WORD_1 src1_sel:DWORD
	v_and_b32_sdwa v81, v75, v170 dst_sel:DWORD dst_unused:UNUSED_PAD src0_sel:WORD_1 src1_sel:DWORD
	v_and_b32_sdwa v78, v76, v170 dst_sel:DWORD dst_unused:UNUSED_PAD src0_sel:WORD_1 src1_sel:DWORD
	v_and_b32_sdwa v79, v74, v170 dst_sel:DWORD dst_unused:UNUSED_PAD src0_sel:WORD_1 src1_sel:DWORD
	v_add3_u32 v77, v77, v80, s56
	v_add3_u32 v75, v75, v81, s56
	v_add3_u32 v74, v74, v79, s56
	v_add3_u32 v76, v76, v78, s56
	v_and_b32_e32 v77, 0xffff0000, v77
	v_and_b32_e32 v78, 0xffff0000, v75
	v_or_b32_sdwa v75, v77, v76 dst_sel:DWORD dst_unused:UNUSED_PAD src0_sel:DWORD src1_sel:WORD_1
	v_or_b32_sdwa v74, v78, v74 dst_sel:DWORD dst_unused:UNUSED_PAD src0_sel:DWORD src1_sel:WORD_1
	global_store_dwordx2 v[92:93], v[74:75], off offset:32
	global_load_dwordx4 v[74:77], v[82:83], off offset:128
	s_nop 0
	global_load_dwordx4 v[78:81], v[84:85], off offset:128
	s_waitcnt vmcnt(0)
	v_pk_fma_f32 v[58:59], v[58:59], v[76:77], v[80:81]
	v_pk_fma_f32 v[56:57], v[56:57], v[74:75], v[78:79]
	global_store_dwordx4 v[84:85], v[56:59], off offset:128
	global_load_dwordx4 v[74:77], v[52:53], off offset:128
	global_load_dwordx4 v[78:81], v[86:87], off offset:128
	s_waitcnt vmcnt(1)
	v_pk_mul_f32 v[76:77], v[58:59], v[76:77]
	v_pk_mul_f32 v[74:75], v[56:57], v[74:75]
	s_waitcnt vmcnt(0)
	v_pk_add_f32 v[80:81], v[80:81], 1.0 op_sel_hi:[1,0]
	v_pk_add_f32 v[78:79], v[78:79], 1.0 op_sel_hi:[1,0]
	v_pk_mul_f32 v[76:77], v[76:77], v[80:81]
	v_pk_mul_f32 v[74:75], v[74:75], v[78:79]
	v_and_b32_sdwa v80, v77, v170 dst_sel:DWORD dst_unused:UNUSED_PAD src0_sel:WORD_1 src1_sel:DWORD
	v_and_b32_sdwa v81, v75, v170 dst_sel:DWORD dst_unused:UNUSED_PAD src0_sel:WORD_1 src1_sel:DWORD
	v_and_b32_sdwa v78, v76, v170 dst_sel:DWORD dst_unused:UNUSED_PAD src0_sel:WORD_1 src1_sel:DWORD
	v_and_b32_sdwa v79, v74, v170 dst_sel:DWORD dst_unused:UNUSED_PAD src0_sel:WORD_1 src1_sel:DWORD
	v_add3_u32 v77, v77, v80, s56
	v_add3_u32 v75, v75, v81, s56
	v_add3_u32 v74, v74, v79, s56
	v_add3_u32 v76, v76, v78, s56
	v_and_b32_e32 v77, 0xffff0000, v77
	v_and_b32_e32 v78, 0xffff0000, v75
	v_or_b32_sdwa v75, v77, v76 dst_sel:DWORD dst_unused:UNUSED_PAD src0_sel:DWORD src1_sel:WORD_1
	v_or_b32_sdwa v74, v78, v74 dst_sel:DWORD dst_unused:UNUSED_PAD src0_sel:DWORD src1_sel:WORD_1
	global_store_dwordx2 v[92:93], v[74:75], off offset:64
	global_load_dwordx4 v[74:77], v[82:83], off offset:192
	s_nop 0
	global_load_dwordx4 v[78:81], v[84:85], off offset:192
	s_waitcnt vmcnt(0)
	v_pk_fma_f32 v[76:77], v[50:51], v[76:77], v[80:81]
	v_pk_fma_f32 v[74:75], v[48:49], v[74:75], v[78:79]
	global_store_dwordx4 v[84:85], v[74:77], off offset:192
	global_load_dwordx4 v[78:81], v[52:53], off offset:192
	s_nop 0
	global_load_dwordx4 v[82:85], v[86:87], off offset:192
	v_mul_f32_e32 v48, v67, v67
	v_mul_f32_e32 v49, v71, v71
	v_fmac_f32_e32 v48, v66, v66
	v_fmac_f32_e32 v49, v70, v70
	v_fmac_f32_e32 v48, v68, v68
	v_fmac_f32_e32 v49, v72, v72
	v_fmac_f32_e32 v48, v69, v69
	v_fmac_f32_e32 v49, v73, v73
	v_add_f32_e32 v48, v48, v49
	v_mul_f32_e32 v49, v57, v57
	v_fmac_f32_e32 v49, v56, v56
	v_fmac_f32_e32 v49, v58, v58
	v_fmac_f32_e32 v49, v59, v59
	v_add_f32_e32 v48, v48, v49
	v_mul_f32_e32 v49, v75, v75
	v_fmac_f32_e32 v49, v74, v74
	v_fmac_f32_e32 v49, v76, v76
	v_fmac_f32_e32 v49, v77, v77
	v_add_f32_e32 v50, v48, v49
	ds_bpermute_b32 v51, v105, v50
	v_lshrrev_b32_e32 v48, 6, v65
	v_mul_lo_u32 v48, v48, s16
	v_ashrrev_i32_e32 v49, 31, v48
	v_lshl_add_u64 v[48:49], s[38:39], 0, v[48:49]
	s_waitcnt lgkmcnt(0)
	v_add_f32_e32 v50, v50, v51
	ds_bpermute_b32 v51, v104, v50
	v_lshl_add_u64 v[48:49], v[62:63], 2, v[48:49]
	s_waitcnt vmcnt(1)
	v_pk_mul_f32 v[56:57], v[76:77], v[80:81]
	v_pk_mul_f32 v[58:59], v[74:75], v[78:79]
	s_waitcnt vmcnt(0)
	v_pk_add_f32 v[66:67], v[84:85], 1.0 op_sel_hi:[1,0]
	v_pk_add_f32 v[68:69], v[82:83], 1.0 op_sel_hi:[1,0]
	v_pk_mul_f32 v[56:57], v[56:57], v[66:67]
	v_pk_mul_f32 v[58:59], v[58:59], v[68:69]
	v_cvt_pk_bf16_f32 v57, v56, v57
	v_cvt_pk_bf16_f32 v56, v58, v59
	global_store_dwordx2 v[92:93], v[56:57], off offset:96
	s_and_saveexec_b64 s[24:25], s[36:37]
	s_cbranch_execz .LBB0_409
	s_waitcnt lgkmcnt(0)
	v_add_f32_e32 v50, v50, v51
	global_store_dword v[48:49], v50, off

.LBB0_422:
	s_or_b64 exec, exec, s[2:3]
	v_add_u32_e32 v13, 0xffffe010, v18
	s_waitcnt lgkmcnt(0)
	v_lshl_add_u64 v[14:15], s[0:1], 0, v[128:129]
	v_or_b32_e32 v12, 16, v12
	v_lshrrev_b32_e32 v13, 10, v13
	s_movk_i32 s0, 0x1800
	v_mad_u32_u24 v13, v13, s0, s0
	v_cmp_lt_i32_e64 s[0:1], s13, v12
	s_nop 1
	v_cndmask_b32_e64 v18, 0, v13, s[0:1]
	v_ashrrev_i32_e32 v19, 31, v18
	v_lshlrev_b64 v[34:35], 2, v[18:19]
	v_ashrrev_i32_e32 v13, 31, v12
	v_lshl_add_u64 v[18:19], s[40:41], 0, v[34:35]
	v_readlane_b32 s0, v250, 15
	v_lshl_add_u64 v[20:21], v[18:19], 0, v[128:129]
	v_lshlrev_b64 v[18:19], 12, v[12:13]
	v_readlane_b32 s1, v250, 16
	s_nop 0
	v_lshl_add_u64 v[18:19], s[0:1], 0, v[18:19]
	v_lshl_add_u64 v[18:19], v[18:19], 0, v[128:129]
	v_readlane_b32 s0, v250, 21
	v_readlane_b32 s1, v250, 22
	s_waitcnt vmcnt(16)
	v_pk_fma_f32 v[28:29], v[38:39], v[74:75], v[212:213]
	v_pk_fma_f32 v[26:27], v[36:37], v[72:73], v[210:211]
	v_lshl_add_u64 v[22:23], s[42:43], 0, v[34:35]
	global_store_dwordx4 v[18:19], v[26:29], off
	v_lshl_add_u64 v[22:23], v[22:23], 0, v[128:129]
	v_mul_f32_e32 v38, v27, v27
	v_fmac_f32_e32 v38, v26, v26
	v_fmac_f32_e32 v38, v28, v28
	v_fmac_f32_e32 v38, v29, v29
	v_pk_mul_f32 v[24:25], v[28:29], v[142:143]
	v_pk_add_f32 v[28:29], v[158:159], 1.0 op_sel_hi:[1,0]
	v_pk_mul_f32 v[26:27], v[26:27], v[140:141]
	v_pk_add_f32 v[30:31], v[156:157], 1.0 op_sel_hi:[1,0]
	v_pk_mul_f32 v[24:25], v[24:25], v[28:29]
	v_lshlrev_b64 v[28:29], 11, v[12:13]
	v_pk_mul_f32 v[26:27], v[26:27], v[30:31]
	v_lshl_add_u64 v[28:29], s[0:1], 0, v[28:29]
	v_lshl_add_u64 v[16:17], v[28:29], 0, v[16:17]
	v_cvt_pk_bf16_f32 v25, v24, v25
	v_cvt_pk_bf16_f32 v24, v26, v27
	global_store_dwordx2 v[16:17], v[24:25], off
	s_nop 0
	v_pk_fma_f32 v[8:9], v[8:9], v[80:81], v[214:215]
	s_nop 0
	v_mul_f32_e32 v24, v9, v9
	v_pk_fma_f32 v[10:11], v[10:11], v[82:83], v[216:217]
	v_fmac_f32_e32 v24, v8, v8
	v_fmac_f32_e32 v24, v10, v10
	global_store_dwordx4 v[18:19], v[8:11], off offset:64
	v_fmac_f32_e32 v24, v11, v11
	v_add_f32_e32 v32, v38, v24
	v_pk_mul_f32 v[10:11], v[10:11], v[146:147]
	v_pk_mul_f32 v[8:9], v[8:9], v[144:145]
	v_pk_add_f32 v[24:25], v[162:163], 1.0 op_sel_hi:[1,0]
	v_pk_add_f32 v[26:27], v[160:161], 1.0 op_sel_hi:[1,0]
	v_pk_mul_f32 v[10:11], v[10:11], v[24:25]
	v_pk_mul_f32 v[8:9], v[8:9], v[26:27]
	v_and_b32_sdwa v24, v10, v170 dst_sel:DWORD dst_unused:UNUSED_PAD src0_sel:WORD_1 src1_sel:DWORD
	v_and_b32_sdwa v25, v8, v170 dst_sel:DWORD dst_unused:UNUSED_PAD src0_sel:WORD_1 src1_sel:DWORD
	v_add3_u32 v8, v8, v25, s56
	v_add3_u32 v10, v10, v24, s56
	v_and_b32_sdwa v24, v11, v170 dst_sel:DWORD dst_unused:UNUSED_PAD src0_sel:WORD_1 src1_sel:DWORD
	v_and_b32_sdwa v25, v9, v170 dst_sel:DWORD dst_unused:UNUSED_PAD src0_sel:WORD_1 src1_sel:DWORD
	v_add3_u32 v11, v11, v24, s56
	v_add3_u32 v9, v9, v25, s56
	v_and_b32_e32 v11, 0xffff0000, v11
	v_and_b32_e32 v24, 0xffff0000, v9
	v_or_b32_sdwa v9, v11, v10 dst_sel:DWORD dst_unused:UNUSED_PAD src0_sel:DWORD src1_sel:WORD_1
	v_or_b32_sdwa v8, v24, v8 dst_sel:DWORD dst_unused:UNUSED_PAD src0_sel:DWORD src1_sel:WORD_1
	global_store_dwordx2 v[16:17], v[8:9], off offset:32
	s_nop 0
	v_pk_fma_f32 v[4:5], v[4:5], v[88:89], v[218:219]
	s_nop 0
	v_mul_f32_e32 v8, v5, v5
	v_pk_fma_f32 v[6:7], v[6:7], v[90:91], v[220:221]
	v_fmac_f32_e32 v8, v4, v4
	v_fmac_f32_e32 v8, v6, v6
	global_store_dwordx4 v[18:19], v[4:7], off offset:128
	v_fmac_f32_e32 v8, v7, v7
	v_add_f32_e32 v28, v32, v8
	v_pk_mul_f32 v[6:7], v[6:7], v[150:151]
	v_pk_mul_f32 v[4:5], v[4:5], v[148:149]
	v_pk_add_f32 v[8:9], v[182:183], 1.0 op_sel_hi:[1,0]
	v_pk_add_f32 v[10:11], v[180:181], 1.0 op_sel_hi:[1,0]
	v_pk_mul_f32 v[6:7], v[6:7], v[8:9]
	v_pk_mul_f32 v[4:5], v[4:5], v[10:11]
	v_and_b32_sdwa v8, v6, v170 dst_sel:DWORD dst_unused:UNUSED_PAD src0_sel:WORD_1 src1_sel:DWORD
	v_and_b32_sdwa v9, v4, v170 dst_sel:DWORD dst_unused:UNUSED_PAD src0_sel:WORD_1 src1_sel:DWORD
	v_add3_u32 v4, v4, v9, s56
	v_add3_u32 v6, v6, v8, s56
	v_and_b32_sdwa v8, v7, v170 dst_sel:DWORD dst_unused:UNUSED_PAD src0_sel:WORD_1 src1_sel:DWORD
	v_and_b32_sdwa v9, v5, v170 dst_sel:DWORD dst_unused:UNUSED_PAD src0_sel:WORD_1 src1_sel:DWORD
	v_add3_u32 v7, v7, v8, s56
	v_add3_u32 v5, v5, v9, s56
	v_and_b32_e32 v7, 0xffff0000, v7
	v_and_b32_e32 v8, 0xffff0000, v5
	v_or_b32_sdwa v5, v7, v6 dst_sel:DWORD dst_unused:UNUSED_PAD src0_sel:DWORD src1_sel:WORD_1
	v_or_b32_sdwa v4, v8, v4 dst_sel:DWORD dst_unused:UNUSED_PAD src0_sel:DWORD src1_sel:WORD_1
	global_store_dwordx2 v[16:17], v[4:5], off offset:64
	s_nop 0
	v_pk_fma_f32 v[0:1], v[0:1], v[136:137], v[222:223]
	s_nop 0
	v_mul_f32_e32 v4, v1, v1
	v_pk_fma_f32 v[2:3], v[2:3], v[138:139], v[224:225]
	v_fmac_f32_e32 v4, v0, v0
	v_fmac_f32_e32 v4, v2, v2
	global_store_dwordx4 v[18:19], v[0:3], off offset:192
	v_fmac_f32_e32 v4, v3, v3
	v_add_f32_e32 v18, v28, v4
	v_pk_mul_f32 v[2:3], v[2:3], v[154:155]
	v_pk_mul_f32 v[0:1], v[0:1], v[152:153]
	v_pk_add_f32 v[4:5], v[192:193], 1.0 op_sel_hi:[1,0]
	v_pk_add_f32 v[6:7], v[190:191], 1.0 op_sel_hi:[1,0]
	v_pk_mul_f32 v[2:3], v[2:3], v[4:5]
	v_pk_mul_f32 v[0:1], v[0:1], v[6:7]
	v_and_b32_sdwa v4, v2, v170 dst_sel:DWORD dst_unused:UNUSED_PAD src0_sel:WORD_1 src1_sel:DWORD
	v_and_b32_sdwa v5, v0, v170 dst_sel:DWORD dst_unused:UNUSED_PAD src0_sel:WORD_1 src1_sel:DWORD
	v_add3_u32 v0, v0, v5, s56
	v_add3_u32 v2, v2, v4, s56
	v_and_b32_sdwa v4, v3, v170 dst_sel:DWORD dst_unused:UNUSED_PAD src0_sel:WORD_1 src1_sel:DWORD
	v_and_b32_sdwa v5, v1, v170 dst_sel:DWORD dst_unused:UNUSED_PAD src0_sel:WORD_1 src1_sel:DWORD
	v_add3_u32 v3, v3, v4, s56
	v_add3_u32 v1, v1, v5, s56
	v_and_b32_e32 v3, 0xffff0000, v3
	v_and_b32_e32 v4, 0xffff0000, v1
	v_or_b32_sdwa v1, v3, v2 dst_sel:DWORD dst_unused:UNUSED_PAD src0_sel:DWORD src1_sel:WORD_1
	v_or_b32_sdwa v0, v4, v0 dst_sel:DWORD dst_unused:UNUSED_PAD src0_sel:DWORD src1_sel:WORD_1
	global_store_dwordx2 v[16:17], v[0:1], off offset:96
	ds_bpermute_b32 v0, v105, v18
	s_waitcnt lgkmcnt(0)
	v_add_f32_e32 v0, v18, v0
	ds_bpermute_b32 v1, v104, v0
	s_and_saveexec_b64 s[0:1], vcc
	s_movk_i32 s89, 0xff
	s_cbranch_execz .LBB0_424
	v_readlane_b32 s2, v253, 20
	s_add_u32 s2, s38, s2
	s_addc_u32 s3, s39, 0
	v_lshl_add_u64 v[2:3], v[12:13], 2, s[2:3]
	s_waitcnt lgkmcnt(0)
	v_add_f32_e32 v0, v0, v1
	global_store_dword v[2:3], v0, off

.LBB0_442:
	ds_read_b128 v[82:85], v77
	ds_read_b128 v[86:89], v77 offset:2048
	ds_read_b128 v[94:97], v78
	ds_read_b128 v[102:105], v78 offset:2048
	s_mov_b32 s2, 0x7060302
	s_waitcnt lgkmcnt(3)
	v_mfma_f32_16x16x32_bf16 v[90:93], v[82:85], v[28:31], 0
	s_cmp_lg_u32 s24, 8
	s_waitcnt lgkmcnt(2)
	v_mfma_f32_16x16x32_bf16 v[98:101], v[86:89], v[28:31], 0
	s_waitcnt lgkmcnt(1)
	v_mfma_f32_16x16x32_bf16 v[90:93], v[94:97], v[32:35], v[90:93]
	s_waitcnt lgkmcnt(0)
	v_mfma_f32_16x16x32_bf16 v[98:101], v[102:105], v[32:35], v[98:101]
	v_mfma_f32_16x16x32_bf16 v[82:85], v[82:85], v[36:39], 0
	s_nop 4
	v_max_f32_e32 v59, v91, v91
	v_max_f32_e32 v61, v90, v90
	v_max_f32_e32 v66, v93, v93
	v_max_f32_e32 v67, v92, v92
	v_max_f32_e32 v106, v101, v101
	v_max_f32_e32 v107, v100, v100
	v_max_f32_e32 v59, v61, v59
	v_max_f32_e32 v61, v67, v66
	v_max_f32_e32 v66, v107, v106
	v_max3_f32 v66, v98, v99, v66
	v_max3_f32 v59, v59, v61, v66
	v_mov_b32_e32 v66, v59
	v_mov_b32_e32 v61, v59
	s_nop 1
	v_permlane16_swap_b32_e32 v66, v61
	v_max_f32_e32 v61, v66, v61
	v_mfma_f32_16x16x32_bf16 v[86:89], v[86:89], v[36:39], 0
	v_add_u32_e32 v67, 0x1000, v79
	ds_read2_b64 v[106:109], v67 offset1:4
	s_waitcnt lgkmcnt(1)
	v_max_f32_e32 v61, v61, v61
	v_max_f32_e32 v59, v59, v61
	v_mov_b32_e32 v66, v59
	v_mov_b32_e32 v61, v59
	s_nop 1
	v_permlane32_swap_b32_e32 v66, v61
	v_max_f32_e32 v61, v66, v61
	v_mfma_f32_16x16x32_bf16 v[82:85], v[94:97], v[44:47], v[82:85]
	s_waitcnt lgkmcnt(0)
	v_max3_f32 v59, v81, v59, v61
	v_sub_f32_e32 v61, v81, v59
	v_sub_f32_e32 v81, v91, v59
	v_mul_f32_e32 v81, 0x3fb8aa3b, v81
	v_exp_f32_e32 v110, v81
	v_sub_f32_e32 v81, v93, v59
	v_mul_f32_e32 v81, 0x3fb8aa3b, v81
	v_exp_f32_e32 v114, v81
	v_sub_f32_e32 v81, v98, v59
	v_mul_f32_e32 v81, 0x3fb8aa3b, v81
	v_exp_f32_e32 v116, v81
	v_sub_f32_e32 v81, v99, v59
	v_mul_f32_e32 v81, 0x3fb8aa3b, v81
	v_exp_f32_e32 v118, v81
	v_sub_f32_e32 v81, v101, v59
	v_mul_f32_e32 v81, 0x3fb8aa3b, v81
	v_sub_f32_e32 v66, v90, v59
	v_sub_f32_e32 v90, v92, v59
	v_exp_f32_e32 v120, v81
	v_sub_f32_e32 v81, v100, v59
	v_mul_f32_e32 v66, 0x3fb8aa3b, v66
	v_mul_f32_e32 v90, 0x3fb8aa3b, v90
	v_mul_f32_e32 v81, 0x3fb8aa3b, v81
	v_exp_f32_e32 v66, v66
	v_exp_f32_e32 v112, v90
	v_exp_f32_e32 v122, v81
	v_mfma_f32_16x16x32_bf16 v[86:89], v[102:105], v[44:47], v[86:89]
	v_cvt_pk_bf16_f32 v93, v122, v120
	v_cvt_pk_bf16_f32 v92, v116, v118
	v_cvt_pk_bf16_f32 v91, v112, v114
	v_cvt_pk_bf16_f32 v90, v66, v110
	v_xor_b32_e32 v98, 16, v67
	ds_read2_b64 v[98:101], v98 offset0:128 offset1:132
	v_max_f32_e32 v67, v83, v83
	v_max_f32_e32 v81, v82, v82
	v_max_f32_e32 v67, v81, v67
	v_max_f32_e32 v81, v85, v85
	v_max_f32_e32 v102, v84, v84
	v_max_f32_e32 v81, v102, v81
	v_max_f32_e32 v102, v89, v89
	v_max_f32_e32 v103, v88, v88
	v_max_f32_e32 v102, v103, v102
	v_max3_f32 v102, v86, v87, v102
	v_max3_f32 v67, v67, v81, v102
	v_mov_b32_e32 v103, v67
	v_mov_b32_e32 v81, v67
	s_nop 1
	v_permlane16_swap_b32_e32 v103, v81
	v_max_f32_e32 v81, v103, v81
	v_mul_f32_e32 v61, 0x3fb8aa3b, v61
	v_exp_f32_e32 v124, v61
	v_add_u32_e32 v61, 0x1800, v79
	ds_read2_b64 v[94:97], v61 offset0:4 offset1:0
	v_xor_b32_e32 v102, 16, v61
	ds_read2_b64 v[102:105], v102 offset0:132 offset1:128
	s_waitcnt lgkmcnt(2)
	v_max_f32_e32 v61, v81, v81
	v_max_f32_e32 v61, v67, v61
	v_mov_b32_e32 v81, v61
	v_mov_b32_e32 v67, v61
	s_nop 1
	v_permlane32_swap_b32_e32 v81, v67
	v_max_f32_e32 v67, v81, v67
	v_pk_mul_f32 v[42:43], v[42:43], v[124:125] op_sel_hi:[1,0]
	v_pk_mul_f32 v[40:41], v[40:41], v[124:125] op_sel_hi:[1,0]
	v_pk_mul_f32 v[26:27], v[26:27], v[124:125] op_sel_hi:[1,0]
	v_pk_mul_f32 v[24:25], v[24:25], v[124:125] op_sel_hi:[1,0]
	s_waitcnt lgkmcnt(0)
	v_max3_f32 v61, v80, v61, v67
	v_sub_f32_e32 v81, v83, v61
	v_mul_f32_e32 v81, 0x3fb8aa3b, v81
	v_exp_f32_e32 v111, v81
	v_sub_f32_e32 v81, v84, v61
	v_sub_f32_e32 v67, v80, v61
	v_mul_f32_e32 v81, 0x3fb8aa3b, v81
	v_mul_f32_e32 v80, 0x3fb8aa3b, v67
	v_sub_f32_e32 v67, v82, v61
	v_exp_f32_e32 v113, v81
	v_sub_f32_e32 v81, v85, v61
	v_mul_f32_e32 v67, 0x3fb8aa3b, v67
	v_mul_f32_e32 v81, 0x3fb8aa3b, v81
	v_exp_f32_e32 v67, v67
	v_exp_f32_e32 v115, v81
	v_sub_f32_e32 v81, v86, v61
	v_sub_f32_e32 v82, v87, v61
	v_sub_f32_e32 v83, v88, v61
	v_sub_f32_e32 v84, v89, v61
	v_mul_f32_e32 v81, 0x3fb8aa3b, v81
	v_mul_f32_e32 v82, 0x3fb8aa3b, v82
	v_mul_f32_e32 v83, 0x3fb8aa3b, v83
	v_mul_f32_e32 v84, 0x3fb8aa3b, v84
	v_exp_f32_e32 v121, v84
	v_exp_f32_e32 v123, v83
	v_exp_f32_e32 v119, v82
	v_exp_f32_e32 v117, v81
	v_pk_mul_f32 v[22:23], v[22:23], v[124:125] op_sel_hi:[1,0]
	v_pk_mul_f32 v[20:21], v[20:21], v[124:125] op_sel_hi:[1,0]
	v_pk_mul_f32 v[18:19], v[18:19], v[124:125] op_sel_hi:[1,0]
	v_pk_mul_f32 v[16:17], v[16:17], v[124:125] op_sel_hi:[1,0]
	v_bfe_u32 v88, v67, 16, 1
	v_exp_f32_e32 v125, v80
	v_add3_u32 v88, v67, v88, s56
	v_pk_add_f32 v[66:67], v[66:67], 0 op_sel_hi:[1,0]
	v_pk_add_f32 v[66:67], v[110:111], v[66:67]
	v_bfe_u32 v85, v115, 16, 1
	v_bfe_u32 v86, v113, 16, 1
	v_bfe_u32 v87, v111, 16, 1
	v_pk_add_f32 v[66:67], v[112:113], v[66:67]
	v_add3_u32 v87, v111, v87, s56
	v_add3_u32 v86, v113, v86, s56
	v_add3_u32 v85, v115, v85, s56
	v_pk_add_f32 v[66:67], v[114:115], v[66:67]
	v_cvt_pk_bf16_f32 v83, v123, v121
	v_cvt_pk_bf16_f32 v82, v117, v119
	v_mov_b32_e32 v84, v125
	v_pk_add_f32 v[66:67], v[116:117], v[66:67]
	v_perm_b32 v81, v85, v86, s2
	v_perm_b32 v80, v87, v88, s2
	v_pk_mul_f32 v[14:15], v[14:15], v[84:85] op_sel_hi:[1,0]
	v_pk_mul_f32 v[12:13], v[12:13], v[84:85] op_sel_hi:[1,0]
	v_pk_mul_f32 v[10:11], v[10:11], v[84:85] op_sel_hi:[1,0]
	v_pk_mul_f32 v[8:9], v[8:9], v[84:85] op_sel_hi:[1,0]
	v_pk_mul_f32 v[6:7], v[6:7], v[84:85] op_sel_hi:[1,0]
	v_pk_mul_f32 v[4:5], v[4:5], v[84:85] op_sel_hi:[1,0]
	v_pk_mul_f32 v[2:3], v[2:3], v[84:85] op_sel_hi:[1,0]
	v_pk_mul_f32 v[0:1], v[0:1], v[84:85] op_sel_hi:[1,0]
	v_mfma_f32_16x16x32_bf16 v[40:43], v[106:109], v[90:93], v[40:43]
	v_add_f32_e64 v66, v118, v66
	v_add_f32_e64 v67, v119, v67
	v_pk_add_f32 v[66:67], v[122:123], v[66:67]
	v_mfma_f32_16x16x32_bf16 v[24:27], v[98:101], v[90:93], v[24:27]
	v_add_f32_e64 v66, v120, v66
	v_add_f32_e64 v67, v121, v67
	v_pk_fma_f32 v[50:51], v[50:51], v[124:125], v[66:67]
	v_mfma_f32_16x16x32_bf16 v[20:23], v[94:97], v[90:93], v[20:23]
	v_mfma_f32_16x16x32_bf16 v[16:19], v[102:105], v[90:93], v[16:19]
	v_mfma_f32_16x16x32_bf16 v[12:15], v[106:109], v[80:83], v[12:15]
	v_mfma_f32_16x16x32_bf16 v[8:11], v[98:101], v[80:83], v[8:11]
	v_mfma_f32_16x16x32_bf16 v[4:7], v[94:97], v[80:83], v[4:7]
	v_mfma_f32_16x16x32_bf16 v[0:3], v[102:105], v[80:83], v[0:3]
	v_mov_b32_e32 v81, v59
	v_mov_b32_e32 v80, v61
	s_cbranch_scc0 .LBB0_447
.LBB0_443:
	v_mov_b32_e32 v59, v129
	v_lshl_add_u64 v[62:63], v[62:63], 0, v[58:59]
	v_mov_b32_e32 v61, v129
	v_lshl_add_u64 v[82:83], v[64:65], 0, v[128:129]
	v_lshl_add_u64 v[62:63], v[62:63], 0, v[60:61]
	global_load_dwordx4 v[64:67], v[82:83], off offset:16
	s_nop 0
	global_load_dwordx4 v[82:85], v[82:83], off
	s_nop 0
	global_load_dwordx4 v[86:89], v[62:63], off offset:64
	global_load_dwordx4 v[90:93], v[62:63], off
	s_barrier
	s_mov_b32 s2, s24
	s_add_i32 s24, s24, 1
	s_cmp_lt_u32 s2, 7
	s_cselect_b32 s2, s24, s2
	s_lshl_b32 s3, s2, 5
	s_add_i32 s25, s3, 0xffffff00
	s_cmp_lt_u32 s2, 8
	s_cselect_b32 s3, s3, s25
	s_cmp_gt_u32 s2, 7
	s_waitcnt vmcnt(0)
	v_and_b32_sdwa v63, v91, v170 dst_sel:DWORD dst_unused:UNUSED_PAD src0_sel:WORD_1 src1_sel:DWORD
	v_and_b32_sdwa v61, v90, v170 dst_sel:DWORD dst_unused:UNUSED_PAD src0_sel:WORD_1 src1_sel:DWORD
	v_add3_u32 v63, v91, v63, s56
	v_add3_u32 v61, v90, v61, s56
	v_and_b32_e32 v90, 0xffff0000, v63
	v_cvt_pk_bf16_f32 v63, v92, v93
	v_or_b32_sdwa v62, v90, v61 dst_sel:DWORD dst_unused:UNUSED_PAD src0_sel:DWORD src1_sel:WORD_1
	ds_write_b64 v74, v[62:63]
	v_and_b32_sdwa v63, v87, v170 dst_sel:DWORD dst_unused:UNUSED_PAD src0_sel:WORD_1 src1_sel:DWORD
	v_and_b32_sdwa v61, v86, v170 dst_sel:DWORD dst_unused:UNUSED_PAD src0_sel:WORD_1 src1_sel:DWORD
	v_add3_u32 v63, v87, v63, s56
	v_add3_u32 v61, v86, v61, s56
	v_and_b32_e32 v86, 0xffff0000, v63
	v_cvt_pk_bf16_f32 v63, v88, v89
	v_bfe_u32 v59, v82, 16, 1
	v_or_b32_sdwa v62, v86, v61 dst_sel:DWORD dst_unused:UNUSED_PAD src0_sel:DWORD src1_sel:WORD_1
	v_add3_u32 v59, v82, v59, s56
	ds_write_b64 v75, v[62:63]
	ds_write_b16_d16_hi v76, v59 offset:4096
	v_bfe_u32 v59, v64, 16, 1
	v_add3_u32 v59, v64, v59, s56
	ds_write_b16_d16_hi v76, v59 offset:4352
	v_bfe_u32 v59, v83, 16, 1
	v_add3_u32 v59, v83, v59, s56
	ds_write_b16_d16_hi v76, v59 offset:4160
	v_bfe_u32 v59, v65, 16, 1
	v_add3_u32 v59, v65, v59, s56
	ds_write_b16_d16_hi v76, v59 offset:4416
	v_bfe_u32 v59, v84, 16, 1
	v_add3_u32 v59, v84, v59, s56
	ds_write_b16_d16_hi v76, v59 offset:4224
	v_bfe_u32 v59, v66, 16, 1
	v_add3_u32 v59, v66, v59, s56
	ds_write_b16_d16_hi v76, v59 offset:4480
	v_bfe_u32 v59, v85, 16, 1
	v_add3_u32 v59, v85, v59, s56
	ds_write_b16_d16_hi v76, v59 offset:4288
	v_bfe_u32 v59, v67, 16, 1
	v_add3_u32 v59, v67, v59, s56
	v_add_u32_e32 v66, s3, v73
	s_mov_b64 s[2:3], -1
	ds_write_b16_d16_hi v76, v59 offset:4544
	s_waitcnt lgkmcnt(0)
	s_barrier
	s_cbranch_scc0 .LBB0_445
	v_ashrrev_i32_e32 v67, 31, v66
	v_lshl_add_u64 v[62:63], v[66:67], 0, v[54:55]
	v_lshlrev_b64 v[64:65], 9, v[62:63]
	v_readlane_b32 s68, v253, 56
	v_lshl_or_b32 v64, v52, 2, v64
	v_readlane_b32 s74, v253, 62
	v_readlane_b32 s75, v253, 63
	v_readlane_b32 s76, v254, 0
	v_readlane_b32 s77, v254, 1
	v_readlane_b32 s69, v253, 57
	v_readlane_b32 s70, v253, 58
	v_readlane_b32 s71, v253, 59
	v_readlane_b32 s72, v253, 60
	v_readlane_b32 s73, v253, 61
	v_readlane_b32 s78, v254, 2
	v_readlane_b32 s79, v254, 3
	v_readlane_b32 s80, v254, 4
	v_readlane_b32 s81, v254, 5
	v_readlane_b32 s82, v254, 6
	v_readlane_b32 s83, v254, 7
	v_lshl_add_u64 v[62:63], s[74:75], 0, v[64:65]
	v_lshl_add_u64 v[64:65], s[76:77], 0, v[64:65]
	s_mov_b64 s[2:3], 0

.LBB0_447:
	ds_bpermute_b32 v30, v72, v50
	v_readlane_b32 s2, v251, 20
	v_readlane_b32 s3, v251, 21
	v_or3_b32 v31, v70, v69, v68
	v_lshlrev_b32_e32 v128, 3, v53
	s_waitcnt lgkmcnt(0)
	v_add_f32_e32 v32, v50, v30
	ds_bpermute_b32 v33, v71, v32
	v_lshl_add_u64 v[28:29], v[48:49], 1, s[2:3]
	v_lshl_add_u64 v[28:29], v[28:29], 0, v[128:129]
	v_lshlrev_b32_e32 v128, 11, v31
	v_mov_b32_e32 v30, v40
	s_waitcnt lgkmcnt(0)
	v_add_f32_e32 v31, v32, v33
	v_div_scale_f32 v32, s[2:3], v31, v31, 1.0
	v_rcp_f32_e32 v33, v32
	v_div_scale_f32 v34, vcc, 1.0, v31, 1.0
	v_lshl_add_u64 v[28:29], v[28:29], 0, v[128:129]
	v_fma_f32 v35, -v32, v33, 1.0
	v_fmac_f32_e32 v33, v35, v33
	v_mul_f32_e32 v35, v34, v33
	v_fma_f32 v36, -v32, v35, v34
	v_fmac_f32_e32 v35, v36, v33
	v_fma_f32 v32, -v32, v35, v34
	v_div_fmas_f32 v32, v32, v33, v35
	v_div_fixup_f32 v32, v32, v31, 1.0
	v_mov_b32_e32 v31, v42
	v_pk_mul_f32 v[30:31], v[30:31], v[32:33] op_sel_hi:[1,0]
	v_mov_b32_e32 v42, v41
	v_pk_mul_f32 v[34:35], v[42:43], v[32:33] op_sel_hi:[1,0]
	v_and_b32_sdwa v33, v31, v170 dst_sel:DWORD dst_unused:UNUSED_PAD src0_sel:WORD_1 src1_sel:DWORD
	v_add3_u32 v31, v31, v33, s56
	v_and_b32_sdwa v33, v35, v170 dst_sel:DWORD dst_unused:UNUSED_PAD src0_sel:WORD_1 src1_sel:DWORD
	v_add3_u32 v33, v35, v33, s56
	v_and_b32_e32 v33, 0xffff0000, v33
	v_or_b32_sdwa v31, v33, v31 dst_sel:DWORD dst_unused:UNUSED_PAD src0_sel:DWORD src1_sel:WORD_1
	v_cvt_pk_bf16_f32 v30, v30, v34
	global_store_dwordx2 v[28:29], v[30:31], off
	v_mov_b32_e32 v30, v24
	v_mov_b32_e32 v31, v26
	v_pk_mul_f32 v[30:31], v[30:31], v[32:33] op_sel_hi:[1,0]
	v_mov_b32_e32 v26, v25
	v_pk_mul_f32 v[24:25], v[26:27], v[32:33] op_sel_hi:[1,0]
	v_and_b32_sdwa v26, v31, v170 dst_sel:DWORD dst_unused:UNUSED_PAD src0_sel:WORD_1 src1_sel:DWORD
	v_and_b32_sdwa v27, v30, v170 dst_sel:DWORD dst_unused:UNUSED_PAD src0_sel:WORD_1 src1_sel:DWORD
	v_add3_u32 v27, v30, v27, s56
	v_add3_u32 v26, v31, v26, s56
	v_and_b32_sdwa v30, v25, v170 dst_sel:DWORD dst_unused:UNUSED_PAD src0_sel:WORD_1 src1_sel:DWORD
	v_and_b32_sdwa v31, v24, v170 dst_sel:DWORD dst_unused:UNUSED_PAD src0_sel:WORD_1 src1_sel:DWORD
	v_add3_u32 v25, v25, v30, s56
	v_add3_u32 v24, v24, v31, s56
	v_and_b32_e32 v25, 0xffff0000, v25
	v_and_b32_e32 v24, 0xffff0000, v24
	v_or_b32_sdwa v25, v25, v26 dst_sel:DWORD dst_unused:UNUSED_PAD src0_sel:DWORD src1_sel:WORD_1
	v_or_b32_sdwa v24, v24, v27 dst_sel:DWORD dst_unused:UNUSED_PAD src0_sel:DWORD src1_sel:WORD_1
	global_store_dwordx2 v[28:29], v[24:25], off offset:32
	v_mov_b32_e32 v24, v20
	v_mov_b32_e32 v25, v22
	v_pk_mul_f32 v[24:25], v[24:25], v[32:33] op_sel_hi:[1,0]
	v_mov_b32_e32 v22, v21
	v_pk_mul_f32 v[20:21], v[22:23], v[32:33] op_sel_hi:[1,0]
	v_and_b32_sdwa v23, v24, v170 dst_sel:DWORD dst_unused:UNUSED_PAD src0_sel:WORD_1 src1_sel:DWORD
	v_add3_u32 v23, v24, v23, s56
	v_cvt_pk_bf16_f32 v21, v25, v21
	ds_bpermute_b32 v22, v72, v51
	v_and_b32_sdwa v25, v20, v170 dst_sel:DWORD dst_unused:UNUSED_PAD src0_sel:WORD_1 src1_sel:DWORD
	v_add3_u32 v20, v20, v25, s56
	v_and_b32_e32 v20, 0xffff0000, v20
	v_or_b32_sdwa v20, v20, v23 dst_sel:DWORD dst_unused:UNUSED_PAD src0_sel:DWORD src1_sel:WORD_1
	s_waitcnt lgkmcnt(0)
	v_add_f32_e32 v22, v51, v22
	ds_bpermute_b32 v23, v71, v22
	global_store_dwordx2 v[28:29], v[20:21], off offset:64
	v_mov_b32_e32 v20, v16
	v_mov_b32_e32 v21, v18
	v_pk_mul_f32 v[20:21], v[20:21], v[32:33] op_sel_hi:[1,0]
	v_mov_b32_e32 v18, v17
	v_pk_mul_f32 v[16:17], v[18:19], v[32:33] op_sel_hi:[1,0]
	v_and_b32_sdwa v19, v20, v170 dst_sel:DWORD dst_unused:UNUSED_PAD src0_sel:WORD_1 src1_sel:DWORD
	v_and_b32_sdwa v18, v21, v170 dst_sel:DWORD dst_unused:UNUSED_PAD src0_sel:WORD_1 src1_sel:DWORD
	v_add3_u32 v19, v20, v19, s56
	v_and_b32_sdwa v20, v17, v170 dst_sel:DWORD dst_unused:UNUSED_PAD src0_sel:WORD_1 src1_sel:DWORD
	v_add3_u32 v18, v21, v18, s56
	v_and_b32_sdwa v21, v16, v170 dst_sel:DWORD dst_unused:UNUSED_PAD src0_sel:WORD_1 src1_sel:DWORD
	v_add3_u32 v17, v17, v20, s56
	s_waitcnt lgkmcnt(0)
	v_add_f32_e32 v20, v22, v23
	v_add3_u32 v16, v16, v21, s56
	v_div_scale_f32 v21, s[2:3], v20, v20, 1.0
	v_rcp_f32_e32 v22, v21
	v_and_b32_e32 v17, 0xffff0000, v17
	v_and_b32_e32 v16, 0xffff0000, v16
	v_or_b32_sdwa v17, v17, v18 dst_sel:DWORD dst_unused:UNUSED_PAD src0_sel:DWORD src1_sel:WORD_1
	v_or_b32_sdwa v16, v16, v19 dst_sel:DWORD dst_unused:UNUSED_PAD src0_sel:DWORD src1_sel:WORD_1
	global_store_dwordx2 v[28:29], v[16:17], off offset:96
	v_fma_f32 v16, -v21, v22, 1.0
	v_fmac_f32_e32 v22, v16, v22
	v_div_scale_f32 v16, vcc, 1.0, v20, 1.0
	v_mul_f32_e32 v17, v16, v22
	v_fma_f32 v18, -v21, v17, v16
	v_fmac_f32_e32 v17, v18, v22
	v_fma_f32 v16, -v21, v17, v16
	v_div_fmas_f32 v16, v16, v22, v17
	v_div_fixup_f32 v16, v16, v20, 1.0
	v_mov_b32_e32 v18, v12
	v_mov_b32_e32 v19, v14
	v_mov_b32_e32 v14, v13
	v_pk_mul_f32 v[18:19], v[18:19], v[16:17] op_sel_hi:[1,0]
	v_pk_mul_f32 v[12:13], v[14:15], v[16:17] op_sel_hi:[1,0]
	v_and_b32_sdwa v17, v13, v170 dst_sel:DWORD dst_unused:UNUSED_PAD src0_sel:WORD_1 src1_sel:DWORD
	v_and_b32_sdwa v14, v19, v170 dst_sel:DWORD dst_unused:UNUSED_PAD src0_sel:WORD_1 src1_sel:DWORD
	v_add3_u32 v13, v13, v17, s56
	v_add3_u32 v14, v19, v14, s56
	v_and_b32_e32 v13, 0xffff0000, v13
	s_mov_b32 s2, 0x8000
	v_or_b32_sdwa v13, v13, v14 dst_sel:DWORD dst_unused:UNUSED_PAD src0_sel:DWORD src1_sel:WORD_1
	v_add_co_u32_e32 v14, vcc, s2, v28
	v_cvt_pk_bf16_f32 v12, v18, v12
	s_nop 0
	v_addc_co_u32_e32 v15, vcc, 0, v29, vcc
	global_store_dwordx2 v[14:15], v[12:13], off
	v_mov_b32_e32 v12, v8
	v_mov_b32_e32 v13, v10
	v_pk_mul_f32 v[12:13], v[12:13], v[16:17] op_sel_hi:[1,0]
	v_mov_b32_e32 v10, v9
	v_pk_mul_f32 v[8:9], v[10:11], v[16:17] op_sel_hi:[1,0]
	v_and_b32_sdwa v10, v13, v170 dst_sel:DWORD dst_unused:UNUSED_PAD src0_sel:WORD_1 src1_sel:DWORD
	v_and_b32_sdwa v11, v12, v170 dst_sel:DWORD dst_unused:UNUSED_PAD src0_sel:WORD_1 src1_sel:DWORD
	v_add3_u32 v11, v12, v11, s56
	v_add3_u32 v10, v13, v10, s56
	v_and_b32_sdwa v12, v9, v170 dst_sel:DWORD dst_unused:UNUSED_PAD src0_sel:WORD_1 src1_sel:DWORD
	v_and_b32_sdwa v13, v8, v170 dst_sel:DWORD dst_unused:UNUSED_PAD src0_sel:WORD_1 src1_sel:DWORD
	v_add3_u32 v9, v9, v12, s56
	v_add3_u32 v8, v8, v13, s56
	v_and_b32_e32 v9, 0xffff0000, v9
	v_and_b32_e32 v8, 0xffff0000, v8
	v_or_b32_sdwa v9, v9, v10 dst_sel:DWORD dst_unused:UNUSED_PAD src0_sel:DWORD src1_sel:WORD_1
	v_or_b32_sdwa v8, v8, v11 dst_sel:DWORD dst_unused:UNUSED_PAD src0_sel:DWORD src1_sel:WORD_1
	global_store_dwordx2 v[14:15], v[8:9], off offset:32
	v_mov_b32_e32 v8, v4
	v_mov_b32_e32 v9, v6
	v_pk_mul_f32 v[8:9], v[8:9], v[16:17] op_sel_hi:[1,0]
	v_mov_b32_e32 v6, v5
	v_pk_mul_f32 v[4:5], v[6:7], v[16:17] op_sel_hi:[1,0]
	v_and_b32_sdwa v6, v9, v170 dst_sel:DWORD dst_unused:UNUSED_PAD src0_sel:WORD_1 src1_sel:DWORD
	v_and_b32_sdwa v7, v8, v170 dst_sel:DWORD dst_unused:UNUSED_PAD src0_sel:WORD_1 src1_sel:DWORD
	v_add3_u32 v7, v8, v7, s56
	v_add3_u32 v6, v9, v6, s56
	v_and_b32_sdwa v8, v5, v170 dst_sel:DWORD dst_unused:UNUSED_PAD src0_sel:WORD_1 src1_sel:DWORD
	v_and_b32_sdwa v9, v4, v170 dst_sel:DWORD dst_unused:UNUSED_PAD src0_sel:WORD_1 src1_sel:DWORD
	v_add3_u32 v5, v5, v8, s56
	v_add3_u32 v4, v4, v9, s56
	v_and_b32_e32 v5, 0xffff0000, v5
	v_and_b32_e32 v4, 0xffff0000, v4
	v_or_b32_sdwa v5, v5, v6 dst_sel:DWORD dst_unused:UNUSED_PAD src0_sel:DWORD src1_sel:WORD_1
	v_or_b32_sdwa v4, v4, v7 dst_sel:DWORD dst_unused:UNUSED_PAD src0_sel:DWORD src1_sel:WORD_1
	global_store_dwordx2 v[14:15], v[4:5], off offset:64
	v_mov_b32_e32 v4, v0
	v_mov_b32_e32 v5, v2
	v_pk_mul_f32 v[4:5], v[4:5], v[16:17] op_sel_hi:[1,0]
	v_mov_b32_e32 v2, v1
	v_pk_mul_f32 v[0:1], v[2:3], v[16:17] op_sel_hi:[1,0]
	v_and_b32_sdwa v2, v5, v170 dst_sel:DWORD dst_unused:UNUSED_PAD src0_sel:WORD_1 src1_sel:DWORD
	v_and_b32_sdwa v3, v4, v170 dst_sel:DWORD dst_unused:UNUSED_PAD src0_sel:WORD_1 src1_sel:DWORD
	v_add3_u32 v3, v4, v3, s56
	v_add3_u32 v2, v5, v2, s56
	v_and_b32_sdwa v4, v1, v170 dst_sel:DWORD dst_unused:UNUSED_PAD src0_sel:WORD_1 src1_sel:DWORD
	v_and_b32_sdwa v5, v0, v170 dst_sel:DWORD dst_unused:UNUSED_PAD src0_sel:WORD_1 src1_sel:DWORD
	v_add3_u32 v1, v1, v4, s56
	v_add3_u32 v0, v0, v5, s56
	v_and_b32_e32 v1, 0xffff0000, v1
	v_and_b32_e32 v0, 0xffff0000, v0
	v_or_b32_sdwa v1, v1, v2 dst_sel:DWORD dst_unused:UNUSED_PAD src0_sel:DWORD src1_sel:WORD_1
	v_or_b32_sdwa v0, v0, v3 dst_sel:DWORD dst_unused:UNUSED_PAD src0_sel:DWORD src1_sel:WORD_1
	global_store_dwordx2 v[14:15], v[0:1], off offset:96
	v_readlane_b32 s69, v254, 49

.LBB0_463:
	s_waitcnt lgkmcnt(0)
	s_barrier
	global_load_dwordx4 v[8:11], v[76:77], off
	global_load_dwordx4 v[16:19], v[78:79], off
	global_load_dwordx4 v[12:15], v[78:79], off offset:2048
	global_load_dwordx4 v[4:7], v[80:81], off
	global_load_dwordx4 v[0:3], v[82:83], off
	v_xor_b32_e32 v64, s26, v128
	s_xor_b64 s[24:25], s[0:1], -1
	v_lshl_or_b32 v175, v64, 7, v130
	s_mov_b64 s[40:41], -1
	s_mov_b32 s27, 0
	s_waitcnt vmcnt(3)
	v_pk_fma_f32 v[60:61], v[60:61], v[18:19], v[10:11]
	v_pk_fma_f32 v[62:63], v[62:63], v[16:17], v[8:9]
	s_waitcnt vmcnt(2)
	v_pk_fma_f32 v[60:61], v[56:57], v[14:15], v[60:61]
	v_pk_fma_f32 v[62:63], v[58:59], v[12:13], v[62:63]
	s_waitcnt vmcnt(1)
	v_pk_fma_f32 v[60:61], v[52:53], v[6:7], v[60:61]
	v_pk_fma_f32 v[62:63], v[54:55], v[4:5], v[62:63]
	s_waitcnt vmcnt(0)
	v_pk_fma_f32 v[60:61], v[48:49], v[2:3], v[60:61]
	v_pk_fma_f32 v[62:63], v[50:51], v[0:1], v[62:63]
	v_pk_fma_f32 v[56:57], v[56:57], v[18:19], v[10:11]
	v_pk_fma_f32 v[58:59], v[58:59], v[16:17], v[8:9]
	v_pk_fma_f32 v[56:57], v[52:53], v[14:15], v[56:57]
	v_pk_fma_f32 v[58:59], v[54:55], v[12:13], v[58:59]
	v_pk_fma_f32 v[56:57], v[48:49], v[6:7], v[56:57]
	v_pk_fma_f32 v[58:59], v[50:51], v[4:5], v[58:59]
	v_pk_fma_f32 v[56:57], v[40:41], v[2:3], v[56:57]
	v_pk_fma_f32 v[58:59], v[44:45], v[0:1], v[58:59]
	v_cvt_pk_bf16_f32 v61, v60, v61
	v_cvt_pk_bf16_f32 v60, v62, v63
	v_pk_fma_f32 v[52:53], v[52:53], v[18:19], v[10:11]
	v_pk_fma_f32 v[54:55], v[54:55], v[16:17], v[8:9]
	v_pk_fma_f32 v[52:53], v[48:49], v[14:15], v[52:53]
	v_pk_fma_f32 v[54:55], v[50:51], v[12:13], v[54:55]
	v_pk_fma_f32 v[52:53], v[40:41], v[6:7], v[52:53]
	v_pk_fma_f32 v[54:55], v[44:45], v[4:5], v[54:55]
	v_cvt_pk_bf16_f32 v57, v56, v57
	v_cvt_pk_bf16_f32 v56, v58, v59
	v_pk_fma_f32 v[52:53], v[32:33], v[2:3], v[52:53]
	v_pk_fma_f32 v[54:55], v[36:37], v[0:1], v[54:55]
	ds_write2_b64 v228, v[60:61], v[56:57] offset1:16
	v_pk_fma_f32 v[48:49], v[48:49], v[18:19], v[10:11]
	v_pk_fma_f32 v[50:51], v[50:51], v[16:17], v[8:9]
	v_pk_fma_f32 v[48:49], v[40:41], v[14:15], v[48:49]
	v_pk_fma_f32 v[50:51], v[44:45], v[12:13], v[50:51]
	v_pk_fma_f32 v[48:49], v[32:33], v[6:7], v[48:49]
	v_pk_fma_f32 v[50:51], v[36:37], v[4:5], v[50:51]
	v_cvt_pk_bf16_f32 v53, v52, v53
	v_cvt_pk_bf16_f32 v52, v54, v55
	v_pk_fma_f32 v[48:49], v[24:25], v[2:3], v[48:49]
	v_pk_fma_f32 v[50:51], v[28:29], v[0:1], v[50:51]
	ds_write_b64 v229, v[52:53]
	v_pk_fma_f32 v[40:41], v[40:41], v[18:19], v[10:11]
	v_pk_fma_f32 v[44:45], v[44:45], v[16:17], v[8:9]
	v_pk_fma_f32 v[40:41], v[32:33], v[14:15], v[40:41]
	v_pk_fma_f32 v[44:45], v[36:37], v[12:13], v[44:45]
	v_pk_fma_f32 v[40:41], v[24:25], v[6:7], v[40:41]
	v_pk_fma_f32 v[44:45], v[28:29], v[4:5], v[44:45]
	v_cvt_pk_bf16_f32 v49, v48, v49
	v_cvt_pk_bf16_f32 v48, v50, v51
	v_pk_fma_f32 v[40:41], v[20:21], v[2:3], v[40:41]
	v_pk_fma_f32 v[44:45], v[22:23], v[0:1], v[44:45]
	ds_write_b64 v230, v[48:49]
	v_pk_fma_f32 v[32:33], v[32:33], v[18:19], v[10:11]
	v_pk_fma_f32 v[36:37], v[36:37], v[16:17], v[8:9]
	v_pk_fma_f32 v[32:33], v[24:25], v[14:15], v[32:33]
	v_pk_fma_f32 v[36:37], v[28:29], v[12:13], v[36:37]
	v_pk_fma_f32 v[32:33], v[20:21], v[6:7], v[32:33]
	v_pk_fma_f32 v[36:37], v[22:23], v[4:5], v[36:37]
	v_cvt_pk_bf16_f32 v41, v40, v41
	v_cvt_pk_bf16_f32 v40, v44, v45
	v_pk_fma_f32 v[32:33], v[26:27], v[2:3], v[32:33]
	v_pk_fma_f32 v[36:37], v[30:31], v[0:1], v[36:37]
	ds_write_b64 v231, v[40:41]
	v_pk_fma_f32 v[24:25], v[24:25], v[18:19], v[10:11]
	v_pk_fma_f32 v[28:29], v[28:29], v[16:17], v[8:9]
	v_pk_fma_f32 v[10:11], v[20:21], v[18:19], v[10:11]
	v_pk_fma_f32 v[8:9], v[22:23], v[16:17], v[8:9]
	v_pk_fma_f32 v[24:25], v[20:21], v[14:15], v[24:25]
	v_pk_fma_f32 v[28:29], v[22:23], v[12:13], v[28:29]
	v_pk_fma_f32 v[10:11], v[26:27], v[14:15], v[10:11]
	v_pk_fma_f32 v[8:9], v[30:31], v[12:13], v[8:9]
	v_pk_fma_f32 v[24:25], v[26:27], v[6:7], v[24:25]
	v_pk_fma_f32 v[28:29], v[30:31], v[4:5], v[28:29]
	v_pk_fma_f32 v[6:7], v[34:35], v[6:7], v[10:11]
	v_pk_fma_f32 v[4:5], v[38:39], v[4:5], v[8:9]
	v_cvt_pk_bf16_f32 v33, v32, v33
	v_cvt_pk_bf16_f32 v32, v36, v37
	v_pk_fma_f32 v[24:25], v[34:35], v[2:3], v[24:25]
	v_pk_fma_f32 v[28:29], v[38:39], v[0:1], v[28:29]
	v_pk_fma_f32 v[2:3], v[42:43], v[2:3], v[6:7]
	v_pk_fma_f32 v[0:1], v[46:47], v[0:1], v[4:5]
	ds_write_b64 v232, v[32:33]
	v_and_b32_sdwa v4, v2, v170 dst_sel:DWORD dst_unused:UNUSED_PAD src0_sel:WORD_1 src1_sel:DWORD
	v_and_b32_sdwa v5, v0, v170 dst_sel:DWORD dst_unused:UNUSED_PAD src0_sel:WORD_1 src1_sel:DWORD
	v_add3_u32 v0, v0, v5, s56
	v_add3_u32 v2, v2, v4, s56
	v_and_b32_sdwa v4, v3, v170 dst_sel:DWORD dst_unused:UNUSED_PAD src0_sel:WORD_1 src1_sel:DWORD
	v_and_b32_sdwa v5, v1, v170 dst_sel:DWORD dst_unused:UNUSED_PAD src0_sel:WORD_1 src1_sel:DWORD
	v_add3_u32 v3, v3, v4, s56
	v_add3_u32 v1, v1, v5, s56
	v_and_b32_e32 v3, 0xffff0000, v3
	v_and_b32_e32 v4, 0xffff0000, v1
	v_cvt_pk_bf16_f32 v25, v24, v25
	v_cvt_pk_bf16_f32 v24, v28, v29
	v_or_b32_sdwa v1, v3, v2 dst_sel:DWORD dst_unused:UNUSED_PAD src0_sel:DWORD src1_sel:WORD_1
	v_or_b32_sdwa v0, v4, v0 dst_sel:DWORD dst_unused:UNUSED_PAD src0_sel:DWORD src1_sel:WORD_1
	ds_write_b64 v233, v[24:25]
	ds_write_b64 v234, v[0:1]
	global_load_dwordx4 v[40:43], v[140:141], off offset:3072
	global_load_dwordx4 v[36:39], v[142:143], off offset:3072
	global_load_dwordx4 v[32:35], v[144:145], off offset:3072
	global_load_dwordx4 v[28:31], v[146:147], off offset:3072
	global_load_dwordx4 v[24:27], v[148:149], off offset:3072
	global_load_dwordx4 v[20:23], v[150:151], off offset:3072
	global_load_dwordx4 v[16:19], v[152:153], off offset:3072
	global_load_dwordx4 v[12:15], v[154:155], off offset:3072
	global_load_dwordx4 v[8:11], v[156:157], off offset:3072
	global_load_dwordx4 v[4:7], v[158:159], off offset:3072
	global_load_dwordx4 v[0:3], v[160:161], off offset:3072
	s_waitcnt lgkmcnt(0)
	s_barrier
	s_branch .LBB0_465

.LBB0_521:
	s_or_b64 exec, exec, s[28:29]
	v_max_f32_e32 v115, v101, v101
	v_max_f32_e32 v156, v100, v100
	v_max_f32_e32 v115, v156, v115
	v_max_f32_e32 v156, v103, v103
	v_max_f32_e32 v157, v102, v102
	v_max_f32_e32 v156, v157, v156
	v_max_f32_e32 v157, v99, v99
	v_max_f32_e32 v158, v98, v98
	v_max_f32_e32 v157, v158, v157
	v_max3_f32 v157, v96, v97, v157
	v_max3_f32 v115, v115, v156, v157
	v_mov_b32_e32 v157, v115
	v_mov_b32_e32 v156, v115
	s_nop 1
	v_permlane16_swap_b32_e32 v157, v156
	v_max_f32_e32 v156, v157, v156
	v_mfma_f32_16x16x32_bf16 v[80:83], v[80:83], v[40:43], 0
	s_mov_b32 s16, 0x7060302
	s_waitcnt lgkmcnt(0)
	v_max_f32_e32 v156, v156, v156
	v_max_f32_e32 v115, v115, v156
	v_mov_b32_e32 v157, v115
	v_mov_b32_e32 v156, v115
	s_nop 1
	v_permlane32_swap_b32_e32 v157, v156
	v_max_f32_e32 v156, v157, v156
	v_mfma_f32_16x16x32_bf16 v[84:87], v[84:87], v[44:47], v[80:83]
	s_waitcnt lgkmcnt(0)
	v_max3_f32 v115, v152, v115, v156
	v_sub_f32_e32 v152, v152, v115
	v_sub_f32_e32 v97, v97, v115
	v_mul_f32_e32 v156, 0x3fb8aa3b, v152
	v_mul_f32_e32 v152, 0x3fb8aa3b, v97
	v_sub_f32_e32 v97, v98, v115
	v_sub_f32_e32 v96, v96, v115
	v_mul_f32_e32 v98, 0x3fb8aa3b, v97
	v_sub_f32_e32 v97, v99, v115
	v_mul_f32_e32 v96, 0x3fb8aa3b, v96
	v_mul_f32_e32 v97, 0x3fb8aa3b, v97
	v_exp_f32_e32 v97, v97
	v_exp_f32_e32 v99, v152
	v_exp_f32_e32 v152, v96
	v_sub_f32_e32 v100, v100, v115
	v_sub_f32_e32 v101, v101, v115
	v_sub_f32_e32 v102, v102, v115
	v_sub_f32_e32 v103, v103, v115
	v_mul_f32_e32 v100, 0x3fb8aa3b, v100
	v_mul_f32_e32 v101, 0x3fb8aa3b, v101
	v_mul_f32_e32 v102, 0x3fb8aa3b, v102
	v_mul_f32_e32 v103, 0x3fb8aa3b, v103
	v_exp_f32_e32 v100, v100
	v_exp_f32_e32 v101, v101
	v_exp_f32_e32 v102, v102
	v_exp_f32_e32 v103, v103
	v_exp_f32_e32 v98, v98
	v_exp_f32_e32 v96, v156
	v_mfma_f32_16x16x32_bf16 v[80:83], v[88:91], v[40:43], 0
	v_cvt_pk_bf16_f32 v159, v98, v97
	v_cvt_pk_bf16_f32 v158, v152, v99
	v_cvt_pk_bf16_f32 v157, v102, v103
	v_cvt_pk_bf16_f32 v156, v100, v101
	v_pk_mul_f32 v[30:31], v[30:31], v[96:97] op_sel_hi:[1,0]
	v_pk_mul_f32 v[28:29], v[28:29], v[96:97] op_sel_hi:[1,0]
	v_pk_mul_f32 v[26:27], v[26:27], v[96:97] op_sel_hi:[1,0]
	v_pk_mul_f32 v[24:25], v[24:25], v[96:97] op_sel_hi:[1,0]
	v_pk_mul_f32 v[22:23], v[22:23], v[96:97] op_sel_hi:[1,0]
	v_pk_mul_f32 v[20:21], v[20:21], v[96:97] op_sel_hi:[1,0]
	v_pk_mul_f32 v[18:19], v[18:19], v[96:97] op_sel_hi:[1,0]
	v_pk_mul_f32 v[16:17], v[16:17], v[96:97] op_sel_hi:[1,0]
	v_mfma_f32_16x16x32_bf16 v[28:31], v[76:79], v[156:159], v[28:31]
	v_mfma_f32_16x16x32_bf16 v[24:27], v[72:75], v[156:159], v[24:27]
	v_mfma_f32_16x16x32_bf16 v[20:23], v[68:71], v[156:159], v[20:23]
	v_mfma_f32_16x16x32_bf16 v[16:19], v[64:67], v[156:159], v[16:19]
	v_mfma_f32_16x16x32_bf16 v[80:83], v[92:95], v[44:47], v[80:83]
	s_and_saveexec_b64 s[28:29], s[0:1]
	s_cbranch_execz .LBB0_512
	v_sub_u32_e32 v88, v123, v154
	v_sub_u32_e32 v89, 0, v88
	v_max_i32_e32 v88, v88, v89
	s_movk_i32 s0, 0x80
	v_cmp_lt_u32_e64 s[0:1], s0, v88
	v_not_b32_e32 v88, v154
	v_add_u32_e32 v89, v123, v88
	v_sub_u32_e32 v90, 0, v89
	v_mov_b32_e32 v91, 0xf149f2ca
	v_max_i32_e32 v89, v89, v90
	s_movk_i32 s16, 0x81
	v_cndmask_b32_e64 v84, v84, v91, s[0:1]
	v_cmp_gt_u32_e64 s[0:1], s16, v89
	v_sub_u32_e32 v89, v140, v154
	v_sub_u32_e32 v90, 0, v89
	v_max_i32_e32 v89, v89, v90
	v_cndmask_b32_e64 v85, v91, v85, s[0:1]
	v_cmp_gt_u32_e64 s[0:1], s16, v89
	v_sub_u32_e32 v89, v141, v154
	v_sub_u32_e32 v90, 0, v89
	v_max_i32_e32 v89, v89, v90
	v_cndmask_b32_e64 v86, v91, v86, s[0:1]
	v_cmp_gt_u32_e64 s[0:1], s16, v89
	v_sub_u32_e32 v89, 0, v155
	v_max_i32_e32 v89, v155, v89
	v_add_u32_e32 v88, v122, v88
	v_cndmask_b32_e64 v87, v91, v87, s[0:1]
	v_cmp_gt_u32_e64 s[0:1], s16, v89
	v_sub_u32_e32 v89, 0, v88
	v_max_i32_e32 v88, v88, v89
	v_cndmask_b32_e64 v80, v91, v80, s[0:1]
	v_cmp_gt_u32_e64 s[0:1], s16, v88
	v_sub_u32_e32 v88, 0, v153
	v_max_i32_e32 v88, v153, v88
	v_cndmask_b32_e64 v81, v91, v81, s[0:1]
	v_cmp_gt_u32_e64 s[0:1], s16, v88
	v_sub_u32_e32 v88, 0, v117
	v_max_i32_e32 v88, v117, v88
	v_cndmask_b32_e64 v82, v91, v82, s[0:1]
	v_cmp_gt_u32_e64 s[0:1], s16, v88
	s_nop 1
	v_cndmask_b32_e64 v83, v91, v83, s[0:1]
	s_branch .LBB0_512

.LBB0_524:
	s_or_b64 exec, exec, s[24:25]
	v_cmp_lt_i32_e32 vcc, v130, v34
	v_readlane_b32 s0, v251, 20
	v_readlane_b32 s1, v251, 21
	v_cndmask_b32_e32 v32, v33, v130, vcc
	v_lshlrev_b32_e32 v35, 2, v32
	ds_bpermute_b32 v32, v35, v88
	v_cmp_lt_i32_e32 vcc, v127, v34
	v_or3_b32 v37, v107, v118, v109
	s_waitcnt lgkmcnt(0)
	v_add_f32_e32 v34, v88, v32
	v_cndmask_b32_e32 v33, v33, v127, vcc
	v_lshlrev_b32_e32 v38, 2, v33
	ds_bpermute_b32 v36, v38, v34
	v_lshl_add_u64 v[32:33], v[104:105], 1, s[0:1]
	v_lshl_add_u64 v[32:33], v[128:129], 1, v[32:33]
	v_lshlrev_b32_e32 v128, 11, v37
	v_mov_b32_e32 v37, v30
	s_waitcnt lgkmcnt(0)
	v_add_f32_e32 v34, v34, v36
	v_div_scale_f32 v36, s[0:1], v34, v34, 1.0
	v_rcp_f32_e32 v39, v36
	v_div_scale_f32 v40, vcc, 1.0, v34, 1.0
	v_mov_b32_e32 v30, v29
	v_fma_f32 v41, -v36, v39, 1.0
	v_fmac_f32_e32 v39, v41, v39
	v_mul_f32_e32 v41, v40, v39
	v_fma_f32 v42, -v36, v41, v40
	v_fmac_f32_e32 v41, v42, v39
	v_fma_f32 v36, -v36, v41, v40
	v_div_fmas_f32 v36, v36, v39, v41
	v_div_fixup_f32 v34, v36, v34, 1.0
	v_mov_b32_e32 v36, v28
	v_pk_mul_f32 v[36:37], v[36:37], v[34:35] op_sel_hi:[1,0]
	v_pk_mul_f32 v[28:29], v[30:31], v[34:35] op_sel_hi:[1,0]
	v_and_b32_sdwa v30, v37, v170 dst_sel:DWORD dst_unused:UNUSED_PAD src0_sel:WORD_1 src1_sel:DWORD
	v_and_b32_sdwa v31, v36, v170 dst_sel:DWORD dst_unused:UNUSED_PAD src0_sel:WORD_1 src1_sel:DWORD
	v_add3_u32 v31, v36, v31, s56
	v_add3_u32 v30, v37, v30, s56
	v_and_b32_sdwa v36, v29, v170 dst_sel:DWORD dst_unused:UNUSED_PAD src0_sel:WORD_1 src1_sel:DWORD
	v_and_b32_sdwa v37, v28, v170 dst_sel:DWORD dst_unused:UNUSED_PAD src0_sel:WORD_1 src1_sel:DWORD
	v_add3_u32 v29, v29, v36, s56
	v_add3_u32 v28, v28, v37, s56
	v_and_b32_e32 v29, 0xffff0000, v29
	v_and_b32_e32 v28, 0xffff0000, v28
	v_lshl_add_u64 v[32:33], v[32:33], 0, v[128:129]
	v_or_b32_sdwa v29, v29, v30 dst_sel:DWORD dst_unused:UNUSED_PAD src0_sel:DWORD src1_sel:WORD_1
	v_or_b32_sdwa v28, v28, v31 dst_sel:DWORD dst_unused:UNUSED_PAD src0_sel:DWORD src1_sel:WORD_1
	global_store_dwordx2 v[32:33], v[28:29], off
	v_mov_b32_e32 v28, v24
	v_mov_b32_e32 v29, v26
	v_pk_mul_f32 v[28:29], v[28:29], v[34:35] op_sel_hi:[1,0]
	v_mov_b32_e32 v26, v25
	v_pk_mul_f32 v[24:25], v[26:27], v[34:35] op_sel_hi:[1,0]
	v_and_b32_sdwa v26, v29, v170 dst_sel:DWORD dst_unused:UNUSED_PAD src0_sel:WORD_1 src1_sel:DWORD
	v_and_b32_sdwa v27, v28, v170 dst_sel:DWORD dst_unused:UNUSED_PAD src0_sel:WORD_1 src1_sel:DWORD
	v_add3_u32 v27, v28, v27, s56
	v_add3_u32 v26, v29, v26, s56
	v_and_b32_sdwa v28, v25, v170 dst_sel:DWORD dst_unused:UNUSED_PAD src0_sel:WORD_1 src1_sel:DWORD
	v_and_b32_sdwa v29, v24, v170 dst_sel:DWORD dst_unused:UNUSED_PAD src0_sel:WORD_1 src1_sel:DWORD
	v_add3_u32 v25, v25, v28, s56
	v_add3_u32 v24, v24, v29, s56
	v_and_b32_e32 v25, 0xffff0000, v25
	v_and_b32_e32 v24, 0xffff0000, v24
	v_or_b32_sdwa v25, v25, v26 dst_sel:DWORD dst_unused:UNUSED_PAD src0_sel:DWORD src1_sel:WORD_1
	v_or_b32_sdwa v24, v24, v27 dst_sel:DWORD dst_unused:UNUSED_PAD src0_sel:DWORD src1_sel:WORD_1
	global_store_dwordx2 v[32:33], v[24:25], off offset:32
	v_mov_b32_e32 v24, v20
	v_mov_b32_e32 v25, v22
	v_pk_mul_f32 v[24:25], v[24:25], v[34:35] op_sel_hi:[1,0]
	v_mov_b32_e32 v22, v21
	v_pk_mul_f32 v[20:21], v[22:23], v[34:35] op_sel_hi:[1,0]
	v_and_b32_sdwa v23, v24, v170 dst_sel:DWORD dst_unused:UNUSED_PAD src0_sel:WORD_1 src1_sel:DWORD
	v_add3_u32 v23, v24, v23, s56
	v_cvt_pk_bf16_f32 v21, v25, v21
	ds_bpermute_b32 v22, v35, v126
	v_and_b32_sdwa v25, v20, v170 dst_sel:DWORD dst_unused:UNUSED_PAD src0_sel:WORD_1 src1_sel:DWORD
	v_add3_u32 v20, v20, v25, s56
	v_and_b32_e32 v20, 0xffff0000, v20
	v_or_b32_sdwa v20, v20, v23 dst_sel:DWORD dst_unused:UNUSED_PAD src0_sel:DWORD src1_sel:WORD_1
	s_waitcnt lgkmcnt(0)
	v_add_f32_e32 v22, v126, v22
	ds_bpermute_b32 v23, v38, v22
	global_store_dwordx2 v[32:33], v[20:21], off offset:64
	v_mov_b32_e32 v20, v16
	v_mov_b32_e32 v21, v18
	v_pk_mul_f32 v[20:21], v[20:21], v[34:35] op_sel_hi:[1,0]
	v_mov_b32_e32 v18, v17
	v_pk_mul_f32 v[16:17], v[18:19], v[34:35] op_sel_hi:[1,0]
	v_and_b32_sdwa v19, v20, v170 dst_sel:DWORD dst_unused:UNUSED_PAD src0_sel:WORD_1 src1_sel:DWORD
	v_and_b32_sdwa v18, v21, v170 dst_sel:DWORD dst_unused:UNUSED_PAD src0_sel:WORD_1 src1_sel:DWORD
	v_add3_u32 v19, v20, v19, s56
	v_and_b32_sdwa v20, v17, v170 dst_sel:DWORD dst_unused:UNUSED_PAD src0_sel:WORD_1 src1_sel:DWORD
	v_add3_u32 v18, v21, v18, s56
	v_and_b32_sdwa v21, v16, v170 dst_sel:DWORD dst_unused:UNUSED_PAD src0_sel:WORD_1 src1_sel:DWORD
	v_add3_u32 v17, v17, v20, s56
	s_waitcnt lgkmcnt(0)
	v_add_f32_e32 v20, v22, v23
	v_add3_u32 v16, v16, v21, s56
	v_div_scale_f32 v21, s[0:1], v20, v20, 1.0
	v_rcp_f32_e32 v22, v21
	v_and_b32_e32 v17, 0xffff0000, v17
	v_and_b32_e32 v16, 0xffff0000, v16
	v_or_b32_sdwa v17, v17, v18 dst_sel:DWORD dst_unused:UNUSED_PAD src0_sel:DWORD src1_sel:WORD_1
	v_or_b32_sdwa v16, v16, v19 dst_sel:DWORD dst_unused:UNUSED_PAD src0_sel:DWORD src1_sel:WORD_1
	global_store_dwordx2 v[32:33], v[16:17], off offset:96
	v_fma_f32 v16, -v21, v22, 1.0
	v_fmac_f32_e32 v22, v16, v22
	v_div_scale_f32 v16, vcc, 1.0, v20, 1.0
	v_mul_f32_e32 v17, v16, v22
	v_fma_f32 v18, -v21, v17, v16
	v_fmac_f32_e32 v17, v18, v22
	v_fma_f32 v16, -v21, v17, v16
	v_div_fmas_f32 v16, v16, v22, v17
	v_div_fixup_f32 v16, v16, v20, 1.0
	v_mov_b32_e32 v18, v12
	v_mov_b32_e32 v19, v14
	v_mov_b32_e32 v14, v13
	v_pk_mul_f32 v[18:19], v[18:19], v[16:17] op_sel_hi:[1,0]
	v_pk_mul_f32 v[12:13], v[14:15], v[16:17] op_sel_hi:[1,0]
	v_and_b32_sdwa v17, v13, v170 dst_sel:DWORD dst_unused:UNUSED_PAD src0_sel:WORD_1 src1_sel:DWORD
	v_and_b32_sdwa v14, v19, v170 dst_sel:DWORD dst_unused:UNUSED_PAD src0_sel:WORD_1 src1_sel:DWORD
	v_add3_u32 v13, v13, v17, s56
	v_add3_u32 v14, v19, v14, s56
	v_and_b32_e32 v13, 0xffff0000, v13
	s_mov_b32 s0, 0x8000
	v_or_b32_sdwa v13, v13, v14 dst_sel:DWORD dst_unused:UNUSED_PAD src0_sel:DWORD src1_sel:WORD_1
	v_add_co_u32_e32 v14, vcc, s0, v32
	v_cvt_pk_bf16_f32 v12, v18, v12
	s_nop 0
	v_addc_co_u32_e32 v15, vcc, 0, v33, vcc
	global_store_dwordx2 v[14:15], v[12:13], off
	v_mov_b32_e32 v12, v8
	v_mov_b32_e32 v13, v10
	v_pk_mul_f32 v[12:13], v[12:13], v[16:17] op_sel_hi:[1,0]
	v_mov_b32_e32 v10, v9
	v_pk_mul_f32 v[8:9], v[10:11], v[16:17] op_sel_hi:[1,0]
	v_and_b32_sdwa v10, v13, v170 dst_sel:DWORD dst_unused:UNUSED_PAD src0_sel:WORD_1 src1_sel:DWORD
	v_and_b32_sdwa v11, v12, v170 dst_sel:DWORD dst_unused:UNUSED_PAD src0_sel:WORD_1 src1_sel:DWORD
	v_add3_u32 v11, v12, v11, s56
	v_add3_u32 v10, v13, v10, s56
	v_and_b32_sdwa v12, v9, v170 dst_sel:DWORD dst_unused:UNUSED_PAD src0_sel:WORD_1 src1_sel:DWORD
	v_and_b32_sdwa v13, v8, v170 dst_sel:DWORD dst_unused:UNUSED_PAD src0_sel:WORD_1 src1_sel:DWORD
	v_add3_u32 v9, v9, v12, s56
	v_add3_u32 v8, v8, v13, s56
	v_and_b32_e32 v9, 0xffff0000, v9
	v_and_b32_e32 v8, 0xffff0000, v8
	v_or_b32_sdwa v9, v9, v10 dst_sel:DWORD dst_unused:UNUSED_PAD src0_sel:DWORD src1_sel:WORD_1
	v_or_b32_sdwa v8, v8, v11 dst_sel:DWORD dst_unused:UNUSED_PAD src0_sel:DWORD src1_sel:WORD_1
	global_store_dwordx2 v[14:15], v[8:9], off offset:32
	v_mov_b32_e32 v8, v4
	v_mov_b32_e32 v9, v6
	v_pk_mul_f32 v[8:9], v[8:9], v[16:17] op_sel_hi:[1,0]
	v_mov_b32_e32 v6, v5
	v_pk_mul_f32 v[4:5], v[6:7], v[16:17] op_sel_hi:[1,0]
	v_and_b32_sdwa v6, v9, v170 dst_sel:DWORD dst_unused:UNUSED_PAD src0_sel:WORD_1 src1_sel:DWORD
	v_and_b32_sdwa v7, v8, v170 dst_sel:DWORD dst_unused:UNUSED_PAD src0_sel:WORD_1 src1_sel:DWORD
	v_add3_u32 v7, v8, v7, s56
	v_add3_u32 v6, v9, v6, s56
	v_and_b32_sdwa v8, v5, v170 dst_sel:DWORD dst_unused:UNUSED_PAD src0_sel:WORD_1 src1_sel:DWORD
	v_and_b32_sdwa v9, v4, v170 dst_sel:DWORD dst_unused:UNUSED_PAD src0_sel:WORD_1 src1_sel:DWORD
	v_add3_u32 v5, v5, v8, s56
	v_add3_u32 v4, v4, v9, s56
	v_and_b32_e32 v5, 0xffff0000, v5
	v_and_b32_e32 v4, 0xffff0000, v4
	v_or_b32_sdwa v5, v5, v6 dst_sel:DWORD dst_unused:UNUSED_PAD src0_sel:DWORD src1_sel:WORD_1
	v_or_b32_sdwa v4, v4, v7 dst_sel:DWORD dst_unused:UNUSED_PAD src0_sel:DWORD src1_sel:WORD_1
	global_store_dwordx2 v[14:15], v[4:5], off offset:64
	v_mov_b32_e32 v4, v0
	v_mov_b32_e32 v5, v2
	v_pk_mul_f32 v[4:5], v[4:5], v[16:17] op_sel_hi:[1,0]
	v_mov_b32_e32 v2, v1
	v_pk_mul_f32 v[0:1], v[2:3], v[16:17] op_sel_hi:[1,0]
	v_and_b32_sdwa v2, v5, v170 dst_sel:DWORD dst_unused:UNUSED_PAD src0_sel:WORD_1 src1_sel:DWORD
	v_and_b32_sdwa v3, v4, v170 dst_sel:DWORD dst_unused:UNUSED_PAD src0_sel:WORD_1 src1_sel:DWORD
	v_add3_u32 v3, v4, v3, s56
	v_add3_u32 v2, v5, v2, s56
	v_and_b32_sdwa v4, v1, v170 dst_sel:DWORD dst_unused:UNUSED_PAD src0_sel:WORD_1 src1_sel:DWORD
	v_and_b32_sdwa v5, v0, v170 dst_sel:DWORD dst_unused:UNUSED_PAD src0_sel:WORD_1 src1_sel:DWORD
	v_add3_u32 v1, v1, v4, s56
	v_add3_u32 v0, v0, v5, s56
	v_and_b32_e32 v1, 0xffff0000, v1
	v_and_b32_e32 v0, 0xffff0000, v0
	v_or_b32_sdwa v1, v1, v2 dst_sel:DWORD dst_unused:UNUSED_PAD src0_sel:DWORD src1_sel:WORD_1
	v_or_b32_sdwa v0, v0, v3 dst_sel:DWORD dst_unused:UNUSED_PAD src0_sel:DWORD src1_sel:WORD_1
	global_store_dwordx2 v[14:15], v[0:1], off offset:96

.LBB0_539:
	s_sub_i32 s1, 7, s24
	v_mov_b32_e32 v0, s1
	v_mov_b32_e32 v1, s24
	v_cndmask_b32_e64 v124, v0, v1, s[38:39]
	s_waitcnt lgkmcnt(0)
	s_barrier
	global_load_dwordx4 v[8:11], v[70:71], off
	global_load_dwordx4 v[16:19], v[72:73], off
	global_load_dwordx4 v[12:15], v[72:73], off offset:2048
	global_load_dwordx4 v[4:7], v[76:77], off
	global_load_dwordx4 v[0:3], v[78:79], off
	s_mov_b32 s0, s24
	s_add_i32 s24, s24, 1
	s_cmp_lg_u32 s0, 7
	s_cselect_b32 s0, s24, 7
	s_sub_i32 s1, 7, s0
	v_lshl_add_u32 v124, v124, 7, v97
	s_mov_b64 s[2:3], -1
	s_mov_b32 s25, 0
	s_waitcnt vmcnt(3)
	v_pk_fma_f32 v[38:39], v[90:91], v[18:19], v[10:11]
	v_pk_fma_f32 v[40:41], v[92:93], v[16:17], v[8:9]
	s_waitcnt vmcnt(2)
	v_pk_fma_f32 v[38:39], v[62:63], v[14:15], v[38:39]
	v_pk_fma_f32 v[40:41], v[64:65], v[12:13], v[40:41]
	s_waitcnt vmcnt(1)
	v_pk_fma_f32 v[38:39], v[58:59], v[6:7], v[38:39]
	v_pk_fma_f32 v[40:41], v[60:61], v[4:5], v[40:41]
	s_waitcnt vmcnt(0)
	v_pk_fma_f32 v[38:39], v[54:55], v[2:3], v[38:39]
	v_pk_fma_f32 v[40:41], v[56:57], v[0:1], v[40:41]
	v_cvt_pk_bf16_f32 v39, v38, v39
	v_cvt_pk_bf16_f32 v38, v40, v41
	v_pk_fma_f32 v[40:41], v[62:63], v[18:19], v[10:11]
	v_pk_fma_f32 v[42:43], v[64:65], v[16:17], v[8:9]
	v_pk_fma_f32 v[40:41], v[58:59], v[14:15], v[40:41]
	v_pk_fma_f32 v[42:43], v[60:61], v[12:13], v[42:43]
	v_pk_fma_f32 v[40:41], v[54:55], v[6:7], v[40:41]
	v_pk_fma_f32 v[42:43], v[56:57], v[4:5], v[42:43]
	v_pk_fma_f32 v[40:41], v[50:51], v[2:3], v[40:41]
	v_pk_fma_f32 v[42:43], v[52:53], v[0:1], v[42:43]
	v_cvt_pk_bf16_f32 v41, v40, v41
	v_cvt_pk_bf16_f32 v40, v42, v43
	ds_write2_b64 v115, v[38:39], v[40:41] offset1:16
	v_pk_fma_f32 v[38:39], v[58:59], v[18:19], v[10:11]
	v_pk_fma_f32 v[40:41], v[60:61], v[16:17], v[8:9]
	v_pk_fma_f32 v[38:39], v[54:55], v[14:15], v[38:39]
	v_pk_fma_f32 v[40:41], v[56:57], v[12:13], v[40:41]
	v_pk_fma_f32 v[38:39], v[50:51], v[6:7], v[38:39]
	v_pk_fma_f32 v[40:41], v[52:53], v[4:5], v[40:41]
	v_pk_fma_f32 v[38:39], v[46:47], v[2:3], v[38:39]
	v_pk_fma_f32 v[40:41], v[48:49], v[0:1], v[40:41]
	v_cvt_pk_bf16_f32 v39, v38, v39
	v_cvt_pk_bf16_f32 v38, v40, v41
	ds_write_b64 v116, v[38:39]
	v_pk_fma_f32 v[38:39], v[54:55], v[18:19], v[10:11]
	v_pk_fma_f32 v[40:41], v[56:57], v[16:17], v[8:9]
	v_pk_fma_f32 v[38:39], v[50:51], v[14:15], v[38:39]
	v_pk_fma_f32 v[40:41], v[52:53], v[12:13], v[40:41]
	v_pk_fma_f32 v[38:39], v[46:47], v[6:7], v[38:39]
	v_pk_fma_f32 v[40:41], v[48:49], v[4:5], v[40:41]
	v_pk_fma_f32 v[38:39], v[26:27], v[2:3], v[38:39]
	v_pk_fma_f32 v[40:41], v[44:45], v[0:1], v[40:41]
	v_cvt_pk_bf16_f32 v39, v38, v39
	v_cvt_pk_bf16_f32 v38, v40, v41
	ds_write_b64 v117, v[38:39]
	v_pk_fma_f32 v[38:39], v[50:51], v[18:19], v[10:11]
	v_pk_fma_f32 v[40:41], v[52:53], v[16:17], v[8:9]
	v_pk_fma_f32 v[38:39], v[46:47], v[14:15], v[38:39]
	v_pk_fma_f32 v[40:41], v[48:49], v[12:13], v[40:41]
	v_pk_fma_f32 v[38:39], v[26:27], v[6:7], v[38:39]
	v_pk_fma_f32 v[40:41], v[44:45], v[4:5], v[40:41]
	v_pk_fma_f32 v[38:39], v[20:21], v[2:3], v[38:39]
	v_pk_fma_f32 v[40:41], v[22:23], v[0:1], v[40:41]
	v_cvt_pk_bf16_f32 v39, v38, v39
	v_cvt_pk_bf16_f32 v38, v40, v41
	ds_write_b64 v118, v[38:39]
	v_pk_fma_f32 v[38:39], v[46:47], v[18:19], v[10:11]
	v_pk_fma_f32 v[40:41], v[48:49], v[16:17], v[8:9]
	v_pk_fma_f32 v[38:39], v[26:27], v[14:15], v[38:39]
	v_pk_fma_f32 v[40:41], v[44:45], v[12:13], v[40:41]
	v_pk_fma_f32 v[38:39], v[20:21], v[6:7], v[38:39]
	v_pk_fma_f32 v[40:41], v[22:23], v[4:5], v[40:41]
	v_pk_fma_f32 v[38:39], v[24:25], v[2:3], v[38:39]
	v_pk_fma_f32 v[40:41], v[28:29], v[0:1], v[40:41]
	v_cvt_pk_bf16_f32 v39, v38, v39
	v_cvt_pk_bf16_f32 v38, v40, v41
	ds_write_b64 v119, v[38:39]
	v_pk_fma_f32 v[26:27], v[26:27], v[18:19], v[10:11]
	v_pk_fma_f32 v[38:39], v[44:45], v[16:17], v[8:9]
	v_pk_fma_f32 v[10:11], v[20:21], v[18:19], v[10:11]
	v_pk_fma_f32 v[8:9], v[22:23], v[16:17], v[8:9]
	v_pk_fma_f32 v[26:27], v[20:21], v[14:15], v[26:27]
	v_pk_fma_f32 v[38:39], v[22:23], v[12:13], v[38:39]
	v_pk_fma_f32 v[10:11], v[24:25], v[14:15], v[10:11]
	v_pk_fma_f32 v[8:9], v[28:29], v[12:13], v[8:9]
	v_pk_fma_f32 v[26:27], v[24:25], v[6:7], v[26:27]
	v_pk_fma_f32 v[38:39], v[28:29], v[4:5], v[38:39]
	v_pk_fma_f32 v[6:7], v[30:31], v[6:7], v[10:11]
	v_pk_fma_f32 v[4:5], v[32:33], v[4:5], v[8:9]
	v_pk_fma_f32 v[26:27], v[30:31], v[2:3], v[26:27]
	v_pk_fma_f32 v[38:39], v[32:33], v[0:1], v[38:39]
	v_pk_fma_f32 v[2:3], v[34:35], v[2:3], v[6:7]
	v_pk_fma_f32 v[0:1], v[36:37], v[0:1], v[4:5]
	v_and_b32_sdwa v4, v2, v170 dst_sel:DWORD dst_unused:UNUSED_PAD src0_sel:WORD_1 src1_sel:DWORD
	v_and_b32_sdwa v5, v0, v170 dst_sel:DWORD dst_unused:UNUSED_PAD src0_sel:WORD_1 src1_sel:DWORD
	v_add3_u32 v0, v0, v5, s56
	v_add3_u32 v2, v2, v4, s56
	v_and_b32_sdwa v4, v3, v170 dst_sel:DWORD dst_unused:UNUSED_PAD src0_sel:WORD_1 src1_sel:DWORD
	v_and_b32_sdwa v5, v1, v170 dst_sel:DWORD dst_unused:UNUSED_PAD src0_sel:WORD_1 src1_sel:DWORD
	v_add3_u32 v3, v3, v4, s56
	v_add3_u32 v1, v1, v5, s56
	v_and_b32_e32 v3, 0xffff0000, v3
	v_and_b32_e32 v4, 0xffff0000, v1
	v_cvt_pk_bf16_f32 v27, v26, v27
	v_cvt_pk_bf16_f32 v26, v38, v39
	v_or_b32_sdwa v1, v3, v2 dst_sel:DWORD dst_unused:UNUSED_PAD src0_sel:DWORD src1_sel:WORD_1
	v_or_b32_sdwa v0, v4, v0 dst_sel:DWORD dst_unused:UNUSED_PAD src0_sel:DWORD src1_sel:WORD_1
	ds_write_b64 v120, v[26:27]
	ds_write_b64 v121, v[0:1]
	v_mov_b32_e32 v0, s1
	v_mov_b32_e32 v1, s0
	v_cndmask_b32_e64 v0, v0, v1, s[38:39]
	v_lshl_add_u32 v122, v0, 7, v98
	v_min_i32_e32 v0, 0x401, v122
	v_or_b32_e32 v4, 1, v122
	v_add_u32_e32 v0, -2, v0
	v_cmp_lt_i32_e32 vcc, 1, v122
	v_min_i32_e32 v5, 0x401, v4
	v_or_b32_e32 v8, 2, v122
	v_or_b32_e32 v12, 3, v122
	v_or_b32_e32 v16, 4, v122
	v_or_b32_e32 v20, 5, v122
	v_or_b32_e32 v24, 6, v122
	v_or_b32_e32 v28, 7, v122
	v_cndmask_b32_e32 v0, 0, v0, vcc
	v_add_u32_e32 v5, -2, v5
	v_cmp_lt_i32_e32 vcc, 1, v4
	v_min_i32_e32 v8, 0x401, v8
	v_min_i32_e32 v12, 0x401, v12
	v_min_i32_e32 v16, 0x401, v16
	v_min_i32_e32 v20, 0x401, v20
	v_min_i32_e32 v24, 0x401, v24
	v_min_i32_e32 v28, 0x401, v28
	v_add_u32_e32 v123, 8, v122
	v_cndmask_b32_e32 v4, 0, v5, vcc
	v_cmp_gt_i32_e32 vcc, 0, v122
	v_add_u32_e32 v8, -2, v8
	v_add_u32_e32 v12, -2, v12
	v_add_u32_e32 v16, -2, v16
	v_add_u32_e32 v20, -2, v20
	v_add_u32_e32 v24, -2, v24
	v_add_u32_e32 v28, -2, v28
	v_min_i32_e32 v32, 0x401, v123
	v_cndmask_b32_e64 v8, v8, 0, vcc
	v_cndmask_b32_e64 v12, v12, 0, vcc
	v_cndmask_b32_e64 v16, v16, 0, vcc
	v_cndmask_b32_e64 v20, v20, 0, vcc
	v_cndmask_b32_e64 v24, v24, 0, vcc
	v_cndmask_b32_e64 v28, v28, 0, vcc
	v_add_u32_e32 v32, -2, v32
	v_cmp_lt_i32_e32 vcc, 1, v123
	v_min_i32_e32 v36, 0x3f8, v122
	v_or_b32_e32 v36, 7, v36
	v_cndmask_b32_e32 v32, 0, v32, vcc
	v_cmp_lt_i32_e32 vcc, -8, v122
	v_add_u32_e32 v0, v0, v97
	v_add_u32_e32 v4, v4, v97
	v_cndmask_b32_e32 v36, 0, v36, vcc
	v_add_u32_e32 v36, v36, v97
	v_ashrrev_i32_e32 v37, 31, v36
	v_lshlrev_b64 v[36:37], 13, v[36:37]
	v_lshl_add_u64 v[36:37], v[88:89], 0, v[36:37]
	global_load_dwordx4 v[40:43], v[36:37], off offset:3072
	v_min_i32_e32 v36, 0x3f7, v122
	v_add_u32_e32 v36, 8, v36
	v_cmp_lt_i32_e32 vcc, -9, v122
	v_add_u32_e32 v8, v8, v97
	v_add_u32_e32 v12, v12, v97
	v_cndmask_b32_e32 v36, 0, v36, vcc
	v_add_u32_e32 v16, v16, v97
	v_add_u32_e32 v20, v20, v97
	v_add_u32_e32 v24, v24, v97
	v_add_u32_e32 v28, v28, v97
	v_add_u32_e32 v32, v32, v97
	v_add_u32_e32 v36, v36, v97
	v_ashrrev_i32_e32 v1, 31, v0
	v_ashrrev_i32_e32 v5, 31, v4
	v_ashrrev_i32_e32 v9, 31, v8
	v_ashrrev_i32_e32 v13, 31, v12
	v_ashrrev_i32_e32 v17, 31, v16
	v_ashrrev_i32_e32 v21, 31, v20
	v_ashrrev_i32_e32 v25, 31, v24
	v_ashrrev_i32_e32 v29, 31, v28
	v_ashrrev_i32_e32 v33, 31, v32
	v_ashrrev_i32_e32 v37, 31, v36
	v_lshlrev_b64 v[0:1], 13, v[0:1]
	v_lshlrev_b64 v[4:5], 13, v[4:5]
	v_lshlrev_b64 v[8:9], 13, v[8:9]
	v_lshlrev_b64 v[12:13], 13, v[12:13]
	v_lshlrev_b64 v[16:17], 13, v[16:17]
	v_lshlrev_b64 v[20:21], 13, v[20:21]
	v_lshlrev_b64 v[24:25], 13, v[24:25]
	v_lshlrev_b64 v[28:29], 13, v[28:29]
	v_lshlrev_b64 v[32:33], 13, v[32:33]
	v_lshlrev_b64 v[36:37], 13, v[36:37]
	v_lshl_add_u64 v[0:1], v[88:89], 0, v[0:1]
	v_lshl_add_u64 v[4:5], v[88:89], 0, v[4:5]
	v_lshl_add_u64 v[8:9], v[88:89], 0, v[8:9]
	v_lshl_add_u64 v[12:13], v[88:89], 0, v[12:13]
	v_lshl_add_u64 v[16:17], v[88:89], 0, v[16:17]
	v_lshl_add_u64 v[20:21], v[88:89], 0, v[20:21]
	v_lshl_add_u64 v[24:25], v[88:89], 0, v[24:25]
	v_lshl_add_u64 v[28:29], v[88:89], 0, v[28:29]
	v_lshl_add_u64 v[32:33], v[88:89], 0, v[32:33]
	v_lshl_add_u64 v[36:37], v[88:89], 0, v[36:37]
	global_load_dwordx4 v[0:3], v[0:1], off offset:3072
	s_nop 0
	global_load_dwordx4 v[4:7], v[4:5], off offset:3072
	s_nop 0
	global_load_dwordx4 v[8:11], v[8:9], off offset:3072
	s_nop 0
	global_load_dwordx4 v[12:15], v[12:13], off offset:3072
	s_nop 0
	global_load_dwordx4 v[16:19], v[16:17], off offset:3072
	s_nop 0
	global_load_dwordx4 v[20:23], v[20:21], off offset:3072
	s_nop 0
	global_load_dwordx4 v[24:27], v[24:25], off offset:3072
	s_nop 0
	global_load_dwordx4 v[28:31], v[28:29], off offset:3072
	s_nop 0
	global_load_dwordx4 v[32:35], v[32:33], off offset:3072
	s_nop 0
	global_load_dwordx4 v[36:39], v[36:37], off offset:3072
	s_waitcnt lgkmcnt(0)
	s_barrier
	s_branch .LBB0_541

.Ltail582:
	s_add_i32 s0, s1, 2
	v_add_u32_e32 v111, v104, v105
	ds_read_b128 v[136:139], v111 offset:16384
	ds_read_b128 v[140:143], v111 offset:18432
	ds_read_b128 v[144:147], v111 offset:20480
	ds_read_b128 v[148:151], v111 offset:22528
	v_add_u32_e32 v110, v103, v105
	ds_read_b128 v[116:119], v110
	s_add_i32 s1, s1, 4
	ds_read_b128 v[120:123], v110 offset:2048
	s_min_u32 s1, s1, 63
	v_add_u32_e32 v113, v104, v114
	s_lshl_b32 s92, s1, 7
	ds_read_b128 v[124:127], v110 offset:4096
	v_add_u32_e32 v112, v103, v114
	ds_read_b128 v[194:197], v113 offset:16384
	ds_read_b128 v[198:201], v113 offset:18432
	ds_read_b128 v[202:205], v113 offset:20480
	ds_read_b128 v[206:209], v113 offset:22528
	v_lshl_add_u64 v[164:165], v[98:99], 0, s[92:93]
	ds_read_b128 v[132:135], v110 offset:6144
	ds_read_b128 v[152:155], v112
	ds_read_b128 v[156:159], v112 offset:2048
	ds_read_b128 v[160:163], v112 offset:4096
	ds_read_b128 v[190:193], v112 offset:6144
	s_waitcnt lgkmcnt(11)
	v_mfma_f32_16x16x32_bf16 v[92:95], v[136:139], v[116:119], v[92:95]
	v_mfma_f32_16x16x32_bf16 v[88:91], v[140:143], v[116:119], v[88:91]
	v_mfma_f32_16x16x32_bf16 v[52:55], v[144:147], v[116:119], v[52:55]
	v_mfma_f32_16x16x32_bf16 v[48:51], v[148:151], v[116:119], v[48:51]
	s_waitcnt vmcnt(7)
	ds_write_b128 v109, v[56:59] offset:32768
	v_add_co_u32_e32 v56, vcc, s7, v164
	s_waitcnt lgkmcnt(11)
	v_mfma_f32_16x16x32_bf16 v[44:47], v[136:139], v[120:123], v[44:47]
	v_addc_co_u32_e32 v57, vcc, 0, v165, vcc
	v_mfma_f32_16x16x32_bf16 v[40:43], v[140:143], v[120:123], v[40:43]
	v_mfma_f32_16x16x32_bf16 v[36:39], v[144:147], v[120:123], v[36:39]
	v_mfma_f32_16x16x32_bf16 v[32:35], v[148:151], v[120:123], v[32:35]
	v_add_co_u32_e32 v56, vcc, s52, v164
	s_waitcnt vmcnt(6)
	ds_write_b128 v109, v[60:63] offset:36864
	s_nop 0
	v_addc_co_u32_e32 v57, vcc, 0, v165, vcc
	s_waitcnt lgkmcnt(11)
	v_mfma_f32_16x16x32_bf16 v[28:31], v[136:139], v[124:127], v[28:31]
	v_mfma_f32_16x16x32_bf16 v[24:27], v[140:143], v[124:127], v[24:27]
	v_mfma_f32_16x16x32_bf16 v[20:23], v[144:147], v[124:127], v[20:23]
	v_mfma_f32_16x16x32_bf16 v[16:19], v[148:151], v[124:127], v[16:19]
	v_add_co_u32_e32 v56, vcc, s34, v164
	s_waitcnt vmcnt(5)
	ds_write_b128 v109, v[64:67] offset:40960
	s_nop 0
	v_addc_co_u32_e32 v57, vcc, 0, v165, vcc
	v_lshl_add_u64 v[64:65], v[100:101], 0, s[92:93]
	v_add_co_u32_e32 v66, vcc, s7, v64
	s_waitcnt lgkmcnt(7)
	v_mfma_f32_16x16x32_bf16 v[12:15], v[136:139], v[132:135], v[12:15]
	v_addc_co_u32_e32 v67, vcc, 0, v65, vcc
	v_mfma_f32_16x16x32_bf16 v[8:11], v[140:143], v[132:135], v[8:11]
	v_mfma_f32_16x16x32_bf16 v[4:7], v[144:147], v[132:135], v[4:7]
	v_mfma_f32_16x16x32_bf16 v[0:3], v[148:151], v[132:135], v[0:3]
	s_waitcnt vmcnt(4)
	ds_write_b128 v109, v[72:75] offset:45056
	s_waitcnt lgkmcnt(7)
	v_mfma_f32_16x16x32_bf16 v[56:59], v[194:197], v[152:155], v[92:95]
	v_mfma_f32_16x16x32_bf16 v[60:63], v[198:201], v[152:155], v[88:91]
	v_mfma_f32_16x16x32_bf16 v[52:55], v[202:205], v[152:155], v[52:55]
	v_mfma_f32_16x16x32_bf16 v[48:51], v[206:209], v[152:155], v[48:51]
	s_waitcnt vmcnt(3)
	ds_write_b128 v109, v[68:71] offset:49152
	s_waitcnt lgkmcnt(7)
	v_mfma_f32_16x16x32_bf16 v[44:47], v[194:197], v[156:159], v[44:47]
	v_mfma_f32_16x16x32_bf16 v[40:43], v[198:201], v[156:159], v[40:43]
	v_mfma_f32_16x16x32_bf16 v[36:39], v[202:205], v[156:159], v[36:39]
	v_mfma_f32_16x16x32_bf16 v[32:35], v[206:209], v[156:159], v[32:35]
	v_add_co_u32_e32 v66, vcc, s52, v64
	s_waitcnt vmcnt(2)
	ds_write_b128 v109, v[76:79] offset:53248
	v_addc_co_u32_e32 v67, vcc, 0, v65, vcc
	v_add_co_u32_e32 v64, vcc, s34, v64
	s_waitcnt lgkmcnt(7)
	v_mfma_f32_16x16x32_bf16 v[28:31], v[194:197], v[160:163], v[28:31]
	v_addc_co_u32_e32 v65, vcc, 0, v65, vcc
	v_mfma_f32_16x16x32_bf16 v[24:27], v[198:201], v[160:163], v[24:27]
	v_mfma_f32_16x16x32_bf16 v[20:23], v[202:205], v[160:163], v[20:23]
	v_mfma_f32_16x16x32_bf16 v[16:19], v[206:209], v[160:163], v[16:19]
	s_waitcnt vmcnt(1)
	ds_write_b128 v109, v[80:83] offset:57344
	s_waitcnt lgkmcnt(7)
	v_mfma_f32_16x16x32_bf16 v[12:15], v[194:197], v[190:193], v[12:15]
	v_mfma_f32_16x16x32_bf16 v[8:11], v[198:201], v[190:193], v[8:11]
	v_mfma_f32_16x16x32_bf16 v[4:7], v[202:205], v[190:193], v[4:7]
	v_mfma_f32_16x16x32_bf16 v[0:3], v[206:209], v[190:193], v[0:3]
	s_waitcnt vmcnt(0)
	ds_write_b128 v109, v[84:87] offset:61440
	s_waitcnt lgkmcnt(0)
	s_barrier
	ds_read_b128 v[84:87], v111 offset:51200
	ds_read_b128 v[80:83], v111 offset:49152
	ds_read_b128 v[88:91], v111 offset:53248
	ds_read_b128 v[92:95], v111 offset:55296
	ds_read_b128 v[64:67], v110 offset:32768
	s_min_u32 s1, s0, 60
	s_lshl_b32 s92, s1, 7
	ds_read_b128 v[68:71], v110 offset:34816
	v_lshl_add_u64 v[164:165], v[98:99], 0, s[92:93]
	ds_read_b128 v[72:75], v110 offset:36864
	ds_read_b128 v[76:79], v110 offset:38912
	ds_read_b128 v[152:155], v112 offset:32768
	ds_read_b128 v[156:159], v112 offset:34816
	ds_read_b128 v[160:163], v112 offset:36864
	ds_read_b128 v[190:193], v112 offset:38912
	ds_read_b128 v[194:197], v113 offset:49152
	ds_read_b128 v[198:201], v113 offset:51200
	ds_read_b128 v[202:205], v113 offset:53248
	ds_read_b128 v[206:209], v113 offset:55296
	s_waitcnt lgkmcnt(11)
	v_mfma_f32_16x16x32_bf16 v[214:217], v[84:87], v[64:67], v[60:63]
	v_mfma_f32_16x16x32_bf16 v[210:213], v[80:83], v[64:67], v[56:59]
	s_nop 1
	v_add_co_u32_e32 v60, vcc, s7, v164
	s_nop 1
	v_addc_co_u32_e32 v61, vcc, 0, v165, vcc
	v_mfma_f32_16x16x32_bf16 v[52:55], v[88:91], v[64:67], v[52:55]
	v_mfma_f32_16x16x32_bf16 v[48:51], v[92:95], v[64:67], v[48:51]
	v_add_co_u32_e32 v64, vcc, s52, v164
	s_nop 0
	v_addc_co_u32_e32 v65, vcc, 0, v165, vcc
	s_waitcnt lgkmcnt(10)
	v_mfma_f32_16x16x32_bf16 v[44:47], v[80:83], v[68:71], v[44:47]
	v_mfma_f32_16x16x32_bf16 v[40:43], v[84:87], v[68:71], v[40:43]
	v_mfma_f32_16x16x32_bf16 v[36:39], v[88:91], v[68:71], v[36:39]
	v_mfma_f32_16x16x32_bf16 v[32:35], v[92:95], v[68:71], v[32:35]
	v_add_co_u32_e32 v68, vcc, s34, v164
	s_waitcnt lgkmcnt(9)
	v_mfma_f32_16x16x32_bf16 v[28:31], v[80:83], v[72:75], v[28:31]
	v_addc_co_u32_e32 v69, vcc, 0, v165, vcc
	v_mfma_f32_16x16x32_bf16 v[24:27], v[84:87], v[72:75], v[24:27]
	v_mfma_f32_16x16x32_bf16 v[20:23], v[88:91], v[72:75], v[20:23]
	v_mfma_f32_16x16x32_bf16 v[16:19], v[92:95], v[72:75], v[16:19]
	s_waitcnt lgkmcnt(8)
	v_mfma_f32_16x16x32_bf16 v[8:11], v[84:87], v[76:79], v[8:11]
	v_lshl_add_u64 v[84:85], v[100:101], 0, s[92:93]
	v_mfma_f32_16x16x32_bf16 v[12:15], v[80:83], v[76:79], v[12:15]
	v_mfma_f32_16x16x32_bf16 v[4:7], v[88:91], v[76:79], v[4:7]
	v_mfma_f32_16x16x32_bf16 v[0:3], v[92:95], v[76:79], v[0:3]
	v_add_co_u32_e32 v76, vcc, s7, v84
	s_nop 0
	v_addc_co_u32_e32 v77, vcc, 0, v85, vcc
	v_add_co_u32_e32 v80, vcc, s52, v84
	v_addc_co_u32_e32 v81, vcc, 0, v85, vcc
	s_waitcnt lgkmcnt(3)
	v_mfma_f32_16x16x32_bf16 v[92:95], v[194:197], v[152:155], v[210:213]
	s_waitcnt lgkmcnt(2)
	v_mfma_f32_16x16x32_bf16 v[88:91], v[198:201], v[152:155], v[214:217]
	s_waitcnt lgkmcnt(1)
	v_mfma_f32_16x16x32_bf16 v[52:55], v[202:205], v[152:155], v[52:55]
	s_waitcnt lgkmcnt(0)
	v_mfma_f32_16x16x32_bf16 v[48:51], v[206:209], v[152:155], v[48:51]
	v_add_co_u32_e32 v84, vcc, s34, v84
	v_addc_co_u32_e32 v85, vcc, 0, v85, vcc
	v_mfma_f32_16x16x32_bf16 v[44:47], v[194:197], v[156:159], v[44:47]
	v_mfma_f32_16x16x32_bf16 v[40:43], v[198:201], v[156:159], v[40:43]
	v_mfma_f32_16x16x32_bf16 v[36:39], v[202:205], v[156:159], v[36:39]
	v_mfma_f32_16x16x32_bf16 v[32:35], v[206:209], v[156:159], v[32:35]
	v_mfma_f32_16x16x32_bf16 v[28:31], v[194:197], v[160:163], v[28:31]
	v_mfma_f32_16x16x32_bf16 v[24:27], v[198:201], v[160:163], v[24:27]
	v_mfma_f32_16x16x32_bf16 v[20:23], v[202:205], v[160:163], v[20:23]
	v_mfma_f32_16x16x32_bf16 v[16:19], v[206:209], v[160:163], v[16:19]
	v_mfma_f32_16x16x32_bf16 v[12:15], v[194:197], v[190:193], v[12:15]
	v_mfma_f32_16x16x32_bf16 v[8:11], v[198:201], v[190:193], v[8:11]
	v_mfma_f32_16x16x32_bf16 v[4:7], v[202:205], v[190:193], v[4:7]
	v_mfma_f32_16x16x32_bf16 v[0:3], v[206:209], v[190:193], v[0:3]
	s_mov_b32 s1, s0
	s_waitcnt lgkmcnt(0)
	s_barrier
	s_or_b32 s0, s69, 1
	s_mul_i32 s1, s69, 0x12000
	v_readlane_b32 s26, v250, 25
	v_readlane_b32 s27, v250, 26
	s_add_u32 s1, s26, s1
	s_addc_u32 s24, s27, 0
	s_add_u32 s38, s1, 0x5000
	v_readlane_b32 s1, v251, 5
	v_lshlrev_b32_e32 v114, 6, v102
	v_lshlrev_b32_e32 v115, 2, v97
	s_waitcnt vmcnt(5)
	v_add_u32_e32 v64, s1, v108
	v_readlane_b32 s1, v251, 6
	v_add_u32_e32 v56, 0xffffe000, v64
	v_or_b32_e32 v62, v64, v107
	v_or_b32_e32 v65, s1, v114
	v_lshrrev_b32_e32 v56, 10, v56
	s_movk_i32 s1, 0x1800
	v_mad_u32_u24 v56, v56, s1, s1
	v_cmp_lt_i32_e32 vcc, s13, v62
	v_or_b32_e32 v58, v65, v115
	s_addc_u32 s39, s24, 0
	v_cndmask_b32_e32 v56, 0, v56, vcc
	v_ashrrev_i32_e32 v57, 31, v56
	s_waitcnt vmcnt(4)
	v_lshlrev_b64 v[74:75], 2, v[56:57]
	v_ashrrev_i32_e32 v59, 31, v58
	v_ashrrev_i32_e32 v63, 31, v62
	v_lshl_add_u64 v[56:57], s[38:39], 0, v[74:75]
	v_lshlrev_b64 v[60:61], 2, v[58:59]
	v_readlane_b32 s16, v250, 15
	s_waitcnt vmcnt(1)
	v_lshl_add_u64 v[82:83], v[56:57], 0, v[60:61]
	v_lshlrev_b64 v[56:57], 12, v[62:63]
	v_readlane_b32 s17, v250, 16
	v_readlane_b32 s68, v250, 41
	s_mul_i32 s24, s0, 0x12000
	v_lshl_add_u64 v[56:57], s[16:17], 0, v[56:57]
	s_waitcnt vmcnt(0)
	v_lshl_add_u64 v[84:85], v[56:57], 0, v[60:61]
	global_load_dwordx4 v[116:119], v[82:83], off
	global_load_dwordx4 v[120:123], v[82:83], off offset:64
	global_load_dwordx4 v[124:127], v[82:83], off offset:128
	global_load_dwordx4 v[132:135], v[82:83], off offset:192
	global_load_dwordx4 v[190:193], v[84:85], off
	global_load_dwordx4 v[194:197], v[84:85], off offset:64
	global_load_dwordx4 v[198:201], v[84:85], off offset:128
	global_load_dwordx4 v[202:205], v[84:85], off offset:192
	v_add_co_u32_e32 v164, vcc, 0x10000, v84
	s_nop 1
	v_addc_co_u32_e32 v165, vcc, 0, v85, vcc
	v_add_co_u32_e32 v222, vcc, 0x20000, v84
	s_nop 1
	v_addc_co_u32_e32 v223, vcc, 0, v85, vcc
	v_add_co_u32_e32 v224, vcc, 0x30000, v84
	s_nop 1
	v_addc_co_u32_e32 v225, vcc, 0, v85, vcc
	global_load_dwordx4 v[206:209], v[164:165], off
	global_load_dwordx4 v[210:213], v[164:165], off offset:64
	global_load_dwordx4 v[214:217], v[164:165], off offset:128
	global_load_dwordx4 v[218:221], v[164:165], off offset:192
	s_lshl_b32 s0, s0, 12
	v_readlane_b32 s70, v250, 43
	v_readlane_b32 s71, v250, 44
	s_add_u32 s0, s70, s0
	s_addc_u32 s1, s71, 0
	s_add_u32 s24, s26, s24
	s_addc_u32 s25, s27, 0
	s_add_u32 s40, s24, 0x1000
	s_addc_u32 s41, s25, 0
	v_lshl_add_u64 v[74:75], s[40:41], 0, v[74:75]
	v_lshl_add_u64 v[56:57], s[0:1], 0, v[60:61]
	v_lshl_add_u64 v[86:87], v[74:75], 0, v[60:61]
	v_readlane_b32 s16, v250, 21
	v_lshlrev_b64 v[78:79], 11, v[62:63]
	v_readlane_b32 s17, v250, 22
	v_readlane_b32 s69, v250, 42
	v_readlane_b32 s69, v254, 49
	v_lshl_add_u64 v[78:79], s[16:17], 0, v[78:79]
	s_mul_i32 s24, s69, 0x140000
	s_add_u32 s24, s86, s24
	s_mov_b32 s16, 0xa000
	s_addc_u32 s25, s87, 0
	s_add_u32 s26, s24, 0xafba000
	s_addc_u32 s27, s25, 0
	v_cmp_eq_u32_e64 s[36:37], 0, v97
	v_readlane_b32 s72, v250, 45
	v_readlane_b32 s73, v250, 46
	v_readlane_b32 s74, v250, 47
	v_readlane_b32 s75, v250, 48
	v_readlane_b32 s76, v250, 49
	v_readlane_b32 s77, v250, 50
	v_readlane_b32 s78, v250, 51
	v_readlane_b32 s79, v250, 52
	v_readlane_b32 s80, v250, 53
	v_readlane_b32 s81, v250, 54
	v_readlane_b32 s82, v250, 55
	v_readlane_b32 s83, v250, 56
	s_waitcnt vmcnt(4)
	v_pk_fma_f32 v[68:69], v[94:95], v[118:119], v[192:193]
	v_pk_fma_f32 v[66:67], v[92:93], v[116:117], v[190:191]
	global_store_dwordx4 v[84:85], v[66:69], off
	global_load_dwordx4 v[136:139], v[56:57], off
	global_load_dwordx4 v[140:143], v[56:57], off offset:64
	global_load_dwordx4 v[144:147], v[56:57], off offset:128
	global_load_dwordx4 v[148:151], v[56:57], off offset:192
	global_load_dwordx4 v[152:155], v[86:87], off
	global_load_dwordx4 v[156:159], v[86:87], off offset:64
	global_load_dwordx4 v[160:163], v[86:87], off offset:128
	global_load_dwordx4 v[180:183], v[86:87], off offset:192
	v_lshl_add_u64 v[92:93], v[58:59], 1, v[78:79]
	s_waitcnt vmcnt(0)
	v_pk_mul_f32 v[72:73], v[68:69], v[138:139]
	v_pk_mul_f32 v[70:71], v[66:67], v[136:137]
	s_waitcnt vmcnt(0)
	v_pk_add_f32 v[76:77], v[154:155], 1.0 op_sel_hi:[1,0]
	v_pk_add_f32 v[74:75], v[152:153], 1.0 op_sel_hi:[1,0]
	v_pk_mul_f32 v[72:73], v[72:73], v[76:77]
	v_pk_mul_f32 v[70:71], v[70:71], v[74:75]
	v_and_b32_sdwa v76, v73, v170 dst_sel:DWORD dst_unused:UNUSED_PAD src0_sel:WORD_1 src1_sel:DWORD
	v_and_b32_sdwa v77, v71, v170 dst_sel:DWORD dst_unused:UNUSED_PAD src0_sel:WORD_1 src1_sel:DWORD
	v_and_b32_sdwa v74, v72, v170 dst_sel:DWORD dst_unused:UNUSED_PAD src0_sel:WORD_1 src1_sel:DWORD
	v_and_b32_sdwa v75, v70, v170 dst_sel:DWORD dst_unused:UNUSED_PAD src0_sel:WORD_1 src1_sel:DWORD
	v_add3_u32 v73, v73, v76, s56
	v_add3_u32 v71, v71, v77, s56
	v_add3_u32 v70, v70, v75, s56
	v_add3_u32 v72, v72, v74, s56
	v_and_b32_e32 v73, 0xffff0000, v73
	v_and_b32_e32 v74, 0xffff0000, v71
	v_or_b32_sdwa v71, v73, v72 dst_sel:DWORD dst_unused:UNUSED_PAD src0_sel:DWORD src1_sel:WORD_1
	v_or_b32_sdwa v70, v74, v70 dst_sel:DWORD dst_unused:UNUSED_PAD src0_sel:DWORD src1_sel:WORD_1
	global_store_dwordx2 v[92:93], v[70:71], off
	s_nop 0
	s_waitcnt vmcnt(0)
	v_pk_fma_f32 v[72:73], v[90:91], v[122:123], v[196:197]
	v_pk_fma_f32 v[70:71], v[88:89], v[120:121], v[194:195]
	global_store_dwordx4 v[84:85], v[70:73], off offset:64
	v_pk_mul_f32 v[76:77], v[72:73], v[142:143]
	v_pk_mul_f32 v[74:75], v[70:71], v[140:141]
	v_pk_add_f32 v[80:81], v[158:159], 1.0 op_sel_hi:[1,0]
	v_pk_add_f32 v[78:79], v[156:157], 1.0 op_sel_hi:[1,0]
	v_pk_mul_f32 v[76:77], v[76:77], v[80:81]
	v_pk_mul_f32 v[74:75], v[74:75], v[78:79]
	v_and_b32_sdwa v80, v77, v170 dst_sel:DWORD dst_unused:UNUSED_PAD src0_sel:WORD_1 src1_sel:DWORD
	v_and_b32_sdwa v81, v75, v170 dst_sel:DWORD dst_unused:UNUSED_PAD src0_sel:WORD_1 src1_sel:DWORD
	v_and_b32_sdwa v78, v76, v170 dst_sel:DWORD dst_unused:UNUSED_PAD src0_sel:WORD_1 src1_sel:DWORD
	v_and_b32_sdwa v79, v74, v170 dst_sel:DWORD dst_unused:UNUSED_PAD src0_sel:WORD_1 src1_sel:DWORD
	v_add3_u32 v77, v77, v80, s56
	v_add3_u32 v75, v75, v81, s56
	v_add3_u32 v74, v74, v79, s56
	v_add3_u32 v76, v76, v78, s56
	v_and_b32_e32 v77, 0xffff0000, v77
	v_and_b32_e32 v78, 0xffff0000, v75
	v_or_b32_sdwa v75, v77, v76 dst_sel:DWORD dst_unused:UNUSED_PAD src0_sel:DWORD src1_sel:WORD_1
	v_or_b32_sdwa v74, v78, v74 dst_sel:DWORD dst_unused:UNUSED_PAD src0_sel:DWORD src1_sel:WORD_1
	global_store_dwordx2 v[92:93], v[74:75], off offset:32
	s_nop 0
	v_pk_fma_f32 v[54:55], v[54:55], v[126:127], v[200:201]
	v_pk_fma_f32 v[52:53], v[52:53], v[124:125], v[198:199]
	global_store_dwordx4 v[84:85], v[52:55], off offset:128
	v_pk_mul_f32 v[76:77], v[54:55], v[146:147]
	v_pk_mul_f32 v[74:75], v[52:53], v[144:145]
	v_pk_add_f32 v[80:81], v[162:163], 1.0 op_sel_hi:[1,0]
	v_pk_add_f32 v[78:79], v[160:161], 1.0 op_sel_hi:[1,0]
	v_pk_mul_f32 v[76:77], v[76:77], v[80:81]
	v_pk_mul_f32 v[74:75], v[74:75], v[78:79]
	v_and_b32_sdwa v80, v77, v170 dst_sel:DWORD dst_unused:UNUSED_PAD src0_sel:WORD_1 src1_sel:DWORD
	v_and_b32_sdwa v81, v75, v170 dst_sel:DWORD dst_unused:UNUSED_PAD src0_sel:WORD_1 src1_sel:DWORD
	v_and_b32_sdwa v78, v76, v170 dst_sel:DWORD dst_unused:UNUSED_PAD src0_sel:WORD_1 src1_sel:DWORD
	v_and_b32_sdwa v79, v74, v170 dst_sel:DWORD dst_unused:UNUSED_PAD src0_sel:WORD_1 src1_sel:DWORD
	v_add3_u32 v77, v77, v80, s56
	v_add3_u32 v75, v75, v81, s56
	v_add3_u32 v74, v74, v79, s56
	v_add3_u32 v76, v76, v78, s56
	v_and_b32_e32 v77, 0xffff0000, v77
	v_and_b32_e32 v78, 0xffff0000, v75
	v_or_b32_sdwa v75, v77, v76 dst_sel:DWORD dst_unused:UNUSED_PAD src0_sel:DWORD src1_sel:WORD_1
	v_or_b32_sdwa v74, v78, v74 dst_sel:DWORD dst_unused:UNUSED_PAD src0_sel:DWORD src1_sel:WORD_1
	global_store_dwordx2 v[92:93], v[74:75], off offset:64
	s_nop 0
	v_pk_fma_f32 v[76:77], v[50:51], v[134:135], v[204:205]
	v_pk_fma_f32 v[74:75], v[48:49], v[132:133], v[202:203]
	global_store_dwordx4 v[84:85], v[74:77], off offset:192
	s_nop 0
	v_mul_f32_e32 v50, v67, v67
	v_mul_f32_e32 v51, v71, v71
	v_fmac_f32_e32 v50, v66, v66
	v_fmac_f32_e32 v51, v70, v70
	v_fmac_f32_e32 v50, v68, v68
	v_fmac_f32_e32 v51, v72, v72
	v_fmac_f32_e32 v50, v69, v69
	v_fmac_f32_e32 v51, v73, v73
	v_add_f32_e32 v50, v50, v51
	v_mul_f32_e32 v51, v53, v53
	v_fmac_f32_e32 v51, v52, v52
	v_fmac_f32_e32 v51, v54, v54
	v_fmac_f32_e32 v51, v55, v55
	v_add_f32_e32 v50, v50, v51
	v_mul_f32_e32 v51, v75, v75
	v_xor_b32_e32 v48, 16, v176
	v_fmac_f32_e32 v51, v74, v74
	v_cmp_lt_i32_e32 vcc, v48, v177
	v_fmac_f32_e32 v51, v76, v76
	v_fmac_f32_e32 v51, v77, v77
	v_cndmask_b32_e32 v48, v176, v48, vcc
	v_lshlrev_b32_e32 v105, 2, v48
	v_add_f32_e32 v50, v50, v51
	ds_bpermute_b32 v51, v105, v50
	v_xor_b32_e32 v49, 32, v176
	v_cmp_lt_i32_e32 vcc, v49, v177
	v_lshrrev_b32_e32 v48, 6, v65
	v_mul_lo_u32 v48, v48, s16
	v_cndmask_b32_e32 v49, v176, v49, vcc
	v_lshlrev_b32_e32 v104, 2, v49
	s_waitcnt lgkmcnt(0)
	v_add_f32_e32 v50, v50, v51
	ds_bpermute_b32 v51, v104, v50
	v_ashrrev_i32_e32 v49, 31, v48
	v_lshl_add_u64 v[48:49], s[26:27], 0, v[48:49]
	v_lshl_add_u64 v[48:49], v[62:63], 2, v[48:49]
	v_pk_mul_f32 v[52:53], v[76:77], v[150:151]
	v_pk_mul_f32 v[54:55], v[74:75], v[148:149]
	v_pk_add_f32 v[66:67], v[182:183], 1.0 op_sel_hi:[1,0]
	v_pk_add_f32 v[68:69], v[180:181], 1.0 op_sel_hi:[1,0]
	v_pk_mul_f32 v[52:53], v[52:53], v[66:67]
	v_pk_mul_f32 v[54:55], v[54:55], v[68:69]
	v_cvt_pk_bf16_f32 v53, v52, v53
	v_cvt_pk_bf16_f32 v52, v54, v55
	global_store_dwordx2 v[92:93], v[52:53], off offset:96
	s_and_saveexec_b64 s[24:25], s[36:37]
	s_cbranch_execz .LBB0_585
	s_waitcnt lgkmcnt(0)
	v_add_f32_e32 v50, v50, v51
	global_store_dword v[48:49], v50, off
.LBB0_585:
	s_or_b64 exec, exec, s[24:25]
	v_add_u32_e32 v50, 0xffffe010, v64
	v_or_b32_e32 v54, 16, v62
	v_lshrrev_b32_e32 v50, 10, v50
	s_movk_i32 s5, 0x1800
	s_movk_i32 s13, 0x1fff
	v_mad_u32_u24 v50, v50, s5, s5
	v_cmp_lt_i32_e32 vcc, s13, v54
	v_ashrrev_i32_e32 v55, 31, v54
	v_readlane_b32 s16, v250, 15
	v_cndmask_b32_e32 v50, 0, v50, vcc
	s_waitcnt lgkmcnt(0)
	v_ashrrev_i32_e32 v51, 31, v50
	v_lshlrev_b64 v[70:71], 2, v[50:51]
	v_lshl_add_u64 v[50:51], s[38:39], 0, v[70:71]
	v_lshl_add_u64 v[72:73], v[50:51], 0, v[60:61]
	v_lshlrev_b64 v[50:51], 12, v[54:55]
	v_readlane_b32 s17, v250, 16
	v_lshl_add_u64 v[70:71], s[40:41], 0, v[70:71]
	v_lshl_add_u64 v[70:71], v[70:71], 0, v[60:61]
	v_lshl_add_u64 v[50:51], s[16:17], 0, v[50:51]
	v_lshl_add_u64 v[74:75], v[50:51], 0, v[60:61]
	v_readlane_b32 s16, v250, 21
	v_lshlrev_b64 v[54:55], 11, v[54:55]
	v_readlane_b32 s17, v250, 22
	global_load_dwordx4 v[190:193], v[222:223], off
	global_load_dwordx4 v[194:197], v[222:223], off offset:64
	global_load_dwordx4 v[198:201], v[222:223], off offset:128
	global_load_dwordx4 v[202:205], v[222:223], off offset:192
	s_waitcnt vmcnt(20)
	v_pk_fma_f32 v[46:47], v[46:47], v[118:119], v[208:209]
	v_pk_fma_f32 v[44:45], v[44:45], v[116:117], v[206:207]
	global_store_dwordx4 v[74:75], v[44:47], off
	v_lshl_add_u64 v[54:55], s[16:17], 0, v[54:55]
	v_lshl_add_u64 v[54:55], v[58:59], 1, v[54:55]
	v_pk_mul_f32 v[52:53], v[46:47], v[138:139]
	v_pk_mul_f32 v[50:51], v[44:45], v[136:137]
	v_pk_add_f32 v[68:69], v[154:155], 1.0 op_sel_hi:[1,0]
	v_pk_add_f32 v[66:67], v[152:153], 1.0 op_sel_hi:[1,0]
	v_pk_mul_f32 v[52:53], v[52:53], v[68:69]
	v_pk_mul_f32 v[50:51], v[50:51], v[66:67]
	v_and_b32_sdwa v66, v53, v170 dst_sel:DWORD dst_unused:UNUSED_PAD src0_sel:WORD_1 src1_sel:DWORD
	v_and_b32_sdwa v67, v51, v170 dst_sel:DWORD dst_unused:UNUSED_PAD src0_sel:WORD_1 src1_sel:DWORD
	v_and_b32_sdwa v63, v52, v170 dst_sel:DWORD dst_unused:UNUSED_PAD src0_sel:WORD_1 src1_sel:DWORD
	v_and_b32_sdwa v65, v50, v170 dst_sel:DWORD dst_unused:UNUSED_PAD src0_sel:WORD_1 src1_sel:DWORD
	v_add3_u32 v53, v53, v66, s56
	v_add3_u32 v51, v51, v67, s56
	v_add3_u32 v50, v50, v65, s56
	v_add3_u32 v52, v52, v63, s56
	v_and_b32_e32 v53, 0xffff0000, v53
	v_and_b32_e32 v63, 0xffff0000, v51
	v_or_b32_sdwa v51, v53, v52 dst_sel:DWORD dst_unused:UNUSED_PAD src0_sel:DWORD src1_sel:WORD_1
	v_or_b32_sdwa v50, v63, v50 dst_sel:DWORD dst_unused:UNUSED_PAD src0_sel:DWORD src1_sel:WORD_1
	global_store_dwordx2 v[54:55], v[50:51], off
	s_nop 0
	v_pk_fma_f32 v[42:43], v[42:43], v[122:123], v[212:213]
	v_pk_fma_f32 v[40:41], v[40:41], v[120:121], v[210:211]
	global_store_dwordx4 v[74:75], v[40:43], off offset:64
	v_pk_mul_f32 v[52:53], v[42:43], v[142:143]
	v_pk_mul_f32 v[50:51], v[40:41], v[140:141]
	v_pk_add_f32 v[68:69], v[158:159], 1.0 op_sel_hi:[1,0]
	v_pk_add_f32 v[66:67], v[156:157], 1.0 op_sel_hi:[1,0]
	v_pk_mul_f32 v[52:53], v[52:53], v[68:69]
	v_pk_mul_f32 v[50:51], v[50:51], v[66:67]
	v_and_b32_sdwa v66, v53, v170 dst_sel:DWORD dst_unused:UNUSED_PAD src0_sel:WORD_1 src1_sel:DWORD
	v_and_b32_sdwa v67, v51, v170 dst_sel:DWORD dst_unused:UNUSED_PAD src0_sel:WORD_1 src1_sel:DWORD
	v_and_b32_sdwa v63, v52, v170 dst_sel:DWORD dst_unused:UNUSED_PAD src0_sel:WORD_1 src1_sel:DWORD
	v_and_b32_sdwa v65, v50, v170 dst_sel:DWORD dst_unused:UNUSED_PAD src0_sel:WORD_1 src1_sel:DWORD
	v_add3_u32 v53, v53, v66, s56
	v_add3_u32 v51, v51, v67, s56
	v_add3_u32 v50, v50, v65, s56
	v_add3_u32 v52, v52, v63, s56
	v_and_b32_e32 v53, 0xffff0000, v53
	v_and_b32_e32 v63, 0xffff0000, v51
	v_or_b32_sdwa v51, v53, v52 dst_sel:DWORD dst_unused:UNUSED_PAD src0_sel:DWORD src1_sel:WORD_1
	v_or_b32_sdwa v50, v63, v50 dst_sel:DWORD dst_unused:UNUSED_PAD src0_sel:DWORD src1_sel:WORD_1
	global_store_dwordx2 v[54:55], v[50:51], off offset:32
	s_nop 0
	v_pk_fma_f32 v[38:39], v[38:39], v[126:127], v[216:217]
	v_pk_fma_f32 v[36:37], v[36:37], v[124:125], v[214:215]
	global_store_dwordx4 v[74:75], v[36:39], off offset:128
	v_pk_mul_f32 v[52:53], v[38:39], v[146:147]
	v_pk_mul_f32 v[50:51], v[36:37], v[144:145]
	v_pk_add_f32 v[68:69], v[162:163], 1.0 op_sel_hi:[1,0]
	v_pk_add_f32 v[66:67], v[160:161], 1.0 op_sel_hi:[1,0]
	v_pk_mul_f32 v[52:53], v[52:53], v[68:69]
	v_pk_mul_f32 v[50:51], v[50:51], v[66:67]
	v_and_b32_sdwa v66, v53, v170 dst_sel:DWORD dst_unused:UNUSED_PAD src0_sel:WORD_1 src1_sel:DWORD
	v_and_b32_sdwa v67, v51, v170 dst_sel:DWORD dst_unused:UNUSED_PAD src0_sel:WORD_1 src1_sel:DWORD
	v_and_b32_sdwa v63, v52, v170 dst_sel:DWORD dst_unused:UNUSED_PAD src0_sel:WORD_1 src1_sel:DWORD
	v_and_b32_sdwa v65, v50, v170 dst_sel:DWORD dst_unused:UNUSED_PAD src0_sel:WORD_1 src1_sel:DWORD
	v_add3_u32 v53, v53, v66, s56
	v_add3_u32 v51, v51, v67, s56
	v_add3_u32 v50, v50, v65, s56
	v_add3_u32 v52, v52, v63, s56
	v_and_b32_e32 v53, 0xffff0000, v53
	v_and_b32_e32 v63, 0xffff0000, v51
	v_or_b32_sdwa v51, v53, v52 dst_sel:DWORD dst_unused:UNUSED_PAD src0_sel:DWORD src1_sel:WORD_1
	v_or_b32_sdwa v50, v63, v50 dst_sel:DWORD dst_unused:UNUSED_PAD src0_sel:DWORD src1_sel:WORD_1
	global_store_dwordx2 v[54:55], v[50:51], off offset:64
	s_nop 0
	v_pk_fma_f32 v[52:53], v[34:35], v[134:135], v[220:221]
	v_pk_fma_f32 v[50:51], v[32:33], v[132:133], v[218:219]
	global_store_dwordx4 v[74:75], v[50:53], off offset:192
	s_nop 0
	v_mul_f32_e32 v32, v45, v45
	v_mul_f32_e32 v33, v41, v41
	v_fmac_f32_e32 v32, v44, v44
	v_fmac_f32_e32 v33, v40, v40
	v_fmac_f32_e32 v32, v46, v46
	v_fmac_f32_e32 v33, v42, v42
	v_fmac_f32_e32 v32, v47, v47
	v_fmac_f32_e32 v33, v43, v43
	v_add_f32_e32 v32, v32, v33
	v_mul_f32_e32 v33, v37, v37
	v_fmac_f32_e32 v33, v36, v36
	v_fmac_f32_e32 v33, v38, v38
	v_fmac_f32_e32 v33, v39, v39
	v_add_f32_e32 v32, v32, v33
	v_mul_f32_e32 v33, v51, v51
	v_fmac_f32_e32 v33, v50, v50
	v_fmac_f32_e32 v33, v52, v52
	v_fmac_f32_e32 v33, v53, v53
	v_add_f32_e32 v32, v32, v33
	ds_bpermute_b32 v33, v105, v32
	s_waitcnt lgkmcnt(0)
	v_add_f32_e32 v32, v32, v33
	ds_bpermute_b32 v33, v104, v32
	v_pk_mul_f32 v[34:35], v[52:53], v[150:151]
	v_pk_mul_f32 v[36:37], v[50:51], v[148:149]
	v_pk_add_f32 v[38:39], v[182:183], 1.0 op_sel_hi:[1,0]
	v_pk_add_f32 v[40:41], v[180:181], 1.0 op_sel_hi:[1,0]
	v_pk_mul_f32 v[34:35], v[34:35], v[38:39]
	v_pk_mul_f32 v[36:37], v[36:37], v[40:41]
	v_cvt_pk_bf16_f32 v35, v34, v35
	v_cvt_pk_bf16_f32 v34, v36, v37
	global_store_dwordx2 v[54:55], v[34:35], off offset:96
	s_and_saveexec_b64 s[24:25], s[36:37]
	s_cbranch_execz .LBB0_587
	s_waitcnt lgkmcnt(0)
	v_add_f32_e32 v32, v32, v33
	global_store_dword v[48:49], v32, off offset:64
.LBB0_587:
	s_or_b64 exec, exec, s[24:25]
	v_add_u32_e32 v32, 0xffffe020, v64
	v_or_b32_e32 v40, 32, v62
	v_lshrrev_b32_e32 v32, 10, v32
	v_mad_u32_u24 v32, v32, s5, s5
	v_cmp_lt_i32_e32 vcc, s13, v40
	v_ashrrev_i32_e32 v41, 31, v40
	v_readlane_b32 s16, v250, 15
	v_cndmask_b32_e32 v32, 0, v32, vcc
	s_waitcnt lgkmcnt(0)
	v_ashrrev_i32_e32 v33, 31, v32
	v_lshlrev_b64 v[42:43], 2, v[32:33]
	v_lshl_add_u64 v[32:33], s[38:39], 0, v[42:43]
	v_lshl_add_u64 v[44:45], v[32:33], 0, v[60:61]
	v_lshlrev_b64 v[32:33], 12, v[40:41]
	v_readlane_b32 s17, v250, 16
	v_lshl_add_u64 v[42:43], s[40:41], 0, v[42:43]
	v_lshl_add_u64 v[42:43], v[42:43], 0, v[60:61]
	v_lshl_add_u64 v[32:33], s[16:17], 0, v[32:33]
	v_lshl_add_u64 v[46:47], v[32:33], 0, v[60:61]
	v_readlane_b32 s16, v250, 21
	v_lshlrev_b64 v[40:41], 11, v[40:41]
	v_readlane_b32 s17, v250, 22
	global_load_dwordx4 v[206:209], v[224:225], off
	global_load_dwordx4 v[210:213], v[224:225], off offset:64
	global_load_dwordx4 v[214:217], v[224:225], off offset:128
	global_load_dwordx4 v[218:221], v[224:225], off offset:192
	s_waitcnt vmcnt(12)
	v_pk_fma_f32 v[30:31], v[30:31], v[118:119], v[192:193]
	v_pk_fma_f32 v[28:29], v[28:29], v[116:117], v[190:191]
	global_store_dwordx4 v[46:47], v[28:31], off
	v_lshl_add_u64 v[40:41], s[16:17], 0, v[40:41]
	v_lshl_add_u64 v[50:51], v[58:59], 1, v[40:41]
	v_pk_mul_f32 v[34:35], v[30:31], v[138:139]
	v_pk_mul_f32 v[32:33], v[28:29], v[136:137]
	v_pk_add_f32 v[38:39], v[154:155], 1.0 op_sel_hi:[1,0]
	v_pk_add_f32 v[36:37], v[152:153], 1.0 op_sel_hi:[1,0]
	v_pk_mul_f32 v[34:35], v[34:35], v[38:39]
	v_pk_mul_f32 v[32:33], v[32:33], v[36:37]
	v_and_b32_sdwa v38, v35, v170 dst_sel:DWORD dst_unused:UNUSED_PAD src0_sel:WORD_1 src1_sel:DWORD
	v_and_b32_sdwa v39, v33, v170 dst_sel:DWORD dst_unused:UNUSED_PAD src0_sel:WORD_1 src1_sel:DWORD
	v_and_b32_sdwa v36, v34, v170 dst_sel:DWORD dst_unused:UNUSED_PAD src0_sel:WORD_1 src1_sel:DWORD
	v_and_b32_sdwa v37, v32, v170 dst_sel:DWORD dst_unused:UNUSED_PAD src0_sel:WORD_1 src1_sel:DWORD
	v_add3_u32 v35, v35, v38, s56
	v_add3_u32 v33, v33, v39, s56
	v_add3_u32 v32, v32, v37, s56
	v_add3_u32 v34, v34, v36, s56
	v_and_b32_e32 v35, 0xffff0000, v35
	v_and_b32_e32 v36, 0xffff0000, v33
	v_or_b32_sdwa v33, v35, v34 dst_sel:DWORD dst_unused:UNUSED_PAD src0_sel:DWORD src1_sel:WORD_1
	v_or_b32_sdwa v32, v36, v32 dst_sel:DWORD dst_unused:UNUSED_PAD src0_sel:DWORD src1_sel:WORD_1
	global_store_dwordx2 v[50:51], v[32:33], off
	s_nop 0
	v_pk_fma_f32 v[26:27], v[26:27], v[122:123], v[196:197]
	v_pk_fma_f32 v[24:25], v[24:25], v[120:121], v[194:195]
	global_store_dwordx4 v[46:47], v[24:27], off offset:64
	v_pk_mul_f32 v[34:35], v[26:27], v[142:143]
	v_pk_mul_f32 v[32:33], v[24:25], v[140:141]
	v_pk_add_f32 v[38:39], v[158:159], 1.0 op_sel_hi:[1,0]
	v_pk_add_f32 v[36:37], v[156:157], 1.0 op_sel_hi:[1,0]
	v_pk_mul_f32 v[34:35], v[34:35], v[38:39]
	v_pk_mul_f32 v[32:33], v[32:33], v[36:37]
	v_and_b32_sdwa v38, v35, v170 dst_sel:DWORD dst_unused:UNUSED_PAD src0_sel:WORD_1 src1_sel:DWORD
	v_and_b32_sdwa v39, v33, v170 dst_sel:DWORD dst_unused:UNUSED_PAD src0_sel:WORD_1 src1_sel:DWORD
	v_and_b32_sdwa v36, v34, v170 dst_sel:DWORD dst_unused:UNUSED_PAD src0_sel:WORD_1 src1_sel:DWORD
	v_and_b32_sdwa v37, v32, v170 dst_sel:DWORD dst_unused:UNUSED_PAD src0_sel:WORD_1 src1_sel:DWORD
	v_add3_u32 v35, v35, v38, s56
	v_add3_u32 v33, v33, v39, s56
	v_add3_u32 v32, v32, v37, s56
	v_add3_u32 v34, v34, v36, s56
	v_and_b32_e32 v35, 0xffff0000, v35
	v_and_b32_e32 v36, 0xffff0000, v33
	v_or_b32_sdwa v33, v35, v34 dst_sel:DWORD dst_unused:UNUSED_PAD src0_sel:DWORD src1_sel:WORD_1
	v_or_b32_sdwa v32, v36, v32 dst_sel:DWORD dst_unused:UNUSED_PAD src0_sel:DWORD src1_sel:WORD_1
	global_store_dwordx2 v[50:51], v[32:33], off offset:32
	s_nop 0
	v_pk_fma_f32 v[22:23], v[22:23], v[126:127], v[200:201]
	v_pk_fma_f32 v[20:21], v[20:21], v[124:125], v[198:199]
	global_store_dwordx4 v[46:47], v[20:23], off offset:128
	v_pk_mul_f32 v[34:35], v[22:23], v[146:147]
	v_pk_mul_f32 v[32:33], v[20:21], v[144:145]
	v_pk_add_f32 v[38:39], v[162:163], 1.0 op_sel_hi:[1,0]
	v_pk_add_f32 v[36:37], v[160:161], 1.0 op_sel_hi:[1,0]
	v_pk_mul_f32 v[34:35], v[34:35], v[38:39]
	v_pk_mul_f32 v[32:33], v[32:33], v[36:37]
	v_and_b32_sdwa v38, v35, v170 dst_sel:DWORD dst_unused:UNUSED_PAD src0_sel:WORD_1 src1_sel:DWORD
	v_and_b32_sdwa v39, v33, v170 dst_sel:DWORD dst_unused:UNUSED_PAD src0_sel:WORD_1 src1_sel:DWORD
	v_and_b32_sdwa v36, v34, v170 dst_sel:DWORD dst_unused:UNUSED_PAD src0_sel:WORD_1 src1_sel:DWORD
	v_and_b32_sdwa v37, v32, v170 dst_sel:DWORD dst_unused:UNUSED_PAD src0_sel:WORD_1 src1_sel:DWORD
	v_add3_u32 v35, v35, v38, s56
	v_add3_u32 v33, v33, v39, s56
	v_add3_u32 v32, v32, v37, s56
	v_add3_u32 v34, v34, v36, s56
	v_and_b32_e32 v35, 0xffff0000, v35
	v_and_b32_e32 v36, 0xffff0000, v33
	v_or_b32_sdwa v33, v35, v34 dst_sel:DWORD dst_unused:UNUSED_PAD src0_sel:DWORD src1_sel:WORD_1
	v_or_b32_sdwa v32, v36, v32 dst_sel:DWORD dst_unused:UNUSED_PAD src0_sel:DWORD src1_sel:WORD_1
	global_store_dwordx2 v[50:51], v[32:33], off offset:64
	s_nop 0
	v_pk_fma_f32 v[34:35], v[18:19], v[134:135], v[204:205]
	v_pk_fma_f32 v[32:33], v[16:17], v[132:133], v[202:203]
	global_store_dwordx4 v[46:47], v[32:35], off offset:192
	s_nop 0
	v_mul_f32_e32 v16, v29, v29
	v_mul_f32_e32 v17, v25, v25
	v_fmac_f32_e32 v16, v28, v28
	v_fmac_f32_e32 v17, v24, v24
	v_fmac_f32_e32 v16, v30, v30
	v_fmac_f32_e32 v17, v26, v26
	v_fmac_f32_e32 v16, v31, v31
	v_fmac_f32_e32 v17, v27, v27
	v_add_f32_e32 v16, v16, v17
	v_mul_f32_e32 v17, v21, v21
	v_fmac_f32_e32 v17, v20, v20
	v_fmac_f32_e32 v17, v22, v22
	v_fmac_f32_e32 v17, v23, v23
	v_add_f32_e32 v16, v16, v17
	v_mul_f32_e32 v17, v33, v33
	v_fmac_f32_e32 v17, v32, v32
	v_fmac_f32_e32 v17, v34, v34
	v_fmac_f32_e32 v17, v35, v35
	v_add_f32_e32 v16, v16, v17
	ds_bpermute_b32 v17, v105, v16
	s_waitcnt lgkmcnt(0)
	v_add_f32_e32 v16, v16, v17
	ds_bpermute_b32 v17, v104, v16
	v_pk_mul_f32 v[18:19], v[34:35], v[150:151]
	v_pk_mul_f32 v[20:21], v[32:33], v[148:149]
	v_pk_add_f32 v[22:23], v[182:183], 1.0 op_sel_hi:[1,0]
	v_pk_add_f32 v[24:25], v[180:181], 1.0 op_sel_hi:[1,0]
	v_pk_mul_f32 v[18:19], v[18:19], v[22:23]
	v_pk_mul_f32 v[20:21], v[20:21], v[24:25]
	v_cvt_pk_bf16_f32 v19, v18, v19
	v_cvt_pk_bf16_f32 v18, v20, v21
	global_store_dwordx2 v[50:51], v[18:19], off offset:96
	s_and_saveexec_b64 s[24:25], s[36:37]
	s_movk_i32 s8, 0x400
	s_mov_b32 s5, 0xffff0000
	s_mov_b32 s9, 0x12000
	s_movk_i32 s89, 0xff
	s_cbranch_execz .LBB0_589
	s_waitcnt lgkmcnt(0)
	v_add_f32_e32 v16, v16, v17
	global_store_dword v[48:49], v16, off offset:128
.LBB0_589:
	s_or_b64 exec, exec, s[24:25]
	v_add_u32_e32 v16, 0xffffe030, v64
	v_or_b32_e32 v24, 48, v62
	v_lshrrev_b32_e32 v16, 10, v16
	s_movk_i32 s16, 0x1800
	v_mad_u32_u24 v16, v16, s16, s16
	v_cmp_lt_i32_e32 vcc, s13, v24
	v_ashrrev_i32_e32 v25, 31, v24
	v_readlane_b32 s16, v250, 15
	v_cndmask_b32_e32 v16, 0, v16, vcc
	s_waitcnt lgkmcnt(0)
	v_ashrrev_i32_e32 v17, 31, v16
	v_lshlrev_b64 v[26:27], 2, v[16:17]
	v_lshl_add_u64 v[16:17], s[38:39], 0, v[26:27]
	v_lshl_add_u64 v[28:29], v[16:17], 0, v[60:61]
	v_lshlrev_b64 v[16:17], 12, v[24:25]
	v_readlane_b32 s17, v250, 16
	v_lshl_add_u64 v[26:27], s[40:41], 0, v[26:27]
	v_lshl_add_u64 v[26:27], v[26:27], 0, v[60:61]
	v_lshl_add_u64 v[16:17], s[16:17], 0, v[16:17]
	v_lshl_add_u64 v[30:31], v[16:17], 0, v[60:61]
	v_readlane_b32 s16, v250, 21
	v_lshlrev_b64 v[24:25], 11, v[24:25]
	v_readlane_b32 s17, v250, 22
	s_waitcnt vmcnt(8)
	v_pk_fma_f32 v[14:15], v[14:15], v[118:119], v[208:209]
	v_pk_fma_f32 v[12:13], v[12:13], v[116:117], v[206:207]
	global_store_dwordx4 v[30:31], v[12:15], off
	v_lshl_add_u64 v[24:25], s[16:17], 0, v[24:25]
	v_lshl_add_u64 v[32:33], v[58:59], 1, v[24:25]
	v_pk_mul_f32 v[18:19], v[14:15], v[138:139]
	v_pk_mul_f32 v[16:17], v[12:13], v[136:137]
	v_pk_add_f32 v[22:23], v[154:155], 1.0 op_sel_hi:[1,0]
	v_pk_add_f32 v[20:21], v[152:153], 1.0 op_sel_hi:[1,0]
	v_pk_mul_f32 v[18:19], v[18:19], v[22:23]
	v_pk_mul_f32 v[16:17], v[16:17], v[20:21]
	v_and_b32_sdwa v22, v19, v170 dst_sel:DWORD dst_unused:UNUSED_PAD src0_sel:WORD_1 src1_sel:DWORD
	v_and_b32_sdwa v23, v17, v170 dst_sel:DWORD dst_unused:UNUSED_PAD src0_sel:WORD_1 src1_sel:DWORD
	v_and_b32_sdwa v20, v18, v170 dst_sel:DWORD dst_unused:UNUSED_PAD src0_sel:WORD_1 src1_sel:DWORD
	v_and_b32_sdwa v21, v16, v170 dst_sel:DWORD dst_unused:UNUSED_PAD src0_sel:WORD_1 src1_sel:DWORD
	v_add3_u32 v19, v19, v22, s56
	v_add3_u32 v17, v17, v23, s56
	v_add3_u32 v16, v16, v21, s56
	v_add3_u32 v18, v18, v20, s56
	v_and_b32_e32 v19, 0xffff0000, v19
	v_and_b32_e32 v20, 0xffff0000, v17
	v_or_b32_sdwa v17, v19, v18 dst_sel:DWORD dst_unused:UNUSED_PAD src0_sel:DWORD src1_sel:WORD_1
	v_or_b32_sdwa v16, v20, v16 dst_sel:DWORD dst_unused:UNUSED_PAD src0_sel:DWORD src1_sel:WORD_1
	global_store_dwordx2 v[32:33], v[16:17], off
	s_nop 0
	v_pk_fma_f32 v[10:11], v[10:11], v[122:123], v[212:213]
	v_pk_fma_f32 v[8:9], v[8:9], v[120:121], v[210:211]
	global_store_dwordx4 v[30:31], v[8:11], off offset:64
	v_pk_mul_f32 v[18:19], v[10:11], v[142:143]
	v_pk_mul_f32 v[16:17], v[8:9], v[140:141]
	v_pk_add_f32 v[22:23], v[158:159], 1.0 op_sel_hi:[1,0]
	v_pk_add_f32 v[20:21], v[156:157], 1.0 op_sel_hi:[1,0]
	v_pk_mul_f32 v[18:19], v[18:19], v[22:23]
	v_pk_mul_f32 v[16:17], v[16:17], v[20:21]
	v_and_b32_sdwa v22, v19, v170 dst_sel:DWORD dst_unused:UNUSED_PAD src0_sel:WORD_1 src1_sel:DWORD
	v_and_b32_sdwa v23, v17, v170 dst_sel:DWORD dst_unused:UNUSED_PAD src0_sel:WORD_1 src1_sel:DWORD
	v_and_b32_sdwa v20, v18, v170 dst_sel:DWORD dst_unused:UNUSED_PAD src0_sel:WORD_1 src1_sel:DWORD
	v_and_b32_sdwa v21, v16, v170 dst_sel:DWORD dst_unused:UNUSED_PAD src0_sel:WORD_1 src1_sel:DWORD
	v_add3_u32 v19, v19, v22, s56
	v_add3_u32 v17, v17, v23, s56
	v_add3_u32 v16, v16, v21, s56
	v_add3_u32 v18, v18, v20, s56
	v_and_b32_e32 v19, 0xffff0000, v19
	v_and_b32_e32 v20, 0xffff0000, v17
	v_or_b32_sdwa v17, v19, v18 dst_sel:DWORD dst_unused:UNUSED_PAD src0_sel:DWORD src1_sel:WORD_1
	v_or_b32_sdwa v16, v20, v16 dst_sel:DWORD dst_unused:UNUSED_PAD src0_sel:DWORD src1_sel:WORD_1
	global_store_dwordx2 v[32:33], v[16:17], off offset:32
	s_nop 0
	v_pk_fma_f32 v[6:7], v[6:7], v[126:127], v[216:217]
	v_pk_fma_f32 v[4:5], v[4:5], v[124:125], v[214:215]
	global_store_dwordx4 v[30:31], v[4:7], off offset:128
	v_pk_mul_f32 v[18:19], v[6:7], v[146:147]
	v_pk_mul_f32 v[16:17], v[4:5], v[144:145]
	v_pk_add_f32 v[22:23], v[162:163], 1.0 op_sel_hi:[1,0]
	v_pk_add_f32 v[20:21], v[160:161], 1.0 op_sel_hi:[1,0]
	v_pk_mul_f32 v[18:19], v[18:19], v[22:23]
	v_pk_mul_f32 v[16:17], v[16:17], v[20:21]
	v_and_b32_sdwa v22, v19, v170 dst_sel:DWORD dst_unused:UNUSED_PAD src0_sel:WORD_1 src1_sel:DWORD
	v_and_b32_sdwa v23, v17, v170 dst_sel:DWORD dst_unused:UNUSED_PAD src0_sel:WORD_1 src1_sel:DWORD
	v_and_b32_sdwa v20, v18, v170 dst_sel:DWORD dst_unused:UNUSED_PAD src0_sel:WORD_1 src1_sel:DWORD
	v_and_b32_sdwa v21, v16, v170 dst_sel:DWORD dst_unused:UNUSED_PAD src0_sel:WORD_1 src1_sel:DWORD
	v_add3_u32 v19, v19, v22, s56
	v_add3_u32 v17, v17, v23, s56
	v_add3_u32 v16, v16, v21, s56
	v_add3_u32 v18, v18, v20, s56
	v_and_b32_e32 v19, 0xffff0000, v19
	v_and_b32_e32 v20, 0xffff0000, v17
	v_or_b32_sdwa v17, v19, v18 dst_sel:DWORD dst_unused:UNUSED_PAD src0_sel:DWORD src1_sel:WORD_1
	v_or_b32_sdwa v16, v20, v16 dst_sel:DWORD dst_unused:UNUSED_PAD src0_sel:DWORD src1_sel:WORD_1
	global_store_dwordx2 v[32:33], v[16:17], off offset:64
	s_nop 0
	v_pk_fma_f32 v[18:19], v[2:3], v[134:135], v[220:221]
	v_pk_fma_f32 v[16:17], v[0:1], v[132:133], v[218:219]
	global_store_dwordx4 v[30:31], v[16:19], off offset:192
	s_nop 0
	v_mul_f32_e32 v0, v13, v13
	v_mul_f32_e32 v1, v9, v9
	v_fmac_f32_e32 v0, v12, v12
	v_fmac_f32_e32 v1, v8, v8
	v_fmac_f32_e32 v0, v14, v14
	v_fmac_f32_e32 v1, v10, v10
	v_fmac_f32_e32 v0, v15, v15
	v_fmac_f32_e32 v1, v11, v11
	v_add_f32_e32 v0, v0, v1
	v_mul_f32_e32 v1, v5, v5
	v_fmac_f32_e32 v1, v4, v4
	v_fmac_f32_e32 v1, v6, v6
	v_fmac_f32_e32 v1, v7, v7
	v_add_f32_e32 v0, v0, v1
	v_mul_f32_e32 v1, v17, v17
	v_fmac_f32_e32 v1, v16, v16
	v_fmac_f32_e32 v1, v18, v18
	v_fmac_f32_e32 v1, v19, v19
	v_add_f32_e32 v0, v0, v1
	ds_bpermute_b32 v1, v105, v0
	s_waitcnt lgkmcnt(0)
	v_add_f32_e32 v0, v0, v1
	ds_bpermute_b32 v1, v104, v0
	v_pk_mul_f32 v[2:3], v[18:19], v[150:151]
	v_pk_mul_f32 v[4:5], v[16:17], v[148:149]
	v_pk_add_f32 v[6:7], v[182:183], 1.0 op_sel_hi:[1,0]
	v_pk_add_f32 v[8:9], v[180:181], 1.0 op_sel_hi:[1,0]
	v_pk_mul_f32 v[2:3], v[2:3], v[6:7]
	v_pk_mul_f32 v[4:5], v[4:5], v[8:9]
	v_cvt_pk_bf16_f32 v3, v2, v3
	v_cvt_pk_bf16_f32 v2, v4, v5
	global_store_dwordx2 v[32:33], v[2:3], off offset:96
	s_and_saveexec_b64 s[24:25], s[36:37]
	s_cbranch_execz .LBB0_591
	s_waitcnt lgkmcnt(0)
	v_add_f32_e32 v0, v0, v1
	global_store_dword v[48:49], v0, off offset:192

.Ltail596:
	s_add_i32 s29, s42, 2
	ds_read_b128 v[136:139], v111 offset:16384
	ds_read_b128 v[140:143], v111 offset:18432
	ds_read_b128 v[144:147], v111 offset:20480
	ds_read_b128 v[148:151], v111 offset:22528
	ds_read_b128 v[116:119], v110
	s_add_i32 s42, s42, 4
	ds_read_b128 v[120:123], v110 offset:2048
	s_min_u32 s42, s42, 63
	s_lshl_b32 s92, s42, 7
	ds_read_b128 v[124:127], v110 offset:4096
	ds_read_b128 v[194:197], v113 offset:16384
	ds_read_b128 v[198:201], v113 offset:18432
	ds_read_b128 v[202:205], v113 offset:20480
	ds_read_b128 v[206:209], v113 offset:22528
	v_lshl_add_u64 v[164:165], v[100:101], 0, s[92:93]
	ds_read_b128 v[132:135], v110 offset:6144
	ds_read_b128 v[152:155], v112
	ds_read_b128 v[156:159], v112 offset:2048
	ds_read_b128 v[160:163], v112 offset:4096
	ds_read_b128 v[190:193], v112 offset:6144
	s_waitcnt lgkmcnt(11)
	v_mfma_f32_16x16x32_bf16 v[92:95], v[136:139], v[116:119], v[92:95]
	v_mfma_f32_16x16x32_bf16 v[88:91], v[140:143], v[116:119], v[88:91]
	v_mfma_f32_16x16x32_bf16 v[56:59], v[144:147], v[116:119], v[56:59]
	v_mfma_f32_16x16x32_bf16 v[48:51], v[148:151], v[116:119], v[48:51]
	s_waitcnt vmcnt(7)
	ds_write_b128 v109, v[52:55] offset:32768
	v_add_co_u32_e32 v52, vcc, s7, v164
	s_waitcnt lgkmcnt(11)
	v_mfma_f32_16x16x32_bf16 v[44:47], v[136:139], v[120:123], v[44:47]
	v_addc_co_u32_e32 v53, vcc, 0, v165, vcc
	v_mfma_f32_16x16x32_bf16 v[40:43], v[140:143], v[120:123], v[40:43]
	v_mfma_f32_16x16x32_bf16 v[36:39], v[144:147], v[120:123], v[36:39]
	v_mfma_f32_16x16x32_bf16 v[32:35], v[148:151], v[120:123], v[32:35]
	v_add_co_u32_e32 v52, vcc, s52, v164
	s_waitcnt vmcnt(6)
	ds_write_b128 v109, v[60:63] offset:36864
	s_nop 0
	v_addc_co_u32_e32 v53, vcc, 0, v165, vcc
	s_waitcnt lgkmcnt(11)
	v_mfma_f32_16x16x32_bf16 v[28:31], v[136:139], v[124:127], v[28:31]
	v_mfma_f32_16x16x32_bf16 v[24:27], v[140:143], v[124:127], v[24:27]
	v_mfma_f32_16x16x32_bf16 v[20:23], v[144:147], v[124:127], v[20:23]
	v_mfma_f32_16x16x32_bf16 v[16:19], v[148:151], v[124:127], v[16:19]
	v_add_co_u32_e32 v52, vcc, s34, v164
	s_waitcnt vmcnt(5)
	ds_write_b128 v109, v[64:67] offset:40960
	s_nop 0
	v_addc_co_u32_e32 v53, vcc, 0, v165, vcc
	v_lshl_add_u64 v[64:65], v[102:103], 0, s[92:93]
	v_add_co_u32_e32 v66, vcc, s7, v64
	s_waitcnt lgkmcnt(7)
	v_mfma_f32_16x16x32_bf16 v[12:15], v[136:139], v[132:135], v[12:15]
	v_addc_co_u32_e32 v67, vcc, 0, v65, vcc
	v_mfma_f32_16x16x32_bf16 v[8:11], v[140:143], v[132:135], v[8:11]
	v_mfma_f32_16x16x32_bf16 v[4:7], v[144:147], v[132:135], v[4:7]
	v_mfma_f32_16x16x32_bf16 v[0:3], v[148:151], v[132:135], v[0:3]
	s_waitcnt vmcnt(4)
	ds_write_b128 v109, v[72:75] offset:45056
	s_waitcnt lgkmcnt(7)
	v_mfma_f32_16x16x32_bf16 v[52:55], v[194:197], v[152:155], v[92:95]
	v_mfma_f32_16x16x32_bf16 v[60:63], v[198:201], v[152:155], v[88:91]
	v_mfma_f32_16x16x32_bf16 v[56:59], v[202:205], v[152:155], v[56:59]
	v_mfma_f32_16x16x32_bf16 v[48:51], v[206:209], v[152:155], v[48:51]
	s_waitcnt vmcnt(3)
	ds_write_b128 v109, v[68:71] offset:49152
	s_waitcnt lgkmcnt(7)
	v_mfma_f32_16x16x32_bf16 v[44:47], v[194:197], v[156:159], v[44:47]
	v_mfma_f32_16x16x32_bf16 v[40:43], v[198:201], v[156:159], v[40:43]
	v_mfma_f32_16x16x32_bf16 v[36:39], v[202:205], v[156:159], v[36:39]
	v_mfma_f32_16x16x32_bf16 v[32:35], v[206:209], v[156:159], v[32:35]
	v_add_co_u32_e32 v66, vcc, s52, v64
	s_waitcnt vmcnt(2)
	ds_write_b128 v109, v[76:79] offset:53248
	v_addc_co_u32_e32 v67, vcc, 0, v65, vcc
	v_add_co_u32_e32 v64, vcc, s34, v64
	s_waitcnt lgkmcnt(7)
	v_mfma_f32_16x16x32_bf16 v[28:31], v[194:197], v[160:163], v[28:31]
	v_addc_co_u32_e32 v65, vcc, 0, v65, vcc
	v_mfma_f32_16x16x32_bf16 v[24:27], v[198:201], v[160:163], v[24:27]
	v_mfma_f32_16x16x32_bf16 v[20:23], v[202:205], v[160:163], v[20:23]
	v_mfma_f32_16x16x32_bf16 v[16:19], v[206:209], v[160:163], v[16:19]
	s_waitcnt vmcnt(1)
	ds_write_b128 v109, v[80:83] offset:57344
	s_waitcnt lgkmcnt(7)
	v_mfma_f32_16x16x32_bf16 v[12:15], v[194:197], v[190:193], v[12:15]
	v_mfma_f32_16x16x32_bf16 v[8:11], v[198:201], v[190:193], v[8:11]
	v_mfma_f32_16x16x32_bf16 v[4:7], v[202:205], v[190:193], v[4:7]
	v_mfma_f32_16x16x32_bf16 v[0:3], v[206:209], v[190:193], v[0:3]
	s_waitcnt vmcnt(0)
	ds_write_b128 v109, v[84:87] offset:61440
	s_waitcnt lgkmcnt(0)
	s_barrier
	ds_read_b128 v[84:87], v111 offset:51200
	ds_read_b128 v[80:83], v111 offset:49152
	ds_read_b128 v[88:91], v111 offset:53248
	ds_read_b128 v[92:95], v111 offset:55296
	ds_read_b128 v[64:67], v110 offset:32768
	s_min_u32 s42, s29, 60
	s_lshl_b32 s92, s42, 7
	ds_read_b128 v[68:71], v110 offset:34816
	v_lshl_add_u64 v[164:165], v[100:101], 0, s[92:93]
	ds_read_b128 v[72:75], v110 offset:36864
	ds_read_b128 v[76:79], v110 offset:38912
	ds_read_b128 v[152:155], v112 offset:32768
	ds_read_b128 v[156:159], v112 offset:34816
	ds_read_b128 v[160:163], v112 offset:36864
	ds_read_b128 v[190:193], v112 offset:38912
	ds_read_b128 v[194:197], v113 offset:49152
	ds_read_b128 v[198:201], v113 offset:51200
	ds_read_b128 v[202:205], v113 offset:53248
	ds_read_b128 v[206:209], v113 offset:55296
	s_waitcnt lgkmcnt(11)
	v_mfma_f32_16x16x32_bf16 v[214:217], v[84:87], v[64:67], v[60:63]
	v_mfma_f32_16x16x32_bf16 v[210:213], v[80:83], v[64:67], v[52:55]
	s_nop 1
	v_add_co_u32_e32 v60, vcc, s7, v164
	s_nop 1
	v_addc_co_u32_e32 v61, vcc, 0, v165, vcc
	v_mfma_f32_16x16x32_bf16 v[56:59], v[88:91], v[64:67], v[56:59]
	v_mfma_f32_16x16x32_bf16 v[48:51], v[92:95], v[64:67], v[48:51]
	v_add_co_u32_e32 v64, vcc, s52, v164
	s_nop 0
	v_addc_co_u32_e32 v65, vcc, 0, v165, vcc
	s_waitcnt lgkmcnt(10)
	v_mfma_f32_16x16x32_bf16 v[44:47], v[80:83], v[68:71], v[44:47]
	v_mfma_f32_16x16x32_bf16 v[40:43], v[84:87], v[68:71], v[40:43]
	v_mfma_f32_16x16x32_bf16 v[36:39], v[88:91], v[68:71], v[36:39]
	v_mfma_f32_16x16x32_bf16 v[32:35], v[92:95], v[68:71], v[32:35]
	v_add_co_u32_e32 v68, vcc, s34, v164
	s_waitcnt lgkmcnt(9)
	v_mfma_f32_16x16x32_bf16 v[28:31], v[80:83], v[72:75], v[28:31]
	v_addc_co_u32_e32 v69, vcc, 0, v165, vcc
	v_mfma_f32_16x16x32_bf16 v[24:27], v[84:87], v[72:75], v[24:27]
	v_mfma_f32_16x16x32_bf16 v[20:23], v[88:91], v[72:75], v[20:23]
	v_mfma_f32_16x16x32_bf16 v[16:19], v[92:95], v[72:75], v[16:19]
	s_waitcnt lgkmcnt(8)
	v_mfma_f32_16x16x32_bf16 v[8:11], v[84:87], v[76:79], v[8:11]
	v_lshl_add_u64 v[84:85], v[102:103], 0, s[92:93]
	v_mfma_f32_16x16x32_bf16 v[12:15], v[80:83], v[76:79], v[12:15]
	v_mfma_f32_16x16x32_bf16 v[4:7], v[88:91], v[76:79], v[4:7]
	v_mfma_f32_16x16x32_bf16 v[0:3], v[92:95], v[76:79], v[0:3]
	v_add_co_u32_e32 v76, vcc, s7, v84
	s_nop 0
	v_addc_co_u32_e32 v77, vcc, 0, v85, vcc
	v_add_co_u32_e32 v80, vcc, s52, v84
	v_addc_co_u32_e32 v81, vcc, 0, v85, vcc
	s_waitcnt lgkmcnt(3)
	v_mfma_f32_16x16x32_bf16 v[92:95], v[194:197], v[152:155], v[210:213]
	s_waitcnt lgkmcnt(2)
	v_mfma_f32_16x16x32_bf16 v[88:91], v[198:201], v[152:155], v[214:217]
	s_waitcnt lgkmcnt(1)
	v_mfma_f32_16x16x32_bf16 v[56:59], v[202:205], v[152:155], v[56:59]
	s_waitcnt lgkmcnt(0)
	v_mfma_f32_16x16x32_bf16 v[48:51], v[206:209], v[152:155], v[48:51]
	v_add_co_u32_e32 v84, vcc, s34, v84
	v_addc_co_u32_e32 v85, vcc, 0, v85, vcc
	v_mfma_f32_16x16x32_bf16 v[44:47], v[194:197], v[156:159], v[44:47]
	v_mfma_f32_16x16x32_bf16 v[40:43], v[198:201], v[156:159], v[40:43]
	v_mfma_f32_16x16x32_bf16 v[36:39], v[202:205], v[156:159], v[36:39]
	v_mfma_f32_16x16x32_bf16 v[32:35], v[206:209], v[156:159], v[32:35]
	v_mfma_f32_16x16x32_bf16 v[28:31], v[194:197], v[160:163], v[28:31]
	v_mfma_f32_16x16x32_bf16 v[24:27], v[198:201], v[160:163], v[24:27]
	v_mfma_f32_16x16x32_bf16 v[20:23], v[202:205], v[160:163], v[20:23]
	v_mfma_f32_16x16x32_bf16 v[16:19], v[206:209], v[160:163], v[16:19]
	v_mfma_f32_16x16x32_bf16 v[12:15], v[194:197], v[190:193], v[12:15]
	v_mfma_f32_16x16x32_bf16 v[8:11], v[198:201], v[190:193], v[8:11]
	v_mfma_f32_16x16x32_bf16 v[4:7], v[202:205], v[190:193], v[4:7]
	v_mfma_f32_16x16x32_bf16 v[0:3], v[206:209], v[190:193], v[0:3]
	s_mov_b32 s42, s29
	s_waitcnt lgkmcnt(0)
	s_barrier
	s_waitcnt vmcnt(5)
	v_add_u32_e32 v64, s24, v108
	v_add_u32_e32 v52, 0xffffe000, v64
	v_or_b32_e32 v62, v64, v107
	v_lshrrev_b32_e32 v52, 10, v52
	s_movk_i32 s16, 0x1800
	v_mad_u32_u24 v52, v52, s16, s16
	v_cmp_lt_i32_e32 vcc, s13, v62
	v_or_b32_e32 v65, s25, v114
	v_or_b32_e32 v54, v65, v115
	v_cndmask_b32_e32 v52, 0, v52, vcc
	v_ashrrev_i32_e32 v53, 31, v52
	s_waitcnt vmcnt(4)
	v_lshlrev_b64 v[74:75], 2, v[52:53]
	v_ashrrev_i32_e32 v55, 31, v54
	v_ashrrev_i32_e32 v63, 31, v62
	v_lshl_add_u64 v[52:53], s[38:39], 0, v[74:75]
	v_lshlrev_b64 v[60:61], 2, v[54:55]
	v_readlane_b32 s16, v250, 15
	s_waitcnt vmcnt(1)
	v_lshl_add_u64 v[82:83], v[52:53], 0, v[60:61]
	v_lshlrev_b64 v[52:53], 12, v[62:63]
	v_readlane_b32 s17, v250, 16
	v_lshl_add_u64 v[74:75], s[40:41], 0, v[74:75]
	s_waitcnt vmcnt(0)
	v_lshl_add_u64 v[86:87], v[74:75], 0, v[60:61]
	v_lshl_add_u64 v[52:53], s[16:17], 0, v[52:53]
	v_lshl_add_u64 v[84:85], v[52:53], 0, v[60:61]
	global_load_dwordx4 v[66:69], v[82:83], off
	global_load_dwordx4 v[70:73], v[84:85], off
	v_lshl_add_u64 v[52:53], s[0:1], 0, v[60:61]
	v_readlane_b32 s16, v250, 21
	v_lshlrev_b64 v[78:79], 11, v[62:63]
	v_readlane_b32 s17, v250, 22
	s_waitcnt vmcnt(0)
	v_pk_fma_f32 v[68:69], v[94:95], v[68:69], v[72:73]
	v_pk_fma_f32 v[66:67], v[92:93], v[66:67], v[70:71]
	global_store_dwordx4 v[84:85], v[66:69], off
	global_load_dwordx4 v[70:73], v[52:53], off
	global_load_dwordx4 v[74:77], v[86:87], off
	v_lshl_add_u64 v[78:79], s[16:17], 0, v[78:79]
	v_lshl_add_u64 v[92:93], v[54:55], 1, v[78:79]
	s_mov_b32 s16, 0xa000
	s_waitcnt vmcnt(1)
	v_pk_mul_f32 v[72:73], v[68:69], v[72:73]
	v_pk_mul_f32 v[70:71], v[66:67], v[70:71]
	s_waitcnt vmcnt(0)
	v_pk_add_f32 v[76:77], v[76:77], 1.0 op_sel_hi:[1,0]
	v_pk_add_f32 v[74:75], v[74:75], 1.0 op_sel_hi:[1,0]
	v_pk_mul_f32 v[72:73], v[72:73], v[76:77]
	v_pk_mul_f32 v[70:71], v[70:71], v[74:75]
	v_and_b32_sdwa v76, v73, v170 dst_sel:DWORD dst_unused:UNUSED_PAD src0_sel:WORD_1 src1_sel:DWORD
	v_and_b32_sdwa v77, v71, v170 dst_sel:DWORD dst_unused:UNUSED_PAD src0_sel:WORD_1 src1_sel:DWORD
	v_and_b32_sdwa v74, v72, v170 dst_sel:DWORD dst_unused:UNUSED_PAD src0_sel:WORD_1 src1_sel:DWORD
	v_and_b32_sdwa v75, v70, v170 dst_sel:DWORD dst_unused:UNUSED_PAD src0_sel:WORD_1 src1_sel:DWORD
	v_add3_u32 v73, v73, v76, s56
	v_add3_u32 v71, v71, v77, s56
	v_add3_u32 v70, v70, v75, s56
	v_add3_u32 v72, v72, v74, s56
	v_and_b32_e32 v73, 0xffff0000, v73
	v_and_b32_e32 v74, 0xffff0000, v71
	v_or_b32_sdwa v71, v73, v72 dst_sel:DWORD dst_unused:UNUSED_PAD src0_sel:DWORD src1_sel:WORD_1
	v_or_b32_sdwa v70, v74, v70 dst_sel:DWORD dst_unused:UNUSED_PAD src0_sel:DWORD src1_sel:WORD_1
	global_store_dwordx2 v[92:93], v[70:71], off
	global_load_dwordx4 v[70:73], v[82:83], off offset:64
	s_nop 0
	global_load_dwordx4 v[74:77], v[84:85], off offset:64
	s_waitcnt vmcnt(0)
	v_pk_fma_f32 v[72:73], v[90:91], v[72:73], v[76:77]
	v_pk_fma_f32 v[70:71], v[88:89], v[70:71], v[74:75]
	global_store_dwordx4 v[84:85], v[70:73], off offset:64
	global_load_dwordx4 v[74:77], v[52:53], off offset:64
	global_load_dwordx4 v[78:81], v[86:87], off offset:64
	s_waitcnt vmcnt(1)
	v_pk_mul_f32 v[76:77], v[72:73], v[76:77]
	v_pk_mul_f32 v[74:75], v[70:71], v[74:75]
	s_waitcnt vmcnt(0)
	v_pk_add_f32 v[80:81], v[80:81], 1.0 op_sel_hi:[1,0]
	v_pk_add_f32 v[78:79], v[78:79], 1.0 op_sel_hi:[1,0]
	v_pk_mul_f32 v[76:77], v[76:77], v[80:81]
	v_pk_mul_f32 v[74:75], v[74:75], v[78:79]
	v_and_b32_sdwa v80, v77, v170 dst_sel:DWORD dst_unused:UNUSED_PAD src0_sel:WORD_1 src1_sel:DWORD
	v_and_b32_sdwa v81, v75, v170 dst_sel:DWORD dst_unused:UNUSED_PAD src0_sel:WORD_1 src1_sel:DWORD
	v_and_b32_sdwa v78, v76, v170 dst_sel:DWORD dst_unused:UNUSED_PAD src0_sel:WORD_1 src1_sel:DWORD
	v_and_b32_sdwa v79, v74, v170 dst_sel:DWORD dst_unused:UNUSED_PAD src0_sel:WORD_1 src1_sel:DWORD
	v_add3_u32 v77, v77, v80, s56
	v_add3_u32 v75, v75, v81, s56
	v_add3_u32 v74, v74, v79, s56
	v_add3_u32 v76, v76, v78, s56
	v_and_b32_e32 v77, 0xffff0000, v77
	v_and_b32_e32 v78, 0xffff0000, v75
	v_or_b32_sdwa v75, v77, v76 dst_sel:DWORD dst_unused:UNUSED_PAD src0_sel:DWORD src1_sel:WORD_1
	v_or_b32_sdwa v74, v78, v74 dst_sel:DWORD dst_unused:UNUSED_PAD src0_sel:DWORD src1_sel:WORD_1
	global_store_dwordx2 v[92:93], v[74:75], off offset:32
	global_load_dwordx4 v[74:77], v[82:83], off offset:128
	s_nop 0
	global_load_dwordx4 v[78:81], v[84:85], off offset:128
	s_waitcnt vmcnt(0)
	v_pk_fma_f32 v[58:59], v[58:59], v[76:77], v[80:81]
	v_pk_fma_f32 v[56:57], v[56:57], v[74:75], v[78:79]
	global_store_dwordx4 v[84:85], v[56:59], off offset:128
	global_load_dwordx4 v[74:77], v[52:53], off offset:128
	global_load_dwordx4 v[78:81], v[86:87], off offset:128
	s_waitcnt vmcnt(1)
	v_pk_mul_f32 v[76:77], v[58:59], v[76:77]
	v_pk_mul_f32 v[74:75], v[56:57], v[74:75]
	s_waitcnt vmcnt(0)
	v_pk_add_f32 v[80:81], v[80:81], 1.0 op_sel_hi:[1,0]
	v_pk_add_f32 v[78:79], v[78:79], 1.0 op_sel_hi:[1,0]
	v_pk_mul_f32 v[76:77], v[76:77], v[80:81]
	v_pk_mul_f32 v[74:75], v[74:75], v[78:79]
	v_and_b32_sdwa v80, v77, v170 dst_sel:DWORD dst_unused:UNUSED_PAD src0_sel:WORD_1 src1_sel:DWORD
	v_and_b32_sdwa v81, v75, v170 dst_sel:DWORD dst_unused:UNUSED_PAD src0_sel:WORD_1 src1_sel:DWORD
	v_and_b32_sdwa v78, v76, v170 dst_sel:DWORD dst_unused:UNUSED_PAD src0_sel:WORD_1 src1_sel:DWORD
	v_and_b32_sdwa v79, v74, v170 dst_sel:DWORD dst_unused:UNUSED_PAD src0_sel:WORD_1 src1_sel:DWORD
	v_add3_u32 v77, v77, v80, s56
	v_add3_u32 v75, v75, v81, s56
	v_add3_u32 v74, v74, v79, s56
	v_add3_u32 v76, v76, v78, s56
	v_and_b32_e32 v77, 0xffff0000, v77
	v_and_b32_e32 v78, 0xffff0000, v75
	v_or_b32_sdwa v75, v77, v76 dst_sel:DWORD dst_unused:UNUSED_PAD src0_sel:DWORD src1_sel:WORD_1
	v_or_b32_sdwa v74, v78, v74 dst_sel:DWORD dst_unused:UNUSED_PAD src0_sel:DWORD src1_sel:WORD_1
	global_store_dwordx2 v[92:93], v[74:75], off offset:64
	global_load_dwordx4 v[74:77], v[82:83], off offset:192
	s_nop 0
	global_load_dwordx4 v[78:81], v[84:85], off offset:192
	s_waitcnt vmcnt(0)
	v_pk_fma_f32 v[76:77], v[50:51], v[76:77], v[80:81]
	v_pk_fma_f32 v[74:75], v[48:49], v[74:75], v[78:79]
	global_store_dwordx4 v[84:85], v[74:77], off offset:192
	global_load_dwordx4 v[78:81], v[52:53], off offset:192
	s_nop 0
	global_load_dwordx4 v[82:85], v[86:87], off offset:192
	v_mul_f32_e32 v48, v67, v67
	v_mul_f32_e32 v49, v71, v71
	v_fmac_f32_e32 v48, v66, v66
	v_fmac_f32_e32 v49, v70, v70
	v_fmac_f32_e32 v48, v68, v68
	v_fmac_f32_e32 v49, v72, v72
	v_fmac_f32_e32 v48, v69, v69
	v_fmac_f32_e32 v49, v73, v73
	v_add_f32_e32 v48, v48, v49
	v_mul_f32_e32 v49, v57, v57
	v_fmac_f32_e32 v49, v56, v56
	v_fmac_f32_e32 v49, v58, v58
	v_fmac_f32_e32 v49, v59, v59
	v_add_f32_e32 v48, v48, v49
	v_mul_f32_e32 v49, v75, v75
	v_fmac_f32_e32 v49, v74, v74
	v_fmac_f32_e32 v49, v76, v76
	v_fmac_f32_e32 v49, v77, v77
	v_add_f32_e32 v50, v48, v49
	ds_bpermute_b32 v51, v105, v50
	v_lshrrev_b32_e32 v48, 6, v65
	v_mul_lo_u32 v48, v48, s16
	v_ashrrev_i32_e32 v49, 31, v48
	v_lshl_add_u64 v[48:49], s[26:27], 0, v[48:49]
	s_waitcnt lgkmcnt(0)
	v_add_f32_e32 v50, v50, v51
	ds_bpermute_b32 v51, v104, v50
	v_lshl_add_u64 v[48:49], v[62:63], 2, v[48:49]
	s_waitcnt vmcnt(1)
	v_pk_mul_f32 v[56:57], v[76:77], v[80:81]
	v_pk_mul_f32 v[58:59], v[74:75], v[78:79]
	s_waitcnt vmcnt(0)
	v_pk_add_f32 v[66:67], v[84:85], 1.0 op_sel_hi:[1,0]
	v_pk_add_f32 v[68:69], v[82:83], 1.0 op_sel_hi:[1,0]
	v_pk_mul_f32 v[56:57], v[56:57], v[66:67]
	v_pk_mul_f32 v[58:59], v[58:59], v[68:69]
	v_cvt_pk_bf16_f32 v57, v56, v57
	v_cvt_pk_bf16_f32 v56, v58, v59
	global_store_dwordx2 v[92:93], v[56:57], off offset:96
	s_and_saveexec_b64 s[24:25], s[36:37]
	s_cbranch_execz .LBB0_599
	s_waitcnt lgkmcnt(0)
	v_add_f32_e32 v50, v50, v51
	global_store_dword v[48:49], v50, off
.LBB0_599:
	s_or_b64 exec, exec, s[24:25]
	s_waitcnt lgkmcnt(0)
	v_add_u32_e32 v51, 0xffffe010, v64
	v_or_b32_e32 v50, 16, v62
	v_lshrrev_b32_e32 v51, 10, v51
	s_movk_i32 s16, 0x1800
	v_mad_u32_u24 v51, v51, s16, s16
	v_cmp_lt_i32_e32 vcc, s13, v50
	v_readlane_b32 s16, v250, 15
	v_readlane_b32 s17, v250, 16
	v_cndmask_b32_e32 v56, 0, v51, vcc
	v_ashrrev_i32_e32 v57, 31, v56
	v_lshlrev_b64 v[70:71], 2, v[56:57]
	v_ashrrev_i32_e32 v51, 31, v50
	v_lshl_add_u64 v[56:57], s[38:39], 0, v[70:71]
	v_lshl_add_u64 v[72:73], v[56:57], 0, v[60:61]
	v_lshlrev_b64 v[56:57], 12, v[50:51]
	v_lshl_add_u64 v[56:57], s[16:17], 0, v[56:57]
	v_lshl_add_u64 v[74:75], v[56:57], 0, v[60:61]
	global_load_dwordx4 v[56:59], v[72:73], off
	global_load_dwordx4 v[66:69], v[74:75], off
	v_lshl_add_u64 v[70:71], s[40:41], 0, v[70:71]
	v_lshl_add_u64 v[70:71], v[70:71], 0, v[60:61]
	v_readlane_b32 s16, v250, 21
	v_lshlrev_b64 v[50:51], 11, v[50:51]
	v_readlane_b32 s17, v250, 22
	s_waitcnt vmcnt(0)
	v_pk_fma_f32 v[46:47], v[46:47], v[58:59], v[68:69]
	v_pk_fma_f32 v[44:45], v[44:45], v[56:57], v[66:67]
	global_store_dwordx4 v[74:75], v[44:47], off
	global_load_dwordx4 v[56:59], v[52:53], off
	global_load_dwordx4 v[66:69], v[70:71], off
	v_lshl_add_u64 v[50:51], s[16:17], 0, v[50:51]
	v_lshl_add_u64 v[50:51], v[54:55], 1, v[50:51]
	s_waitcnt vmcnt(1)
	v_pk_mul_f32 v[58:59], v[46:47], v[58:59]
	v_pk_mul_f32 v[56:57], v[44:45], v[56:57]
	s_waitcnt vmcnt(0)
	v_pk_add_f32 v[68:69], v[68:69], 1.0 op_sel_hi:[1,0]
	v_pk_add_f32 v[66:67], v[66:67], 1.0 op_sel_hi:[1,0]
	v_pk_mul_f32 v[58:59], v[58:59], v[68:69]
	v_pk_mul_f32 v[56:57], v[56:57], v[66:67]
	v_and_b32_sdwa v66, v59, v170 dst_sel:DWORD dst_unused:UNUSED_PAD src0_sel:WORD_1 src1_sel:DWORD
	v_and_b32_sdwa v67, v57, v170 dst_sel:DWORD dst_unused:UNUSED_PAD src0_sel:WORD_1 src1_sel:DWORD
	v_and_b32_sdwa v63, v58, v170 dst_sel:DWORD dst_unused:UNUSED_PAD src0_sel:WORD_1 src1_sel:DWORD
	v_and_b32_sdwa v65, v56, v170 dst_sel:DWORD dst_unused:UNUSED_PAD src0_sel:WORD_1 src1_sel:DWORD
	v_add3_u32 v59, v59, v66, s56
	v_add3_u32 v57, v57, v67, s56
	v_add3_u32 v56, v56, v65, s56
	v_add3_u32 v58, v58, v63, s56
	v_and_b32_e32 v59, 0xffff0000, v59
	v_and_b32_e32 v63, 0xffff0000, v57
	v_or_b32_sdwa v57, v59, v58 dst_sel:DWORD dst_unused:UNUSED_PAD src0_sel:DWORD src1_sel:WORD_1
	v_or_b32_sdwa v56, v63, v56 dst_sel:DWORD dst_unused:UNUSED_PAD src0_sel:DWORD src1_sel:WORD_1
	global_store_dwordx2 v[50:51], v[56:57], off
	global_load_dwordx4 v[56:59], v[72:73], off offset:64
	s_nop 0
	global_load_dwordx4 v[66:69], v[74:75], off offset:64
	s_waitcnt vmcnt(0)
	v_pk_fma_f32 v[42:43], v[42:43], v[58:59], v[68:69]
	v_pk_fma_f32 v[40:41], v[40:41], v[56:57], v[66:67]
	global_store_dwordx4 v[74:75], v[40:43], off offset:64
	global_load_dwordx4 v[56:59], v[52:53], off offset:64
	global_load_dwordx4 v[66:69], v[70:71], off offset:64
	s_waitcnt vmcnt(1)
	v_pk_mul_f32 v[58:59], v[42:43], v[58:59]
	v_pk_mul_f32 v[56:57], v[40:41], v[56:57]
	s_waitcnt vmcnt(0)
	v_pk_add_f32 v[68:69], v[68:69], 1.0 op_sel_hi:[1,0]
	v_pk_add_f32 v[66:67], v[66:67], 1.0 op_sel_hi:[1,0]
	v_pk_mul_f32 v[58:59], v[58:59], v[68:69]
	v_pk_mul_f32 v[56:57], v[56:57], v[66:67]
	v_and_b32_sdwa v66, v59, v170 dst_sel:DWORD dst_unused:UNUSED_PAD src0_sel:WORD_1 src1_sel:DWORD
	v_and_b32_sdwa v67, v57, v170 dst_sel:DWORD dst_unused:UNUSED_PAD src0_sel:WORD_1 src1_sel:DWORD
	v_and_b32_sdwa v63, v58, v170 dst_sel:DWORD dst_unused:UNUSED_PAD src0_sel:WORD_1 src1_sel:DWORD
	v_and_b32_sdwa v65, v56, v170 dst_sel:DWORD dst_unused:UNUSED_PAD src0_sel:WORD_1 src1_sel:DWORD
	v_add3_u32 v59, v59, v66, s56
	v_add3_u32 v57, v57, v67, s56
	v_add3_u32 v56, v56, v65, s56
	v_add3_u32 v58, v58, v63, s56
	v_and_b32_e32 v59, 0xffff0000, v59
	v_and_b32_e32 v63, 0xffff0000, v57
	v_or_b32_sdwa v57, v59, v58 dst_sel:DWORD dst_unused:UNUSED_PAD src0_sel:DWORD src1_sel:WORD_1
	v_or_b32_sdwa v56, v63, v56 dst_sel:DWORD dst_unused:UNUSED_PAD src0_sel:DWORD src1_sel:WORD_1
	global_store_dwordx2 v[50:51], v[56:57], off offset:32
	global_load_dwordx4 v[56:59], v[72:73], off offset:128
	s_nop 0
	global_load_dwordx4 v[66:69], v[74:75], off offset:128
	s_waitcnt vmcnt(0)
	v_pk_fma_f32 v[38:39], v[38:39], v[58:59], v[68:69]
	v_pk_fma_f32 v[36:37], v[36:37], v[56:57], v[66:67]
	global_store_dwordx4 v[74:75], v[36:39], off offset:128
	global_load_dwordx4 v[56:59], v[52:53], off offset:128
	global_load_dwordx4 v[66:69], v[70:71], off offset:128
	s_waitcnt vmcnt(1)
	v_pk_mul_f32 v[58:59], v[38:39], v[58:59]
	v_pk_mul_f32 v[56:57], v[36:37], v[56:57]
	s_waitcnt vmcnt(0)
	v_pk_add_f32 v[68:69], v[68:69], 1.0 op_sel_hi:[1,0]
	v_pk_add_f32 v[66:67], v[66:67], 1.0 op_sel_hi:[1,0]
	v_pk_mul_f32 v[58:59], v[58:59], v[68:69]
	v_pk_mul_f32 v[56:57], v[56:57], v[66:67]
	v_and_b32_sdwa v66, v59, v170 dst_sel:DWORD dst_unused:UNUSED_PAD src0_sel:WORD_1 src1_sel:DWORD
	v_and_b32_sdwa v67, v57, v170 dst_sel:DWORD dst_unused:UNUSED_PAD src0_sel:WORD_1 src1_sel:DWORD
	v_and_b32_sdwa v63, v58, v170 dst_sel:DWORD dst_unused:UNUSED_PAD src0_sel:WORD_1 src1_sel:DWORD
	v_and_b32_sdwa v65, v56, v170 dst_sel:DWORD dst_unused:UNUSED_PAD src0_sel:WORD_1 src1_sel:DWORD
	v_add3_u32 v59, v59, v66, s56
	v_add3_u32 v57, v57, v67, s56
	v_add3_u32 v56, v56, v65, s56
	v_add3_u32 v58, v58, v63, s56
	v_and_b32_e32 v59, 0xffff0000, v59
	v_and_b32_e32 v63, 0xffff0000, v57
	v_or_b32_sdwa v57, v59, v58 dst_sel:DWORD dst_unused:UNUSED_PAD src0_sel:DWORD src1_sel:WORD_1
	v_or_b32_sdwa v56, v63, v56 dst_sel:DWORD dst_unused:UNUSED_PAD src0_sel:DWORD src1_sel:WORD_1
	global_store_dwordx2 v[50:51], v[56:57], off offset:64
	global_load_dwordx4 v[56:59], v[72:73], off offset:192
	s_nop 0
	global_load_dwordx4 v[66:69], v[74:75], off offset:192
	s_waitcnt vmcnt(0)
	v_pk_fma_f32 v[58:59], v[34:35], v[58:59], v[68:69]
	v_pk_fma_f32 v[56:57], v[32:33], v[56:57], v[66:67]
	global_store_dwordx4 v[74:75], v[56:59], off offset:192
	global_load_dwordx4 v[66:69], v[52:53], off offset:192
	s_nop 0
	global_load_dwordx4 v[70:73], v[70:71], off offset:192
	v_mul_f32_e32 v32, v45, v45
	v_mul_f32_e32 v33, v41, v41
	v_fmac_f32_e32 v32, v44, v44
	v_fmac_f32_e32 v33, v40, v40
	v_fmac_f32_e32 v32, v46, v46
	v_fmac_f32_e32 v33, v42, v42
	v_fmac_f32_e32 v32, v47, v47
	v_fmac_f32_e32 v33, v43, v43
	v_add_f32_e32 v32, v32, v33
	v_mul_f32_e32 v33, v37, v37
	v_fmac_f32_e32 v33, v36, v36
	v_fmac_f32_e32 v33, v38, v38
	v_fmac_f32_e32 v33, v39, v39
	v_add_f32_e32 v32, v32, v33
	v_mul_f32_e32 v33, v57, v57
	v_fmac_f32_e32 v33, v56, v56
	v_fmac_f32_e32 v33, v58, v58
	v_fmac_f32_e32 v33, v59, v59
	v_add_f32_e32 v32, v32, v33
	ds_bpermute_b32 v33, v105, v32
	s_waitcnt lgkmcnt(0)
	v_add_f32_e32 v32, v32, v33
	ds_bpermute_b32 v33, v104, v32
	s_waitcnt vmcnt(1)
	v_pk_mul_f32 v[34:35], v[58:59], v[68:69]
	v_pk_mul_f32 v[36:37], v[56:57], v[66:67]
	s_waitcnt vmcnt(0)
	v_pk_add_f32 v[38:39], v[72:73], 1.0 op_sel_hi:[1,0]
	v_pk_add_f32 v[40:41], v[70:71], 1.0 op_sel_hi:[1,0]
	v_pk_mul_f32 v[34:35], v[34:35], v[38:39]
	v_pk_mul_f32 v[36:37], v[36:37], v[40:41]
	v_cvt_pk_bf16_f32 v35, v34, v35
	v_cvt_pk_bf16_f32 v34, v36, v37
	global_store_dwordx2 v[50:51], v[34:35], off offset:96
	s_and_saveexec_b64 s[24:25], s[36:37]
	s_cbranch_execz .LBB0_601
	s_waitcnt lgkmcnt(0)
	v_add_f32_e32 v32, v32, v33
	global_store_dword v[48:49], v32, off offset:64
.LBB0_601:
	s_or_b64 exec, exec, s[24:25]
	v_add_u32_e32 v32, 0xffffe020, v64
	v_or_b32_e32 v40, 32, v62
	v_lshrrev_b32_e32 v32, 10, v32
	s_movk_i32 s16, 0x1800
	v_mad_u32_u24 v32, v32, s16, s16
	v_cmp_lt_i32_e32 vcc, s13, v40
	v_ashrrev_i32_e32 v41, 31, v40
	v_readlane_b32 s16, v250, 15
	v_cndmask_b32_e32 v32, 0, v32, vcc
	s_waitcnt lgkmcnt(0)
	v_ashrrev_i32_e32 v33, 31, v32
	v_lshlrev_b64 v[42:43], 2, v[32:33]
	v_lshl_add_u64 v[32:33], s[38:39], 0, v[42:43]
	v_lshl_add_u64 v[44:45], v[32:33], 0, v[60:61]
	v_lshlrev_b64 v[32:33], 12, v[40:41]
	v_readlane_b32 s17, v250, 16
	v_lshl_add_u64 v[42:43], s[40:41], 0, v[42:43]
	v_lshl_add_u64 v[42:43], v[42:43], 0, v[60:61]
	v_lshl_add_u64 v[32:33], s[16:17], 0, v[32:33]
	v_lshl_add_u64 v[46:47], v[32:33], 0, v[60:61]
	global_load_dwordx4 v[32:35], v[44:45], off
	global_load_dwordx4 v[36:39], v[46:47], off
	v_readlane_b32 s16, v250, 21
	v_lshlrev_b64 v[40:41], 11, v[40:41]
	v_readlane_b32 s17, v250, 22
	s_waitcnt vmcnt(0)
	v_pk_fma_f32 v[30:31], v[30:31], v[34:35], v[38:39]
	v_pk_fma_f32 v[28:29], v[28:29], v[32:33], v[36:37]
	global_store_dwordx4 v[46:47], v[28:31], off
	global_load_dwordx4 v[32:35], v[52:53], off
	global_load_dwordx4 v[36:39], v[42:43], off
	v_lshl_add_u64 v[40:41], s[16:17], 0, v[40:41]
	v_lshl_add_u64 v[50:51], v[54:55], 1, v[40:41]
	s_waitcnt vmcnt(1)
	v_pk_mul_f32 v[34:35], v[30:31], v[34:35]
	v_pk_mul_f32 v[32:33], v[28:29], v[32:33]
	s_waitcnt vmcnt(0)
	v_pk_add_f32 v[38:39], v[38:39], 1.0 op_sel_hi:[1,0]
	v_pk_add_f32 v[36:37], v[36:37], 1.0 op_sel_hi:[1,0]
	v_pk_mul_f32 v[34:35], v[34:35], v[38:39]
	v_pk_mul_f32 v[32:33], v[32:33], v[36:37]
	v_and_b32_sdwa v38, v35, v170 dst_sel:DWORD dst_unused:UNUSED_PAD src0_sel:WORD_1 src1_sel:DWORD
	v_and_b32_sdwa v39, v33, v170 dst_sel:DWORD dst_unused:UNUSED_PAD src0_sel:WORD_1 src1_sel:DWORD
	v_and_b32_sdwa v36, v34, v170 dst_sel:DWORD dst_unused:UNUSED_PAD src0_sel:WORD_1 src1_sel:DWORD
	v_and_b32_sdwa v37, v32, v170 dst_sel:DWORD dst_unused:UNUSED_PAD src0_sel:WORD_1 src1_sel:DWORD
	v_add3_u32 v35, v35, v38, s56
	v_add3_u32 v33, v33, v39, s56
	v_add3_u32 v32, v32, v37, s56
	v_add3_u32 v34, v34, v36, s56
	v_and_b32_e32 v35, 0xffff0000, v35
	v_and_b32_e32 v36, 0xffff0000, v33
	v_or_b32_sdwa v33, v35, v34 dst_sel:DWORD dst_unused:UNUSED_PAD src0_sel:DWORD src1_sel:WORD_1
	v_or_b32_sdwa v32, v36, v32 dst_sel:DWORD dst_unused:UNUSED_PAD src0_sel:DWORD src1_sel:WORD_1
	global_store_dwordx2 v[50:51], v[32:33], off
	global_load_dwordx4 v[32:35], v[44:45], off offset:64
	s_nop 0
	global_load_dwordx4 v[36:39], v[46:47], off offset:64
	s_waitcnt vmcnt(0)
	v_pk_fma_f32 v[26:27], v[26:27], v[34:35], v[38:39]
	v_pk_fma_f32 v[24:25], v[24:25], v[32:33], v[36:37]
	global_store_dwordx4 v[46:47], v[24:27], off offset:64
	global_load_dwordx4 v[32:35], v[52:53], off offset:64
	global_load_dwordx4 v[36:39], v[42:43], off offset:64
	s_waitcnt vmcnt(1)
	v_pk_mul_f32 v[34:35], v[26:27], v[34:35]
	v_pk_mul_f32 v[32:33], v[24:25], v[32:33]
	s_waitcnt vmcnt(0)
	v_pk_add_f32 v[38:39], v[38:39], 1.0 op_sel_hi:[1,0]
	v_pk_add_f32 v[36:37], v[36:37], 1.0 op_sel_hi:[1,0]
	v_pk_mul_f32 v[34:35], v[34:35], v[38:39]
	v_pk_mul_f32 v[32:33], v[32:33], v[36:37]
	v_and_b32_sdwa v38, v35, v170 dst_sel:DWORD dst_unused:UNUSED_PAD src0_sel:WORD_1 src1_sel:DWORD
	v_and_b32_sdwa v39, v33, v170 dst_sel:DWORD dst_unused:UNUSED_PAD src0_sel:WORD_1 src1_sel:DWORD
	v_and_b32_sdwa v36, v34, v170 dst_sel:DWORD dst_unused:UNUSED_PAD src0_sel:WORD_1 src1_sel:DWORD
	v_and_b32_sdwa v37, v32, v170 dst_sel:DWORD dst_unused:UNUSED_PAD src0_sel:WORD_1 src1_sel:DWORD
	v_add3_u32 v35, v35, v38, s56
	v_add3_u32 v33, v33, v39, s56
	v_add3_u32 v32, v32, v37, s56
	v_add3_u32 v34, v34, v36, s56
	v_and_b32_e32 v35, 0xffff0000, v35
	v_and_b32_e32 v36, 0xffff0000, v33
	v_or_b32_sdwa v33, v35, v34 dst_sel:DWORD dst_unused:UNUSED_PAD src0_sel:DWORD src1_sel:WORD_1
	v_or_b32_sdwa v32, v36, v32 dst_sel:DWORD dst_unused:UNUSED_PAD src0_sel:DWORD src1_sel:WORD_1
	global_store_dwordx2 v[50:51], v[32:33], off offset:32
	global_load_dwordx4 v[32:35], v[44:45], off offset:128
	s_nop 0
	global_load_dwordx4 v[36:39], v[46:47], off offset:128
	s_waitcnt vmcnt(0)
	v_pk_fma_f32 v[22:23], v[22:23], v[34:35], v[38:39]
	v_pk_fma_f32 v[20:21], v[20:21], v[32:33], v[36:37]
	global_store_dwordx4 v[46:47], v[20:23], off offset:128
	global_load_dwordx4 v[32:35], v[52:53], off offset:128
	global_load_dwordx4 v[36:39], v[42:43], off offset:128
	s_waitcnt vmcnt(1)
	v_pk_mul_f32 v[34:35], v[22:23], v[34:35]
	v_pk_mul_f32 v[32:33], v[20:21], v[32:33]
	s_waitcnt vmcnt(0)
	v_pk_add_f32 v[38:39], v[38:39], 1.0 op_sel_hi:[1,0]
	v_pk_add_f32 v[36:37], v[36:37], 1.0 op_sel_hi:[1,0]
	v_pk_mul_f32 v[34:35], v[34:35], v[38:39]
	v_pk_mul_f32 v[32:33], v[32:33], v[36:37]
	v_and_b32_sdwa v38, v35, v170 dst_sel:DWORD dst_unused:UNUSED_PAD src0_sel:WORD_1 src1_sel:DWORD
	v_and_b32_sdwa v39, v33, v170 dst_sel:DWORD dst_unused:UNUSED_PAD src0_sel:WORD_1 src1_sel:DWORD
	v_and_b32_sdwa v36, v34, v170 dst_sel:DWORD dst_unused:UNUSED_PAD src0_sel:WORD_1 src1_sel:DWORD
	v_and_b32_sdwa v37, v32, v170 dst_sel:DWORD dst_unused:UNUSED_PAD src0_sel:WORD_1 src1_sel:DWORD
	v_add3_u32 v35, v35, v38, s56
	v_add3_u32 v33, v33, v39, s56
	v_add3_u32 v32, v32, v37, s56
	v_add3_u32 v34, v34, v36, s56
	v_and_b32_e32 v35, 0xffff0000, v35
	v_and_b32_e32 v36, 0xffff0000, v33
	v_or_b32_sdwa v33, v35, v34 dst_sel:DWORD dst_unused:UNUSED_PAD src0_sel:DWORD src1_sel:WORD_1
	v_or_b32_sdwa v32, v36, v32 dst_sel:DWORD dst_unused:UNUSED_PAD src0_sel:DWORD src1_sel:WORD_1
	global_store_dwordx2 v[50:51], v[32:33], off offset:64
	global_load_dwordx4 v[32:35], v[44:45], off offset:192
	s_nop 0
	global_load_dwordx4 v[36:39], v[46:47], off offset:192
	s_waitcnt vmcnt(0)
	v_pk_fma_f32 v[34:35], v[18:19], v[34:35], v[38:39]
	v_pk_fma_f32 v[32:33], v[16:17], v[32:33], v[36:37]
	global_store_dwordx4 v[46:47], v[32:35], off offset:192
	global_load_dwordx4 v[36:39], v[52:53], off offset:192
	s_nop 0
	global_load_dwordx4 v[40:43], v[42:43], off offset:192
	v_mul_f32_e32 v16, v29, v29
	v_mul_f32_e32 v17, v25, v25
	v_fmac_f32_e32 v16, v28, v28
	v_fmac_f32_e32 v17, v24, v24
	v_fmac_f32_e32 v16, v30, v30
	v_fmac_f32_e32 v17, v26, v26
	v_fmac_f32_e32 v16, v31, v31
	v_fmac_f32_e32 v17, v27, v27
	v_add_f32_e32 v16, v16, v17
	v_mul_f32_e32 v17, v21, v21
	v_fmac_f32_e32 v17, v20, v20
	v_fmac_f32_e32 v17, v22, v22
	v_fmac_f32_e32 v17, v23, v23
	v_add_f32_e32 v16, v16, v17
	v_mul_f32_e32 v17, v33, v33
	v_fmac_f32_e32 v17, v32, v32
	v_fmac_f32_e32 v17, v34, v34
	v_fmac_f32_e32 v17, v35, v35
	v_add_f32_e32 v16, v16, v17
	ds_bpermute_b32 v17, v105, v16
	s_waitcnt lgkmcnt(0)
	v_add_f32_e32 v16, v16, v17
	ds_bpermute_b32 v17, v104, v16
	s_waitcnt vmcnt(1)
	v_pk_mul_f32 v[18:19], v[34:35], v[38:39]
	v_pk_mul_f32 v[20:21], v[32:33], v[36:37]
	s_waitcnt vmcnt(0)
	v_pk_add_f32 v[22:23], v[42:43], 1.0 op_sel_hi:[1,0]
	v_pk_add_f32 v[24:25], v[40:41], 1.0 op_sel_hi:[1,0]
	v_pk_mul_f32 v[18:19], v[18:19], v[22:23]
	v_pk_mul_f32 v[20:21], v[20:21], v[24:25]
	v_cvt_pk_bf16_f32 v19, v18, v19
	v_cvt_pk_bf16_f32 v18, v20, v21
	global_store_dwordx2 v[50:51], v[18:19], off offset:96
	s_and_saveexec_b64 s[24:25], s[36:37]
	s_movk_i32 s89, 0xff
	s_cbranch_execz .LBB0_603
	s_waitcnt lgkmcnt(0)
	v_add_f32_e32 v16, v16, v17
	global_store_dword v[48:49], v16, off offset:128
.LBB0_603:
	s_or_b64 exec, exec, s[24:25]
	v_add_u32_e32 v16, 0xffffe030, v64
	v_or_b32_e32 v24, 48, v62
	v_lshrrev_b32_e32 v16, 10, v16
	s_movk_i32 s16, 0x1800
	v_mad_u32_u24 v16, v16, s16, s16
	v_cmp_lt_i32_e32 vcc, s13, v24
	v_ashrrev_i32_e32 v25, 31, v24
	v_readlane_b32 s16, v250, 15
	v_cndmask_b32_e32 v16, 0, v16, vcc
	s_waitcnt lgkmcnt(0)
	v_ashrrev_i32_e32 v17, 31, v16
	v_lshlrev_b64 v[26:27], 2, v[16:17]
	v_lshl_add_u64 v[16:17], s[38:39], 0, v[26:27]
	v_lshl_add_u64 v[28:29], v[16:17], 0, v[60:61]
	v_lshlrev_b64 v[16:17], 12, v[24:25]
	v_readlane_b32 s17, v250, 16
	v_lshl_add_u64 v[26:27], s[40:41], 0, v[26:27]
	v_lshl_add_u64 v[26:27], v[26:27], 0, v[60:61]
	v_lshl_add_u64 v[16:17], s[16:17], 0, v[16:17]
	v_lshl_add_u64 v[30:31], v[16:17], 0, v[60:61]
	global_load_dwordx4 v[16:19], v[28:29], off
	global_load_dwordx4 v[20:23], v[30:31], off
	v_readlane_b32 s16, v250, 21
	v_lshlrev_b64 v[24:25], 11, v[24:25]
	v_readlane_b32 s17, v250, 22
	s_waitcnt vmcnt(0)
	v_pk_fma_f32 v[14:15], v[14:15], v[18:19], v[22:23]
	v_pk_fma_f32 v[12:13], v[12:13], v[16:17], v[20:21]
	global_store_dwordx4 v[30:31], v[12:15], off
	global_load_dwordx4 v[16:19], v[52:53], off
	global_load_dwordx4 v[20:23], v[26:27], off
	v_lshl_add_u64 v[24:25], s[16:17], 0, v[24:25]
	v_lshl_add_u64 v[32:33], v[54:55], 1, v[24:25]
	s_waitcnt vmcnt(1)
	v_pk_mul_f32 v[18:19], v[14:15], v[18:19]
	v_pk_mul_f32 v[16:17], v[12:13], v[16:17]
	s_waitcnt vmcnt(0)
	v_pk_add_f32 v[22:23], v[22:23], 1.0 op_sel_hi:[1,0]
	v_pk_add_f32 v[20:21], v[20:21], 1.0 op_sel_hi:[1,0]
	v_pk_mul_f32 v[18:19], v[18:19], v[22:23]
	v_pk_mul_f32 v[16:17], v[16:17], v[20:21]
	v_and_b32_sdwa v22, v19, v170 dst_sel:DWORD dst_unused:UNUSED_PAD src0_sel:WORD_1 src1_sel:DWORD
	v_and_b32_sdwa v23, v17, v170 dst_sel:DWORD dst_unused:UNUSED_PAD src0_sel:WORD_1 src1_sel:DWORD
	v_and_b32_sdwa v20, v18, v170 dst_sel:DWORD dst_unused:UNUSED_PAD src0_sel:WORD_1 src1_sel:DWORD
	v_and_b32_sdwa v21, v16, v170 dst_sel:DWORD dst_unused:UNUSED_PAD src0_sel:WORD_1 src1_sel:DWORD
	v_add3_u32 v19, v19, v22, s56
	v_add3_u32 v17, v17, v23, s56
	v_add3_u32 v16, v16, v21, s56
	v_add3_u32 v18, v18, v20, s56
	v_and_b32_e32 v19, 0xffff0000, v19
	v_and_b32_e32 v20, 0xffff0000, v17
	v_or_b32_sdwa v17, v19, v18 dst_sel:DWORD dst_unused:UNUSED_PAD src0_sel:DWORD src1_sel:WORD_1
	v_or_b32_sdwa v16, v20, v16 dst_sel:DWORD dst_unused:UNUSED_PAD src0_sel:DWORD src1_sel:WORD_1
	global_store_dwordx2 v[32:33], v[16:17], off
	global_load_dwordx4 v[16:19], v[28:29], off offset:64
	s_nop 0
	global_load_dwordx4 v[20:23], v[30:31], off offset:64
	s_waitcnt vmcnt(0)
	v_pk_fma_f32 v[10:11], v[10:11], v[18:19], v[22:23]
	v_pk_fma_f32 v[8:9], v[8:9], v[16:17], v[20:21]
	global_store_dwordx4 v[30:31], v[8:11], off offset:64
	global_load_dwordx4 v[16:19], v[52:53], off offset:64
	global_load_dwordx4 v[20:23], v[26:27], off offset:64
	s_waitcnt vmcnt(1)
	v_pk_mul_f32 v[18:19], v[10:11], v[18:19]
	v_pk_mul_f32 v[16:17], v[8:9], v[16:17]
	s_waitcnt vmcnt(0)
	v_pk_add_f32 v[22:23], v[22:23], 1.0 op_sel_hi:[1,0]
	v_pk_add_f32 v[20:21], v[20:21], 1.0 op_sel_hi:[1,0]
	v_pk_mul_f32 v[18:19], v[18:19], v[22:23]
	v_pk_mul_f32 v[16:17], v[16:17], v[20:21]
	v_and_b32_sdwa v22, v19, v170 dst_sel:DWORD dst_unused:UNUSED_PAD src0_sel:WORD_1 src1_sel:DWORD
	v_and_b32_sdwa v23, v17, v170 dst_sel:DWORD dst_unused:UNUSED_PAD src0_sel:WORD_1 src1_sel:DWORD
	v_and_b32_sdwa v20, v18, v170 dst_sel:DWORD dst_unused:UNUSED_PAD src0_sel:WORD_1 src1_sel:DWORD
	v_and_b32_sdwa v21, v16, v170 dst_sel:DWORD dst_unused:UNUSED_PAD src0_sel:WORD_1 src1_sel:DWORD
	v_add3_u32 v19, v19, v22, s56
	v_add3_u32 v17, v17, v23, s56
	v_add3_u32 v16, v16, v21, s56
	v_add3_u32 v18, v18, v20, s56
	v_and_b32_e32 v19, 0xffff0000, v19
	v_and_b32_e32 v20, 0xffff0000, v17
	v_or_b32_sdwa v17, v19, v18 dst_sel:DWORD dst_unused:UNUSED_PAD src0_sel:DWORD src1_sel:WORD_1
	v_or_b32_sdwa v16, v20, v16 dst_sel:DWORD dst_unused:UNUSED_PAD src0_sel:DWORD src1_sel:WORD_1
	global_store_dwordx2 v[32:33], v[16:17], off offset:32
	global_load_dwordx4 v[16:19], v[28:29], off offset:128
	s_nop 0
	global_load_dwordx4 v[20:23], v[30:31], off offset:128
	s_waitcnt vmcnt(0)
	v_pk_fma_f32 v[6:7], v[6:7], v[18:19], v[22:23]
	v_pk_fma_f32 v[4:5], v[4:5], v[16:17], v[20:21]
	global_store_dwordx4 v[30:31], v[4:7], off offset:128
	global_load_dwordx4 v[16:19], v[52:53], off offset:128
	global_load_dwordx4 v[20:23], v[26:27], off offset:128
	s_waitcnt vmcnt(1)
	v_pk_mul_f32 v[18:19], v[6:7], v[18:19]
	v_pk_mul_f32 v[16:17], v[4:5], v[16:17]
	s_waitcnt vmcnt(0)
	v_pk_add_f32 v[22:23], v[22:23], 1.0 op_sel_hi:[1,0]
	v_pk_add_f32 v[20:21], v[20:21], 1.0 op_sel_hi:[1,0]
	v_pk_mul_f32 v[18:19], v[18:19], v[22:23]
	v_pk_mul_f32 v[16:17], v[16:17], v[20:21]
	v_and_b32_sdwa v22, v19, v170 dst_sel:DWORD dst_unused:UNUSED_PAD src0_sel:WORD_1 src1_sel:DWORD
	v_and_b32_sdwa v23, v17, v170 dst_sel:DWORD dst_unused:UNUSED_PAD src0_sel:WORD_1 src1_sel:DWORD
	v_and_b32_sdwa v20, v18, v170 dst_sel:DWORD dst_unused:UNUSED_PAD src0_sel:WORD_1 src1_sel:DWORD
	v_and_b32_sdwa v21, v16, v170 dst_sel:DWORD dst_unused:UNUSED_PAD src0_sel:WORD_1 src1_sel:DWORD
	v_add3_u32 v19, v19, v22, s56
	v_add3_u32 v17, v17, v23, s56
	v_add3_u32 v16, v16, v21, s56
	v_add3_u32 v18, v18, v20, s56
	v_and_b32_e32 v19, 0xffff0000, v19
	v_and_b32_e32 v20, 0xffff0000, v17
	v_or_b32_sdwa v17, v19, v18 dst_sel:DWORD dst_unused:UNUSED_PAD src0_sel:DWORD src1_sel:WORD_1
	v_or_b32_sdwa v16, v20, v16 dst_sel:DWORD dst_unused:UNUSED_PAD src0_sel:DWORD src1_sel:WORD_1
	global_store_dwordx2 v[32:33], v[16:17], off offset:64
	global_load_dwordx4 v[16:19], v[28:29], off offset:192
	s_nop 0
	global_load_dwordx4 v[20:23], v[30:31], off offset:192
	s_waitcnt vmcnt(0)
	v_pk_fma_f32 v[18:19], v[2:3], v[18:19], v[22:23]
	v_pk_fma_f32 v[16:17], v[0:1], v[16:17], v[20:21]
	global_store_dwordx4 v[30:31], v[16:19], off offset:192
	global_load_dwordx4 v[20:23], v[52:53], off offset:192
	s_nop 0
	global_load_dwordx4 v[24:27], v[26:27], off offset:192
	v_mul_f32_e32 v0, v13, v13
	v_mul_f32_e32 v1, v9, v9
	v_fmac_f32_e32 v0, v12, v12
	v_fmac_f32_e32 v1, v8, v8
	v_fmac_f32_e32 v0, v14, v14
	v_fmac_f32_e32 v1, v10, v10
	v_fmac_f32_e32 v0, v15, v15
	v_fmac_f32_e32 v1, v11, v11
	v_add_f32_e32 v0, v0, v1
	v_mul_f32_e32 v1, v5, v5
	v_fmac_f32_e32 v1, v4, v4
	v_fmac_f32_e32 v1, v6, v6
	v_fmac_f32_e32 v1, v7, v7
	v_add_f32_e32 v0, v0, v1
	v_mul_f32_e32 v1, v17, v17
	v_fmac_f32_e32 v1, v16, v16
	v_fmac_f32_e32 v1, v18, v18
	v_fmac_f32_e32 v1, v19, v19
	v_add_f32_e32 v0, v0, v1
	ds_bpermute_b32 v1, v105, v0
	s_waitcnt lgkmcnt(0)
	v_add_f32_e32 v0, v0, v1
	ds_bpermute_b32 v1, v104, v0
	s_waitcnt vmcnt(1)
	v_pk_mul_f32 v[2:3], v[18:19], v[22:23]
	v_pk_mul_f32 v[4:5], v[16:17], v[20:21]
	s_waitcnt vmcnt(0)
	v_pk_add_f32 v[6:7], v[26:27], 1.0 op_sel_hi:[1,0]
	v_pk_add_f32 v[8:9], v[24:25], 1.0 op_sel_hi:[1,0]
	v_pk_mul_f32 v[2:3], v[2:3], v[6:7]
	v_pk_mul_f32 v[4:5], v[4:5], v[8:9]
	v_cvt_pk_bf16_f32 v3, v2, v3
	v_cvt_pk_bf16_f32 v2, v4, v5
	global_store_dwordx2 v[32:33], v[2:3], off offset:96
	s_and_saveexec_b64 s[24:25], s[36:37]
	s_cbranch_execz .LBB0_594
	s_waitcnt lgkmcnt(0)
	v_add_f32_e32 v0, v0, v1
	global_store_dword v[48:49], v0, off offset:192
	s_branch .LBB0_594

.LBB0_612:
	s_or_b64 exec, exec, s[2:3]
	v_add_u32_e32 v13, 0xffffe010, v18
	s_waitcnt lgkmcnt(0)
	v_lshl_add_u64 v[14:15], s[0:1], 0, v[128:129]
	v_or_b32_e32 v12, 16, v12
	v_lshrrev_b32_e32 v13, 10, v13
	s_movk_i32 s0, 0x1800
	v_mad_u32_u24 v13, v13, s0, s0
	v_cmp_lt_i32_e64 s[0:1], s13, v12
	s_nop 1
	v_cndmask_b32_e64 v18, 0, v13, s[0:1]
	v_ashrrev_i32_e32 v19, 31, v18
	v_lshlrev_b64 v[34:35], 2, v[18:19]
	v_ashrrev_i32_e32 v13, 31, v12
	v_lshl_add_u64 v[18:19], s[38:39], 0, v[34:35]
	v_readlane_b32 s0, v250, 15
	v_lshl_add_u64 v[20:21], v[18:19], 0, v[128:129]
	v_lshlrev_b64 v[18:19], 12, v[12:13]
	v_readlane_b32 s1, v250, 16
	s_nop 0
	v_lshl_add_u64 v[18:19], s[0:1], 0, v[18:19]
	v_lshl_add_u64 v[18:19], v[18:19], 0, v[128:129]
	v_readlane_b32 s0, v250, 21
	v_readlane_b32 s1, v250, 22
	s_waitcnt vmcnt(16)
	v_pk_fma_f32 v[28:29], v[38:39], v[74:75], v[212:213]
	v_pk_fma_f32 v[26:27], v[36:37], v[72:73], v[210:211]
	v_lshl_add_u64 v[22:23], s[40:41], 0, v[34:35]
	global_store_dwordx4 v[18:19], v[26:29], off
	v_lshl_add_u64 v[22:23], v[22:23], 0, v[128:129]
	v_mul_f32_e32 v38, v27, v27
	v_fmac_f32_e32 v38, v26, v26
	v_fmac_f32_e32 v38, v28, v28
	v_fmac_f32_e32 v38, v29, v29
	v_pk_mul_f32 v[24:25], v[28:29], v[142:143]
	v_pk_add_f32 v[28:29], v[158:159], 1.0 op_sel_hi:[1,0]
	v_pk_mul_f32 v[26:27], v[26:27], v[140:141]
	v_pk_add_f32 v[30:31], v[156:157], 1.0 op_sel_hi:[1,0]
	v_pk_mul_f32 v[24:25], v[24:25], v[28:29]
	v_lshlrev_b64 v[28:29], 11, v[12:13]
	v_pk_mul_f32 v[26:27], v[26:27], v[30:31]
	v_lshl_add_u64 v[28:29], s[0:1], 0, v[28:29]
	v_lshl_add_u64 v[16:17], v[28:29], 0, v[16:17]
	v_cvt_pk_bf16_f32 v25, v24, v25
	v_cvt_pk_bf16_f32 v24, v26, v27
	global_store_dwordx2 v[16:17], v[24:25], off
	s_nop 0
	v_pk_fma_f32 v[8:9], v[8:9], v[80:81], v[214:215]
	s_nop 0
	v_mul_f32_e32 v24, v9, v9
	v_pk_fma_f32 v[10:11], v[10:11], v[82:83], v[216:217]
	v_fmac_f32_e32 v24, v8, v8
	v_fmac_f32_e32 v24, v10, v10
	global_store_dwordx4 v[18:19], v[8:11], off offset:64
	v_fmac_f32_e32 v24, v11, v11
	v_add_f32_e32 v32, v38, v24
	v_pk_mul_f32 v[10:11], v[10:11], v[146:147]
	v_pk_mul_f32 v[8:9], v[8:9], v[144:145]
	v_pk_add_f32 v[24:25], v[162:163], 1.0 op_sel_hi:[1,0]
	v_pk_add_f32 v[26:27], v[160:161], 1.0 op_sel_hi:[1,0]
	v_pk_mul_f32 v[10:11], v[10:11], v[24:25]
	v_pk_mul_f32 v[8:9], v[8:9], v[26:27]
	v_and_b32_sdwa v24, v10, v170 dst_sel:DWORD dst_unused:UNUSED_PAD src0_sel:WORD_1 src1_sel:DWORD
	v_and_b32_sdwa v25, v8, v170 dst_sel:DWORD dst_unused:UNUSED_PAD src0_sel:WORD_1 src1_sel:DWORD
	v_add3_u32 v8, v8, v25, s56
	v_add3_u32 v10, v10, v24, s56
	v_and_b32_sdwa v24, v11, v170 dst_sel:DWORD dst_unused:UNUSED_PAD src0_sel:WORD_1 src1_sel:DWORD
	v_and_b32_sdwa v25, v9, v170 dst_sel:DWORD dst_unused:UNUSED_PAD src0_sel:WORD_1 src1_sel:DWORD
	v_add3_u32 v11, v11, v24, s56
	v_add3_u32 v9, v9, v25, s56
	v_and_b32_e32 v11, 0xffff0000, v11
	v_and_b32_e32 v24, 0xffff0000, v9
	v_or_b32_sdwa v9, v11, v10 dst_sel:DWORD dst_unused:UNUSED_PAD src0_sel:DWORD src1_sel:WORD_1
	v_or_b32_sdwa v8, v24, v8 dst_sel:DWORD dst_unused:UNUSED_PAD src0_sel:DWORD src1_sel:WORD_1
	global_store_dwordx2 v[16:17], v[8:9], off offset:32
	s_nop 0
	v_pk_fma_f32 v[4:5], v[4:5], v[88:89], v[218:219]
	s_nop 0
	v_mul_f32_e32 v8, v5, v5
	v_pk_fma_f32 v[6:7], v[6:7], v[90:91], v[220:221]
	v_fmac_f32_e32 v8, v4, v4
	v_fmac_f32_e32 v8, v6, v6
	global_store_dwordx4 v[18:19], v[4:7], off offset:128
	v_fmac_f32_e32 v8, v7, v7
	v_add_f32_e32 v28, v32, v8
	v_pk_mul_f32 v[6:7], v[6:7], v[150:151]
	v_pk_mul_f32 v[4:5], v[4:5], v[148:149]
	v_pk_add_f32 v[8:9], v[182:183], 1.0 op_sel_hi:[1,0]
	v_pk_add_f32 v[10:11], v[180:181], 1.0 op_sel_hi:[1,0]
	v_pk_mul_f32 v[6:7], v[6:7], v[8:9]
	v_pk_mul_f32 v[4:5], v[4:5], v[10:11]
	v_and_b32_sdwa v8, v6, v170 dst_sel:DWORD dst_unused:UNUSED_PAD src0_sel:WORD_1 src1_sel:DWORD
	v_and_b32_sdwa v9, v4, v170 dst_sel:DWORD dst_unused:UNUSED_PAD src0_sel:WORD_1 src1_sel:DWORD
	v_add3_u32 v4, v4, v9, s56
	v_add3_u32 v6, v6, v8, s56
	v_and_b32_sdwa v8, v7, v170 dst_sel:DWORD dst_unused:UNUSED_PAD src0_sel:WORD_1 src1_sel:DWORD
	v_and_b32_sdwa v9, v5, v170 dst_sel:DWORD dst_unused:UNUSED_PAD src0_sel:WORD_1 src1_sel:DWORD
	v_add3_u32 v7, v7, v8, s56
	v_add3_u32 v5, v5, v9, s56
	v_and_b32_e32 v7, 0xffff0000, v7
	v_and_b32_e32 v8, 0xffff0000, v5
	v_or_b32_sdwa v5, v7, v6 dst_sel:DWORD dst_unused:UNUSED_PAD src0_sel:DWORD src1_sel:WORD_1
	v_or_b32_sdwa v4, v8, v4 dst_sel:DWORD dst_unused:UNUSED_PAD src0_sel:DWORD src1_sel:WORD_1
	global_store_dwordx2 v[16:17], v[4:5], off offset:64
	s_nop 0
	v_pk_fma_f32 v[0:1], v[0:1], v[136:137], v[222:223]
	s_nop 0
	v_mul_f32_e32 v4, v1, v1
	v_pk_fma_f32 v[2:3], v[2:3], v[138:139], v[224:225]
	v_fmac_f32_e32 v4, v0, v0
	v_fmac_f32_e32 v4, v2, v2
	global_store_dwordx4 v[18:19], v[0:3], off offset:192
	v_fmac_f32_e32 v4, v3, v3
	v_add_f32_e32 v18, v28, v4
	v_pk_mul_f32 v[2:3], v[2:3], v[154:155]
	v_pk_mul_f32 v[0:1], v[0:1], v[152:153]
	v_pk_add_f32 v[4:5], v[192:193], 1.0 op_sel_hi:[1,0]
	v_pk_add_f32 v[6:7], v[190:191], 1.0 op_sel_hi:[1,0]
	v_pk_mul_f32 v[2:3], v[2:3], v[4:5]
	v_pk_mul_f32 v[0:1], v[0:1], v[6:7]
	v_and_b32_sdwa v4, v2, v170 dst_sel:DWORD dst_unused:UNUSED_PAD src0_sel:WORD_1 src1_sel:DWORD
	v_and_b32_sdwa v5, v0, v170 dst_sel:DWORD dst_unused:UNUSED_PAD src0_sel:WORD_1 src1_sel:DWORD
	v_add3_u32 v0, v0, v5, s56
	v_add3_u32 v2, v2, v4, s56
	v_and_b32_sdwa v4, v3, v170 dst_sel:DWORD dst_unused:UNUSED_PAD src0_sel:WORD_1 src1_sel:DWORD
	v_and_b32_sdwa v5, v1, v170 dst_sel:DWORD dst_unused:UNUSED_PAD src0_sel:WORD_1 src1_sel:DWORD
	v_add3_u32 v3, v3, v4, s56
	v_add3_u32 v1, v1, v5, s56
	v_and_b32_e32 v3, 0xffff0000, v3
	v_and_b32_e32 v4, 0xffff0000, v1
	v_or_b32_sdwa v1, v3, v2 dst_sel:DWORD dst_unused:UNUSED_PAD src0_sel:DWORD src1_sel:WORD_1
	v_or_b32_sdwa v0, v4, v0 dst_sel:DWORD dst_unused:UNUSED_PAD src0_sel:DWORD src1_sel:WORD_1
	global_store_dwordx2 v[16:17], v[0:1], off offset:96
	ds_bpermute_b32 v0, v105, v18
	s_waitcnt lgkmcnt(0)
	v_add_f32_e32 v0, v18, v0
	ds_bpermute_b32 v1, v104, v0
	s_and_saveexec_b64 s[0:1], vcc
	s_movk_i32 s89, 0xff
	s_cbranch_execz .LBB0_614
	v_readlane_b32 s2, v253, 20
	s_add_u32 s2, s26, s2
	s_addc_u32 s3, s27, 0
	v_lshl_add_u64 v[2:3], v[12:13], 2, s[2:3]
	s_waitcnt lgkmcnt(0)
	v_add_f32_e32 v0, v0, v1
	global_store_dword v[2:3], v0, off
